# all GEMM 16-MFMA segments 8-byte aligned by deleting the redundant lgkmcnt(0) after s_setprio where parity required it
# speedup vs baseline: 1.0061x; 1.0061x over previous
; #define PG8_STAGE(bufoff, gbase, voff) do { _Pragma("unroll") for (int _i = 0; _i < 2; ++_i) \
;     __builtin_amdgcn_global_load_lds((const unsigned*)((const char*)(gbase) + (voff)[_i]), (PG8_LAS unsigned*)(lds + (bufoff) + ldsw + _i * 8192), 16, 0, 0); } while (0)
; #define PG8_LDA(dst, b, h) do { _Pragma("unroll") for (int m = 0; m < 4; ++m) _Pragma("unroll") for (int k = 0; k < 2; ++k) dst[m][k] = *(const PG8_LAS bf16x8*)(lds + PG8_SA(b, h) + aoff + m * 2048 + k * 1024); } while (0)
; #define PG8_LDB(dst, b, h) do { _Pragma("unroll") for (int n = 0; n < 2; ++n) _Pragma("unroll") for (int k = 0; k < 2; ++k) dst[n][k] = *(const PG8_LAS bf16x8*)(lds + PG8_SB(b, h) + boff + n * 2048 + k * 1024); } while (0)
; #define PG8_MMA(ai, bj, At, Bt) do { __builtin_amdgcn_s_setprio(1); _Pragma("unroll") for (int m = 0; m < 4; ++m) _Pragma("unroll") for (int n = 0; n < 2; ++n) _Pragma("unroll") for (int k = 0; k < 2; ++k) \
;     acc[ai][bj][m][n] = __builtin_amdgcn_mfma_f32_16x16x32_bf16(Bt[n][k], At[m][k], acc[ai][bj][m][n], 0, 0, 0); __builtin_amdgcn_s_setprio(0); } while (0)
; #define PG8_WAIT_L(n) asm volatile("s_waitcnt lgkmcnt(" #n ")" ::: "memory")
; #define PG8_BAR __builtin_amdgcn_s_barrier()
; #define PG8_SCHED __builtin_amdgcn_sched_barrier(0)
; template <class Epi>
; DI void gemm_phase(PG8_LAS unsigned char* lds, const Gemm g, const StaticOrder& S, const Epi& E, const int wv) {
;     ...
;       PG8_LDB(B0, 0, 0); PG8_SCHED; PG8_LDA(At, 0, 0); PG8_STAGE(PG8_SA(1, 1), a1 + hstep, voffA);
;       PG8_WAIT_L(8); PG8_BAR; PG8_WAIT_L(0); PG8_MMA(0, 0, At, B0); PG8_BAR; PG8_SCHED;
;       PG8_LDB(B1, 0, 1); PG8_STAGE(PG8_SB(0, 0), b2, voffB);
;       PG8_BAR; PG8_WAIT_L(0); PG8_MMA(0, 1, At, B1); PG8_BAR;
;       PG8_LDA(At, 0, 1); PG8_STAGE(PG8_SA(0, 0), a2, voffA);
;       PG8_BAR; PG8_WAIT_L(0); PG8_MMA(1, 0, At, B0); PG8_BAR; PG8_SCHED;
;       PG8_STAGE(PG8_SB(0, 1), b2 + hstep, voffB);
.LBB0_89:
	ds_read_b128 v[128:131], v165
	ds_read_b128 v[148:151], v165 offset:1024
	ds_read_b128 v[152:155], v165 offset:2048
	ds_read_b128 v[156:159], v165 offset:3072
	s_add_u32 s8, s6, 0xfffc0080
	s_addc_u32 s9, s7, -1
	s_cmp_eq_u32 s49, 12
	s_cselect_b32 s43, s19, s9
	s_cselect_b32 s42, s44, s8
	s_cselect_b32 s9, s17, s47
	s_cselect_b32 s8, s45, s46
	v_lshl_add_u64 v[202:203], s[6:7], 0, v[142:143]
	s_add_i32 m0, s62, 0xc000
	ds_read_b128 v[170:173], v166
	ds_read_b128 v[174:177], v166 offset:1024
	ds_read_b128 v[178:181], v166 offset:2048
	ds_read_b128 v[182:185], v166 offset:3072
	ds_read_b128 v[186:189], v166 offset:4096
	ds_read_b128 v[190:193], v166 offset:5120
	ds_read_b128 v[194:197], v166 offset:6144
	ds_read_b128 v[198:201], v166 offset:7168
	global_load_lds_dwordx4 v[202:203], off
	v_lshl_add_u64 v[202:203], s[6:7], 0, v[144:145]
	s_add_i32 m0, s62, 0xe000
	s_nop 0
	global_load_lds_dwordx4 v[202:203], off
	s_waitcnt lgkmcnt(8)
	s_barrier
	s_waitcnt lgkmcnt(0)
	s_setprio 1
	s_waitcnt lgkmcnt(0)
	v_mfma_f32_16x16x32_bf16 v[124:127], v[128:131], v[170:173], v[124:127]
	v_mfma_f32_16x16x32_bf16 v[120:123], v[152:155], v[170:173], v[120:123]
	v_mfma_f32_16x16x32_bf16 v[108:111], v[128:131], v[178:181], v[108:111]
	v_mfma_f32_16x16x32_bf16 v[104:107], v[152:155], v[178:181], v[104:107]
	v_mfma_f32_16x16x32_bf16 v[92:95], v[128:131], v[186:189], v[92:95]
	v_mfma_f32_16x16x32_bf16 v[88:91], v[152:155], v[186:189], v[88:91]
	v_mfma_f32_16x16x32_bf16 v[76:79], v[128:131], v[194:197], v[76:79]
	v_mfma_f32_16x16x32_bf16 v[72:75], v[152:155], v[194:197], v[72:75]
	v_mfma_f32_16x16x32_bf16 v[124:127], v[148:151], v[174:177], v[124:127]
	v_mfma_f32_16x16x32_bf16 v[120:123], v[156:159], v[174:177], v[120:123]
	v_mfma_f32_16x16x32_bf16 v[108:111], v[148:151], v[182:185], v[108:111]
	v_mfma_f32_16x16x32_bf16 v[104:107], v[156:159], v[182:185], v[104:107]
	v_mfma_f32_16x16x32_bf16 v[92:95], v[148:151], v[190:193], v[92:95]
	v_mfma_f32_16x16x32_bf16 v[88:91], v[156:159], v[190:193], v[88:91]
	v_mfma_f32_16x16x32_bf16 v[76:79], v[148:151], v[198:201], v[76:79]
	v_mfma_f32_16x16x32_bf16 v[72:75], v[156:159], v[198:201], v[72:75]
	s_setprio 0
	s_barrier
	s_add_i32 s50, s73, s61
	v_lshl_add_u64 v[220:221], s[8:9], 0, v[134:135]
	s_mov_b32 m0, s50
	ds_read_b128 v[202:205], v167
	ds_read_b128 v[206:209], v167 offset:1024
	ds_read_b128 v[210:213], v167 offset:2048
	ds_read_b128 v[214:217], v167 offset:3072
	global_load_lds_dwordx4 v[220:221], off
	v_lshl_add_u64 v[222:223], s[8:9], 0, v[138:139]
	s_add_i32 m0, s50, 0x2000
	s_nop 0
	global_load_lds_dwordx4 v[222:223], off
	s_barrier
	s_waitcnt lgkmcnt(0)
	s_setprio 1
	v_mfma_f32_16x16x32_bf16 v[116:119], v[202:205], v[170:173], v[116:119]
	v_mfma_f32_16x16x32_bf16 v[112:115], v[210:213], v[170:173], v[112:115]
	v_mfma_f32_16x16x32_bf16 v[100:103], v[202:205], v[178:181], v[100:103]
	v_mfma_f32_16x16x32_bf16 v[96:99], v[210:213], v[178:181], v[96:99]
	v_mfma_f32_16x16x32_bf16 v[84:87], v[202:205], v[186:189], v[84:87]
	v_mfma_f32_16x16x32_bf16 v[80:83], v[210:213], v[186:189], v[80:83]
	v_mfma_f32_16x16x32_bf16 v[68:71], v[202:205], v[194:197], v[68:71]
	v_mfma_f32_16x16x32_bf16 v[64:67], v[210:213], v[194:197], v[64:67]
	v_mfma_f32_16x16x32_bf16 v[116:119], v[206:209], v[174:177], v[116:119]
	v_mfma_f32_16x16x32_bf16 v[112:115], v[214:217], v[174:177], v[112:115]
	v_mfma_f32_16x16x32_bf16 v[100:103], v[206:209], v[182:185], v[100:103]
	v_mfma_f32_16x16x32_bf16 v[96:99], v[214:217], v[182:185], v[96:99]
	v_mfma_f32_16x16x32_bf16 v[84:87], v[206:209], v[190:193], v[84:87]
	v_mfma_f32_16x16x32_bf16 v[80:83], v[214:217], v[190:193], v[80:83]
	v_mfma_f32_16x16x32_bf16 v[68:71], v[206:209], v[198:201], v[68:71]
	v_mfma_f32_16x16x32_bf16 v[64:67], v[214:217], v[198:201], v[64:67]
	s_setprio 0
	s_mov_b32 m0, s62
	v_lshl_add_u64 v[224:225], s[42:43], 0, v[132:133]
	s_barrier
	ds_read_b128 v[170:173], v166 offset:16384
	ds_read_b128 v[174:177], v166 offset:17408
	ds_read_b128 v[178:181], v166 offset:18432
	ds_read_b128 v[182:185], v166 offset:19456
	ds_read_b128 v[186:189], v166 offset:20480
	ds_read_b128 v[190:193], v166 offset:21504
	ds_read_b128 v[194:197], v166 offset:22528
	ds_read_b128 v[198:201], v166 offset:23552
	global_load_lds_dwordx4 v[224:225], off
	v_lshl_add_u64 v[226:227], s[42:43], 0, v[136:137]
	s_mov_b32 m0, s63
	s_nop 0
	global_load_lds_dwordx4 v[226:227], off
	s_barrier
	s_waitcnt lgkmcnt(0)
	s_setprio 1
	v_mfma_f32_16x16x32_bf16 v[60:63], v[128:131], v[170:173], v[60:63]
	v_mfma_f32_16x16x32_bf16 v[56:59], v[152:155], v[170:173], v[56:59]
	v_mfma_f32_16x16x32_bf16 v[44:47], v[128:131], v[178:181], v[44:47]
	v_mfma_f32_16x16x32_bf16 v[40:43], v[152:155], v[178:181], v[40:43]
	v_mfma_f32_16x16x32_bf16 v[28:31], v[128:131], v[186:189], v[28:31]
	v_mfma_f32_16x16x32_bf16 v[24:27], v[152:155], v[186:189], v[24:27]
	v_mfma_f32_16x16x32_bf16 v[12:15], v[128:131], v[194:197], v[12:15]
	v_mfma_f32_16x16x32_bf16 v[8:11], v[152:155], v[194:197], v[8:11]
	v_mfma_f32_16x16x32_bf16 v[60:63], v[148:151], v[174:177], v[60:63]
	v_mfma_f32_16x16x32_bf16 v[56:59], v[156:159], v[174:177], v[56:59]
	v_mfma_f32_16x16x32_bf16 v[44:47], v[148:151], v[182:185], v[44:47]
	v_mfma_f32_16x16x32_bf16 v[40:43], v[156:159], v[182:185], v[40:43]
	v_mfma_f32_16x16x32_bf16 v[28:31], v[148:151], v[190:193], v[28:31]
	v_mfma_f32_16x16x32_bf16 v[24:27], v[156:159], v[190:193], v[24:27]
	v_mfma_f32_16x16x32_bf16 v[12:15], v[148:151], v[198:201], v[12:15]
	v_mfma_f32_16x16x32_bf16 v[8:11], v[156:159], v[198:201], v[8:11]
	s_setprio 0
	s_barrier
; #define PG8_STAGE(bufoff, gbase, voff) do { _Pragma("unroll") for (int _i = 0; _i < 2; ++_i) \
;     __builtin_amdgcn_global_load_lds((const unsigned*)((const char*)(gbase) + (voff)[_i]), (PG8_LAS unsigned*)(lds + (bufoff) + ldsw + _i * 8192), 16, 0, 0); } while (0)
; #define PG8_LDA(dst, b, h) do { _Pragma("unroll") for (int m = 0; m < 4; ++m) _Pragma("unroll") for (int k = 0; k < 2; ++k) dst[m][k] = *(const PG8_LAS bf16x8*)(lds + PG8_SA(b, h) + aoff + m * 2048 + k * 1024); } while (0)
; #define PG8_LDB(dst, b, h) do { _Pragma("unroll") for (int n = 0; n < 2; ++n) _Pragma("unroll") for (int k = 0; k < 2; ++k) dst[n][k] = *(const PG8_LAS bf16x8*)(lds + PG8_SB(b, h) + boff + n * 2048 + k * 1024); } while (0)
; #define PG8_MMA(ai, bj, At, Bt) do { __builtin_amdgcn_s_setprio(1); _Pragma("unroll") for (int m = 0; m < 4; ++m) _Pragma("unroll") for (int n = 0; n < 2; ++n) _Pragma("unroll") for (int k = 0; k < 2; ++k) \
;     acc[ai][bj][m][n] = __builtin_amdgcn_mfma_f32_16x16x32_bf16(Bt[n][k], At[m][k], acc[ai][bj][m][n], 0, 0, 0); __builtin_amdgcn_s_setprio(0); } while (0)
; #define PG8_WAIT_V(n) asm volatile("s_waitcnt vmcnt(" #n ")" ::: "memory")
; #define PG8_WAIT_L(n) asm volatile("s_waitcnt lgkmcnt(" #n ")" ::: "memory")
; #define PG8_BAR __builtin_amdgcn_s_barrier()
; #define PG8_SCHED __builtin_amdgcn_sched_barrier(0)
; template <class Epi>
; DI void gemm_phase(PG8_LAS unsigned char* lds, const Gemm g, const StaticOrder& S, const Epi& E, const int wv) {
;     ...
;       PG8_STAGE(PG8_SB(0, 1), b2 + hstep, voffB);
;       PG8_WAIT_V(6); PG8_BAR; PG8_MMA(1, 1, At, B1); PG8_BAR;
;       PG8_LDB(B0, 1, 0); PG8_SCHED; PG8_LDA(At, 1, 0); PG8_STAGE(PG8_SA(0, 1), a2 + hstep, voffA);
;       PG8_WAIT_L(8); PG8_BAR; PG8_WAIT_L(0); PG8_MMA(0, 0, At, B0); PG8_BAR; PG8_SCHED;
;       PG8_LDB(B1, 1, 1); PG8_STAGE(PG8_SB(1, 0), b3, voffB);
	s_add_u32 s50, s8, 0x40000
	s_addc_u32 s51, s9, 0
	s_add_i32 s52, s74, s61
	v_lshl_add_u64 v[128:129], s[50:51], 0, v[134:135]
	s_mov_b32 m0, s52
	s_nop 0
	global_load_lds_dwordx4 v[128:129], off
	v_lshl_add_u64 v[128:129], s[50:51], 0, v[138:139]
	s_add_i32 m0, s52, 0x2000
	s_nop 0
	global_load_lds_dwordx4 v[128:129], off
	s_waitcnt vmcnt(6)
	s_barrier
	s_setprio 1
	v_mfma_f32_16x16x32_bf16 v[52:55], v[202:205], v[170:173], v[52:55]
	v_mfma_f32_16x16x32_bf16 v[48:51], v[210:213], v[170:173], v[48:51]
	v_mfma_f32_16x16x32_bf16 v[36:39], v[202:205], v[178:181], v[36:39]
	v_mfma_f32_16x16x32_bf16 v[32:35], v[210:213], v[178:181], v[32:35]
	v_mfma_f32_16x16x32_bf16 v[20:23], v[202:205], v[186:189], v[20:23]
	v_mfma_f32_16x16x32_bf16 v[16:19], v[210:213], v[186:189], v[16:19]
	v_mfma_f32_16x16x32_bf16 v[4:7], v[202:205], v[194:197], v[4:7]
	v_mfma_f32_16x16x32_bf16 v[0:3], v[210:213], v[194:197], v[0:3]
	v_mfma_f32_16x16x32_bf16 v[52:55], v[206:209], v[174:177], v[52:55]
	v_mfma_f32_16x16x32_bf16 v[48:51], v[214:217], v[174:177], v[48:51]
	v_mfma_f32_16x16x32_bf16 v[36:39], v[206:209], v[182:185], v[36:39]
	v_mfma_f32_16x16x32_bf16 v[32:35], v[214:217], v[182:185], v[32:35]
	v_mfma_f32_16x16x32_bf16 v[20:23], v[206:209], v[190:193], v[20:23]
	v_mfma_f32_16x16x32_bf16 v[16:19], v[214:217], v[190:193], v[16:19]
	v_mfma_f32_16x16x32_bf16 v[4:7], v[206:209], v[198:201], v[4:7]
	v_mfma_f32_16x16x32_bf16 v[0:3], v[214:217], v[198:201], v[0:3]
	s_setprio 0
	s_add_i32 s50, 0, 0x18000
	v_add_u32_e32 v140, s50, v163
	s_barrier
	ds_read_b128 v[128:131], v140
	ds_read_b128 v[148:151], v140 offset:1024
	ds_read_b128 v[152:155], v140 offset:2048
	ds_read_b128 v[156:159], v140 offset:3072
	s_add_u32 s42, s42, 0x40000
	s_addc_u32 s43, s43, 0
	s_mov_b32 m0, s64
	v_lshl_add_u64 v[202:203], s[42:43], 0, v[132:133]
	ds_read_b128 v[170:173], v166 offset:32768
	ds_read_b128 v[174:177], v166 offset:33792
	ds_read_b128 v[178:181], v166 offset:34816
	ds_read_b128 v[182:185], v166 offset:35840
	ds_read_b128 v[186:189], v166 offset:36864
	ds_read_b128 v[190:193], v166 offset:37888
	ds_read_b128 v[194:197], v166 offset:38912
	ds_read_b128 v[198:201], v166 offset:39936
	global_load_lds_dwordx4 v[202:203], off
	v_lshl_add_u64 v[202:203], s[42:43], 0, v[136:137]
	s_mov_b32 m0, s65
	s_nop 0
	global_load_lds_dwordx4 v[202:203], off
	s_waitcnt lgkmcnt(8)
	s_barrier
	s_waitcnt lgkmcnt(0)
	s_setprio 1
	s_waitcnt lgkmcnt(0)
	v_mfma_f32_16x16x32_bf16 v[124:127], v[128:131], v[170:173], v[124:127]
	v_mfma_f32_16x16x32_bf16 v[120:123], v[152:155], v[170:173], v[120:123]
	v_mfma_f32_16x16x32_bf16 v[108:111], v[128:131], v[178:181], v[108:111]
	v_mfma_f32_16x16x32_bf16 v[104:107], v[152:155], v[178:181], v[104:107]
	v_mfma_f32_16x16x32_bf16 v[92:95], v[128:131], v[186:189], v[92:95]
	v_mfma_f32_16x16x32_bf16 v[88:91], v[152:155], v[186:189], v[88:91]
	v_mfma_f32_16x16x32_bf16 v[76:79], v[128:131], v[194:197], v[76:79]
	v_mfma_f32_16x16x32_bf16 v[72:75], v[152:155], v[194:197], v[72:75]
	v_mfma_f32_16x16x32_bf16 v[124:127], v[148:151], v[174:177], v[124:127]
	v_mfma_f32_16x16x32_bf16 v[120:123], v[156:159], v[174:177], v[120:123]
	v_mfma_f32_16x16x32_bf16 v[108:111], v[148:151], v[182:185], v[108:111]
	v_mfma_f32_16x16x32_bf16 v[104:107], v[156:159], v[182:185], v[104:107]
	v_mfma_f32_16x16x32_bf16 v[92:95], v[148:151], v[190:193], v[92:95]
	v_mfma_f32_16x16x32_bf16 v[88:91], v[156:159], v[190:193], v[88:91]
	v_mfma_f32_16x16x32_bf16 v[76:79], v[148:151], v[198:201], v[76:79]
	v_mfma_f32_16x16x32_bf16 v[72:75], v[156:159], v[198:201], v[72:75]
	s_setprio 0
	s_barrier
	s_add_i32 s42, 0, 0x1c000
	s_add_i32 s43, s50, s61
	v_add_u32_e32 v140, s42, v163
	v_lshl_add_u64 v[220:221], v[220:221], 0, s[34:35]
	s_mov_b32 m0, s43
	ds_read_b128 v[202:205], v140
	ds_read_b128 v[206:209], v140 offset:1024
	ds_read_b128 v[210:213], v140 offset:2048
	ds_read_b128 v[214:217], v140 offset:3072
	global_load_lds_dwordx4 v[220:221], off
	v_lshl_add_u64 v[220:221], v[222:223], 0, s[34:35]
	s_add_i32 m0, s43, 0x2000
	s_nop 0
	global_load_lds_dwordx4 v[220:221], off
	s_barrier
	s_waitcnt lgkmcnt(0)
	s_setprio 1
	s_waitcnt lgkmcnt(0)
	v_mfma_f32_16x16x32_bf16 v[116:119], v[202:205], v[170:173], v[116:119]
	v_mfma_f32_16x16x32_bf16 v[112:115], v[210:213], v[170:173], v[112:115]
	v_mfma_f32_16x16x32_bf16 v[100:103], v[202:205], v[178:181], v[100:103]
	v_mfma_f32_16x16x32_bf16 v[96:99], v[210:213], v[178:181], v[96:99]
	v_mfma_f32_16x16x32_bf16 v[84:87], v[202:205], v[186:189], v[84:87]
	v_mfma_f32_16x16x32_bf16 v[80:83], v[210:213], v[186:189], v[80:83]
	v_mfma_f32_16x16x32_bf16 v[68:71], v[202:205], v[194:197], v[68:71]
	v_mfma_f32_16x16x32_bf16 v[64:67], v[210:213], v[194:197], v[64:67]
	v_mfma_f32_16x16x32_bf16 v[116:119], v[206:209], v[174:177], v[116:119]
	v_mfma_f32_16x16x32_bf16 v[112:115], v[214:217], v[174:177], v[112:115]
	v_mfma_f32_16x16x32_bf16 v[100:103], v[206:209], v[182:185], v[100:103]
	v_mfma_f32_16x16x32_bf16 v[96:99], v[214:217], v[182:185], v[96:99]
	v_mfma_f32_16x16x32_bf16 v[84:87], v[206:209], v[190:193], v[84:87]
	v_mfma_f32_16x16x32_bf16 v[80:83], v[214:217], v[190:193], v[80:83]
	v_mfma_f32_16x16x32_bf16 v[68:71], v[206:209], v[198:201], v[68:71]
	v_mfma_f32_16x16x32_bf16 v[64:67], v[214:217], v[198:201], v[64:67]
	s_setprio 0
	s_mov_b32 m0, s68
	v_lshl_add_u64 v[220:221], v[224:225], 0, s[34:35]
	s_barrier
; #define PG8_STAGE(bufoff, gbase, voff) do { _Pragma("unroll") for (int _i = 0; _i < 2; ++_i) \
;     __builtin_amdgcn_global_load_lds((const unsigned*)((const char*)(gbase) + (voff)[_i]), (PG8_LAS unsigned*)(lds + (bufoff) + ldsw + _i * 8192), 16, 0, 0); } while (0)
; #define PG8_BAR __builtin_amdgcn_s_barrier()
; template <class Epi>
; DI void gemm_phase(PG8_LAS unsigned char* lds, const Gemm g, const StaticOrder& S, const Epi& E, const int wv) {
;     ...
;       PG8_BAR; PG8_WAIT_L(0); PG8_MMA(0, 1, At, B1); PG8_BAR;
;       PG8_LDA(At, 1, 1); PG8_STAGE(PG8_SA(1, 0), a3, voffA);
;       PG8_BAR; PG8_WAIT_L(0); PG8_MMA(1, 0, At, B0); PG8_BAR; PG8_SCHED;
;       PG8_STAGE(PG8_SB(1, 1), b3 + hstep, voffB);
;       PG8_WAIT_V(6); PG8_BAR; PG8_MMA(1, 1, At, B1); PG8_BAR;
;     }
;     E(acc, cur, wr, wc, fr, fq);
;   DI void operator()(AccRef acc, const pg8::Unit& u, int wr, int wc, int fr, int fq) const {
;     ...
;         if (u.pn < 5) {
;           const int col0 = u.pn * 256 + wc * 32 + 8 * fq;
;           float s2q = 0.f, s2kv = 0.f;
; #pragma unroll
;           for (int bj = 0; bj < 2; ++bj) {
;             const int col = col0 + bj * 128;
;             if (col < 1216) {
;               const f32x4 v0 = acc[ai][bj][m][0], v1 = acc[ai][bj][m][1];
;               const u32x4 w = pack8v(v0, v1);
;               const float s2 = v0[0] * v0[0] + v0[1] * v0[1] + v0[2] * v0[2] + v0[3] * v0[3] + v1[0] * v1[0] + v1[1] * v1[1] + v1[2] * v1[2] + v1[3] * v1[3];
;               if (col < 384)      { *(u32x4*)(cq + (size_t)row * 384 + col) = w; s2q += s2; }
;               else if (col < 640) { *(u32x4*)(ckv + (size_t)row * 256 + (col - 384)) = w; s2kv += s2; }
;               else if (col < 704) { *(u32x4*)(kr + (size_t)row * 64 + (col - 640)) = w; }
;               else                { *(u32x4*)(rp + col) = w; }
;             }
;           }
;           if (u.pn <= 2) {
;             s2q += __shfl_xor(s2q, 16); s2q += __shfl_xor(s2q, 32);
;             s2kv += __shfl_xor(s2kv, 16); s2kv += __shfl_xor(s2kv, 32);
;             if (fq == 0 && u.pn <= 1) atomicAdd(ssq_ + row, s2q);
;             if (fq == 0 && u.pn >= 1) atomicAdd(sskv_ + row, s2kv);
;           }
;         } else {
;           const int col0 = 1216 + (u.pn - 5) * 128 + wc * 32 + 8 * fq;
;           *(u32x4*)(rp + col0) = pack8v(acc[ai][0][m][0] * acc[ai][1][m][0], acc[ai][0][m][1] * acc[ai][1][m][1]);
	ds_read_b128 v[170:173], v166 offset:49152
	ds_read_b128 v[174:177], v166 offset:50176
	ds_read_b128 v[178:181], v166 offset:51200
	ds_read_b128 v[182:185], v166 offset:52224
	ds_read_b128 v[186:189], v166 offset:53248
	ds_read_b128 v[190:193], v166 offset:54272
	ds_read_b128 v[194:197], v166 offset:55296
	ds_read_b128 v[198:201], v166 offset:56320
	global_load_lds_dwordx4 v[220:221], off
	v_lshl_add_u64 v[220:221], v[226:227], 0, s[34:35]
	s_mov_b32 m0, s69
	s_nop 0
	global_load_lds_dwordx4 v[220:221], off
	s_barrier
	s_waitcnt lgkmcnt(0)
	s_setprio 1
	v_mfma_f32_16x16x32_bf16 v[60:63], v[128:131], v[170:173], v[60:63]
	v_mfma_f32_16x16x32_bf16 v[56:59], v[152:155], v[170:173], v[56:59]
	v_mfma_f32_16x16x32_bf16 v[44:47], v[128:131], v[178:181], v[44:47]
	v_mfma_f32_16x16x32_bf16 v[40:43], v[152:155], v[178:181], v[40:43]
	v_mfma_f32_16x16x32_bf16 v[28:31], v[128:131], v[186:189], v[28:31]
	v_mfma_f32_16x16x32_bf16 v[24:27], v[152:155], v[186:189], v[24:27]
	v_mfma_f32_16x16x32_bf16 v[12:15], v[128:131], v[194:197], v[12:15]
	v_mfma_f32_16x16x32_bf16 v[8:11], v[152:155], v[194:197], v[8:11]
	v_mfma_f32_16x16x32_bf16 v[60:63], v[148:151], v[174:177], v[60:63]
	v_mfma_f32_16x16x32_bf16 v[56:59], v[156:159], v[174:177], v[56:59]
	v_mfma_f32_16x16x32_bf16 v[44:47], v[148:151], v[182:185], v[44:47]
	v_mfma_f32_16x16x32_bf16 v[40:43], v[156:159], v[182:185], v[40:43]
	v_mfma_f32_16x16x32_bf16 v[28:31], v[148:151], v[190:193], v[28:31]
	v_mfma_f32_16x16x32_bf16 v[24:27], v[156:159], v[190:193], v[24:27]
	v_mfma_f32_16x16x32_bf16 v[12:15], v[148:151], v[198:201], v[12:15]
	v_mfma_f32_16x16x32_bf16 v[8:11], v[156:159], v[198:201], v[8:11]
	s_setprio 0
	s_barrier
	s_add_u32 s8, s8, 0x40080
	s_addc_u32 s9, s9, 0
	s_add_i32 s42, s42, s61
	v_lshl_add_u64 v[128:129], s[8:9], 0, v[134:135]
	s_mov_b32 m0, s42
	s_nop 0
	global_load_lds_dwordx4 v[128:129], off
	v_lshl_add_u64 v[128:129], s[8:9], 0, v[138:139]
	s_add_i32 m0, s42, 0x2000
	s_nop 0
	global_load_lds_dwordx4 v[128:129], off
	s_waitcnt vmcnt(6)
	s_barrier
	s_setprio 1
	v_mfma_f32_16x16x32_bf16 v[52:55], v[202:205], v[170:173], v[52:55]
	v_mfma_f32_16x16x32_bf16 v[48:51], v[210:213], v[170:173], v[48:51]
	v_mfma_f32_16x16x32_bf16 v[36:39], v[202:205], v[178:181], v[36:39]
	v_mfma_f32_16x16x32_bf16 v[32:35], v[210:213], v[178:181], v[32:35]
	v_mfma_f32_16x16x32_bf16 v[20:23], v[202:205], v[186:189], v[20:23]
	v_mfma_f32_16x16x32_bf16 v[16:19], v[210:213], v[186:189], v[16:19]
	v_mfma_f32_16x16x32_bf16 v[4:7], v[202:205], v[194:197], v[4:7]
	v_mfma_f32_16x16x32_bf16 v[0:3], v[210:213], v[194:197], v[0:3]
	v_mfma_f32_16x16x32_bf16 v[52:55], v[206:209], v[174:177], v[52:55]
	v_mfma_f32_16x16x32_bf16 v[48:51], v[214:217], v[174:177], v[48:51]
	v_mfma_f32_16x16x32_bf16 v[36:39], v[206:209], v[182:185], v[36:39]
	v_mfma_f32_16x16x32_bf16 v[32:35], v[214:217], v[182:185], v[32:35]
	v_mfma_f32_16x16x32_bf16 v[20:23], v[206:209], v[190:193], v[20:23]
	v_mfma_f32_16x16x32_bf16 v[16:19], v[214:217], v[190:193], v[16:19]
	v_mfma_f32_16x16x32_bf16 v[4:7], v[206:209], v[198:201], v[4:7]
	v_mfma_f32_16x16x32_bf16 v[0:3], v[214:217], v[198:201], v[0:3]
	s_setprio 0
	s_add_i32 s49, s49, 2
	s_add_u32 s6, s6, 0x100
	s_addc_u32 s7, s7, 0
	s_add_u32 s46, s46, 0x100
	s_addc_u32 s47, s47, 0
	s_cmp_gt_u32 s49, 13
	s_barrier
	s_cbranch_scc0 .LBB0_89
	s_cmp_gt_i32 s48, 4
	s_cselect_b64 s[8:9], -1, 0
	s_lshl_b32 s19, s48, 8
	s_or_b32 s17, s19, s67
	s_cmp_lt_i32 s48, 3
	s_cselect_b64 s[46:47], -1, 0
	s_cmp_lg_u32 s48, 2
	s_cselect_b64 s[6:7], -1, 0
	s_and_b64 s[44:45], s[4:5], s[6:7]
	s_cmp_gt_i32 s48, 0
	s_cselect_b64 s[6:7], -1, 0
	s_and_b64 s[42:43], s[4:5], s[6:7]
	v_lshl_add_u32 v150, s81, 8, v161
	v_lshl_add_u32 v140, s48, 7, v164
	s_cmpk_gt_i32 s81, 0x181
	v_or_b32_e32 v148, s17, v162
	s_cbranch_scc1 .LBB0_239
	v_mov_b64_e32 v[128:129], s[20:21]
	v_mad_i64_i32 v[152:153], s[6:7], v150, s75, v[128:129]
	s_mov_b64 s[6:7], -1
	s_and_b64 vcc, exec, s[8:9]
	s_cbranch_vccz .LBB0_93
	v_pk_mul_f32 v[130:131], v[126:127], v[118:119]
	v_pk_mul_f32 v[128:129], v[124:125], v[116:117]
	v_pk_mul_f32 v[154:155], v[122:123], v[114:115]
	v_pk_mul_f32 v[156:157], v[120:121], v[112:113]
	v_cvt_pk_bf16_f32 v128, v128, v129
	v_cvt_pk_bf16_f32 v129, v130, v131
	v_cvt_pk_bf16_f32 v130, v156, v157
	v_cvt_pk_bf16_f32 v131, v154, v155
	v_lshl_add_u64 v[154:155], v[140:141], 1, v[152:153]
	global_store_dwordx4 v[154:155], v[128:131], off
	s_mov_b64 s[6:7], 0

; #define PG8_STAGE(bufoff, gbase, voff) do { _Pragma("unroll") for (int _i = 0; _i < 2; ++_i) \
;     __builtin_amdgcn_global_load_lds((const unsigned*)((const char*)(gbase) + (voff)[_i]), (PG8_LAS unsigned*)(lds + (bufoff) + ldsw + _i * 8192), 16, 0, 0); } while (0)
; #define PG8_LDA(dst, b, h) do { _Pragma("unroll") for (int m = 0; m < 4; ++m) _Pragma("unroll") for (int k = 0; k < 2; ++k) dst[m][k] = *(const PG8_LAS bf16x8*)(lds + PG8_SA(b, h) + aoff + m * 2048 + k * 1024); } while (0)
; #define PG8_LDB(dst, b, h) do { _Pragma("unroll") for (int n = 0; n < 2; ++n) _Pragma("unroll") for (int k = 0; k < 2; ++k) dst[n][k] = *(const PG8_LAS bf16x8*)(lds + PG8_SB(b, h) + boff + n * 2048 + k * 1024); } while (0)
; #define PG8_MMA(ai, bj, At, Bt) do { __builtin_amdgcn_s_setprio(1); _Pragma("unroll") for (int m = 0; m < 4; ++m) _Pragma("unroll") for (int n = 0; n < 2; ++n) _Pragma("unroll") for (int k = 0; k < 2; ++k) \
;     acc[ai][bj][m][n] = __builtin_amdgcn_mfma_f32_16x16x32_bf16(Bt[n][k], At[m][k], acc[ai][bj][m][n], 0, 0, 0); __builtin_amdgcn_s_setprio(0); } while (0)
; #define PG8_WAIT_L(n) asm volatile("s_waitcnt lgkmcnt(" #n ")" ::: "memory")
; #define PG8_BAR __builtin_amdgcn_s_barrier()
; #define PG8_SCHED __builtin_amdgcn_sched_barrier(0)
; template <class Epi>
; DI void gemm_phase(PG8_LAS unsigned char* lds, const Gemm g, const StaticOrder& S, const Epi& E, const int wv) {
;     ...
;       PG8_LDB(B0, 0, 0); PG8_SCHED; PG8_LDA(At, 0, 0); PG8_STAGE(PG8_SA(1, 1), a1 + hstep, voffA);
;       PG8_WAIT_L(8); PG8_BAR; PG8_WAIT_L(0); PG8_MMA(0, 0, At, B0); PG8_BAR; PG8_SCHED;
;       PG8_LDB(B1, 0, 1); PG8_STAGE(PG8_SB(0, 0), b2, voffB);
;       PG8_BAR; PG8_WAIT_L(0); PG8_MMA(0, 1, At, B1); PG8_BAR;
;       PG8_LDA(At, 0, 1); PG8_STAGE(PG8_SA(0, 0), a2, voffA);
;       PG8_BAR; PG8_WAIT_L(0); PG8_MMA(1, 0, At, B0); PG8_BAR; PG8_SCHED;
;       PG8_STAGE(PG8_SB(0, 1), b2 + hstep, voffB);
.LBB0_521:
	ds_read_b128 v[142:145], v149
	ds_read_b128 v[154:157], v149 offset:1024
	ds_read_b128 v[162:165], v149 offset:2048
	ds_read_b128 v[166:169], v149 offset:3072
	s_add_u32 s4, s6, 0x100
	s_addc_u32 s5, s7, 0
	s_cmp_eq_u32 s58, 2
	s_cselect_b32 s27, s23, s5
	s_cselect_b32 s26, s22, s4
	s_cselect_b32 s9, s25, s57
	s_cselect_b32 s8, s24, s55
	v_lshl_add_u64 v[158:159], s[6:7], 0, v[136:137]
	s_add_i32 m0, s38, 0xc000
	ds_read_b128 v[170:173], v150
	ds_read_b128 v[174:177], v150 offset:1024
	ds_read_b128 v[178:181], v150 offset:2048
	ds_read_b128 v[182:185], v150 offset:3072
	ds_read_b128 v[186:189], v150 offset:4096
	ds_read_b128 v[190:193], v150 offset:5120
	ds_read_b128 v[194:197], v150 offset:6144
	ds_read_b128 v[198:201], v150 offset:7168
	global_load_lds_dwordx4 v[158:159], off
	v_lshl_add_u64 v[158:159], s[6:7], 0, v[138:139]
	s_add_i32 m0, s38, 0xe000
	s_nop 0
	global_load_lds_dwordx4 v[158:159], off
	s_waitcnt lgkmcnt(8)
	s_barrier
	s_waitcnt lgkmcnt(0)
	s_setprio 1
	s_waitcnt lgkmcnt(0)
	v_mfma_f32_16x16x32_bf16 v[124:127], v[142:145], v[170:173], v[124:127]
	v_mfma_f32_16x16x32_bf16 v[120:123], v[162:165], v[170:173], v[120:123]
	v_mfma_f32_16x16x32_bf16 v[116:119], v[142:145], v[178:181], v[116:119]
	v_mfma_f32_16x16x32_bf16 v[112:115], v[162:165], v[178:181], v[112:115]
	v_mfma_f32_16x16x32_bf16 v[100:103], v[142:145], v[186:189], v[100:103]
	v_mfma_f32_16x16x32_bf16 v[96:99], v[162:165], v[186:189], v[96:99]
	v_mfma_f32_16x16x32_bf16 v[84:87], v[142:145], v[194:197], v[84:87]
	v_mfma_f32_16x16x32_bf16 v[76:79], v[162:165], v[194:197], v[76:79]
	v_mfma_f32_16x16x32_bf16 v[124:127], v[154:157], v[174:177], v[124:127]
	v_mfma_f32_16x16x32_bf16 v[120:123], v[166:169], v[174:177], v[120:123]
	v_mfma_f32_16x16x32_bf16 v[116:119], v[154:157], v[182:185], v[116:119]
	v_mfma_f32_16x16x32_bf16 v[112:115], v[166:169], v[182:185], v[112:115]
	v_mfma_f32_16x16x32_bf16 v[100:103], v[154:157], v[190:193], v[100:103]
	v_mfma_f32_16x16x32_bf16 v[96:99], v[166:169], v[190:193], v[96:99]
	v_mfma_f32_16x16x32_bf16 v[84:87], v[154:157], v[198:201], v[84:87]
	v_mfma_f32_16x16x32_bf16 v[76:79], v[166:169], v[198:201], v[76:79]
	s_setprio 0
	s_barrier
	s_add_i32 s6, s47, s37
	v_lshl_add_u64 v[158:159], s[8:9], 0, v[130:131]
	s_mov_b32 m0, s6
	ds_read_b128 v[202:205], v151
	ds_read_b128 v[206:209], v151 offset:1024
	ds_read_b128 v[210:213], v151 offset:2048
	ds_read_b128 v[214:217], v151 offset:3072
	global_load_lds_dwordx4 v[158:159], off
	v_lshl_add_u64 v[220:221], s[8:9], 0, v[134:135]
	s_add_i32 m0, s6, 0x2000
	s_nop 0
	global_load_lds_dwordx4 v[220:221], off
	s_barrier
	s_waitcnt lgkmcnt(0)
	s_setprio 1
	v_mfma_f32_16x16x32_bf16 v[108:111], v[202:205], v[170:173], v[108:111]
	v_mfma_f32_16x16x32_bf16 v[104:107], v[210:213], v[170:173], v[104:107]
	v_mfma_f32_16x16x32_bf16 v[92:95], v[202:205], v[178:181], v[92:95]
	v_mfma_f32_16x16x32_bf16 v[88:91], v[210:213], v[178:181], v[88:91]
	v_mfma_f32_16x16x32_bf16 v[80:83], v[202:205], v[186:189], v[80:83]
	v_mfma_f32_16x16x32_bf16 v[72:75], v[210:213], v[186:189], v[72:75]
	v_mfma_f32_16x16x32_bf16 v[68:71], v[202:205], v[194:197], v[68:71]
	v_mfma_f32_16x16x32_bf16 v[64:67], v[210:213], v[194:197], v[64:67]
	v_mfma_f32_16x16x32_bf16 v[108:111], v[206:209], v[174:177], v[108:111]
	v_mfma_f32_16x16x32_bf16 v[104:107], v[214:217], v[174:177], v[104:107]
	v_mfma_f32_16x16x32_bf16 v[92:95], v[206:209], v[182:185], v[92:95]
	v_mfma_f32_16x16x32_bf16 v[88:91], v[214:217], v[182:185], v[88:91]
	v_mfma_f32_16x16x32_bf16 v[80:83], v[206:209], v[190:193], v[80:83]
	v_mfma_f32_16x16x32_bf16 v[72:75], v[214:217], v[190:193], v[72:75]
	v_mfma_f32_16x16x32_bf16 v[68:71], v[206:209], v[198:201], v[68:71]
	v_mfma_f32_16x16x32_bf16 v[64:67], v[214:217], v[198:201], v[64:67]
	s_setprio 0
	s_mov_b32 m0, s38
	v_lshl_add_u64 v[222:223], s[26:27], 0, v[128:129]
	s_barrier
	ds_read_b128 v[170:173], v150 offset:16384
	ds_read_b128 v[174:177], v150 offset:17408
	ds_read_b128 v[178:181], v150 offset:18432
	ds_read_b128 v[182:185], v150 offset:19456
	ds_read_b128 v[186:189], v150 offset:20480
	ds_read_b128 v[190:193], v150 offset:21504
	ds_read_b128 v[194:197], v150 offset:22528
	ds_read_b128 v[198:201], v150 offset:23552
	global_load_lds_dwordx4 v[222:223], off
	v_lshl_add_u64 v[224:225], s[26:27], 0, v[132:133]
	s_mov_b32 m0, s39
	s_nop 0
	global_load_lds_dwordx4 v[224:225], off
	s_barrier
	s_waitcnt lgkmcnt(0)
	s_setprio 1
	v_mfma_f32_16x16x32_bf16 v[60:63], v[142:145], v[170:173], v[60:63]
	v_mfma_f32_16x16x32_bf16 v[56:59], v[162:165], v[170:173], v[56:59]
	v_mfma_f32_16x16x32_bf16 v[52:55], v[142:145], v[178:181], v[52:55]
	v_mfma_f32_16x16x32_bf16 v[48:51], v[162:165], v[178:181], v[48:51]
	v_mfma_f32_16x16x32_bf16 v[44:47], v[142:145], v[186:189], v[44:47]
	v_mfma_f32_16x16x32_bf16 v[32:35], v[162:165], v[186:189], v[32:35]
	v_mfma_f32_16x16x32_bf16 v[20:23], v[142:145], v[194:197], v[20:23]
	v_mfma_f32_16x16x32_bf16 v[12:15], v[162:165], v[194:197], v[12:15]
	v_mfma_f32_16x16x32_bf16 v[60:63], v[154:157], v[174:177], v[60:63]
	v_mfma_f32_16x16x32_bf16 v[56:59], v[166:169], v[174:177], v[56:59]
	v_mfma_f32_16x16x32_bf16 v[52:55], v[154:157], v[182:185], v[52:55]
	v_mfma_f32_16x16x32_bf16 v[48:51], v[166:169], v[182:185], v[48:51]
	v_mfma_f32_16x16x32_bf16 v[44:47], v[154:157], v[190:193], v[44:47]
	v_mfma_f32_16x16x32_bf16 v[32:35], v[166:169], v[190:193], v[32:35]
	v_mfma_f32_16x16x32_bf16 v[20:23], v[154:157], v[198:201], v[20:23]
	v_mfma_f32_16x16x32_bf16 v[12:15], v[166:169], v[198:201], v[12:15]
	s_setprio 0
	s_barrier
; #define PG8_STAGE(bufoff, gbase, voff) do { _Pragma("unroll") for (int _i = 0; _i < 2; ++_i) \
;     __builtin_amdgcn_global_load_lds((const unsigned*)((const char*)(gbase) + (voff)[_i]), (PG8_LAS unsigned*)(lds + (bufoff) + ldsw + _i * 8192), 16, 0, 0); } while (0)
; #define PG8_LDA(dst, b, h) do { _Pragma("unroll") for (int m = 0; m < 4; ++m) _Pragma("unroll") for (int k = 0; k < 2; ++k) dst[m][k] = *(const PG8_LAS bf16x8*)(lds + PG8_SA(b, h) + aoff + m * 2048 + k * 1024); } while (0)
; #define PG8_LDB(dst, b, h) do { _Pragma("unroll") for (int n = 0; n < 2; ++n) _Pragma("unroll") for (int k = 0; k < 2; ++k) dst[n][k] = *(const PG8_LAS bf16x8*)(lds + PG8_SB(b, h) + boff + n * 2048 + k * 1024); } while (0)
; #define PG8_MMA(ai, bj, At, Bt) do { __builtin_amdgcn_s_setprio(1); _Pragma("unroll") for (int m = 0; m < 4; ++m) _Pragma("unroll") for (int n = 0; n < 2; ++n) _Pragma("unroll") for (int k = 0; k < 2; ++k) \
;     acc[ai][bj][m][n] = __builtin_amdgcn_mfma_f32_16x16x32_bf16(Bt[n][k], At[m][k], acc[ai][bj][m][n], 0, 0, 0); __builtin_amdgcn_s_setprio(0); } while (0)
; #define PG8_WAIT_V(n) asm volatile("s_waitcnt vmcnt(" #n ")" ::: "memory")
; #define PG8_WAIT_L(n) asm volatile("s_waitcnt lgkmcnt(" #n ")" ::: "memory")
; #define PG8_BAR __builtin_amdgcn_s_barrier()
; #define PG8_SCHED __builtin_amdgcn_sched_barrier(0)
; template <class Epi>
; DI void gemm_phase(PG8_LAS unsigned char* lds, const Gemm g, const StaticOrder& S, const Epi& E, const int wv) {
;     ...
;       PG8_STAGE(PG8_SB(0, 1), b2 + hstep, voffB);
;       PG8_WAIT_V(6); PG8_BAR; PG8_MMA(1, 1, At, B1); PG8_BAR;
;       PG8_LDB(B0, 1, 0); PG8_SCHED; PG8_LDA(At, 1, 0); PG8_STAGE(PG8_SA(0, 1), a2 + hstep, voffA);
;       PG8_WAIT_L(8); PG8_BAR; PG8_WAIT_L(0); PG8_MMA(0, 0, At, B0); PG8_BAR; PG8_SCHED;
;       PG8_LDB(B1, 1, 1); PG8_STAGE(PG8_SB(1, 0), b3, voffB);
;       PG8_BAR; PG8_WAIT_L(0); PG8_MMA(0, 1, At, B1); PG8_BAR;
;       PG8_LDA(At, 1, 1); PG8_STAGE(PG8_SA(1, 0), a3, voffA);
	s_add_u32 s6, s8, 0x18000
	s_addc_u32 s7, s9, 0
	s_add_i32 s59, s48, s37
	v_lshl_add_u64 v[142:143], s[6:7], 0, v[130:131]
	s_mov_b32 m0, s59
	s_nop 0
	global_load_lds_dwordx4 v[142:143], off
	v_lshl_add_u64 v[142:143], s[6:7], 0, v[134:135]
	s_add_i32 m0, s59, 0x2000
	s_nop 0
	global_load_lds_dwordx4 v[142:143], off
	s_waitcnt vmcnt(6)
	s_barrier
	s_setprio 1
	v_mfma_f32_16x16x32_bf16 v[40:43], v[202:205], v[170:173], v[40:43]
	v_mfma_f32_16x16x32_bf16 v[36:39], v[210:213], v[170:173], v[36:39]
	v_mfma_f32_16x16x32_bf16 v[28:31], v[202:205], v[178:181], v[28:31]
	v_mfma_f32_16x16x32_bf16 v[24:27], v[210:213], v[178:181], v[24:27]
	v_mfma_f32_16x16x32_bf16 v[16:19], v[202:205], v[186:189], v[16:19]
	v_mfma_f32_16x16x32_bf16 v[8:11], v[210:213], v[186:189], v[8:11]
	v_mfma_f32_16x16x32_bf16 v[4:7], v[202:205], v[194:197], v[4:7]
	v_mfma_f32_16x16x32_bf16 v[0:3], v[210:213], v[194:197], v[0:3]
	v_mfma_f32_16x16x32_bf16 v[40:43], v[206:209], v[174:177], v[40:43]
	v_mfma_f32_16x16x32_bf16 v[36:39], v[214:217], v[174:177], v[36:39]
	v_mfma_f32_16x16x32_bf16 v[28:31], v[206:209], v[182:185], v[28:31]
	v_mfma_f32_16x16x32_bf16 v[24:27], v[214:217], v[182:185], v[24:27]
	v_mfma_f32_16x16x32_bf16 v[16:19], v[206:209], v[190:193], v[16:19]
	v_mfma_f32_16x16x32_bf16 v[8:11], v[214:217], v[190:193], v[8:11]
	v_mfma_f32_16x16x32_bf16 v[4:7], v[206:209], v[198:201], v[4:7]
	v_mfma_f32_16x16x32_bf16 v[0:3], v[214:217], v[198:201], v[0:3]
	s_setprio 0
	s_add_i32 s59, 0, 0x18000
	v_add_u32_e32 v153, s59, v147
	s_barrier
	ds_read_b128 v[142:145], v153
	ds_read_b128 v[154:157], v153 offset:1024
	ds_read_b128 v[162:165], v153 offset:2048
	ds_read_b128 v[166:169], v153 offset:3072
	s_add_u32 s6, s26, 0x18000
	s_addc_u32 s7, s27, 0
	s_mov_b32 m0, s40
	v_lshl_add_u64 v[202:203], s[6:7], 0, v[128:129]
	ds_read_b128 v[170:173], v150 offset:32768
	ds_read_b128 v[174:177], v150 offset:33792
	ds_read_b128 v[178:181], v150 offset:34816
	ds_read_b128 v[182:185], v150 offset:35840
	ds_read_b128 v[186:189], v150 offset:36864
	ds_read_b128 v[190:193], v150 offset:37888
	ds_read_b128 v[194:197], v150 offset:38912
	ds_read_b128 v[198:201], v150 offset:39936
	global_load_lds_dwordx4 v[202:203], off
	v_lshl_add_u64 v[202:203], s[6:7], 0, v[132:133]
	s_mov_b32 m0, s41
	s_nop 0
	global_load_lds_dwordx4 v[202:203], off
	s_waitcnt lgkmcnt(8)
	s_barrier
	s_waitcnt lgkmcnt(0)
	s_setprio 1
	s_waitcnt lgkmcnt(0)
	v_mfma_f32_16x16x32_bf16 v[124:127], v[142:145], v[170:173], v[124:127]
	v_mfma_f32_16x16x32_bf16 v[120:123], v[162:165], v[170:173], v[120:123]
	v_mfma_f32_16x16x32_bf16 v[116:119], v[142:145], v[178:181], v[116:119]
	v_mfma_f32_16x16x32_bf16 v[112:115], v[162:165], v[178:181], v[112:115]
	v_mfma_f32_16x16x32_bf16 v[100:103], v[142:145], v[186:189], v[100:103]
	v_mfma_f32_16x16x32_bf16 v[96:99], v[162:165], v[186:189], v[96:99]
	v_mfma_f32_16x16x32_bf16 v[84:87], v[142:145], v[194:197], v[84:87]
	v_mfma_f32_16x16x32_bf16 v[76:79], v[162:165], v[194:197], v[76:79]
	v_mfma_f32_16x16x32_bf16 v[124:127], v[154:157], v[174:177], v[124:127]
	v_mfma_f32_16x16x32_bf16 v[120:123], v[166:169], v[174:177], v[120:123]
	v_mfma_f32_16x16x32_bf16 v[116:119], v[154:157], v[182:185], v[116:119]
	v_mfma_f32_16x16x32_bf16 v[112:115], v[166:169], v[182:185], v[112:115]
	v_mfma_f32_16x16x32_bf16 v[100:103], v[154:157], v[190:193], v[100:103]
	v_mfma_f32_16x16x32_bf16 v[96:99], v[166:169], v[190:193], v[96:99]
	v_mfma_f32_16x16x32_bf16 v[84:87], v[154:157], v[198:201], v[84:87]
	v_mfma_f32_16x16x32_bf16 v[76:79], v[166:169], v[198:201], v[76:79]
	s_setprio 0
	s_barrier
	s_add_i32 s26, 0, 0x1c000
	s_add_i32 s6, s59, s37
	v_add_u32_e32 v153, s26, v147
	v_lshl_add_u64 v[158:159], v[158:159], 0, s[18:19]
	s_mov_b32 m0, s6
	ds_read_b128 v[202:205], v153
	ds_read_b128 v[206:209], v153 offset:1024
	ds_read_b128 v[210:213], v153 offset:2048
	ds_read_b128 v[214:217], v153 offset:3072
	global_load_lds_dwordx4 v[158:159], off
	v_lshl_add_u64 v[158:159], v[220:221], 0, s[18:19]
	s_add_i32 m0, s6, 0x2000
	s_nop 0
	global_load_lds_dwordx4 v[158:159], off
	s_barrier
	s_waitcnt lgkmcnt(0)
	s_setprio 1
	s_waitcnt lgkmcnt(0)
	v_mfma_f32_16x16x32_bf16 v[108:111], v[202:205], v[170:173], v[108:111]
	v_mfma_f32_16x16x32_bf16 v[104:107], v[210:213], v[170:173], v[104:107]
	v_mfma_f32_16x16x32_bf16 v[92:95], v[202:205], v[178:181], v[92:95]
	v_mfma_f32_16x16x32_bf16 v[88:91], v[210:213], v[178:181], v[88:91]
	v_mfma_f32_16x16x32_bf16 v[80:83], v[202:205], v[186:189], v[80:83]
	v_mfma_f32_16x16x32_bf16 v[72:75], v[210:213], v[186:189], v[72:75]
	v_mfma_f32_16x16x32_bf16 v[68:71], v[202:205], v[194:197], v[68:71]
	v_mfma_f32_16x16x32_bf16 v[64:67], v[210:213], v[194:197], v[64:67]
	v_mfma_f32_16x16x32_bf16 v[108:111], v[206:209], v[174:177], v[108:111]
	v_mfma_f32_16x16x32_bf16 v[104:107], v[214:217], v[174:177], v[104:107]
	v_mfma_f32_16x16x32_bf16 v[92:95], v[206:209], v[182:185], v[92:95]
	v_mfma_f32_16x16x32_bf16 v[88:91], v[214:217], v[182:185], v[88:91]
	v_mfma_f32_16x16x32_bf16 v[80:83], v[206:209], v[190:193], v[80:83]
	v_mfma_f32_16x16x32_bf16 v[72:75], v[214:217], v[190:193], v[72:75]
	v_mfma_f32_16x16x32_bf16 v[68:71], v[206:209], v[198:201], v[68:71]
	v_mfma_f32_16x16x32_bf16 v[64:67], v[214:217], v[198:201], v[64:67]
	s_setprio 0
	s_mov_b32 m0, s43
	v_lshl_add_u64 v[158:159], v[222:223], 0, s[18:19]
	s_barrier
	ds_read_b128 v[170:173], v150 offset:49152
	ds_read_b128 v[174:177], v150 offset:50176
	ds_read_b128 v[178:181], v150 offset:51200
	ds_read_b128 v[182:185], v150 offset:52224
	ds_read_b128 v[186:189], v150 offset:53248
	ds_read_b128 v[190:193], v150 offset:54272
	ds_read_b128 v[194:197], v150 offset:55296
	ds_read_b128 v[198:201], v150 offset:56320
	global_load_lds_dwordx4 v[158:159], off
	v_lshl_add_u64 v[158:159], v[224:225], 0, s[18:19]
	s_mov_b32 m0, s44
	s_nop 0
	global_load_lds_dwordx4 v[158:159], off
	s_barrier
; #define PG8_STAGE(bufoff, gbase, voff) do { _Pragma("unroll") for (int _i = 0; _i < 2; ++_i) \
;     __builtin_amdgcn_global_load_lds((const unsigned*)((const char*)(gbase) + (voff)[_i]), (PG8_LAS unsigned*)(lds + (bufoff) + ldsw + _i * 8192), 16, 0, 0); } while (0)
; #define PG8_MMA(ai, bj, At, Bt) do { __builtin_amdgcn_s_setprio(1); _Pragma("unroll") for (int m = 0; m < 4; ++m) _Pragma("unroll") for (int n = 0; n < 2; ++n) _Pragma("unroll") for (int k = 0; k < 2; ++k) \
;     acc[ai][bj][m][n] = __builtin_amdgcn_mfma_f32_16x16x32_bf16(Bt[n][k], At[m][k], acc[ai][bj][m][n], 0, 0, 0); __builtin_amdgcn_s_setprio(0); } while (0)
; #define PG8_WAIT_V(n) asm volatile("s_waitcnt vmcnt(" #n ")" ::: "memory")
; #define PG8_WAIT_L(n) asm volatile("s_waitcnt lgkmcnt(" #n ")" ::: "memory")
; #define PG8_BAR __builtin_amdgcn_s_barrier()
; #define PG8_SCHED __builtin_amdgcn_sched_barrier(0)
; template <class Epi>
; DI void gemm_phase(PG8_LAS unsigned char* lds, const Gemm g, const StaticOrder& S, const Epi& E, const int wv) {
;     ...
;       PG8_BAR; PG8_WAIT_L(0); PG8_MMA(1, 0, At, B0); PG8_BAR; PG8_SCHED;
;       PG8_STAGE(PG8_SB(1, 1), b3 + hstep, voffB);
;       PG8_WAIT_V(6); PG8_BAR; PG8_MMA(1, 1, At, B1); PG8_BAR;
;     }
;     E(acc, cur, wr, wc, fr, fq);
	s_waitcnt lgkmcnt(0)
	s_setprio 1
	v_mfma_f32_16x16x32_bf16 v[60:63], v[142:145], v[170:173], v[60:63]
	v_mfma_f32_16x16x32_bf16 v[56:59], v[162:165], v[170:173], v[56:59]
	v_mfma_f32_16x16x32_bf16 v[52:55], v[142:145], v[178:181], v[52:55]
	v_mfma_f32_16x16x32_bf16 v[48:51], v[162:165], v[178:181], v[48:51]
	v_mfma_f32_16x16x32_bf16 v[44:47], v[142:145], v[186:189], v[44:47]
	v_mfma_f32_16x16x32_bf16 v[32:35], v[162:165], v[186:189], v[32:35]
	v_mfma_f32_16x16x32_bf16 v[20:23], v[142:145], v[194:197], v[20:23]
	v_mfma_f32_16x16x32_bf16 v[12:15], v[162:165], v[194:197], v[12:15]
	v_mfma_f32_16x16x32_bf16 v[60:63], v[154:157], v[174:177], v[60:63]
	v_mfma_f32_16x16x32_bf16 v[56:59], v[166:169], v[174:177], v[56:59]
	v_mfma_f32_16x16x32_bf16 v[52:55], v[154:157], v[182:185], v[52:55]
	v_mfma_f32_16x16x32_bf16 v[48:51], v[166:169], v[182:185], v[48:51]
	v_mfma_f32_16x16x32_bf16 v[44:47], v[154:157], v[190:193], v[44:47]
	v_mfma_f32_16x16x32_bf16 v[32:35], v[166:169], v[190:193], v[32:35]
	v_mfma_f32_16x16x32_bf16 v[20:23], v[154:157], v[198:201], v[20:23]
	v_mfma_f32_16x16x32_bf16 v[12:15], v[166:169], v[198:201], v[12:15]
	s_setprio 0
	s_barrier
	s_add_u32 s6, s8, 0x18080
	s_addc_u32 s7, s9, 0
	s_add_i32 s8, s26, s37
	v_lshl_add_u64 v[142:143], s[6:7], 0, v[130:131]
	s_mov_b32 m0, s8
	s_nop 0
	global_load_lds_dwordx4 v[142:143], off
	v_lshl_add_u64 v[142:143], s[6:7], 0, v[134:135]
	s_add_i32 m0, s8, 0x2000
	s_nop 0
	global_load_lds_dwordx4 v[142:143], off
	s_waitcnt vmcnt(6)
	s_barrier
	s_setprio 1
	v_mfma_f32_16x16x32_bf16 v[40:43], v[202:205], v[170:173], v[40:43]
	v_mfma_f32_16x16x32_bf16 v[36:39], v[210:213], v[170:173], v[36:39]
	v_mfma_f32_16x16x32_bf16 v[28:31], v[202:205], v[178:181], v[28:31]
	v_mfma_f32_16x16x32_bf16 v[24:27], v[210:213], v[178:181], v[24:27]
	v_mfma_f32_16x16x32_bf16 v[16:19], v[202:205], v[186:189], v[16:19]
	v_mfma_f32_16x16x32_bf16 v[8:11], v[210:213], v[186:189], v[8:11]
	v_mfma_f32_16x16x32_bf16 v[4:7], v[202:205], v[194:197], v[4:7]
	v_mfma_f32_16x16x32_bf16 v[0:3], v[210:213], v[194:197], v[0:3]
	v_mfma_f32_16x16x32_bf16 v[40:43], v[206:209], v[174:177], v[40:43]
	v_mfma_f32_16x16x32_bf16 v[36:39], v[214:217], v[174:177], v[36:39]
	v_mfma_f32_16x16x32_bf16 v[28:31], v[206:209], v[182:185], v[28:31]
	v_mfma_f32_16x16x32_bf16 v[24:27], v[214:217], v[182:185], v[24:27]
	v_mfma_f32_16x16x32_bf16 v[16:19], v[206:209], v[190:193], v[16:19]
	v_mfma_f32_16x16x32_bf16 v[8:11], v[214:217], v[190:193], v[8:11]
	v_mfma_f32_16x16x32_bf16 v[4:7], v[206:209], v[198:201], v[4:7]
	v_mfma_f32_16x16x32_bf16 v[0:3], v[214:217], v[198:201], v[0:3]
	s_setprio 0
	s_add_i32 s58, s58, 2
	s_add_u32 s55, s55, 0x100
	s_addc_u32 s57, s57, 0
	s_cmp_gt_u32 s58, 3
	s_mov_b64 s[6:7], s[4:5]
	s_barrier
	s_cbranch_scc0 .LBB0_521
	v_lshl_or_b32 v142, s54, 8, v148
	v_ashrrev_i32_e32 v143, 31, v142
	v_lshl_add_u32 v144, s53, 8, v146
	s_cmpk_gt_i32 s53, 0x181
	v_lshlrev_b64 v[142:143], 1, v[142:143]
	s_cbranch_scc1 .LBB0_524
; DI u32x4 pack8v(f32x4 a, f32x4 b) { return u32x4{cvtpk(a[0], a[1]), cvtpk(a[2], a[3]), cvtpk(b[0], b[1]), cvtpk(b[2], b[3])}; }
; #define EPI_ROWS_BEGIN() \
;   _Pragma("unroll") for (int ai = 0; ai < 2; ++ai) { if (u.pm * 256 + ai * 128 >= T) continue;
;   DI void operator()(AccRef acc, const pg8::Unit& u, int wr, int wc, int fr, int fq) const {
;     const int row0 = u.pm * 256 + wr * 64 + fr, col0 = u.pn * 256 + wc * 32 + 8 * fq;
;     EPI_ROWS_BEGIN()
;       float rs[4];
; #pragma unroll
;       for (int m = 0; m < 4; ++m) rs[m] = ss[row0 + ai * 128 + m * 16];
; #pragma unroll
;       for (int m = 0; m < 4; ++m) rs[m] = rsqrtf(rs[m] * inv_k + EPS);
; #pragma unroll
;       for (int m = 0; m < 4; ++m) {
;         u16* rp = out + (size_t)(row0 + ai * 128 + m * 16) * ldc + col0;
; #pragma unroll
;         for (int bj = 0; bj < 2; ++bj) *(u32x4*)(rp + bj * 128) = pack8v(acc[ai][bj][m][0] * rs[m], acc[ai][bj][m][1] * rs[m]);
;       }
	v_ashrrev_i32_e32 v145, 31, v144
	v_lshl_add_u64 v[154:155], v[144:145], 2, s[16:17]
	global_load_dword v145, v[154:155], off
	v_or_b32_e32 v154, 16, v144
	v_ashrrev_i32_e32 v155, 31, v154
	v_or_b32_e32 v158, 32, v144
	v_or_b32_e32 v164, 48, v144
	v_lshl_add_u64 v[156:157], v[154:155], 2, s[16:17]
	v_ashrrev_i32_e32 v159, 31, v158
	v_ashrrev_i32_e32 v165, 31, v164
	v_lshl_add_u64 v[162:163], v[158:159], 2, s[16:17]
	v_lshl_add_u64 v[166:167], v[164:165], 2, s[16:17]
	global_load_dword v153, v[156:157], off
	global_load_dword v161, v[162:163], off
	global_load_dword v165, v[166:167], off
	v_mov_b64_e32 v[156:157], s[14:15]
	v_mad_i64_i32 v[162:163], s[4:5], v144, s50, v[156:157]
	v_mad_i64_i32 v[154:155], s[4:5], v154, s50, v[156:157]
	v_mad_i64_i32 v[158:159], s[4:5], v158, s50, v[156:157]
	v_lshl_add_u64 v[162:163], v[162:163], 0, v[142:143]
	v_lshl_add_u64 v[154:155], v[154:155], 0, v[142:143]
	v_lshl_add_u64 v[158:159], v[158:159], 0, v[142:143]
	s_waitcnt vmcnt(0)
	v_fmamk_f32 v145, v145, 0x3b2aaaab, v152
	v_mul_f32_e32 v166, 0x4b800000, v145
	v_cmp_gt_f32_e32 vcc, s49, v145
	v_fmamk_f32 v153, v153, 0x3b2aaaab, v152
	v_fmamk_f32 v161, v161, 0x3b2aaaab, v152
	v_fmamk_f32 v165, v165, 0x3b2aaaab, v152
	v_cndmask_b32_e32 v145, v145, v166, vcc
	v_mul_f32_e32 v166, 0x4b800000, v153
	v_cmp_gt_f32_e64 s[4:5], s49, v153
	v_mul_f32_e32 v167, 0x4b800000, v161
	v_mul_f32_e32 v168, 0x4b800000, v165
	v_rsq_f32_e32 v145, v145
	v_cndmask_b32_e64 v153, v153, v166, s[4:5]
	v_cmp_gt_f32_e64 s[6:7], s49, v161
	v_cmp_gt_f32_e64 s[8:9], s49, v165
	v_rsq_f32_e32 v153, v153
	v_cndmask_b32_e64 v161, v161, v167, s[6:7]
	v_cndmask_b32_e64 v165, v165, v168, s[8:9]
	v_rsq_f32_e32 v161, v161
	v_rsq_f32_e32 v165, v165
	v_mul_f32_e32 v166, 0x45800000, v145
	v_cndmask_b32_e32 v166, v145, v166, vcc
	v_mul_f32_e32 v145, 0x45800000, v153
	v_mul_f32_e32 v167, 0x45800000, v161
	v_mul_f32_e32 v169, 0x45800000, v165
	v_cndmask_b32_e64 v168, v153, v145, s[4:5]
	v_pk_mul_f32 v[126:127], v[126:127], v[166:167] op_sel_hi:[1,0]
	v_pk_mul_f32 v[124:125], v[124:125], v[166:167] op_sel_hi:[1,0]
	v_pk_mul_f32 v[122:123], v[122:123], v[166:167] op_sel_hi:[1,0]
	v_pk_mul_f32 v[120:121], v[120:121], v[166:167] op_sel_hi:[1,0]
	v_pk_mul_f32 v[118:119], v[118:119], v[168:169] op_sel_hi:[1,0]
	v_pk_mul_f32 v[116:117], v[116:117], v[168:169] op_sel_hi:[1,0]
	v_pk_mul_f32 v[114:115], v[114:115], v[168:169] op_sel_hi:[1,0]
	v_pk_mul_f32 v[112:113], v[112:113], v[168:169] op_sel_hi:[1,0]
	v_cndmask_b32_e64 v170, v161, v167, s[6:7]
	v_pk_mul_f32 v[110:111], v[110:111], v[166:167] op_sel_hi:[1,0]
	v_pk_mul_f32 v[108:109], v[108:109], v[166:167] op_sel_hi:[1,0]
	v_pk_mul_f32 v[174:175], v[106:107], v[166:167] op_sel_hi:[1,0]
	v_pk_mul_f32 v[166:167], v[104:105], v[166:167] op_sel_hi:[1,0]
	v_cvt_pk_bf16_f32 v104, v124, v125
	v_cvt_pk_bf16_f32 v105, v126, v127
	v_cvt_pk_bf16_f32 v106, v120, v121
	v_cvt_pk_bf16_f32 v107, v122, v123
	v_pk_mul_f32 v[94:95], v[94:95], v[168:169] op_sel_hi:[1,0]
	v_pk_mul_f32 v[92:93], v[92:93], v[168:169] op_sel_hi:[1,0]
	v_pk_mul_f32 v[120:121], v[90:91], v[168:169] op_sel_hi:[1,0]
	v_pk_mul_f32 v[122:123], v[88:89], v[168:169] op_sel_hi:[1,0]
	v_cvt_pk_bf16_f32 v88, v116, v117
	v_cvt_pk_bf16_f32 v89, v118, v119
	v_cvt_pk_bf16_f32 v90, v112, v113
	v_cvt_pk_bf16_f32 v91, v114, v115
	v_cvt_pk_bf16_f32 v108, v108, v109
	v_cvt_pk_bf16_f32 v109, v110, v111
	v_cvt_pk_bf16_f32 v110, v166, v167
	v_cvt_pk_bf16_f32 v111, v174, v175
	global_store_dwordx4 v[162:163], v[104:107], off
	global_store_dwordx4 v[162:163], v[108:111], off offset:256
	v_cvt_pk_bf16_f32 v92, v92, v93
	v_cvt_pk_bf16_f32 v93, v94, v95
	v_cvt_pk_bf16_f32 v94, v122, v123
	v_cvt_pk_bf16_f32 v95, v120, v121
	global_store_dwordx4 v[154:155], v[88:91], off
	global_store_dwordx4 v[154:155], v[92:95], off offset:256
	v_pk_mul_f32 v[82:83], v[82:83], v[170:171] op_sel_hi:[1,0]
	v_pk_mul_f32 v[80:81], v[80:81], v[170:171] op_sel_hi:[1,0]
	v_pk_mul_f32 v[88:89], v[74:75], v[170:171] op_sel_hi:[1,0]
	v_pk_mul_f32 v[74:75], v[72:73], v[170:171] op_sel_hi:[1,0]
	v_cvt_pk_bf16_f32 v72, v80, v81
	v_cvt_pk_bf16_f32 v73, v82, v83
	v_cvt_pk_bf16_f32 v74, v74, v75
	v_cvt_pk_bf16_f32 v75, v88, v89
	v_cndmask_b32_e64 v172, v165, v169, s[8:9]
	global_store_dwordx4 v[158:159], v[72:75], off offset:256
	v_pk_mul_f32 v[78:79], v[78:79], v[172:173] op_sel_hi:[1,0]
	v_pk_mul_f32 v[76:77], v[76:77], v[172:173] op_sel_hi:[1,0]
	v_mad_i64_i32 v[72:73], s[4:5], v164, s50, v[156:157]
	v_lshl_add_u64 v[80:81], v[72:73], 0, v[142:143]
	v_pk_mul_f32 v[74:75], v[86:87], v[172:173] op_sel_hi:[1,0]
	v_pk_mul_f32 v[72:73], v[84:85], v[172:173] op_sel_hi:[1,0]
	v_pk_mul_f32 v[102:103], v[102:103], v[170:171] op_sel_hi:[1,0]
	v_cvt_pk_bf16_f32 v72, v72, v73
	v_cvt_pk_bf16_f32 v73, v74, v75
	v_cvt_pk_bf16_f32 v74, v76, v77
	v_cvt_pk_bf16_f32 v75, v78, v79
	v_pk_mul_f32 v[100:101], v[100:101], v[170:171] op_sel_hi:[1,0]
	v_pk_mul_f32 v[124:125], v[98:99], v[170:171] op_sel_hi:[1,0]
	v_pk_mul_f32 v[98:99], v[96:97], v[170:171] op_sel_hi:[1,0]
	global_store_dwordx4 v[80:81], v[72:75], off
	v_pk_mul_f32 v[70:71], v[70:71], v[172:173] op_sel_hi:[1,0]
	v_pk_mul_f32 v[68:69], v[68:69], v[172:173] op_sel_hi:[1,0]
	v_pk_mul_f32 v[72:73], v[66:67], v[172:173] op_sel_hi:[1,0]
	v_pk_mul_f32 v[66:67], v[64:65], v[172:173] op_sel_hi:[1,0]
	v_cvt_pk_bf16_f32 v96, v100, v101
	v_cvt_pk_bf16_f32 v97, v102, v103
	v_cvt_pk_bf16_f32 v98, v98, v99
	v_cvt_pk_bf16_f32 v99, v124, v125
	v_cvt_pk_bf16_f32 v64, v68, v69
	v_cvt_pk_bf16_f32 v65, v70, v71
	v_cvt_pk_bf16_f32 v66, v66, v67
	v_cvt_pk_bf16_f32 v67, v72, v73
	global_store_dwordx4 v[158:159], v[96:99], off
	global_store_dwordx4 v[80:81], v[64:67], off offset:256

; #define PG8_STAGE(bufoff, gbase, voff) do { _Pragma("unroll") for (int _i = 0; _i < 2; ++_i) \
;     __builtin_amdgcn_global_load_lds((const unsigned*)((const char*)(gbase) + (voff)[_i]), (PG8_LAS unsigned*)(lds + (bufoff) + ldsw + _i * 8192), 16, 0, 0); } while (0)
; #define PG8_LDA(dst, b, h) do { _Pragma("unroll") for (int m = 0; m < 4; ++m) _Pragma("unroll") for (int k = 0; k < 2; ++k) dst[m][k] = *(const PG8_LAS bf16x8*)(lds + PG8_SA(b, h) + aoff + m * 2048 + k * 1024); } while (0)
; #define PG8_LDB(dst, b, h) do { _Pragma("unroll") for (int n = 0; n < 2; ++n) _Pragma("unroll") for (int k = 0; k < 2; ++k) dst[n][k] = *(const PG8_LAS bf16x8*)(lds + PG8_SB(b, h) + boff + n * 2048 + k * 1024); } while (0)
; #define PG8_MMA(ai, bj, At, Bt) do { __builtin_amdgcn_s_setprio(1); _Pragma("unroll") for (int m = 0; m < 4; ++m) _Pragma("unroll") for (int n = 0; n < 2; ++n) _Pragma("unroll") for (int k = 0; k < 2; ++k) \
;     acc[ai][bj][m][n] = __builtin_amdgcn_mfma_f32_16x16x32_bf16(Bt[n][k], At[m][k], acc[ai][bj][m][n], 0, 0, 0); __builtin_amdgcn_s_setprio(0); } while (0)
; #define PG8_WAIT_L(n) asm volatile("s_waitcnt lgkmcnt(" #n ")" ::: "memory")
; #define PG8_BAR __builtin_amdgcn_s_barrier()
; template <class Epi>
; DI void gemm_phase(PG8_LAS unsigned char* lds, const Gemm g, const StaticOrder& S, const Epi& E, const int wv) {
;     ...
;   for (;;) {
;     const bool has_next = S.next(ui + 1, nxt);
;     const char* nA = has_next ? (const char*)g.A + (size_t)nxt.pm * tstep : cA; const char* nB = has_next ? (const char*)g.Bt + (size_t)nxt.pn * tstep : cB;
; #pragma nounroll
;     for (int t = 0; t < nt; t += 2) {
;       const bool last = (t == nt - 2);
;       const char* a1 = cA + (size_t)(t + 1) * kstep;
;       const char* a2 = last ? nA : cA + (size_t)(t + 2) * kstep; const char* b2 = last ? nB : cB + (size_t)(t + 2) * kstep;
;       const char* a3 = a2 + kstep; const char* b3 = b2 + kstep;
;       PG8_LDB(B0, 0, 0); PG8_SCHED; PG8_LDA(At, 0, 0); PG8_STAGE(PG8_SA(1, 1), a1 + hstep, voffA);
;       PG8_WAIT_L(8); PG8_BAR; PG8_WAIT_L(0); PG8_MMA(0, 0, At, B0); PG8_BAR; PG8_SCHED;
;       PG8_LDB(B1, 0, 1); PG8_STAGE(PG8_SB(0, 0), b2, voffB);
;       PG8_BAR; PG8_WAIT_L(0); PG8_MMA(0, 1, At, B1); PG8_BAR;
;       PG8_LDA(At, 0, 1); PG8_STAGE(PG8_SA(0, 0), a2, voffA);
;       PG8_BAR; PG8_WAIT_L(0); PG8_MMA(1, 0, At, B0); PG8_BAR; PG8_SCHED;
.LBB0_537:
	s_add_u32 s48, s8, s40
	s_addc_u32 s49, s9, s41
	s_add_u32 s44, s48, 0x100
	s_addc_u32 s45, s49, 0
	s_and_b64 s[42:43], s[38:39], exec
	s_cselect_b32 s45, s5, s45
	s_cselect_b32 s44, s27, s44
	s_add_u32 s40, s6, s40
	s_addc_u32 s41, s7, s41
	s_add_u32 s40, s40, 0x100
	s_addc_u32 s41, s41, 0
	s_and_b64 s[38:39], s[38:39], exec
	s_cselect_b32 s47, s25, s41
	s_cselect_b32 s46, s35, s40
	s_add_u32 s48, s48, 0x10080
	s_addc_u32 s49, s49, 0
	s_add_i32 s92, s74, s57
	s_add_i32 m0, s60, 0xc000
	s_add_i32 s91, s60, 0xe000
	s_add_i32 s90, s92, 0x2000
	s_add_u32 s42, s46, 0x10000
	s_addc_u32 s43, s47, 0
	s_add_i32 s87, s77, s57
	ds_read_b128 v[142:145], v153
	ds_read_b128 v[162:165], v153 offset:1024
	ds_read_b128 v[166:169], v153 offset:2048
	ds_read_b128 v[170:173], v153 offset:3072
	s_add_i32 s86, s87, 0x2000
	s_add_i32 s85, 0, 0x18000
	s_add_u32 s40, s44, 0x10000
	s_addc_u32 s41, s45, 0
	s_add_i32 s84, s85, s57
	s_add_i32 s83, 0, 0x1c000
	s_add_i32 s82, s84, 0x2000
	s_add_u32 s38, s46, 0x10080
	s_addc_u32 s39, s47, 0
	s_add_i32 s89, s83, s57
	s_add_i32 s88, s89, 0x2000
	v_lshl_add_u64 v[146:147], s[48:49], 0, v[134:135]
	ds_read_b128 v[174:177], v154
	ds_read_b128 v[178:181], v154 offset:1024
	ds_read_b128 v[182:185], v154 offset:2048
	ds_read_b128 v[186:189], v154 offset:3072
	ds_read_b128 v[190:193], v154 offset:4096
	ds_read_b128 v[194:197], v154 offset:5120
	ds_read_b128 v[198:201], v154 offset:6144
	ds_read_b128 v[202:205], v154 offset:7168
	global_load_lds_dwordx4 v[146:147], off
	v_lshl_add_u64 v[146:147], s[48:49], 0, v[130:131]
	s_mov_b32 m0, s91
	s_nop 0
	global_load_lds_dwordx4 v[146:147], off
	s_waitcnt lgkmcnt(8)
	s_barrier
	s_waitcnt lgkmcnt(0)
	s_setprio 1
	v_mfma_f32_16x16x32_bf16 v[124:127], v[142:145], v[174:177], v[124:127]
	v_mfma_f32_16x16x32_bf16 v[120:123], v[166:169], v[174:177], v[120:123]
	v_mfma_f32_16x16x32_bf16 v[112:115], v[142:145], v[182:185], v[112:115]
	v_mfma_f32_16x16x32_bf16 v[108:111], v[166:169], v[182:185], v[108:111]
	v_mfma_f32_16x16x32_bf16 v[96:99], v[142:145], v[190:193], v[96:99]
	v_mfma_f32_16x16x32_bf16 v[92:95], v[166:169], v[190:193], v[92:95]
	v_mfma_f32_16x16x32_bf16 v[80:83], v[142:145], v[198:201], v[80:83]
	v_mfma_f32_16x16x32_bf16 v[76:79], v[166:169], v[198:201], v[76:79]
	v_mfma_f32_16x16x32_bf16 v[124:127], v[162:165], v[178:181], v[124:127]
	v_mfma_f32_16x16x32_bf16 v[120:123], v[170:173], v[178:181], v[120:123]
	v_mfma_f32_16x16x32_bf16 v[112:115], v[162:165], v[186:189], v[112:115]
	v_mfma_f32_16x16x32_bf16 v[108:111], v[170:173], v[186:189], v[108:111]
	v_mfma_f32_16x16x32_bf16 v[96:99], v[162:165], v[194:197], v[96:99]
	v_mfma_f32_16x16x32_bf16 v[92:95], v[170:173], v[194:197], v[92:95]
	v_mfma_f32_16x16x32_bf16 v[80:83], v[162:165], v[202:205], v[80:83]
	v_mfma_f32_16x16x32_bf16 v[76:79], v[170:173], v[202:205], v[76:79]
	s_setprio 0
	s_barrier
	s_mov_b32 m0, s92
	v_lshl_add_u64 v[146:147], s[46:47], 0, v[132:133]
	ds_read_b128 v[206:209], v155
	ds_read_b128 v[210:213], v155 offset:1024
	ds_read_b128 v[214:217], v155 offset:2048
	ds_read_b128 v[220:223], v155 offset:3072
	global_load_lds_dwordx4 v[146:147], off
	v_lshl_add_u64 v[150:151], s[46:47], 0, v[128:129]
	s_mov_b32 m0, s90
	s_nop 0
	global_load_lds_dwordx4 v[150:151], off
	s_barrier
	s_waitcnt lgkmcnt(0)
	s_setprio 1
	v_mfma_f32_16x16x32_bf16 v[116:119], v[206:209], v[174:177], v[116:119]
	v_mfma_f32_16x16x32_bf16 v[104:107], v[214:217], v[174:177], v[104:107]
	v_mfma_f32_16x16x32_bf16 v[100:103], v[206:209], v[182:185], v[100:103]
	v_mfma_f32_16x16x32_bf16 v[88:91], v[214:217], v[182:185], v[88:91]
	v_mfma_f32_16x16x32_bf16 v[84:87], v[206:209], v[190:193], v[84:87]
	v_mfma_f32_16x16x32_bf16 v[72:75], v[214:217], v[190:193], v[72:75]
	v_mfma_f32_16x16x32_bf16 v[68:71], v[206:209], v[198:201], v[68:71]
	v_mfma_f32_16x16x32_bf16 v[64:67], v[214:217], v[198:201], v[64:67]
	v_mfma_f32_16x16x32_bf16 v[116:119], v[210:213], v[178:181], v[116:119]
	v_mfma_f32_16x16x32_bf16 v[104:107], v[220:223], v[178:181], v[104:107]
	v_mfma_f32_16x16x32_bf16 v[100:103], v[210:213], v[186:189], v[100:103]
	v_mfma_f32_16x16x32_bf16 v[88:91], v[220:223], v[186:189], v[88:91]
	v_mfma_f32_16x16x32_bf16 v[84:87], v[210:213], v[194:197], v[84:87]
	v_mfma_f32_16x16x32_bf16 v[72:75], v[220:223], v[194:197], v[72:75]
	v_mfma_f32_16x16x32_bf16 v[68:71], v[210:213], v[202:205], v[68:71]
	v_mfma_f32_16x16x32_bf16 v[64:67], v[220:223], v[202:205], v[64:67]
	s_setprio 0
	s_mov_b32 m0, s60
	v_lshl_add_u64 v[158:159], s[44:45], 0, v[134:135]
	s_barrier
	ds_read_b128 v[174:177], v154 offset:16384
	ds_read_b128 v[178:181], v154 offset:17408
	ds_read_b128 v[182:185], v154 offset:18432
	ds_read_b128 v[186:189], v154 offset:19456
	ds_read_b128 v[190:193], v154 offset:20480
	ds_read_b128 v[194:197], v154 offset:21504
	ds_read_b128 v[198:201], v154 offset:22528
	ds_read_b128 v[202:205], v154 offset:23552
	global_load_lds_dwordx4 v[158:159], off
	v_lshl_add_u64 v[224:225], s[44:45], 0, v[130:131]
	s_mov_b32 m0, s61
	s_nop 0
	global_load_lds_dwordx4 v[224:225], off
	s_barrier
	s_waitcnt lgkmcnt(0)
	s_setprio 1
	v_mfma_f32_16x16x32_bf16 v[60:63], v[142:145], v[174:177], v[60:63]
	v_mfma_f32_16x16x32_bf16 v[56:59], v[166:169], v[174:177], v[56:59]
	v_mfma_f32_16x16x32_bf16 v[48:51], v[142:145], v[182:185], v[48:51]
	v_mfma_f32_16x16x32_bf16 v[44:47], v[166:169], v[182:185], v[44:47]
	v_mfma_f32_16x16x32_bf16 v[32:35], v[142:145], v[190:193], v[32:35]
	v_mfma_f32_16x16x32_bf16 v[28:31], v[166:169], v[190:193], v[28:31]
	v_mfma_f32_16x16x32_bf16 v[16:19], v[142:145], v[198:201], v[16:19]
	v_mfma_f32_16x16x32_bf16 v[12:15], v[166:169], v[198:201], v[12:15]
	v_mfma_f32_16x16x32_bf16 v[60:63], v[162:165], v[178:181], v[60:63]
	v_mfma_f32_16x16x32_bf16 v[56:59], v[170:173], v[178:181], v[56:59]
	v_mfma_f32_16x16x32_bf16 v[48:51], v[162:165], v[186:189], v[48:51]
	v_mfma_f32_16x16x32_bf16 v[44:47], v[170:173], v[186:189], v[44:47]
	v_mfma_f32_16x16x32_bf16 v[32:35], v[162:165], v[194:197], v[32:35]
	v_mfma_f32_16x16x32_bf16 v[28:31], v[170:173], v[194:197], v[28:31]
	v_mfma_f32_16x16x32_bf16 v[16:19], v[162:165], v[202:205], v[16:19]
	v_mfma_f32_16x16x32_bf16 v[12:15], v[170:173], v[202:205], v[12:15]
	s_setprio 0
	s_barrier
; #define PG8_STAGE(bufoff, gbase, voff) do { _Pragma("unroll") for (int _i = 0; _i < 2; ++_i) \
;     __builtin_amdgcn_global_load_lds((const unsigned*)((const char*)(gbase) + (voff)[_i]), (PG8_LAS unsigned*)(lds + (bufoff) + ldsw + _i * 8192), 16, 0, 0); } while (0)
; #define PG8_LDA(dst, b, h) do { _Pragma("unroll") for (int m = 0; m < 4; ++m) _Pragma("unroll") for (int k = 0; k < 2; ++k) dst[m][k] = *(const PG8_LAS bf16x8*)(lds + PG8_SA(b, h) + aoff + m * 2048 + k * 1024); } while (0)
; #define PG8_LDB(dst, b, h) do { _Pragma("unroll") for (int n = 0; n < 2; ++n) _Pragma("unroll") for (int k = 0; k < 2; ++k) dst[n][k] = *(const PG8_LAS bf16x8*)(lds + PG8_SB(b, h) + boff + n * 2048 + k * 1024); } while (0)
; #define PG8_MMA(ai, bj, At, Bt) do { __builtin_amdgcn_s_setprio(1); _Pragma("unroll") for (int m = 0; m < 4; ++m) _Pragma("unroll") for (int n = 0; n < 2; ++n) _Pragma("unroll") for (int k = 0; k < 2; ++k) \
;     acc[ai][bj][m][n] = __builtin_amdgcn_mfma_f32_16x16x32_bf16(Bt[n][k], At[m][k], acc[ai][bj][m][n], 0, 0, 0); __builtin_amdgcn_s_setprio(0); } while (0)
; #define PG8_WAIT_V(n) asm volatile("s_waitcnt vmcnt(" #n ")" ::: "memory")
; #define PG8_WAIT_L(n) asm volatile("s_waitcnt lgkmcnt(" #n ")" ::: "memory")
; #define PG8_BAR __builtin_amdgcn_s_barrier()
; #define PG8_SCHED __builtin_amdgcn_sched_barrier(0)
; template <class Epi>
; DI void gemm_phase(PG8_LAS unsigned char* lds, const Gemm g, const StaticOrder& S, const Epi& E, const int wv) {
;     ...
;       PG8_STAGE(PG8_SB(0, 1), b2 + hstep, voffB);
;       PG8_WAIT_V(6); PG8_BAR; PG8_MMA(1, 1, At, B1); PG8_BAR;
;       PG8_LDB(B0, 1, 0); PG8_SCHED; PG8_LDA(At, 1, 0); PG8_STAGE(PG8_SA(0, 1), a2 + hstep, voffA);
;       PG8_WAIT_L(8); PG8_BAR; PG8_WAIT_L(0); PG8_MMA(0, 0, At, B0); PG8_BAR; PG8_SCHED;
;       PG8_LDB(B1, 1, 1); PG8_STAGE(PG8_SB(1, 0), b3, voffB);
;       PG8_BAR; PG8_WAIT_L(0); PG8_MMA(0, 1, At, B1); PG8_BAR;
;       PG8_LDA(At, 1, 1); PG8_STAGE(PG8_SA(1, 0), a3, voffA);
	s_mov_b32 m0, s87
	v_lshl_add_u64 v[142:143], s[42:43], 0, v[132:133]
	global_load_lds_dwordx4 v[142:143], off
	v_lshl_add_u64 v[142:143], s[42:43], 0, v[128:129]
	s_mov_b32 m0, s86
	s_nop 0
	global_load_lds_dwordx4 v[142:143], off
	s_waitcnt vmcnt(6)
	s_barrier
	s_setprio 1
	v_mfma_f32_16x16x32_bf16 v[52:55], v[206:209], v[174:177], v[52:55]
	v_mfma_f32_16x16x32_bf16 v[40:43], v[214:217], v[174:177], v[40:43]
	v_mfma_f32_16x16x32_bf16 v[36:39], v[206:209], v[182:185], v[36:39]
	v_mfma_f32_16x16x32_bf16 v[24:27], v[214:217], v[182:185], v[24:27]
	v_mfma_f32_16x16x32_bf16 v[20:23], v[206:209], v[190:193], v[20:23]
	v_mfma_f32_16x16x32_bf16 v[8:11], v[214:217], v[190:193], v[8:11]
	v_mfma_f32_16x16x32_bf16 v[4:7], v[206:209], v[198:201], v[4:7]
	v_mfma_f32_16x16x32_bf16 v[0:3], v[214:217], v[198:201], v[0:3]
	v_mfma_f32_16x16x32_bf16 v[52:55], v[210:213], v[178:181], v[52:55]
	v_mfma_f32_16x16x32_bf16 v[40:43], v[220:223], v[178:181], v[40:43]
	v_mfma_f32_16x16x32_bf16 v[36:39], v[210:213], v[186:189], v[36:39]
	v_mfma_f32_16x16x32_bf16 v[24:27], v[220:223], v[186:189], v[24:27]
	v_mfma_f32_16x16x32_bf16 v[20:23], v[210:213], v[194:197], v[20:23]
	v_mfma_f32_16x16x32_bf16 v[8:11], v[220:223], v[194:197], v[8:11]
	v_mfma_f32_16x16x32_bf16 v[4:7], v[210:213], v[202:205], v[4:7]
	v_mfma_f32_16x16x32_bf16 v[0:3], v[220:223], v[202:205], v[0:3]
	s_setprio 0
	v_add_u32_e32 v136, s85, v149
	s_barrier
	ds_read_b128 v[142:145], v136
	ds_read_b128 v[162:165], v136 offset:1024
	ds_read_b128 v[166:169], v136 offset:2048
	ds_read_b128 v[170:173], v136 offset:3072
	s_mov_b32 m0, s62
	v_lshl_add_u64 v[206:207], s[40:41], 0, v[134:135]
	ds_read_b128 v[174:177], v154 offset:32768
	ds_read_b128 v[178:181], v154 offset:33792
	ds_read_b128 v[182:185], v154 offset:34816
	ds_read_b128 v[186:189], v154 offset:35840
	ds_read_b128 v[190:193], v154 offset:36864
	ds_read_b128 v[194:197], v154 offset:37888
	ds_read_b128 v[198:201], v154 offset:38912
	ds_read_b128 v[202:205], v154 offset:39936
	global_load_lds_dwordx4 v[206:207], off
	v_lshl_add_u64 v[206:207], s[40:41], 0, v[130:131]
	s_mov_b32 m0, s63
	s_nop 0
	global_load_lds_dwordx4 v[206:207], off
	s_waitcnt lgkmcnt(8)
	s_barrier
	s_waitcnt lgkmcnt(0)
	s_setprio 1
	v_mfma_f32_16x16x32_bf16 v[124:127], v[142:145], v[174:177], v[124:127]
	v_mfma_f32_16x16x32_bf16 v[120:123], v[166:169], v[174:177], v[120:123]
	v_mfma_f32_16x16x32_bf16 v[112:115], v[142:145], v[182:185], v[112:115]
	v_mfma_f32_16x16x32_bf16 v[108:111], v[166:169], v[182:185], v[108:111]
	v_mfma_f32_16x16x32_bf16 v[96:99], v[142:145], v[190:193], v[96:99]
	v_mfma_f32_16x16x32_bf16 v[92:95], v[166:169], v[190:193], v[92:95]
	v_mfma_f32_16x16x32_bf16 v[80:83], v[142:145], v[198:201], v[80:83]
	v_mfma_f32_16x16x32_bf16 v[76:79], v[166:169], v[198:201], v[76:79]
	v_mfma_f32_16x16x32_bf16 v[124:127], v[162:165], v[178:181], v[124:127]
	v_mfma_f32_16x16x32_bf16 v[120:123], v[170:173], v[178:181], v[120:123]
	v_mfma_f32_16x16x32_bf16 v[112:115], v[162:165], v[186:189], v[112:115]
	v_mfma_f32_16x16x32_bf16 v[108:111], v[170:173], v[186:189], v[108:111]
	v_mfma_f32_16x16x32_bf16 v[96:99], v[162:165], v[194:197], v[96:99]
	v_mfma_f32_16x16x32_bf16 v[92:95], v[170:173], v[194:197], v[92:95]
	v_mfma_f32_16x16x32_bf16 v[80:83], v[162:165], v[202:205], v[80:83]
	v_mfma_f32_16x16x32_bf16 v[76:79], v[170:173], v[202:205], v[76:79]
	s_setprio 0
	s_barrier
	s_mov_b32 m0, s84
	v_add_u32_e32 v136, s83, v149
	v_lshl_add_u64 v[146:147], v[146:147], 0, s[20:21]
	ds_read_b128 v[206:209], v136
	ds_read_b128 v[210:213], v136 offset:1024
	ds_read_b128 v[214:217], v136 offset:2048
	ds_read_b128 v[220:223], v136 offset:3072
	global_load_lds_dwordx4 v[146:147], off
	v_lshl_add_u64 v[146:147], v[150:151], 0, s[20:21]
	s_mov_b32 m0, s82
	s_nop 0
	global_load_lds_dwordx4 v[146:147], off
	s_barrier
	s_waitcnt lgkmcnt(0)
	s_setprio 1
	s_waitcnt lgkmcnt(0)
	v_mfma_f32_16x16x32_bf16 v[116:119], v[206:209], v[174:177], v[116:119]
	v_mfma_f32_16x16x32_bf16 v[104:107], v[214:217], v[174:177], v[104:107]
	v_mfma_f32_16x16x32_bf16 v[100:103], v[206:209], v[182:185], v[100:103]
	v_mfma_f32_16x16x32_bf16 v[88:91], v[214:217], v[182:185], v[88:91]
	v_mfma_f32_16x16x32_bf16 v[84:87], v[206:209], v[190:193], v[84:87]
	v_mfma_f32_16x16x32_bf16 v[72:75], v[214:217], v[190:193], v[72:75]
	v_mfma_f32_16x16x32_bf16 v[68:71], v[206:209], v[198:201], v[68:71]
	v_mfma_f32_16x16x32_bf16 v[64:67], v[214:217], v[198:201], v[64:67]
	v_mfma_f32_16x16x32_bf16 v[116:119], v[210:213], v[178:181], v[116:119]
	v_mfma_f32_16x16x32_bf16 v[104:107], v[220:223], v[178:181], v[104:107]
	v_mfma_f32_16x16x32_bf16 v[100:103], v[210:213], v[186:189], v[100:103]
	v_mfma_f32_16x16x32_bf16 v[88:91], v[220:223], v[186:189], v[88:91]
	v_mfma_f32_16x16x32_bf16 v[84:87], v[210:213], v[194:197], v[84:87]
	v_mfma_f32_16x16x32_bf16 v[72:75], v[220:223], v[194:197], v[72:75]
	v_mfma_f32_16x16x32_bf16 v[68:71], v[210:213], v[202:205], v[68:71]
	v_mfma_f32_16x16x32_bf16 v[64:67], v[220:223], v[202:205], v[64:67]
	s_setprio 0
	s_mov_b32 m0, s67
	v_lshl_add_u64 v[146:147], v[158:159], 0, s[20:21]
	s_barrier
	ds_read_b128 v[174:177], v154 offset:49152
	ds_read_b128 v[178:181], v154 offset:50176
	ds_read_b128 v[182:185], v154 offset:51200
	ds_read_b128 v[186:189], v154 offset:52224
	ds_read_b128 v[190:193], v154 offset:53248
	ds_read_b128 v[194:197], v154 offset:54272
	ds_read_b128 v[198:201], v154 offset:55296
	ds_read_b128 v[202:205], v154 offset:56320
	global_load_lds_dwordx4 v[146:147], off
	v_lshl_add_u64 v[146:147], v[224:225], 0, s[20:21]
	s_mov_b32 m0, s68
	s_nop 0
	global_load_lds_dwordx4 v[146:147], off
	s_barrier
; #define PG8_STAGE(bufoff, gbase, voff) do { _Pragma("unroll") for (int _i = 0; _i < 2; ++_i) \
;     __builtin_amdgcn_global_load_lds((const unsigned*)((const char*)(gbase) + (voff)[_i]), (PG8_LAS unsigned*)(lds + (bufoff) + ldsw + _i * 8192), 16, 0, 0); } while (0)
; #define PG8_MMA(ai, bj, At, Bt) do { __builtin_amdgcn_s_setprio(1); _Pragma("unroll") for (int m = 0; m < 4; ++m) _Pragma("unroll") for (int n = 0; n < 2; ++n) _Pragma("unroll") for (int k = 0; k < 2; ++k) \
;     acc[ai][bj][m][n] = __builtin_amdgcn_mfma_f32_16x16x32_bf16(Bt[n][k], At[m][k], acc[ai][bj][m][n], 0, 0, 0); __builtin_amdgcn_s_setprio(0); } while (0)
; #define PG8_WAIT_V(n) asm volatile("s_waitcnt vmcnt(" #n ")" ::: "memory")
; #define PG8_WAIT_L(n) asm volatile("s_waitcnt lgkmcnt(" #n ")" ::: "memory")
; #define PG8_BAR __builtin_amdgcn_s_barrier()
; #define PG8_SCHED __builtin_amdgcn_sched_barrier(0)
; DI u32x4 pack8v(f32x4 a, f32x4 b) { return u32x4{cvtpk(a[0], a[1]), cvtpk(a[2], a[3]), cvtpk(b[0], b[1]), cvtpk(b[2], b[3])}; }
; DI int vt_pos(int p) { return (p & ~12) | ((p & 4) << 1) | ((p & 8) >> 1); }
; #define EPI_ROWS_BEGIN() \
;   _Pragma("unroll") for (int ai = 0; ai < 2; ++ai) { if (u.pm * 256 + ai * 128 >= T) continue;
; template <class Epi>
; DI void gemm_phase(PG8_LAS unsigned char* lds, const Gemm g, const StaticOrder& S, const Epi& E, const int wv) {
;     ...
;       PG8_BAR; PG8_WAIT_L(0); PG8_MMA(1, 0, At, B0); PG8_BAR; PG8_SCHED;
;       PG8_STAGE(PG8_SB(1, 1), b3 + hstep, voffB);
;       PG8_WAIT_V(6); PG8_BAR; PG8_MMA(1, 1, At, B1); PG8_BAR;
;   DI void operator()(AccRef acc, const pg8::Unit& u, int wr, int wc, int fr, int fq) const {
;     const int row0 = u.pm * 256 + wr * 64 + fr, w0 = wc * 32 + 8 * fq, head = u.pn;
;     EPI_ROWS_BEGIN()
;       float rs[4];
; #pragma unroll
;       for (int m = 0; m < 4; ++m) rs[m] = ss[row0 + ai * 128 + m * 16];
; #pragma unroll
;       for (int m = 0; m < 4; ++m) rs[m] = rsqrtf(rs[m] * (1.f / 256.f) + EPS);
; #pragma unroll
;       for (int m = 0; m < 4; ++m) {
;         const int row = row0 + ai * 128 + m * 16;
;         const int s = row / L, p = row - s * L;
;         *(u32x4*)(kn + (size_t)row * 512 + head * 128 + w0) = pack8v(acc[ai][0][m][0] * rs[m], acc[ai][0][m][1] * rs[m]);
;         u16* vp = vt + (size_t)((s * 4 + head) * 128 + w0) * LP + vt_pos(p);
	s_waitcnt lgkmcnt(0)
	s_setprio 1
	v_mfma_f32_16x16x32_bf16 v[60:63], v[142:145], v[174:177], v[60:63]
	v_mfma_f32_16x16x32_bf16 v[56:59], v[166:169], v[174:177], v[56:59]
	v_mfma_f32_16x16x32_bf16 v[48:51], v[142:145], v[182:185], v[48:51]
	v_mfma_f32_16x16x32_bf16 v[44:47], v[166:169], v[182:185], v[44:47]
	v_mfma_f32_16x16x32_bf16 v[32:35], v[142:145], v[190:193], v[32:35]
	v_mfma_f32_16x16x32_bf16 v[28:31], v[166:169], v[190:193], v[28:31]
	v_mfma_f32_16x16x32_bf16 v[16:19], v[142:145], v[198:201], v[16:19]
	v_mfma_f32_16x16x32_bf16 v[12:15], v[166:169], v[198:201], v[12:15]
	v_mfma_f32_16x16x32_bf16 v[60:63], v[162:165], v[178:181], v[60:63]
	v_mfma_f32_16x16x32_bf16 v[56:59], v[170:173], v[178:181], v[56:59]
	v_mfma_f32_16x16x32_bf16 v[48:51], v[162:165], v[186:189], v[48:51]
	v_mfma_f32_16x16x32_bf16 v[44:47], v[170:173], v[186:189], v[44:47]
	v_mfma_f32_16x16x32_bf16 v[32:35], v[162:165], v[194:197], v[32:35]
	v_mfma_f32_16x16x32_bf16 v[28:31], v[170:173], v[194:197], v[28:31]
	v_mfma_f32_16x16x32_bf16 v[16:19], v[162:165], v[202:205], v[16:19]
	v_mfma_f32_16x16x32_bf16 v[12:15], v[170:173], v[202:205], v[12:15]
	s_setprio 0
	s_barrier
	s_mov_b32 m0, s89
	v_lshl_add_u64 v[142:143], s[38:39], 0, v[132:133]
	global_load_lds_dwordx4 v[142:143], off
	v_lshl_add_u64 v[142:143], s[38:39], 0, v[128:129]
	s_mov_b32 m0, s88
	s_nop 0
	global_load_lds_dwordx4 v[142:143], off
	s_waitcnt vmcnt(6)
	s_barrier
	s_setprio 1
	v_mfma_f32_16x16x32_bf16 v[52:55], v[206:209], v[174:177], v[52:55]
	v_mfma_f32_16x16x32_bf16 v[40:43], v[214:217], v[174:177], v[40:43]
	v_mfma_f32_16x16x32_bf16 v[36:39], v[206:209], v[182:185], v[36:39]
	v_mfma_f32_16x16x32_bf16 v[24:27], v[214:217], v[182:185], v[24:27]
	v_mfma_f32_16x16x32_bf16 v[20:23], v[206:209], v[190:193], v[20:23]
	v_mfma_f32_16x16x32_bf16 v[8:11], v[214:217], v[190:193], v[8:11]
	v_mfma_f32_16x16x32_bf16 v[4:7], v[206:209], v[198:201], v[4:7]
	v_mfma_f32_16x16x32_bf16 v[0:3], v[214:217], v[198:201], v[0:3]
	v_mfma_f32_16x16x32_bf16 v[52:55], v[210:213], v[178:181], v[52:55]
	v_mfma_f32_16x16x32_bf16 v[40:43], v[220:223], v[178:181], v[40:43]
	v_mfma_f32_16x16x32_bf16 v[36:39], v[210:213], v[186:189], v[36:39]
	v_mfma_f32_16x16x32_bf16 v[24:27], v[220:223], v[186:189], v[24:27]
	v_mfma_f32_16x16x32_bf16 v[20:23], v[210:213], v[194:197], v[20:23]
	v_mfma_f32_16x16x32_bf16 v[8:11], v[220:223], v[194:197], v[8:11]
	v_mfma_f32_16x16x32_bf16 v[4:7], v[210:213], v[202:205], v[4:7]
	v_mfma_f32_16x16x32_bf16 v[0:3], v[220:223], v[202:205], v[0:3]
	s_setprio 0
	s_andn2_b64 vcc, exec, s[36:37]
	s_mov_b64 s[38:39], -1
	s_mov_b64 s[36:37], 0
	s_mov_b64 s[40:41], 0x100
	s_barrier
	s_cbranch_vccz .LBB0_537
	s_lshl_b32 s36, s4, 7
	s_ashr_i32 s37, s36, 31
	v_lshl_add_u32 v142, s34, 8, v139
	v_or_b32_e32 v157, s36, v138
	s_cmpk_gt_i32 s34, 0x181
	v_lshlrev_b32_e32 v136, 1, v138
	s_cbranch_scc1 .LBB0_540
	v_ashrrev_i32_e32 v143, 31, v142
	v_lshl_add_u64 v[144:145], v[142:143], 2, s[18:19]
	v_or_b32_e32 v158, 16, v142
	global_load_dword v148, v[144:145], off
	v_ashrrev_i32_e32 v159, 31, v158
	v_or_b32_e32 v150, 32, v142
	v_or_b32_e32 v144, 48, v142
	v_lshl_add_u64 v[146:147], v[158:159], 2, s[18:19]
	v_ashrrev_i32_e32 v151, 31, v150
	v_ashrrev_i32_e32 v145, 31, v144
	v_lshl_add_u64 v[162:163], v[150:151], 2, s[18:19]
	v_lshl_add_u64 v[164:165], v[144:145], 2, s[18:19]
	global_load_dword v161, v[146:147], off
	global_load_dword v172, v[162:163], off
	global_load_dword v173, v[164:165], off
	v_mul_hi_i32 v162, v142, s79
	v_lshrrev_b32_e32 v164, 31, v162
	v_ashrrev_i32_e32 v165, 11, v162
	v_lshlrev_b64 v[162:163], 10, v[142:143]
	v_add_u32_e32 v143, v165, v164
	v_mad_i32_i24 v166, v143, s80, v142
	v_mov_b64_e32 v[146:147], s[16:17]
	v_lshl_add_u32 v143, v143, 9, v157
	v_and_or_b32 v166, v166, -13, v152
	v_mad_i64_i32 v[164:165], s[4:5], v143, s81, v[146:147]
	v_ashrrev_i32_e32 v167, 31, v166
	v_lshl_add_u64 v[164:165], v[166:167], 1, v[164:165]
	v_add_co_u32_e32 v166, vcc, s64, v164
	s_lshl_b64 s[38:39], s[36:37], 1
	s_nop 0
	v_addc_co_u32_e32 v167, vcc, 0, v165, vcc
	v_add_co_u32_e32 v168, vcc, s65, v164
	v_lshl_add_u64 v[162:163], s[14:15], 0, v[162:163]
	s_nop 0
	v_addc_co_u32_e32 v169, vcc, 0, v165, vcc
	v_add_co_u32_e32 v170, vcc, s66, v164
	v_lshl_add_u64 v[162:163], v[162:163], 0, s[38:39]
	s_nop 0
	v_addc_co_u32_e32 v171, vcc, 0, v165, vcc
	v_lshl_add_u64 v[162:163], v[162:163], 0, v[136:137]
	s_waitcnt vmcnt(0)
; DI u16 f2bf(float x) { return (u16)(cvtpk(x, 0.f) & 0xffffu); }
; DI u32x4 pack8v(f32x4 a, f32x4 b) { return u32x4{cvtpk(a[0], a[1]), cvtpk(a[2], a[3]), cvtpk(b[0], b[1]), cvtpk(b[2], b[3])}; }
; DI int vt_pos(int p) { return (p & ~12) | ((p & 4) << 1) | ((p & 8) >> 1); }
;   DI void operator()(AccRef acc, const pg8::Unit& u, int wr, int wc, int fr, int fq) const {
;     ...
;       float rs[4];
; #pragma unroll
;       for (int m = 0; m < 4; ++m) rs[m] = ss[row0 + ai * 128 + m * 16];
; #pragma unroll
;       for (int m = 0; m < 4; ++m) rs[m] = rsqrtf(rs[m] * (1.f / 256.f) + EPS);
; #pragma unroll
;       for (int m = 0; m < 4; ++m) {
;         const int row = row0 + ai * 128 + m * 16;
;         const int s = row / L, p = row - s * L;
;         *(u32x4*)(kn + (size_t)row * 512 + head * 128 + w0) = pack8v(acc[ai][0][m][0] * rs[m], acc[ai][0][m][1] * rs[m]);
;         u16* vp = vt + (size_t)((s * 4 + head) * 128 + w0) * LP + vt_pos(p);
; #pragma unroll
;         for (int n = 0; n < 2; ++n)
; #pragma unroll
;           for (int e = 0; e < 4; ++e) vp[(size_t)(4 * n + e) * LP] = f2bf(acc[ai][1][m][n][e] * rs[m]);
;         asm volatile("" ::: "memory");
	v_fmamk_f32 v143, v148, 0x3b800000, v156
	v_mul_f32_e32 v148, 0x4b800000, v143
	v_cmp_gt_f32_e32 vcc, s78, v143
	v_fmamk_f32 v161, v161, 0x3b800000, v156
	v_fmamk_f32 v172, v172, 0x3b800000, v156
	v_fmamk_f32 v173, v173, 0x3b800000, v156
	v_cndmask_b32_e32 v143, v143, v148, vcc
	v_mul_f32_e32 v148, 0x4b800000, v161
	v_mul_f32_e32 v174, 0x4b800000, v172
	v_mul_f32_e32 v175, 0x4b800000, v173
	v_rsq_f32_e32 v143, v143
	v_cmp_gt_f32_e64 s[4:5], s78, v161
	v_cmp_gt_f32_e64 s[6:7], s78, v172
	v_cmp_gt_f32_e64 s[8:9], s78, v173
	v_cndmask_b32_e64 v148, v161, v148, s[4:5]
	v_cndmask_b32_e64 v161, v172, v174, s[6:7]
	v_cndmask_b32_e64 v172, v173, v175, s[8:9]
	v_rsq_f32_e32 v148, v148
	v_rsq_f32_e32 v161, v161
	v_rsq_f32_e32 v173, v172
	v_mul_f32_e32 v172, 0x45800000, v143
	v_cndmask_b32_e32 v172, v143, v172, vcc
	v_mul_f32_e32 v143, 0x45800000, v148
	v_mul_f32_e32 v175, 0x45800000, v161
	v_mul_f32_e32 v177, 0x45800000, v173
	v_pk_mul_f32 v[126:127], v[126:127], v[172:173] op_sel_hi:[1,0]
	v_pk_mul_f32 v[124:125], v[124:125], v[172:173] op_sel_hi:[1,0]
	v_pk_mul_f32 v[122:123], v[122:123], v[172:173] op_sel_hi:[1,0]
	v_pk_mul_f32 v[120:121], v[120:121], v[172:173] op_sel_hi:[1,0]
	v_cndmask_b32_e64 v174, v148, v143, s[4:5]
	v_cndmask_b32_e64 v176, v161, v175, s[6:7]
	v_cndmask_b32_e64 v148, v173, v177, s[8:9]
	v_mul_f32_e32 v143, v116, v172
	v_mul_f32_e32 v161, v117, v172
	v_mul_f32_e32 v173, v118, v172
	v_mul_f32_e32 v175, v119, v172
	v_cvt_pk_bf16_f32 v116, v124, v125
	v_cvt_pk_bf16_f32 v117, v126, v127
	v_cvt_pk_bf16_f32 v118, v120, v121
	v_cvt_pk_bf16_f32 v119, v122, v123
	v_mul_f32_e32 v104, v104, v172
	v_cvt_pk_bf16_f32 v120, v143, s0
	v_cvt_pk_bf16_f32 v121, v161, s0
	v_cvt_pk_bf16_f32 v122, v173, s0
	v_cvt_pk_bf16_f32 v123, v175, s0
	global_store_dwordx4 v[162:163], v[116:119], off
	global_store_short v[164:165], v120, off
	global_store_short v[166:167], v121, off offset:128
	global_store_short v[168:169], v122, off offset:256
	global_store_short v[170:171], v123, off offset:384
	v_add_co_u32_e32 v116, vcc, s70, v164
	v_cvt_pk_bf16_f32 v104, v104, s0
	s_nop 0
	v_addc_co_u32_e32 v117, vcc, 0, v165, vcc
	global_store_short v[116:117], v104, off offset:512
	v_mul_f32_e32 v104, v105, v172
	v_cvt_pk_bf16_f32 v116, v104, s0
	v_add_co_u32_e32 v104, vcc, s71, v164
	v_pk_mul_f32 v[108:109], v[108:109], v[174:175] op_sel_hi:[1,0]
	s_nop 0
	v_addc_co_u32_e32 v105, vcc, 0, v165, vcc
	global_store_short v[104:105], v116, off offset:640
	v_mul_f32_e32 v104, v106, v172
	v_cvt_pk_bf16_f32 v106, v104, s0
	v_add_co_u32_e32 v104, vcc, s75, v164
	v_pk_mul_f32 v[110:111], v[110:111], v[174:175] op_sel_hi:[1,0]
	s_nop 0
	v_addc_co_u32_e32 v105, vcc, 0, v165, vcc
	global_store_short v[104:105], v106, off offset:768
	v_mul_f32_e32 v104, v107, v172
	v_cvt_pk_bf16_f32 v106, v104, s0
	v_add_co_u32_e32 v104, vcc, s76, v164
	v_mul_f32_e32 v100, v100, v174
	s_nop 0
	v_addc_co_u32_e32 v105, vcc, 0, v165, vcc
	global_store_short v[104:105], v106, off offset:896
	v_mul_hi_i32 v104, v158, s79
	v_lshrrev_b32_e32 v105, 31, v104
	v_ashrrev_i32_e32 v104, 11, v104
	v_add_u32_e32 v116, v104, v105
	v_pk_mul_f32 v[106:107], v[114:115], v[174:175] op_sel_hi:[1,0]
	v_pk_mul_f32 v[104:105], v[112:113], v[174:175] op_sel_hi:[1,0]
	v_mad_i32_i24 v117, v116, s80, v158
	v_cvt_pk_bf16_f32 v104, v104, v105
	v_cvt_pk_bf16_f32 v105, v106, v107
	v_cvt_pk_bf16_f32 v106, v108, v109
	v_lshlrev_b64 v[108:109], 10, v[158:159]
	v_lshl_add_u64 v[108:109], s[14:15], 0, v[108:109]
	v_lshl_add_u64 v[108:109], v[108:109], 0, s[38:39]
	v_cvt_pk_bf16_f32 v107, v110, v111
	v_lshl_add_u64 v[108:109], v[108:109], 0, v[136:137]
	global_store_dwordx4 v[108:109], v[104:107], off
	v_cvt_pk_bf16_f32 v100, v100, s0
	v_mul_f32_e32 v88, v88, v174
	v_lshl_add_u32 v104, v116, 9, v157
	v_and_or_b32 v106, v117, -13, v152
	v_mad_i64_i32 v[104:105], s[4:5], v104, s81, v[146:147]
	v_ashrrev_i32_e32 v107, 31, v106
	v_lshl_add_u64 v[104:105], v[106:107], 1, v[104:105]
	global_store_short v[104:105], v100, off
	v_mul_f32_e32 v100, v101, v174
	v_cvt_pk_bf16_f32 v106, v100, s0
	v_add_co_u32_e32 v100, vcc, s64, v104
	v_cvt_pk_bf16_f32 v88, v88, s0
	s_nop 0
	v_addc_co_u32_e32 v101, vcc, 0, v105, vcc
	global_store_short v[100:101], v106, off offset:128
	v_mul_f32_e32 v100, v102, v174
	v_cvt_pk_bf16_f32 v102, v100, s0
	v_add_co_u32_e32 v100, vcc, s65, v104
	v_pk_mul_f32 v[92:93], v[92:93], v[176:177] op_sel_hi:[1,0]
	s_nop 0
	v_addc_co_u32_e32 v101, vcc, 0, v105, vcc
	global_store_short v[100:101], v102, off offset:256
	v_mul_f32_e32 v100, v103, v174
	v_cvt_pk_bf16_f32 v102, v100, s0
	v_add_co_u32_e32 v100, vcc, s66, v104
	v_pk_mul_f32 v[94:95], v[94:95], v[176:177] op_sel_hi:[1,0]
	s_nop 0
	v_addc_co_u32_e32 v101, vcc, 0, v105, vcc
	global_store_short v[100:101], v102, off offset:384
	v_add_co_u32_e32 v100, vcc, s70, v104
	v_mul_f32_e32 v84, v84, v176
	s_nop 0
	v_addc_co_u32_e32 v101, vcc, 0, v105, vcc
	global_store_short v[100:101], v88, off offset:512
	v_mul_f32_e32 v88, v89, v174
	v_cvt_pk_bf16_f32 v100, v88, s0
	v_add_co_u32_e32 v88, vcc, s71, v104
	v_cvt_pk_bf16_f32 v84, v84, s0
	s_nop 0
	v_addc_co_u32_e32 v89, vcc, 0, v105, vcc
	global_store_short v[88:89], v100, off offset:640
; DI u16 f2bf(float x) { return (u16)(cvtpk(x, 0.f) & 0xffffu); }
; DI u32x4 pack8v(f32x4 a, f32x4 b) { return u32x4{cvtpk(a[0], a[1]), cvtpk(a[2], a[3]), cvtpk(b[0], b[1]), cvtpk(b[2], b[3])}; }
; DI int vt_pos(int p) { return (p & ~12) | ((p & 4) << 1) | ((p & 8) >> 1); }
;   DI void operator()(AccRef acc, const pg8::Unit& u, int wr, int wc, int fr, int fq) const {
;     ...
;       for (int m = 0; m < 4; ++m) {
;         const int row = row0 + ai * 128 + m * 16;
;         const int s = row / L, p = row - s * L;
;         *(u32x4*)(kn + (size_t)row * 512 + head * 128 + w0) = pack8v(acc[ai][0][m][0] * rs[m], acc[ai][0][m][1] * rs[m]);
;         u16* vp = vt + (size_t)((s * 4 + head) * 128 + w0) * LP + vt_pos(p);
; #pragma unroll
;         for (int n = 0; n < 2; ++n)
; #pragma unroll
;           for (int e = 0; e < 4; ++e) vp[(size_t)(4 * n + e) * LP] = f2bf(acc[ai][1][m][n][e] * rs[m]);
;         asm volatile("" ::: "memory");
	v_mul_f32_e32 v88, v90, v174
	v_cvt_pk_bf16_f32 v90, v88, s0
	v_add_co_u32_e32 v88, vcc, s75, v104
	v_mul_f32_e32 v72, v72, v176
	s_nop 0
	v_addc_co_u32_e32 v89, vcc, 0, v105, vcc
	global_store_short v[88:89], v90, off offset:768
	v_mul_f32_e32 v88, v91, v174
	v_cvt_pk_bf16_f32 v90, v88, s0
	v_add_co_u32_e32 v88, vcc, s76, v104
	v_cvt_pk_bf16_f32 v72, v72, s0
	s_nop 0
	v_addc_co_u32_e32 v89, vcc, 0, v105, vcc
	global_store_short v[88:89], v90, off offset:896
	v_mul_hi_i32 v88, v150, s79
	v_lshrrev_b32_e32 v89, 31, v88
	v_ashrrev_i32_e32 v88, 11, v88
	v_add_u32_e32 v100, v88, v89
	v_pk_mul_f32 v[90:91], v[98:99], v[176:177] op_sel_hi:[1,0]
	v_pk_mul_f32 v[88:89], v[96:97], v[176:177] op_sel_hi:[1,0]
	v_mad_i32_i24 v101, v100, s80, v150
	v_cvt_pk_bf16_f32 v88, v88, v89
	v_cvt_pk_bf16_f32 v89, v90, v91
	v_cvt_pk_bf16_f32 v90, v92, v93
	v_lshlrev_b64 v[92:93], 10, v[150:151]
	v_lshl_add_u64 v[92:93], s[14:15], 0, v[92:93]
	v_lshl_add_u64 v[92:93], v[92:93], 0, s[38:39]
	v_cvt_pk_bf16_f32 v91, v94, v95
	v_lshl_add_u64 v[92:93], v[92:93], 0, v[136:137]
	global_store_dwordx4 v[92:93], v[88:91], off
	v_pk_mul_f32 v[76:77], v[76:77], v[148:149] op_sel_hi:[1,0]
	v_pk_mul_f32 v[78:79], v[78:79], v[148:149] op_sel_hi:[1,0]
	v_lshl_add_u32 v88, v100, 9, v157
	v_and_or_b32 v90, v101, -13, v152
	v_mad_i64_i32 v[88:89], s[4:5], v88, s81, v[146:147]
	v_ashrrev_i32_e32 v91, 31, v90
	v_lshl_add_u64 v[88:89], v[90:91], 1, v[88:89]
	global_store_short v[88:89], v84, off
	v_mul_f32_e32 v84, v85, v176
	v_cvt_pk_bf16_f32 v90, v84, s0
	v_add_co_u32_e32 v84, vcc, s64, v88
	v_mul_f32_e32 v68, v68, v148
	s_nop 0
	v_addc_co_u32_e32 v85, vcc, 0, v89, vcc
	global_store_short v[84:85], v90, off offset:128
	v_mul_f32_e32 v84, v86, v176
	v_cvt_pk_bf16_f32 v86, v84, s0
	v_add_co_u32_e32 v84, vcc, s65, v88
	v_cvt_pk_bf16_f32 v68, v68, s0
	s_nop 0
	v_addc_co_u32_e32 v85, vcc, 0, v89, vcc
	global_store_short v[84:85], v86, off offset:256
	v_mul_f32_e32 v84, v87, v176
	v_cvt_pk_bf16_f32 v86, v84, s0
	v_add_co_u32_e32 v84, vcc, s66, v88
	v_mul_f32_e32 v64, v64, v148
	s_nop 0
	v_addc_co_u32_e32 v85, vcc, 0, v89, vcc
	global_store_short v[84:85], v86, off offset:384
	v_add_co_u32_e32 v84, vcc, s70, v88
	v_cvt_pk_bf16_f32 v64, v64, s0
	s_nop 0
	v_addc_co_u32_e32 v85, vcc, 0, v89, vcc
	global_store_short v[84:85], v72, off offset:512
	v_mul_f32_e32 v72, v73, v176
	v_cvt_pk_bf16_f32 v84, v72, s0
	v_add_co_u32_e32 v72, vcc, s71, v88
	s_nop 1
	v_addc_co_u32_e32 v73, vcc, 0, v89, vcc
	global_store_short v[72:73], v84, off offset:640
	v_mul_f32_e32 v72, v74, v176
	v_cvt_pk_bf16_f32 v74, v72, s0
	v_add_co_u32_e32 v72, vcc, s75, v88
	s_nop 1
	v_addc_co_u32_e32 v73, vcc, 0, v89, vcc
	global_store_short v[72:73], v74, off offset:768
	v_mul_f32_e32 v72, v75, v176
	v_cvt_pk_bf16_f32 v74, v72, s0
	v_add_co_u32_e32 v72, vcc, s76, v88
	s_nop 1
	v_addc_co_u32_e32 v73, vcc, 0, v89, vcc
	global_store_short v[72:73], v74, off offset:896
	v_mul_hi_i32 v72, v144, s79
	v_lshrrev_b32_e32 v73, 31, v72
	v_ashrrev_i32_e32 v72, 11, v72
	v_add_u32_e32 v84, v72, v73
	v_pk_mul_f32 v[74:75], v[82:83], v[148:149] op_sel_hi:[1,0]
	v_pk_mul_f32 v[72:73], v[80:81], v[148:149] op_sel_hi:[1,0]
	v_mad_i32_i24 v85, v84, s80, v144
	v_cvt_pk_bf16_f32 v72, v72, v73
	v_cvt_pk_bf16_f32 v73, v74, v75
	v_cvt_pk_bf16_f32 v74, v76, v77
	v_lshlrev_b64 v[76:77], 10, v[144:145]
	v_lshl_add_u64 v[76:77], s[14:15], 0, v[76:77]
	v_lshl_add_u64 v[76:77], v[76:77], 0, s[38:39]
	v_cvt_pk_bf16_f32 v75, v78, v79
	v_lshl_add_u64 v[76:77], v[76:77], 0, v[136:137]
	global_store_dwordx4 v[76:77], v[72:75], off
	s_nop 1
	v_lshl_add_u32 v72, v84, 9, v157
	v_and_or_b32 v74, v85, -13, v152
	v_mad_i64_i32 v[72:73], s[4:5], v72, s81, v[146:147]
	v_ashrrev_i32_e32 v75, 31, v74
	v_lshl_add_u64 v[72:73], v[74:75], 1, v[72:73]
	global_store_short v[72:73], v68, off
	v_mul_f32_e32 v68, v69, v148
	v_cvt_pk_bf16_f32 v74, v68, s0
	v_add_co_u32_e32 v68, vcc, s64, v72
	s_nop 1
	v_addc_co_u32_e32 v69, vcc, 0, v73, vcc
	global_store_short v[68:69], v74, off offset:128
	v_mul_f32_e32 v68, v70, v148
	v_cvt_pk_bf16_f32 v70, v68, s0
	v_add_co_u32_e32 v68, vcc, s65, v72
	s_nop 1
	v_addc_co_u32_e32 v69, vcc, 0, v73, vcc
	global_store_short v[68:69], v70, off offset:256
	v_mul_f32_e32 v68, v71, v148
	v_cvt_pk_bf16_f32 v70, v68, s0
	v_add_co_u32_e32 v68, vcc, s66, v72
	s_nop 1
	v_addc_co_u32_e32 v69, vcc, 0, v73, vcc
	global_store_short v[68:69], v70, off offset:384
	v_add_co_u32_e32 v68, vcc, s70, v72
	s_nop 1
	v_addc_co_u32_e32 v69, vcc, 0, v73, vcc
	global_store_short v[68:69], v64, off offset:512
	v_mul_f32_e32 v64, v65, v148
	v_cvt_pk_bf16_f32 v68, v64, s0
	v_add_co_u32_e32 v64, vcc, s71, v72
	s_nop 1
	v_addc_co_u32_e32 v65, vcc, 0, v73, vcc
	global_store_short v[64:65], v68, off offset:640
	v_mul_f32_e32 v64, v66, v148
	v_cvt_pk_bf16_f32 v66, v64, s0
	v_add_co_u32_e32 v64, vcc, 0xc000, v72
	s_nop 1
	v_addc_co_u32_e32 v65, vcc, 0, v73, vcc
	global_store_short v[64:65], v66, off offset:768
	v_mul_f32_e32 v64, v67, v148
	v_cvt_pk_bf16_f32 v66, v64, s0
	v_add_co_u32_e32 v64, vcc, 0xe000, v72
	s_nop 1
	v_addc_co_u32_e32 v65, vcc, 0, v73, vcc
	global_store_short v[64:65], v66, off offset:896

; #define PG8_STAGE(bufoff, gbase, voff) do { _Pragma("unroll") for (int _i = 0; _i < 2; ++_i) \
;     __builtin_amdgcn_global_load_lds((const unsigned*)((const char*)(gbase) + (voff)[_i]), (PG8_LAS unsigned*)(lds + (bufoff) + ldsw + _i * 8192), 16, 0, 0); } while (0)
; #define PG8_LDA(dst, b, h) do { _Pragma("unroll") for (int m = 0; m < 4; ++m) _Pragma("unroll") for (int k = 0; k < 2; ++k) dst[m][k] = *(const PG8_LAS bf16x8*)(lds + PG8_SA(b, h) + aoff + m * 2048 + k * 1024); } while (0)
; #define PG8_LDB(dst, b, h) do { _Pragma("unroll") for (int n = 0; n < 2; ++n) _Pragma("unroll") for (int k = 0; k < 2; ++k) dst[n][k] = *(const PG8_LAS bf16x8*)(lds + PG8_SB(b, h) + boff + n * 2048 + k * 1024); } while (0)
; #define PG8_MMA(ai, bj, At, Bt) do { __builtin_amdgcn_s_setprio(1); _Pragma("unroll") for (int m = 0; m < 4; ++m) _Pragma("unroll") for (int n = 0; n < 2; ++n) _Pragma("unroll") for (int k = 0; k < 2; ++k) \
;     acc[ai][bj][m][n] = __builtin_amdgcn_mfma_f32_16x16x32_bf16(Bt[n][k], At[m][k], acc[ai][bj][m][n], 0, 0, 0); __builtin_amdgcn_s_setprio(0); } while (0)
; #define PG8_WAIT_L(n) asm volatile("s_waitcnt lgkmcnt(" #n ")" ::: "memory")
; #define PG8_BAR __builtin_amdgcn_s_barrier()
; template <class Epi>
; DI void gemm_phase(PG8_LAS unsigned char* lds, const Gemm g, const StaticOrder& S, const Epi& E, const int wv) {
;     ...
;   for (;;) {
;     const bool has_next = S.next(ui + 1, nxt);
;     const char* nA = has_next ? (const char*)g.A + (size_t)nxt.pm * tstep : cA; const char* nB = has_next ? (const char*)g.Bt + (size_t)nxt.pn * tstep : cB;
; #pragma nounroll
;     for (int t = 0; t < nt; t += 2) {
;       const bool last = (t == nt - 2);
;       const char* a1 = cA + (size_t)(t + 1) * kstep;
;       const char* a2 = last ? nA : cA + (size_t)(t + 2) * kstep; const char* b2 = last ? nB : cB + (size_t)(t + 2) * kstep;
;       const char* a3 = a2 + kstep; const char* b3 = b2 + kstep;
;       PG8_LDB(B0, 0, 0); PG8_SCHED; PG8_LDA(At, 0, 0); PG8_STAGE(PG8_SA(1, 1), a1 + hstep, voffA);
;       PG8_WAIT_L(8); PG8_BAR; PG8_WAIT_L(0); PG8_MMA(0, 0, At, B0); PG8_BAR; PG8_SCHED;
;       PG8_LDB(B1, 0, 1); PG8_STAGE(PG8_SB(0, 0), b2, voffB);
;       PG8_BAR; PG8_WAIT_L(0); PG8_MMA(0, 1, At, B1); PG8_BAR;
;       PG8_LDA(At, 0, 1); PG8_STAGE(PG8_SA(0, 0), a2, voffA);
;       PG8_BAR; PG8_WAIT_L(0); PG8_MMA(1, 0, At, B0); PG8_BAR; PG8_SCHED;
.LBB0_770:
	ds_read_b128 v[128:131], v223
	ds_read_b128 v[132:135], v223 offset:1024
	ds_read_b128 v[136:139], v223 offset:2048
	ds_read_b128 v[140:143], v223 offset:3072
	s_add_u32 s42, s40, 0xfffc0080
	s_addc_u32 s43, s41, -1
	s_cmp_eq_u32 s76, 12
	s_cselect_b32 s45, s29, s43
	s_cselect_b32 s44, s37, s42
	s_cselect_b32 s43, s27, s75
	s_cselect_b32 s42, s39, s74
	v_lshl_add_u64 v[176:177], s[40:41], 0, v[202:203]
	s_add_i32 m0, s53, 0xc000
	ds_read_b128 v[144:147], v224
	ds_read_b128 v[148:151], v224 offset:1024
	ds_read_b128 v[152:155], v224 offset:2048
	ds_read_b128 v[156:159], v224 offset:3072
	ds_read_b128 v[160:163], v224 offset:4096
	ds_read_b128 v[164:167], v224 offset:5120
	ds_read_b128 v[168:171], v224 offset:6144
	ds_read_b128 v[172:175], v224 offset:7168
	global_load_lds_dwordx4 v[176:177], off
	v_lshl_add_u64 v[176:177], s[40:41], 0, v[204:205]
	s_add_i32 m0, s53, 0xe000
	s_nop 0
	global_load_lds_dwordx4 v[176:177], off
	s_waitcnt lgkmcnt(8)
	s_barrier
	s_waitcnt lgkmcnt(0)
	s_setprio 1
	s_waitcnt lgkmcnt(0)
	v_mfma_f32_16x16x32_bf16 v[124:127], v[128:131], v[144:147], v[124:127]
	v_mfma_f32_16x16x32_bf16 v[120:123], v[136:139], v[144:147], v[120:123]
	v_mfma_f32_16x16x32_bf16 v[108:111], v[128:131], v[152:155], v[108:111]
	v_mfma_f32_16x16x32_bf16 v[104:107], v[136:139], v[152:155], v[104:107]
	v_mfma_f32_16x16x32_bf16 v[92:95], v[128:131], v[160:163], v[92:95]
	v_mfma_f32_16x16x32_bf16 v[88:91], v[136:139], v[160:163], v[88:91]
	v_mfma_f32_16x16x32_bf16 v[76:79], v[128:131], v[168:171], v[76:79]
	v_mfma_f32_16x16x32_bf16 v[72:75], v[136:139], v[168:171], v[72:75]
	v_mfma_f32_16x16x32_bf16 v[124:127], v[132:135], v[148:151], v[124:127]
	v_mfma_f32_16x16x32_bf16 v[120:123], v[140:143], v[148:151], v[120:123]
	v_mfma_f32_16x16x32_bf16 v[108:111], v[132:135], v[156:159], v[108:111]
	v_mfma_f32_16x16x32_bf16 v[104:107], v[140:143], v[156:159], v[104:107]
	v_mfma_f32_16x16x32_bf16 v[92:95], v[132:135], v[164:167], v[92:95]
	v_mfma_f32_16x16x32_bf16 v[88:91], v[140:143], v[164:167], v[88:91]
	v_mfma_f32_16x16x32_bf16 v[76:79], v[132:135], v[172:175], v[76:79]
	v_mfma_f32_16x16x32_bf16 v[72:75], v[140:143], v[172:175], v[72:75]
	s_setprio 0
	s_barrier
	s_add_i32 s77, s66, s52
	v_lshl_add_u64 v[208:209], s[42:43], 0, v[194:195]
	s_mov_b32 m0, s77
	ds_read_b128 v[176:179], v225
	ds_read_b128 v[180:183], v225 offset:1024
	ds_read_b128 v[184:187], v225 offset:2048
	ds_read_b128 v[188:191], v225 offset:3072
	global_load_lds_dwordx4 v[208:209], off
	v_lshl_add_u64 v[210:211], s[42:43], 0, v[198:199]
	s_add_i32 m0, s77, 0x2000
	s_nop 0
	global_load_lds_dwordx4 v[210:211], off
	s_barrier
	s_waitcnt lgkmcnt(0)
	s_setprio 1
	v_mfma_f32_16x16x32_bf16 v[116:119], v[176:179], v[144:147], v[116:119]
	v_mfma_f32_16x16x32_bf16 v[112:115], v[184:187], v[144:147], v[112:115]
	v_mfma_f32_16x16x32_bf16 v[100:103], v[176:179], v[152:155], v[100:103]
	v_mfma_f32_16x16x32_bf16 v[96:99], v[184:187], v[152:155], v[96:99]
	v_mfma_f32_16x16x32_bf16 v[84:87], v[176:179], v[160:163], v[84:87]
	v_mfma_f32_16x16x32_bf16 v[80:83], v[184:187], v[160:163], v[80:83]
	v_mfma_f32_16x16x32_bf16 v[68:71], v[176:179], v[168:171], v[68:71]
	v_mfma_f32_16x16x32_bf16 v[64:67], v[184:187], v[168:171], v[64:67]
	v_mfma_f32_16x16x32_bf16 v[116:119], v[180:183], v[148:151], v[116:119]
	v_mfma_f32_16x16x32_bf16 v[112:115], v[188:191], v[148:151], v[112:115]
	v_mfma_f32_16x16x32_bf16 v[100:103], v[180:183], v[156:159], v[100:103]
	v_mfma_f32_16x16x32_bf16 v[96:99], v[188:191], v[156:159], v[96:99]
	v_mfma_f32_16x16x32_bf16 v[84:87], v[180:183], v[164:167], v[84:87]
	v_mfma_f32_16x16x32_bf16 v[80:83], v[188:191], v[164:167], v[80:83]
	v_mfma_f32_16x16x32_bf16 v[68:71], v[180:183], v[172:175], v[68:71]
	v_mfma_f32_16x16x32_bf16 v[64:67], v[188:191], v[172:175], v[64:67]
	s_setprio 0
	s_mov_b32 m0, s53
	v_lshl_add_u64 v[212:213], s[44:45], 0, v[192:193]
	s_barrier
	ds_read_b128 v[144:147], v224 offset:16384
	ds_read_b128 v[148:151], v224 offset:17408
	ds_read_b128 v[152:155], v224 offset:18432
	ds_read_b128 v[156:159], v224 offset:19456
	ds_read_b128 v[160:163], v224 offset:20480
	ds_read_b128 v[164:167], v224 offset:21504
	ds_read_b128 v[168:171], v224 offset:22528
	ds_read_b128 v[172:175], v224 offset:23552
	global_load_lds_dwordx4 v[212:213], off
	v_lshl_add_u64 v[214:215], s[44:45], 0, v[196:197]
	s_mov_b32 m0, s54
	s_nop 0
	global_load_lds_dwordx4 v[214:215], off
	s_barrier
	s_waitcnt lgkmcnt(0)
	s_setprio 1
	v_mfma_f32_16x16x32_bf16 v[60:63], v[128:131], v[144:147], v[60:63]
	v_mfma_f32_16x16x32_bf16 v[56:59], v[136:139], v[144:147], v[56:59]
	v_mfma_f32_16x16x32_bf16 v[44:47], v[128:131], v[152:155], v[44:47]
	v_mfma_f32_16x16x32_bf16 v[40:43], v[136:139], v[152:155], v[40:43]
	v_mfma_f32_16x16x32_bf16 v[28:31], v[128:131], v[160:163], v[28:31]
	v_mfma_f32_16x16x32_bf16 v[24:27], v[136:139], v[160:163], v[24:27]
	v_mfma_f32_16x16x32_bf16 v[12:15], v[128:131], v[168:171], v[12:15]
	v_mfma_f32_16x16x32_bf16 v[8:11], v[136:139], v[168:171], v[8:11]
	v_mfma_f32_16x16x32_bf16 v[60:63], v[132:135], v[148:151], v[60:63]
	v_mfma_f32_16x16x32_bf16 v[56:59], v[140:143], v[148:151], v[56:59]
	v_mfma_f32_16x16x32_bf16 v[44:47], v[132:135], v[156:159], v[44:47]
	v_mfma_f32_16x16x32_bf16 v[40:43], v[140:143], v[156:159], v[40:43]
	v_mfma_f32_16x16x32_bf16 v[28:31], v[132:135], v[164:167], v[28:31]
	v_mfma_f32_16x16x32_bf16 v[24:27], v[140:143], v[164:167], v[24:27]
	v_mfma_f32_16x16x32_bf16 v[12:15], v[132:135], v[172:175], v[12:15]
	v_mfma_f32_16x16x32_bf16 v[8:11], v[140:143], v[172:175], v[8:11]
	s_setprio 0
	s_barrier
; #define PG8_STAGE(bufoff, gbase, voff) do { _Pragma("unroll") for (int _i = 0; _i < 2; ++_i) \
;     __builtin_amdgcn_global_load_lds((const unsigned*)((const char*)(gbase) + (voff)[_i]), (PG8_LAS unsigned*)(lds + (bufoff) + ldsw + _i * 8192), 16, 0, 0); } while (0)
; #define PG8_LDA(dst, b, h) do { _Pragma("unroll") for (int m = 0; m < 4; ++m) _Pragma("unroll") for (int k = 0; k < 2; ++k) dst[m][k] = *(const PG8_LAS bf16x8*)(lds + PG8_SA(b, h) + aoff + m * 2048 + k * 1024); } while (0)
; #define PG8_LDB(dst, b, h) do { _Pragma("unroll") for (int n = 0; n < 2; ++n) _Pragma("unroll") for (int k = 0; k < 2; ++k) dst[n][k] = *(const PG8_LAS bf16x8*)(lds + PG8_SB(b, h) + boff + n * 2048 + k * 1024); } while (0)
; #define PG8_MMA(ai, bj, At, Bt) do { __builtin_amdgcn_s_setprio(1); _Pragma("unroll") for (int m = 0; m < 4; ++m) _Pragma("unroll") for (int n = 0; n < 2; ++n) _Pragma("unroll") for (int k = 0; k < 2; ++k) \
;     acc[ai][bj][m][n] = __builtin_amdgcn_mfma_f32_16x16x32_bf16(Bt[n][k], At[m][k], acc[ai][bj][m][n], 0, 0, 0); __builtin_amdgcn_s_setprio(0); } while (0)
; #define PG8_WAIT_V(n) asm volatile("s_waitcnt vmcnt(" #n ")" ::: "memory")
; #define PG8_WAIT_L(n) asm volatile("s_waitcnt lgkmcnt(" #n ")" ::: "memory")
; #define PG8_BAR __builtin_amdgcn_s_barrier()
; #define PG8_SCHED __builtin_amdgcn_sched_barrier(0)
; template <class Epi>
; DI void gemm_phase(PG8_LAS unsigned char* lds, const Gemm g, const StaticOrder& S, const Epi& E, const int wv) {
;     ...
;       PG8_STAGE(PG8_SB(0, 1), b2 + hstep, voffB);
;       PG8_WAIT_V(6); PG8_BAR; PG8_MMA(1, 1, At, B1); PG8_BAR;
;       PG8_LDB(B0, 1, 0); PG8_SCHED; PG8_LDA(At, 1, 0); PG8_STAGE(PG8_SA(0, 1), a2 + hstep, voffA);
;       PG8_WAIT_L(8); PG8_BAR; PG8_WAIT_L(0); PG8_MMA(0, 0, At, B0); PG8_BAR; PG8_SCHED;
;       PG8_LDB(B1, 1, 1); PG8_STAGE(PG8_SB(1, 0), b3, voffB);
;       PG8_BAR; PG8_WAIT_L(0); PG8_MMA(0, 1, At, B1); PG8_BAR;
;       PG8_LDA(At, 1, 1); PG8_STAGE(PG8_SA(1, 0), a3, voffA);
	s_add_u32 s78, s42, 0x40000
	s_addc_u32 s79, s43, 0
	s_add_i32 s77, s67, s52
	v_lshl_add_u64 v[128:129], s[78:79], 0, v[194:195]
	s_mov_b32 m0, s77
	s_nop 0
	global_load_lds_dwordx4 v[128:129], off
	v_lshl_add_u64 v[128:129], s[78:79], 0, v[198:199]
	s_add_i32 m0, s77, 0x2000
	s_nop 0
	global_load_lds_dwordx4 v[128:129], off
	s_waitcnt vmcnt(6)
	s_barrier
	s_setprio 1
	v_mfma_f32_16x16x32_bf16 v[52:55], v[176:179], v[144:147], v[52:55]
	v_mfma_f32_16x16x32_bf16 v[48:51], v[184:187], v[144:147], v[48:51]
	v_mfma_f32_16x16x32_bf16 v[36:39], v[176:179], v[152:155], v[36:39]
	v_mfma_f32_16x16x32_bf16 v[32:35], v[184:187], v[152:155], v[32:35]
	v_mfma_f32_16x16x32_bf16 v[20:23], v[176:179], v[160:163], v[20:23]
	v_mfma_f32_16x16x32_bf16 v[16:19], v[184:187], v[160:163], v[16:19]
	v_mfma_f32_16x16x32_bf16 v[4:7], v[176:179], v[168:171], v[4:7]
	v_mfma_f32_16x16x32_bf16 v[0:3], v[184:187], v[168:171], v[0:3]
	v_mfma_f32_16x16x32_bf16 v[52:55], v[180:183], v[148:151], v[52:55]
	v_mfma_f32_16x16x32_bf16 v[48:51], v[188:191], v[148:151], v[48:51]
	v_mfma_f32_16x16x32_bf16 v[36:39], v[180:183], v[156:159], v[36:39]
	v_mfma_f32_16x16x32_bf16 v[32:35], v[188:191], v[156:159], v[32:35]
	v_mfma_f32_16x16x32_bf16 v[20:23], v[180:183], v[164:167], v[20:23]
	v_mfma_f32_16x16x32_bf16 v[16:19], v[188:191], v[164:167], v[16:19]
	v_mfma_f32_16x16x32_bf16 v[4:7], v[180:183], v[172:175], v[4:7]
	v_mfma_f32_16x16x32_bf16 v[0:3], v[188:191], v[172:175], v[0:3]
	s_setprio 0
	s_add_i32 s77, 0, 0x18000
	v_add_u32_e32 v140, s77, v221
	s_barrier
	ds_read_b128 v[128:131], v140
	ds_read_b128 v[132:135], v140 offset:1024
	ds_read_b128 v[136:139], v140 offset:2048
	ds_read_b128 v[140:143], v140 offset:3072
	s_add_u32 s44, s44, 0x40000
	s_addc_u32 s45, s45, 0
	s_mov_b32 m0, s55
	v_lshl_add_u64 v[176:177], s[44:45], 0, v[192:193]
	ds_read_b128 v[144:147], v224 offset:32768
	ds_read_b128 v[148:151], v224 offset:33792
	ds_read_b128 v[152:155], v224 offset:34816
	ds_read_b128 v[156:159], v224 offset:35840
	ds_read_b128 v[160:163], v224 offset:36864
	ds_read_b128 v[164:167], v224 offset:37888
	ds_read_b128 v[168:171], v224 offset:38912
	ds_read_b128 v[172:175], v224 offset:39936
	global_load_lds_dwordx4 v[176:177], off
	v_lshl_add_u64 v[176:177], s[44:45], 0, v[196:197]
	s_mov_b32 m0, s57
	s_nop 0
	global_load_lds_dwordx4 v[176:177], off
	s_waitcnt lgkmcnt(8)
	s_barrier
	s_waitcnt lgkmcnt(0)
	s_setprio 1
	s_waitcnt lgkmcnt(0)
	v_mfma_f32_16x16x32_bf16 v[124:127], v[128:131], v[144:147], v[124:127]
	v_mfma_f32_16x16x32_bf16 v[120:123], v[136:139], v[144:147], v[120:123]
	v_mfma_f32_16x16x32_bf16 v[108:111], v[128:131], v[152:155], v[108:111]
	v_mfma_f32_16x16x32_bf16 v[104:107], v[136:139], v[152:155], v[104:107]
	v_mfma_f32_16x16x32_bf16 v[92:95], v[128:131], v[160:163], v[92:95]
	v_mfma_f32_16x16x32_bf16 v[88:91], v[136:139], v[160:163], v[88:91]
	v_mfma_f32_16x16x32_bf16 v[76:79], v[128:131], v[168:171], v[76:79]
	v_mfma_f32_16x16x32_bf16 v[72:75], v[136:139], v[168:171], v[72:75]
	v_mfma_f32_16x16x32_bf16 v[124:127], v[132:135], v[148:151], v[124:127]
	v_mfma_f32_16x16x32_bf16 v[120:123], v[140:143], v[148:151], v[120:123]
	v_mfma_f32_16x16x32_bf16 v[108:111], v[132:135], v[156:159], v[108:111]
	v_mfma_f32_16x16x32_bf16 v[104:107], v[140:143], v[156:159], v[104:107]
	v_mfma_f32_16x16x32_bf16 v[92:95], v[132:135], v[164:167], v[92:95]
	v_mfma_f32_16x16x32_bf16 v[88:91], v[140:143], v[164:167], v[88:91]
	v_mfma_f32_16x16x32_bf16 v[76:79], v[132:135], v[172:175], v[76:79]
	v_mfma_f32_16x16x32_bf16 v[72:75], v[140:143], v[172:175], v[72:75]
	s_setprio 0
	s_barrier
	s_add_i32 s44, 0, 0x1c000
	s_add_i32 s45, s77, s52
	v_add_u32_e32 v188, s44, v221
	v_lshl_add_u64 v[208:209], v[208:209], 0, s[22:23]
	s_mov_b32 m0, s45
	ds_read_b128 v[176:179], v188
	ds_read_b128 v[180:183], v188 offset:1024
	ds_read_b128 v[184:187], v188 offset:2048
	ds_read_b128 v[188:191], v188 offset:3072
	global_load_lds_dwordx4 v[208:209], off
	v_lshl_add_u64 v[208:209], v[210:211], 0, s[22:23]
	s_add_i32 m0, s45, 0x2000
	s_nop 0
	global_load_lds_dwordx4 v[208:209], off
	s_barrier
	s_waitcnt lgkmcnt(0)
	s_setprio 1
	s_waitcnt lgkmcnt(0)
	v_mfma_f32_16x16x32_bf16 v[116:119], v[176:179], v[144:147], v[116:119]
	v_mfma_f32_16x16x32_bf16 v[112:115], v[184:187], v[144:147], v[112:115]
	v_mfma_f32_16x16x32_bf16 v[100:103], v[176:179], v[152:155], v[100:103]
	v_mfma_f32_16x16x32_bf16 v[96:99], v[184:187], v[152:155], v[96:99]
	v_mfma_f32_16x16x32_bf16 v[84:87], v[176:179], v[160:163], v[84:87]
	v_mfma_f32_16x16x32_bf16 v[80:83], v[184:187], v[160:163], v[80:83]
	v_mfma_f32_16x16x32_bf16 v[68:71], v[176:179], v[168:171], v[68:71]
	v_mfma_f32_16x16x32_bf16 v[64:67], v[184:187], v[168:171], v[64:67]
	v_mfma_f32_16x16x32_bf16 v[116:119], v[180:183], v[148:151], v[116:119]
	v_mfma_f32_16x16x32_bf16 v[112:115], v[188:191], v[148:151], v[112:115]
	v_mfma_f32_16x16x32_bf16 v[100:103], v[180:183], v[156:159], v[100:103]
	v_mfma_f32_16x16x32_bf16 v[96:99], v[188:191], v[156:159], v[96:99]
	v_mfma_f32_16x16x32_bf16 v[84:87], v[180:183], v[164:167], v[84:87]
	v_mfma_f32_16x16x32_bf16 v[80:83], v[188:191], v[164:167], v[80:83]
	v_mfma_f32_16x16x32_bf16 v[68:71], v[180:183], v[172:175], v[68:71]
	v_mfma_f32_16x16x32_bf16 v[64:67], v[188:191], v[172:175], v[64:67]
	s_setprio 0
	s_mov_b32 m0, s59
	v_lshl_add_u64 v[208:209], v[212:213], 0, s[22:23]
	s_barrier
; #define PG8_STAGE(bufoff, gbase, voff) do { _Pragma("unroll") for (int _i = 0; _i < 2; ++_i) \
;     __builtin_amdgcn_global_load_lds((const unsigned*)((const char*)(gbase) + (voff)[_i]), (PG8_LAS unsigned*)(lds + (bufoff) + ldsw + _i * 8192), 16, 0, 0); } while (0)
; #define PG8_MMA(ai, bj, At, Bt) do { __builtin_amdgcn_s_setprio(1); _Pragma("unroll") for (int m = 0; m < 4; ++m) _Pragma("unroll") for (int n = 0; n < 2; ++n) _Pragma("unroll") for (int k = 0; k < 2; ++k) \
;     acc[ai][bj][m][n] = __builtin_amdgcn_mfma_f32_16x16x32_bf16(Bt[n][k], At[m][k], acc[ai][bj][m][n], 0, 0, 0); __builtin_amdgcn_s_setprio(0); } while (0)
; #define PG8_WAIT_V(n) asm volatile("s_waitcnt vmcnt(" #n ")" ::: "memory")
; #define PG8_WAIT_L(n) asm volatile("s_waitcnt lgkmcnt(" #n ")" ::: "memory")
; #define PG8_BAR __builtin_amdgcn_s_barrier()
; #define PG8_SCHED __builtin_amdgcn_sched_barrier(0)
; DI const float* xrow(const Params& P, int t) {
;   int s = t / L, p = t - s * L;
;   if (p < NMETA) return P.meta + p * DM;
;   const float* base = s < 8 ? P.xp + (size_t)(s * SEQ) * DM : P.xs + (size_t)((s - 8) * SEQ) * DM;
;   return base + (size_t)(p - NMETA) * DM;
; }
; template <class Epi>
; DI void gemm_phase(PG8_LAS unsigned char* lds, const Gemm g, const StaticOrder& S, const Epi& E, const int wv) {
;     ...
;       PG8_BAR; PG8_WAIT_L(0); PG8_MMA(1, 0, At, B0); PG8_BAR; PG8_SCHED;
;       PG8_STAGE(PG8_SB(1, 1), b3 + hstep, voffB);
;       PG8_WAIT_V(6); PG8_BAR; PG8_MMA(1, 1, At, B1); PG8_BAR;
	ds_read_b128 v[144:147], v224 offset:49152
	ds_read_b128 v[148:151], v224 offset:50176
	ds_read_b128 v[152:155], v224 offset:51200
	ds_read_b128 v[156:159], v224 offset:52224
	ds_read_b128 v[160:163], v224 offset:53248
	ds_read_b128 v[164:167], v224 offset:54272
	ds_read_b128 v[168:171], v224 offset:55296
	ds_read_b128 v[172:175], v224 offset:56320
	global_load_lds_dwordx4 v[208:209], off
	v_lshl_add_u64 v[208:209], v[214:215], 0, s[22:23]
	s_mov_b32 m0, s60
	s_nop 0
	global_load_lds_dwordx4 v[208:209], off
	s_barrier
	s_waitcnt lgkmcnt(0)
	s_setprio 1
	v_mfma_f32_16x16x32_bf16 v[60:63], v[128:131], v[144:147], v[60:63]
	v_mfma_f32_16x16x32_bf16 v[56:59], v[136:139], v[144:147], v[56:59]
	v_mfma_f32_16x16x32_bf16 v[44:47], v[128:131], v[152:155], v[44:47]
	v_mfma_f32_16x16x32_bf16 v[40:43], v[136:139], v[152:155], v[40:43]
	v_mfma_f32_16x16x32_bf16 v[28:31], v[128:131], v[160:163], v[28:31]
	v_mfma_f32_16x16x32_bf16 v[24:27], v[136:139], v[160:163], v[24:27]
	v_mfma_f32_16x16x32_bf16 v[12:15], v[128:131], v[168:171], v[12:15]
	v_mfma_f32_16x16x32_bf16 v[8:11], v[136:139], v[168:171], v[8:11]
	v_mfma_f32_16x16x32_bf16 v[60:63], v[132:135], v[148:151], v[60:63]
	v_mfma_f32_16x16x32_bf16 v[56:59], v[140:143], v[148:151], v[56:59]
	v_mfma_f32_16x16x32_bf16 v[44:47], v[132:135], v[156:159], v[44:47]
	v_mfma_f32_16x16x32_bf16 v[40:43], v[140:143], v[156:159], v[40:43]
	v_mfma_f32_16x16x32_bf16 v[28:31], v[132:135], v[164:167], v[28:31]
	v_mfma_f32_16x16x32_bf16 v[24:27], v[140:143], v[164:167], v[24:27]
	v_mfma_f32_16x16x32_bf16 v[12:15], v[132:135], v[172:175], v[12:15]
	v_mfma_f32_16x16x32_bf16 v[8:11], v[140:143], v[172:175], v[8:11]
	s_setprio 0
	s_barrier
	s_add_u32 s42, s42, 0x40080
	s_addc_u32 s43, s43, 0
	s_add_i32 s44, s44, s52
	v_lshl_add_u64 v[128:129], s[42:43], 0, v[194:195]
	s_mov_b32 m0, s44
	s_nop 0
	global_load_lds_dwordx4 v[128:129], off
	v_lshl_add_u64 v[128:129], s[42:43], 0, v[198:199]
	s_add_i32 m0, s44, 0x2000
	s_nop 0
	global_load_lds_dwordx4 v[128:129], off
	s_waitcnt vmcnt(6)
	s_barrier
	s_setprio 1
	v_mfma_f32_16x16x32_bf16 v[52:55], v[176:179], v[144:147], v[52:55]
	v_mfma_f32_16x16x32_bf16 v[48:51], v[184:187], v[144:147], v[48:51]
	v_mfma_f32_16x16x32_bf16 v[36:39], v[176:179], v[152:155], v[36:39]
	v_mfma_f32_16x16x32_bf16 v[32:35], v[184:187], v[152:155], v[32:35]
	v_mfma_f32_16x16x32_bf16 v[20:23], v[176:179], v[160:163], v[20:23]
	v_mfma_f32_16x16x32_bf16 v[16:19], v[184:187], v[160:163], v[16:19]
	v_mfma_f32_16x16x32_bf16 v[4:7], v[176:179], v[168:171], v[4:7]
	v_mfma_f32_16x16x32_bf16 v[0:3], v[184:187], v[168:171], v[0:3]
	v_mfma_f32_16x16x32_bf16 v[52:55], v[180:183], v[148:151], v[52:55]
	v_mfma_f32_16x16x32_bf16 v[48:51], v[188:191], v[148:151], v[48:51]
	v_mfma_f32_16x16x32_bf16 v[36:39], v[180:183], v[156:159], v[36:39]
	v_mfma_f32_16x16x32_bf16 v[32:35], v[188:191], v[156:159], v[32:35]
	v_mfma_f32_16x16x32_bf16 v[20:23], v[180:183], v[164:167], v[20:23]
	v_mfma_f32_16x16x32_bf16 v[16:19], v[188:191], v[164:167], v[16:19]
	v_mfma_f32_16x16x32_bf16 v[4:7], v[180:183], v[172:175], v[4:7]
	v_mfma_f32_16x16x32_bf16 v[0:3], v[188:191], v[172:175], v[0:3]
	s_setprio 0
	s_add_i32 s76, s76, 2
	s_add_u32 s40, s40, 0x100
	s_addc_u32 s41, s41, 0
	s_add_u32 s74, s74, 0x100
	s_addc_u32 s75, s75, 0
	s_cmp_gt_u32 s76, 13
	s_barrier
	s_cbranch_scc0 .LBB0_770
	v_lshl_or_b32 v208, s38, 8, v222
	v_lshl_add_u32 v210, s36, 8, v220
	s_cmpk_gt_i32 s36, 0x181
	v_ashrrev_i32_e32 v209, 31, v208
	s_cbranch_scc1 .LBB0_797
	v_mul_hi_i32 v128, v210, s68
	v_lshrrev_b32_e32 v129, 31, v128
	v_ashrrev_i32_e32 v128, 11, v128
	v_add_u32_e32 v131, v128, v129
	v_mad_i32_i24 v130, v131, s69, v210
	v_cmp_lt_i32_e32 vcc, 15, v130
	s_and_saveexec_b64 s[38:39], vcc
	s_xor_b64 s[38:39], exec, s[38:39]
	s_cbranch_execz .LBB0_774
	v_lshlrev_b32_e32 v128, 12, v131
	v_add_u32_e32 v131, 0xffff8000, v128
	v_cmp_gt_i32_e32 vcc, s70, v210
	v_ashrrev_i32_e32 v129, 31, v128
	v_mov_b32_e32 v132, s7
	v_cndmask_b32_e32 v128, v131, v128, vcc
	v_mov_b32_e32 v131, s9
	v_cndmask_b32_e32 v129, 0, v129, vcc
	v_cndmask_b32_e32 v133, v131, v132, vcc
	v_mov_b32_e32 v131, s8
	v_mov_b32_e32 v132, s6
	v_cndmask_b32_e32 v132, v131, v132, vcc
	v_lshlrev_b64 v[128:129], 12, v[128:129]
	v_add_u32_e32 v200, -16, v130
	v_lshl_add_u64 v[128:129], v[132:133], 0, v[128:129]
	v_lshlrev_b64 v[130:131], 12, v[200:201]
	v_lshl_add_u64 v[128:129], v[128:129], 0, v[130:131]

; #define PG8_STAGE(bufoff, gbase, voff) do { _Pragma("unroll") for (int _i = 0; _i < 2; ++_i) \
;     __builtin_amdgcn_global_load_lds((const unsigned*)((const char*)(gbase) + (voff)[_i]), (PG8_LAS unsigned*)(lds + (bufoff) + ldsw + _i * 8192), 16, 0, 0); } while (0)
; #define PG8_LDA(dst, b, h) do { _Pragma("unroll") for (int m = 0; m < 4; ++m) _Pragma("unroll") for (int k = 0; k < 2; ++k) dst[m][k] = *(const PG8_LAS bf16x8*)(lds + PG8_SA(b, h) + aoff + m * 2048 + k * 1024); } while (0)
; #define PG8_LDB(dst, b, h) do { _Pragma("unroll") for (int n = 0; n < 2; ++n) _Pragma("unroll") for (int k = 0; k < 2; ++k) dst[n][k] = *(const PG8_LAS bf16x8*)(lds + PG8_SB(b, h) + boff + n * 2048 + k * 1024); } while (0)
; #define PG8_MMA(ai, bj, At, Bt) do { __builtin_amdgcn_s_setprio(1); _Pragma("unroll") for (int m = 0; m < 4; ++m) _Pragma("unroll") for (int n = 0; n < 2; ++n) _Pragma("unroll") for (int k = 0; k < 2; ++k) \
;     acc[ai][bj][m][n] = __builtin_amdgcn_mfma_f32_16x16x32_bf16(Bt[n][k], At[m][k], acc[ai][bj][m][n], 0, 0, 0); __builtin_amdgcn_s_setprio(0); } while (0)
; #define PG8_WAIT_L(n) asm volatile("s_waitcnt lgkmcnt(" #n ")" ::: "memory")
; #define PG8_BAR __builtin_amdgcn_s_barrier()
; template <class Epi>
; DI void gemm_phase(PG8_LAS unsigned char* lds, const Gemm g, const StaticOrder& S, const Epi& E, const int wv) {
;     ...
;   for (;;) {
;     const bool has_next = S.next(ui + 1, nxt);
;     const char* nA = has_next ? (const char*)g.A + (size_t)nxt.pm * tstep : cA; const char* nB = has_next ? (const char*)g.Bt + (size_t)nxt.pn * tstep : cB;
; #pragma nounroll
;     for (int t = 0; t < nt; t += 2) {
;       const bool last = (t == nt - 2);
;       const char* a1 = cA + (size_t)(t + 1) * kstep;
;       const char* a2 = last ? nA : cA + (size_t)(t + 2) * kstep; const char* b2 = last ? nB : cB + (size_t)(t + 2) * kstep;
;       const char* a3 = a2 + kstep; const char* b3 = b2 + kstep;
;       PG8_LDB(B0, 0, 0); PG8_SCHED; PG8_LDA(At, 0, 0); PG8_STAGE(PG8_SA(1, 1), a1 + hstep, voffA);
;       PG8_WAIT_L(8); PG8_BAR; PG8_WAIT_L(0); PG8_MMA(0, 0, At, B0); PG8_BAR; PG8_SCHED;
;       PG8_LDB(B1, 0, 1); PG8_STAGE(PG8_SB(0, 0), b2, voffB);
;       PG8_BAR; PG8_WAIT_L(0); PG8_MMA(0, 1, At, B1); PG8_BAR;
;       PG8_LDA(At, 0, 1); PG8_STAGE(PG8_SA(0, 0), a2, voffA);
;       PG8_BAR; PG8_WAIT_L(0); PG8_MMA(1, 0, At, B0); PG8_BAR; PG8_SCHED;
.LBB0_893:
	ds_read_b128 v[142:145], v155
	ds_read_b128 v[146:149], v155 offset:1024
	ds_read_b128 v[160:163], v155 offset:2048
	ds_read_b128 v[164:167], v155 offset:3072
	s_add_u32 s8, s6, 0xfffc0080
	s_addc_u32 s9, s7, -1
	s_cmp_eq_u32 s62, 12
	s_cselect_b32 s37, s5, s9
	s_cselect_b32 s36, s27, s8
	s_cselect_b32 s9, s25, s61
	s_cselect_b32 s8, s59, s60
	v_lshl_add_u64 v[150:151], s[6:7], 0, v[136:137]
	s_add_i32 m0, s35, 0xc000
	ds_read_b128 v[168:171], v156
	ds_read_b128 v[172:175], v156 offset:1024
	ds_read_b128 v[176:179], v156 offset:2048
	ds_read_b128 v[180:183], v156 offset:3072
	ds_read_b128 v[184:187], v156 offset:4096
	ds_read_b128 v[188:191], v156 offset:5120
	ds_read_b128 v[192:195], v156 offset:6144
	ds_read_b128 v[196:199], v156 offset:7168
	global_load_lds_dwordx4 v[150:151], off
	v_lshl_add_u64 v[150:151], s[6:7], 0, v[138:139]
	s_add_i32 m0, s35, 0xe000
	s_nop 0
	global_load_lds_dwordx4 v[150:151], off
	s_waitcnt lgkmcnt(8)
	s_barrier
	s_waitcnt lgkmcnt(0)
	s_setprio 1
	s_waitcnt lgkmcnt(0)
	v_mfma_f32_16x16x32_bf16 v[116:119], v[142:145], v[168:171], v[116:119]
	v_mfma_f32_16x16x32_bf16 v[112:115], v[160:163], v[168:171], v[112:115]
	v_mfma_f32_16x16x32_bf16 v[108:111], v[142:145], v[176:179], v[108:111]
	v_mfma_f32_16x16x32_bf16 v[100:103], v[160:163], v[176:179], v[100:103]
	v_mfma_f32_16x16x32_bf16 v[92:95], v[142:145], v[184:187], v[92:95]
	v_mfma_f32_16x16x32_bf16 v[84:87], v[160:163], v[184:187], v[84:87]
	v_mfma_f32_16x16x32_bf16 v[76:79], v[142:145], v[192:195], v[76:79]
	v_mfma_f32_16x16x32_bf16 v[68:71], v[160:163], v[192:195], v[68:71]
	v_mfma_f32_16x16x32_bf16 v[116:119], v[146:149], v[172:175], v[116:119]
	v_mfma_f32_16x16x32_bf16 v[112:115], v[164:167], v[172:175], v[112:115]
	v_mfma_f32_16x16x32_bf16 v[108:111], v[146:149], v[180:183], v[108:111]
	v_mfma_f32_16x16x32_bf16 v[100:103], v[164:167], v[180:183], v[100:103]
	v_mfma_f32_16x16x32_bf16 v[92:95], v[146:149], v[188:191], v[92:95]
	v_mfma_f32_16x16x32_bf16 v[84:87], v[164:167], v[188:191], v[84:87]
	v_mfma_f32_16x16x32_bf16 v[76:79], v[146:149], v[196:199], v[76:79]
	v_mfma_f32_16x16x32_bf16 v[68:71], v[164:167], v[196:199], v[68:71]
	s_setprio 0
	s_barrier
	s_add_i32 s63, s54, s45
	v_lshl_add_u64 v[150:151], s[8:9], 0, v[130:131]
	s_mov_b32 m0, s63
	ds_read_b128 v[200:203], v157
	ds_read_b128 v[204:207], v157 offset:1024
	ds_read_b128 v[208:211], v157 offset:2048
	ds_read_b128 v[212:215], v157 offset:3072
	global_load_lds_dwordx4 v[150:151], off
	v_lshl_add_u64 v[216:217], s[8:9], 0, v[134:135]
	s_add_i32 m0, s63, 0x2000
	s_nop 0
	global_load_lds_dwordx4 v[216:217], off
	s_barrier
	s_waitcnt lgkmcnt(0)
	s_setprio 1
	v_mfma_f32_16x16x32_bf16 v[124:127], v[200:203], v[168:171], v[124:127]
	v_mfma_f32_16x16x32_bf16 v[120:123], v[208:211], v[168:171], v[120:123]
	v_mfma_f32_16x16x32_bf16 v[104:107], v[200:203], v[176:179], v[104:107]
	v_mfma_f32_16x16x32_bf16 v[96:99], v[208:211], v[176:179], v[96:99]
	v_mfma_f32_16x16x32_bf16 v[88:91], v[200:203], v[184:187], v[88:91]
	v_mfma_f32_16x16x32_bf16 v[80:83], v[208:211], v[184:187], v[80:83]
	v_mfma_f32_16x16x32_bf16 v[72:75], v[200:203], v[192:195], v[72:75]
	v_mfma_f32_16x16x32_bf16 v[64:67], v[208:211], v[192:195], v[64:67]
	v_mfma_f32_16x16x32_bf16 v[124:127], v[204:207], v[172:175], v[124:127]
	v_mfma_f32_16x16x32_bf16 v[120:123], v[212:215], v[172:175], v[120:123]
	v_mfma_f32_16x16x32_bf16 v[104:107], v[204:207], v[180:183], v[104:107]
	v_mfma_f32_16x16x32_bf16 v[96:99], v[212:215], v[180:183], v[96:99]
	v_mfma_f32_16x16x32_bf16 v[88:91], v[204:207], v[188:191], v[88:91]
	v_mfma_f32_16x16x32_bf16 v[80:83], v[212:215], v[188:191], v[80:83]
	v_mfma_f32_16x16x32_bf16 v[72:75], v[204:207], v[196:199], v[72:75]
	v_mfma_f32_16x16x32_bf16 v[64:67], v[212:215], v[196:199], v[64:67]
	s_setprio 0
	s_mov_b32 m0, s35
	v_lshl_add_u64 v[220:221], s[36:37], 0, v[128:129]
	s_barrier
	ds_read_b128 v[168:171], v156 offset:16384
	ds_read_b128 v[172:175], v156 offset:17408
	ds_read_b128 v[176:179], v156 offset:18432
	ds_read_b128 v[180:183], v156 offset:19456
	ds_read_b128 v[184:187], v156 offset:20480
	ds_read_b128 v[188:191], v156 offset:21504
	ds_read_b128 v[192:195], v156 offset:22528
	ds_read_b128 v[196:199], v156 offset:23552
	global_load_lds_dwordx4 v[220:221], off
	v_lshl_add_u64 v[222:223], s[36:37], 0, v[132:133]
	s_mov_b32 m0, s46
	s_nop 0
	global_load_lds_dwordx4 v[222:223], off
	s_barrier
	s_waitcnt lgkmcnt(0)
	s_setprio 1
	v_mfma_f32_16x16x32_bf16 v[52:55], v[142:145], v[168:171], v[52:55]
	v_mfma_f32_16x16x32_bf16 v[48:51], v[160:163], v[168:171], v[48:51]
	v_mfma_f32_16x16x32_bf16 v[44:47], v[142:145], v[176:179], v[44:47]
	v_mfma_f32_16x16x32_bf16 v[36:39], v[160:163], v[176:179], v[36:39]
	v_mfma_f32_16x16x32_bf16 v[28:31], v[142:145], v[184:187], v[28:31]
	v_mfma_f32_16x16x32_bf16 v[20:23], v[160:163], v[184:187], v[20:23]
	v_mfma_f32_16x16x32_bf16 v[12:15], v[142:145], v[192:195], v[12:15]
	v_mfma_f32_16x16x32_bf16 v[4:7], v[160:163], v[192:195], v[4:7]
	v_mfma_f32_16x16x32_bf16 v[52:55], v[146:149], v[172:175], v[52:55]
	v_mfma_f32_16x16x32_bf16 v[48:51], v[164:167], v[172:175], v[48:51]
	v_mfma_f32_16x16x32_bf16 v[44:47], v[146:149], v[180:183], v[44:47]
	v_mfma_f32_16x16x32_bf16 v[36:39], v[164:167], v[180:183], v[36:39]
	v_mfma_f32_16x16x32_bf16 v[28:31], v[146:149], v[188:191], v[28:31]
	v_mfma_f32_16x16x32_bf16 v[20:23], v[164:167], v[188:191], v[20:23]
	v_mfma_f32_16x16x32_bf16 v[12:15], v[146:149], v[196:199], v[12:15]
	v_mfma_f32_16x16x32_bf16 v[4:7], v[164:167], v[196:199], v[4:7]
	s_setprio 0
	s_barrier
; #define PG8_STAGE(bufoff, gbase, voff) do { _Pragma("unroll") for (int _i = 0; _i < 2; ++_i) \
;     __builtin_amdgcn_global_load_lds((const unsigned*)((const char*)(gbase) + (voff)[_i]), (PG8_LAS unsigned*)(lds + (bufoff) + ldsw + _i * 8192), 16, 0, 0); } while (0)
; #define PG8_LDA(dst, b, h) do { _Pragma("unroll") for (int m = 0; m < 4; ++m) _Pragma("unroll") for (int k = 0; k < 2; ++k) dst[m][k] = *(const PG8_LAS bf16x8*)(lds + PG8_SA(b, h) + aoff + m * 2048 + k * 1024); } while (0)
; #define PG8_LDB(dst, b, h) do { _Pragma("unroll") for (int n = 0; n < 2; ++n) _Pragma("unroll") for (int k = 0; k < 2; ++k) dst[n][k] = *(const PG8_LAS bf16x8*)(lds + PG8_SB(b, h) + boff + n * 2048 + k * 1024); } while (0)
; #define PG8_MMA(ai, bj, At, Bt) do { __builtin_amdgcn_s_setprio(1); _Pragma("unroll") for (int m = 0; m < 4; ++m) _Pragma("unroll") for (int n = 0; n < 2; ++n) _Pragma("unroll") for (int k = 0; k < 2; ++k) \
;     acc[ai][bj][m][n] = __builtin_amdgcn_mfma_f32_16x16x32_bf16(Bt[n][k], At[m][k], acc[ai][bj][m][n], 0, 0, 0); __builtin_amdgcn_s_setprio(0); } while (0)
; #define PG8_WAIT_V(n) asm volatile("s_waitcnt vmcnt(" #n ")" ::: "memory")
; #define PG8_WAIT_L(n) asm volatile("s_waitcnt lgkmcnt(" #n ")" ::: "memory")
; #define PG8_BAR __builtin_amdgcn_s_barrier()
; #define PG8_SCHED __builtin_amdgcn_sched_barrier(0)
; template <class Epi>
; DI void gemm_phase(PG8_LAS unsigned char* lds, const Gemm g, const StaticOrder& S, const Epi& E, const int wv) {
;     ...
;       PG8_STAGE(PG8_SB(0, 1), b2 + hstep, voffB);
;       PG8_WAIT_V(6); PG8_BAR; PG8_MMA(1, 1, At, B1); PG8_BAR;
;       PG8_LDB(B0, 1, 0); PG8_SCHED; PG8_LDA(At, 1, 0); PG8_STAGE(PG8_SA(0, 1), a2 + hstep, voffA);
;       PG8_WAIT_L(8); PG8_BAR; PG8_WAIT_L(0); PG8_MMA(0, 0, At, B0); PG8_BAR; PG8_SCHED;
;       PG8_LDB(B1, 1, 1); PG8_STAGE(PG8_SB(1, 0), b3, voffB);
;       PG8_BAR; PG8_WAIT_L(0); PG8_MMA(0, 1, At, B1); PG8_BAR;
;       PG8_LDA(At, 1, 1); PG8_STAGE(PG8_SA(1, 0), a3, voffA);
	s_add_u32 s64, s8, 0x40000
	s_addc_u32 s65, s9, 0
	s_add_i32 s63, s55, s45
	v_lshl_add_u64 v[142:143], s[64:65], 0, v[130:131]
	s_mov_b32 m0, s63
	s_nop 0
	global_load_lds_dwordx4 v[142:143], off
	v_lshl_add_u64 v[142:143], s[64:65], 0, v[134:135]
	s_add_i32 m0, s63, 0x2000
	s_nop 0
	global_load_lds_dwordx4 v[142:143], off
	s_waitcnt vmcnt(6)
	s_barrier
	s_setprio 1
	v_mfma_f32_16x16x32_bf16 v[60:63], v[200:203], v[168:171], v[60:63]
	v_mfma_f32_16x16x32_bf16 v[56:59], v[208:211], v[168:171], v[56:59]
	v_mfma_f32_16x16x32_bf16 v[40:43], v[200:203], v[176:179], v[40:43]
	v_mfma_f32_16x16x32_bf16 v[32:35], v[208:211], v[176:179], v[32:35]
	v_mfma_f32_16x16x32_bf16 v[24:27], v[200:203], v[184:187], v[24:27]
	v_mfma_f32_16x16x32_bf16 v[16:19], v[208:211], v[184:187], v[16:19]
	v_mfma_f32_16x16x32_bf16 v[8:11], v[200:203], v[192:195], v[8:11]
	v_mfma_f32_16x16x32_bf16 v[0:3], v[208:211], v[192:195], v[0:3]
	v_mfma_f32_16x16x32_bf16 v[60:63], v[204:207], v[172:175], v[60:63]
	v_mfma_f32_16x16x32_bf16 v[56:59], v[212:215], v[172:175], v[56:59]
	v_mfma_f32_16x16x32_bf16 v[40:43], v[204:207], v[180:183], v[40:43]
	v_mfma_f32_16x16x32_bf16 v[32:35], v[212:215], v[180:183], v[32:35]
	v_mfma_f32_16x16x32_bf16 v[24:27], v[204:207], v[188:191], v[24:27]
	v_mfma_f32_16x16x32_bf16 v[16:19], v[212:215], v[188:191], v[16:19]
	v_mfma_f32_16x16x32_bf16 v[8:11], v[204:207], v[196:199], v[8:11]
	v_mfma_f32_16x16x32_bf16 v[0:3], v[212:215], v[196:199], v[0:3]
	s_setprio 0
	s_add_i32 s63, 0, 0x18000
	v_add_u32_e32 v159, s63, v153
	s_barrier
	ds_read_b128 v[142:145], v159
	ds_read_b128 v[146:149], v159 offset:1024
	ds_read_b128 v[160:163], v159 offset:2048
	ds_read_b128 v[164:167], v159 offset:3072
	s_add_u32 s36, s36, 0x40000
	s_addc_u32 s37, s37, 0
	s_mov_b32 m0, s47
	v_lshl_add_u64 v[200:201], s[36:37], 0, v[128:129]
	ds_read_b128 v[168:171], v156 offset:32768
	ds_read_b128 v[172:175], v156 offset:33792
	ds_read_b128 v[176:179], v156 offset:34816
	ds_read_b128 v[180:183], v156 offset:35840
	ds_read_b128 v[184:187], v156 offset:36864
	ds_read_b128 v[188:191], v156 offset:37888
	ds_read_b128 v[192:195], v156 offset:38912
	ds_read_b128 v[196:199], v156 offset:39936
	global_load_lds_dwordx4 v[200:201], off
	v_lshl_add_u64 v[200:201], s[36:37], 0, v[132:133]
	s_mov_b32 m0, s48
	s_nop 0
	global_load_lds_dwordx4 v[200:201], off
	s_waitcnt lgkmcnt(8)
	s_barrier
	s_waitcnt lgkmcnt(0)
	s_setprio 1
	s_waitcnt lgkmcnt(0)
	v_mfma_f32_16x16x32_bf16 v[116:119], v[142:145], v[168:171], v[116:119]
	v_mfma_f32_16x16x32_bf16 v[112:115], v[160:163], v[168:171], v[112:115]
	v_mfma_f32_16x16x32_bf16 v[108:111], v[142:145], v[176:179], v[108:111]
	v_mfma_f32_16x16x32_bf16 v[100:103], v[160:163], v[176:179], v[100:103]
	v_mfma_f32_16x16x32_bf16 v[92:95], v[142:145], v[184:187], v[92:95]
	v_mfma_f32_16x16x32_bf16 v[84:87], v[160:163], v[184:187], v[84:87]
	v_mfma_f32_16x16x32_bf16 v[76:79], v[142:145], v[192:195], v[76:79]
	v_mfma_f32_16x16x32_bf16 v[68:71], v[160:163], v[192:195], v[68:71]
	v_mfma_f32_16x16x32_bf16 v[116:119], v[146:149], v[172:175], v[116:119]
	v_mfma_f32_16x16x32_bf16 v[112:115], v[164:167], v[172:175], v[112:115]
	v_mfma_f32_16x16x32_bf16 v[108:111], v[146:149], v[180:183], v[108:111]
	v_mfma_f32_16x16x32_bf16 v[100:103], v[164:167], v[180:183], v[100:103]
	v_mfma_f32_16x16x32_bf16 v[92:95], v[146:149], v[188:191], v[92:95]
	v_mfma_f32_16x16x32_bf16 v[84:87], v[164:167], v[188:191], v[84:87]
	v_mfma_f32_16x16x32_bf16 v[76:79], v[146:149], v[196:199], v[76:79]
	v_mfma_f32_16x16x32_bf16 v[68:71], v[164:167], v[196:199], v[68:71]
	s_setprio 0
	s_barrier
	s_add_i32 s36, 0, 0x1c000
	s_add_i32 s37, s63, s45
	v_add_u32_e32 v159, s36, v153
	v_lshl_add_u64 v[150:151], v[150:151], 0, s[20:21]
	s_mov_b32 m0, s37
	ds_read_b128 v[200:203], v159
	ds_read_b128 v[204:207], v159 offset:1024
	ds_read_b128 v[208:211], v159 offset:2048
	ds_read_b128 v[212:215], v159 offset:3072
	global_load_lds_dwordx4 v[150:151], off
	v_lshl_add_u64 v[150:151], v[216:217], 0, s[20:21]
	s_add_i32 m0, s37, 0x2000
	s_nop 0
	global_load_lds_dwordx4 v[150:151], off
	s_barrier
	s_waitcnt lgkmcnt(0)
	s_setprio 1
	s_waitcnt lgkmcnt(0)
	v_mfma_f32_16x16x32_bf16 v[124:127], v[200:203], v[168:171], v[124:127]
	v_mfma_f32_16x16x32_bf16 v[120:123], v[208:211], v[168:171], v[120:123]
	v_mfma_f32_16x16x32_bf16 v[104:107], v[200:203], v[176:179], v[104:107]
	v_mfma_f32_16x16x32_bf16 v[96:99], v[208:211], v[176:179], v[96:99]
	v_mfma_f32_16x16x32_bf16 v[88:91], v[200:203], v[184:187], v[88:91]
	v_mfma_f32_16x16x32_bf16 v[80:83], v[208:211], v[184:187], v[80:83]
	v_mfma_f32_16x16x32_bf16 v[72:75], v[200:203], v[192:195], v[72:75]
	v_mfma_f32_16x16x32_bf16 v[64:67], v[208:211], v[192:195], v[64:67]
	v_mfma_f32_16x16x32_bf16 v[124:127], v[204:207], v[172:175], v[124:127]
	v_mfma_f32_16x16x32_bf16 v[120:123], v[212:215], v[172:175], v[120:123]
	v_mfma_f32_16x16x32_bf16 v[104:107], v[204:207], v[180:183], v[104:107]
	v_mfma_f32_16x16x32_bf16 v[96:99], v[212:215], v[180:183], v[96:99]
	v_mfma_f32_16x16x32_bf16 v[88:91], v[204:207], v[188:191], v[88:91]
	v_mfma_f32_16x16x32_bf16 v[80:83], v[212:215], v[188:191], v[80:83]
	v_mfma_f32_16x16x32_bf16 v[72:75], v[204:207], v[196:199], v[72:75]
	v_mfma_f32_16x16x32_bf16 v[64:67], v[212:215], v[196:199], v[64:67]
	s_setprio 0
	s_mov_b32 m0, s50
	v_lshl_add_u64 v[150:151], v[220:221], 0, s[20:21]
	s_barrier
	ds_read_b128 v[168:171], v156 offset:49152
	ds_read_b128 v[172:175], v156 offset:50176
	ds_read_b128 v[176:179], v156 offset:51200
	ds_read_b128 v[180:183], v156 offset:52224
	ds_read_b128 v[184:187], v156 offset:53248
	ds_read_b128 v[188:191], v156 offset:54272
	ds_read_b128 v[192:195], v156 offset:55296
	ds_read_b128 v[196:199], v156 offset:56320
	global_load_lds_dwordx4 v[150:151], off
	v_lshl_add_u64 v[150:151], v[222:223], 0, s[20:21]
	s_mov_b32 m0, s51
	s_nop 0
	global_load_lds_dwordx4 v[150:151], off
	s_barrier
; #define PG8_STAGE(bufoff, gbase, voff) do { _Pragma("unroll") for (int _i = 0; _i < 2; ++_i) \
;     __builtin_amdgcn_global_load_lds((const unsigned*)((const char*)(gbase) + (voff)[_i]), (PG8_LAS unsigned*)(lds + (bufoff) + ldsw + _i * 8192), 16, 0, 0); } while (0)
; #define PG8_MMA(ai, bj, At, Bt) do { __builtin_amdgcn_s_setprio(1); _Pragma("unroll") for (int m = 0; m < 4; ++m) _Pragma("unroll") for (int n = 0; n < 2; ++n) _Pragma("unroll") for (int k = 0; k < 2; ++k) \
;     acc[ai][bj][m][n] = __builtin_amdgcn_mfma_f32_16x16x32_bf16(Bt[n][k], At[m][k], acc[ai][bj][m][n], 0, 0, 0); __builtin_amdgcn_s_setprio(0); } while (0)
; #define PG8_WAIT_V(n) asm volatile("s_waitcnt vmcnt(" #n ")" ::: "memory")
; #define PG8_WAIT_L(n) asm volatile("s_waitcnt lgkmcnt(" #n ")" ::: "memory")
; #define PG8_BAR __builtin_amdgcn_s_barrier()
; #define PG8_SCHED __builtin_amdgcn_sched_barrier(0)
; #define EPI_ROWS_BEGIN() \
;   _Pragma("unroll") for (int ai = 0; ai < 2; ++ai) { if (u.pm * 256 + ai * 128 >= T) continue;
; template <class Epi>
; DI void gemm_phase(PG8_LAS unsigned char* lds, const Gemm g, const StaticOrder& S, const Epi& E, const int wv) {
;     ...
;       PG8_BAR; PG8_WAIT_L(0); PG8_MMA(1, 0, At, B0); PG8_BAR; PG8_SCHED;
;       PG8_STAGE(PG8_SB(1, 1), b3 + hstep, voffB);
;       PG8_WAIT_V(6); PG8_BAR; PG8_MMA(1, 1, At, B1); PG8_BAR;
;   DI void operator()(AccRef acc, const pg8::Unit& u, int wr, int wc, int fr, int fq) const {
;     const int row0 = u.pm * 256 + wr * 64 + fr, col0 = u.pn * 128 + wc * 32 + 8 * fq;
;     EPI_ROWS_BEGIN()
;       float rs[4];
; #pragma unroll
;       for (int m = 0; m < 4; ++m) rs[m] = ss[row0 + ai * 128 + m * 16];
; #pragma unroll
;       for (int m = 0; m < 4; ++m) rs[m] = rsqrtf(rs[m] * (1.f / DM) + EPS);
	s_waitcnt lgkmcnt(0)
	s_setprio 1
	v_mfma_f32_16x16x32_bf16 v[52:55], v[142:145], v[168:171], v[52:55]
	v_mfma_f32_16x16x32_bf16 v[48:51], v[160:163], v[168:171], v[48:51]
	v_mfma_f32_16x16x32_bf16 v[44:47], v[142:145], v[176:179], v[44:47]
	v_mfma_f32_16x16x32_bf16 v[36:39], v[160:163], v[176:179], v[36:39]
	v_mfma_f32_16x16x32_bf16 v[28:31], v[142:145], v[184:187], v[28:31]
	v_mfma_f32_16x16x32_bf16 v[20:23], v[160:163], v[184:187], v[20:23]
	v_mfma_f32_16x16x32_bf16 v[12:15], v[142:145], v[192:195], v[12:15]
	v_mfma_f32_16x16x32_bf16 v[4:7], v[160:163], v[192:195], v[4:7]
	v_mfma_f32_16x16x32_bf16 v[52:55], v[146:149], v[172:175], v[52:55]
	v_mfma_f32_16x16x32_bf16 v[48:51], v[164:167], v[172:175], v[48:51]
	v_mfma_f32_16x16x32_bf16 v[44:47], v[146:149], v[180:183], v[44:47]
	v_mfma_f32_16x16x32_bf16 v[36:39], v[164:167], v[180:183], v[36:39]
	v_mfma_f32_16x16x32_bf16 v[28:31], v[146:149], v[188:191], v[28:31]
	v_mfma_f32_16x16x32_bf16 v[20:23], v[164:167], v[188:191], v[20:23]
	v_mfma_f32_16x16x32_bf16 v[12:15], v[146:149], v[196:199], v[12:15]
	v_mfma_f32_16x16x32_bf16 v[4:7], v[164:167], v[196:199], v[4:7]
	s_setprio 0
	s_barrier
	s_add_u32 s8, s8, 0x40080
	s_addc_u32 s9, s9, 0
	s_add_i32 s36, s36, s45
	v_lshl_add_u64 v[142:143], s[8:9], 0, v[130:131]
	s_mov_b32 m0, s36
	s_nop 0
	global_load_lds_dwordx4 v[142:143], off
	v_lshl_add_u64 v[142:143], s[8:9], 0, v[134:135]
	s_add_i32 m0, s36, 0x2000
	s_nop 0
	global_load_lds_dwordx4 v[142:143], off
	s_waitcnt vmcnt(6)
	s_barrier
	s_setprio 1
	v_mfma_f32_16x16x32_bf16 v[60:63], v[200:203], v[168:171], v[60:63]
	v_mfma_f32_16x16x32_bf16 v[56:59], v[208:211], v[168:171], v[56:59]
	v_mfma_f32_16x16x32_bf16 v[40:43], v[200:203], v[176:179], v[40:43]
	v_mfma_f32_16x16x32_bf16 v[32:35], v[208:211], v[176:179], v[32:35]
	v_mfma_f32_16x16x32_bf16 v[24:27], v[200:203], v[184:187], v[24:27]
	v_mfma_f32_16x16x32_bf16 v[16:19], v[208:211], v[184:187], v[16:19]
	v_mfma_f32_16x16x32_bf16 v[8:11], v[200:203], v[192:195], v[8:11]
	v_mfma_f32_16x16x32_bf16 v[0:3], v[208:211], v[192:195], v[0:3]
	v_mfma_f32_16x16x32_bf16 v[60:63], v[204:207], v[172:175], v[60:63]
	v_mfma_f32_16x16x32_bf16 v[56:59], v[212:215], v[172:175], v[56:59]
	v_mfma_f32_16x16x32_bf16 v[40:43], v[204:207], v[180:183], v[40:43]
	v_mfma_f32_16x16x32_bf16 v[32:35], v[212:215], v[180:183], v[32:35]
	v_mfma_f32_16x16x32_bf16 v[24:27], v[204:207], v[188:191], v[24:27]
	v_mfma_f32_16x16x32_bf16 v[16:19], v[212:215], v[188:191], v[16:19]
	v_mfma_f32_16x16x32_bf16 v[8:11], v[204:207], v[196:199], v[8:11]
	v_mfma_f32_16x16x32_bf16 v[0:3], v[212:215], v[196:199], v[0:3]
	s_setprio 0
	s_add_i32 s62, s62, 2
	s_add_u32 s6, s6, 0x100
	s_addc_u32 s7, s7, 0
	s_add_u32 s60, s60, 0x100
	s_addc_u32 s61, s61, 0
	s_cmp_gt_u32 s62, 13
	s_barrier
	s_cbranch_scc0 .LBB0_893
	v_lshl_or_b32 v142, s4, 7, v154
	v_ashrrev_i32_e32 v143, 31, v142
	v_lshl_add_u32 v144, s34, 8, v152
	s_cmpk_gt_i32 s34, 0x181
	v_lshlrev_b64 v[142:143], 1, v[142:143]
	s_cbranch_scc1 .LBB0_896
	v_ashrrev_i32_e32 v145, 31, v144
	v_lshl_add_u64 v[146:147], v[144:145], 2, s[18:19]
	v_or_b32_e32 v150, 16, v144
	global_load_dword v145, v[146:147], off
	v_ashrrev_i32_e32 v151, 31, v150
	v_or_b32_e32 v148, 32, v144
	v_or_b32_e32 v146, 48, v144
	v_lshl_add_u64 v[160:161], v[150:151], 2, s[18:19]
	v_ashrrev_i32_e32 v149, 31, v148
	v_ashrrev_i32_e32 v147, 31, v146
	v_lshl_add_u64 v[162:163], v[148:149], 2, s[18:19]
	v_lshl_add_u64 v[164:165], v[146:147], 2, s[18:19]
	global_load_dword v147, v[160:161], off
	global_load_dword v149, v[162:163], off
	global_load_dword v151, v[164:165], off
	v_add_u32_e32 v224, 0x80, v144
	v_ashrrev_i32_e32 v225, 31, v224
	v_lshl_add_u64 v[226:227], v[224:225], 2, s[18:19]
	global_load_dword v250, v[226:227], off
	global_load_dword v251, v[226:227], off offset:64
	global_load_dword v252, v[226:227], off offset:128
	global_load_dword v253, v[226:227], off offset:192
	v_pk_mul_f32 v[160:161], v[112:113], v[120:121]
	v_mov_b64_e32 v[120:121], s[16:17]
	v_mad_i64_i32 v[162:163], s[4:5], v144, s58, v[120:121]
	v_pk_mul_f32 v[126:127], v[118:119], v[126:127]
	v_pk_mul_f32 v[124:125], v[116:117], v[124:125]
	v_pk_mul_f32 v[122:123], v[114:115], v[122:123]
	v_pk_mul_f32 v[104:105], v[108:109], v[104:105]
	v_pk_mul_f32 v[106:107], v[110:111], v[106:107]
	v_pk_mul_f32 v[98:99], v[102:103], v[98:99]
	v_lshl_add_u64 v[162:163], v[162:163], 0, v[142:143]
	v_pk_mul_f32 v[96:97], v[100:101], v[96:97]
	v_pk_mul_f32 v[88:89], v[92:93], v[88:89]
	v_pk_mul_f32 v[90:91], v[94:95], v[90:91]
	v_pk_mul_f32 v[82:83], v[86:87], v[82:83]
	v_pk_mul_f32 v[80:81], v[84:85], v[80:81]
	v_pk_mul_f32 v[72:73], v[76:77], v[72:73]
	v_pk_mul_f32 v[74:75], v[78:79], v[74:75]
	v_pk_mul_f32 v[66:67], v[70:71], v[66:67]
	v_pk_mul_f32 v[64:65], v[68:69], v[64:65]
	s_waitcnt vmcnt(4)
; DI u32x4 pack8v(f32x4 a, f32x4 b) { return u32x4{cvtpk(a[0], a[1]), cvtpk(a[2], a[3]), cvtpk(b[0], b[1]), cvtpk(b[2], b[3])}; }
;   DI void operator()(AccRef acc, const pg8::Unit& u, int wr, int wc, int fr, int fq) const {
;     ...
;       for (int m = 0; m < 4; ++m) rs[m] = ss[row0 + ai * 128 + m * 16];
; #pragma unroll
;       for (int m = 0; m < 4; ++m) rs[m] = rsqrtf(rs[m] * (1.f / DM) + EPS);
; #pragma unroll
;       for (int m = 0; m < 4; ++m) {
;         const int row = row0 + ai * 128 + m * 16;
;         const float ne = rs[m] * -1.4426950408889634f, r2 = rs[m] * rs[m];
;         f32x4 y[2];
; #pragma unroll
;         for (int n = 0; n < 2; ++n)
; #pragma unroll
;           for (int e = 0; e < 4; ++e) {
;             const float a = acc[ai][0][m][n][e], b = acc[ai][1][m][n][e];
;             y[n][e] = a * b * r2 * __builtin_amdgcn_rcpf(1.f + __builtin_amdgcn_exp2f(a * ne));
;           }
;         *(u32x4*)(act + (size_t)row * FFN + col0) = pack8v(y[0], y[1]);
	v_fmamk_f32 v145, v145, 0x3a800000, v158
	v_mul_f32_e32 v159, 0x4b800000, v145
	v_cmp_gt_f32_e32 vcc, s57, v145
	v_fmamk_f32 v147, v147, 0x3a800000, v158
	v_fmamk_f32 v149, v149, 0x3a800000, v158
	v_fmamk_f32 v151, v151, 0x3a800000, v158
	v_cndmask_b32_e32 v145, v145, v159, vcc
	v_mul_f32_e32 v159, 0x4b800000, v147
	v_cmp_gt_f32_e64 s[4:5], s57, v147
	v_mul_f32_e32 v164, 0x4b800000, v149
	v_mul_f32_e32 v165, 0x4b800000, v151
	v_rsq_f32_e32 v145, v145
	v_cndmask_b32_e64 v147, v147, v159, s[4:5]
	v_cmp_gt_f32_e64 s[6:7], s57, v149
	v_cmp_gt_f32_e64 s[8:9], s57, v151
	v_rsq_f32_e32 v147, v147
	v_cndmask_b32_e64 v149, v149, v164, s[6:7]
	v_cndmask_b32_e64 v151, v151, v165, s[8:9]
	v_rsq_f32_e32 v149, v149
	v_rsq_f32_e32 v151, v151
	v_mul_f32_e32 v159, 0x45800000, v145
	v_cndmask_b32_e32 v145, v145, v159, vcc
	v_mul_f32_e32 v159, 0x45800000, v147
	v_mul_f32_e32 v164, 0x45800000, v149
	v_mul_f32_e32 v165, 0x45800000, v151
	v_cndmask_b32_e64 v147, v147, v159, s[4:5]
	v_mul_f32_e32 v159, 0xbfb8aa3b, v145
	v_cndmask_b32_e64 v149, v149, v164, s[6:7]
	v_cndmask_b32_e64 v151, v151, v165, s[8:9]
	v_mul_f32_e32 v164, v145, v145
	v_mul_f32_e32 v165, v117, v159
	v_mul_f32_e32 v145, v116, v159
	v_pk_mul_f32 v[116:117], v[124:125], v[164:165] op_sel_hi:[1,0]
	v_mul_f32_e32 v124, v118, v159
	v_mul_f32_e32 v125, v119, v159
	v_pk_mul_f32 v[118:119], v[126:127], v[164:165] op_sel_hi:[1,0]
	v_mul_f32_e32 v126, v112, v159
	v_mul_f32_e32 v127, v113, v159
	v_pk_mul_f32 v[112:113], v[160:161], v[164:165] op_sel_hi:[1,0]
	v_mul_f32_e32 v160, v114, v159
	v_mul_f32_e32 v159, v115, v159
	v_pk_mul_f32 v[114:115], v[122:123], v[164:165] op_sel_hi:[1,0]
	v_mul_f32_e32 v123, 0xbfb8aa3b, v147
	v_mul_f32_e32 v161, v108, v123
	v_mul_f32_e32 v164, v109, v123
	v_mul_f32_e32 v108, v110, v123
	v_mul_f32_e32 v109, v111, v123
	v_mul_f32_e32 v122, v147, v147
	v_exp_f32_e32 v145, v145
	v_exp_f32_e32 v147, v165
	v_exp_f32_e32 v124, v124
	v_exp_f32_e32 v125, v125
	v_exp_f32_e32 v126, v126
	v_exp_f32_e32 v127, v127
	v_exp_f32_e32 v160, v160
	v_exp_f32_e32 v159, v159
	v_exp_f32_e32 v108, v108
	v_exp_f32_e32 v109, v109
	v_exp_f32_e32 v166, v161
	v_exp_f32_e32 v167, v164
	v_add_f32_e32 v145, 1.0, v145
	v_add_f32_e32 v147, 1.0, v147
	v_add_f32_e32 v161, 1.0, v124
	v_add_f32_e32 v164, 1.0, v125
	v_add_f32_e32 v165, 1.0, v126
	v_add_f32_e32 v168, 1.0, v127
	v_add_f32_e32 v169, 1.0, v160
	v_add_f32_e32 v159, 1.0, v159
	v_add_f32_e32 v108, 1.0, v108
	v_add_f32_e32 v109, 1.0, v109
	v_mul_f32_e32 v110, v100, v123
	v_mul_f32_e32 v111, v101, v123
	v_rcp_f32_e32 v124, v145
	v_rcp_f32_e32 v125, v147
	v_rcp_f32_e32 v126, v161
	v_rcp_f32_e32 v127, v164
	v_rcp_f32_e32 v160, v165
	v_rcp_f32_e32 v161, v168
	v_rcp_f32_e32 v164, v169
	v_rcp_f32_e32 v165, v159
	v_rcp_f32_e32 v108, v108
	v_rcp_f32_e32 v109, v109
	v_exp_f32_e32 v110, v110
	v_exp_f32_e32 v111, v111
	v_mul_f32_e32 v102, v102, v123
	v_mul_f32_e32 v103, v103, v123
	v_exp_f32_e32 v102, v102
	v_exp_f32_e32 v103, v103
	v_pk_mul_f32 v[106:107], v[106:107], v[122:123] op_sel_hi:[1,0]
	v_pk_mul_f32 v[116:117], v[116:117], v[124:125]
	v_pk_mul_f32 v[118:119], v[118:119], v[126:127]
	v_pk_mul_f32 v[124:125], v[112:113], v[160:161]
	v_pk_mul_f32 v[126:127], v[114:115], v[164:165]
	v_pk_mul_f32 v[106:107], v[106:107], v[108:109]
	v_add_f32_e32 v108, 1.0, v110
	v_add_f32_e32 v109, 1.0, v111
	v_cvt_pk_bf16_f32 v112, v116, v117
	v_cvt_pk_bf16_f32 v113, v118, v119
	v_cvt_pk_bf16_f32 v114, v124, v125
	v_cvt_pk_bf16_f32 v115, v126, v127
	v_rcp_f32_e32 v108, v108
	v_rcp_f32_e32 v109, v109
	v_add_f32_e32 v100, 1.0, v102
	v_add_f32_e32 v101, 1.0, v103
	v_add_f32_e32 v145, 1.0, v166
	global_store_dwordx4 v[162:163], v[112:115], off
	v_rcp_f32_e32 v100, v100
	v_rcp_f32_e32 v101, v101
	v_add_f32_e32 v113, 1.0, v167
	v_rcp_f32_e32 v112, v145
	v_rcp_f32_e32 v113, v113
; DI u32x4 pack8v(f32x4 a, f32x4 b) { return u32x4{cvtpk(a[0], a[1]), cvtpk(a[2], a[3]), cvtpk(b[0], b[1]), cvtpk(b[2], b[3])}; }
;   DI void operator()(AccRef acc, const pg8::Unit& u, int wr, int wc, int fr, int fq) const {
;     ...
;       for (int m = 0; m < 4; ++m) {
;         const int row = row0 + ai * 128 + m * 16;
;         const float ne = rs[m] * -1.4426950408889634f, r2 = rs[m] * rs[m];
;         f32x4 y[2];
; #pragma unroll
;         for (int n = 0; n < 2; ++n)
; #pragma unroll
;           for (int e = 0; e < 4; ++e) {
;             const float a = acc[ai][0][m][n][e], b = acc[ai][1][m][n][e];
;             y[n][e] = a * b * r2 * __builtin_amdgcn_rcpf(1.f + __builtin_amdgcn_exp2f(a * ne));
;           }
;         *(u32x4*)(act + (size_t)row * FFN + col0) = pack8v(y[0], y[1]);
	v_pk_mul_f32 v[96:97], v[96:97], v[122:123] op_sel_hi:[1,0]
	v_pk_mul_f32 v[104:105], v[104:105], v[122:123] op_sel_hi:[1,0]
	v_pk_mul_f32 v[102:103], v[96:97], v[108:109]
	v_pk_mul_f32 v[96:97], v[98:99], v[122:123] op_sel_hi:[1,0]
	v_pk_mul_f32 v[104:105], v[104:105], v[112:113]
	v_pk_mul_f32 v[100:101], v[96:97], v[100:101]
	v_cvt_pk_bf16_f32 v96, v104, v105
	v_cvt_pk_bf16_f32 v99, v100, v101
	v_mad_i64_i32 v[100:101], s[4:5], v150, s58, v[120:121]
	v_cvt_pk_bf16_f32 v97, v106, v107
	v_cvt_pk_bf16_f32 v98, v102, v103
	v_lshl_add_u64 v[100:101], v[100:101], 0, v[142:143]
	global_store_dwordx4 v[100:101], v[96:99], off
	s_nop 1
	v_mul_f32_e32 v97, 0xbfb8aa3b, v149
	v_mul_f32_e32 v96, v92, v97
	v_exp_f32_e32 v98, v96
	v_mul_f32_e32 v96, v93, v97
	v_mul_f32_e32 v92, v94, v97
	v_mul_f32_e32 v93, v95, v97
	v_exp_f32_e32 v92, v92
	v_exp_f32_e32 v93, v93
	v_mul_f32_e32 v94, v84, v97
	v_mul_f32_e32 v95, v85, v97
	v_add_f32_e32 v92, 1.0, v92
	v_add_f32_e32 v93, 1.0, v93
	v_rcp_f32_e32 v92, v92
	v_rcp_f32_e32 v93, v93
	v_exp_f32_e32 v94, v94
	v_exp_f32_e32 v95, v95
	v_mul_f32_e32 v86, v86, v97
	v_mul_f32_e32 v87, v87, v97
	v_exp_f32_e32 v86, v86
	v_exp_f32_e32 v87, v87
	v_exp_f32_e32 v99, v96
	v_mul_f32_e32 v96, v149, v149
	v_pk_mul_f32 v[90:91], v[90:91], v[96:97] op_sel_hi:[1,0]
	v_add_f32_e32 v84, 1.0, v86
	v_pk_mul_f32 v[90:91], v[90:91], v[92:93]
	v_add_f32_e32 v92, 1.0, v94
	v_add_f32_e32 v93, 1.0, v95
	v_rcp_f32_e32 v92, v92
	v_rcp_f32_e32 v93, v93
	v_add_f32_e32 v85, 1.0, v87
	v_add_f32_e32 v98, 1.0, v98
	v_add_f32_e32 v99, 1.0, v99
	v_rcp_f32_e32 v84, v84
	v_rcp_f32_e32 v85, v85
	v_rcp_f32_e32 v98, v98
	v_rcp_f32_e32 v99, v99
	v_pk_mul_f32 v[80:81], v[80:81], v[96:97] op_sel_hi:[1,0]
	v_pk_mul_f32 v[88:89], v[88:89], v[96:97] op_sel_hi:[1,0]
	v_pk_mul_f32 v[86:87], v[80:81], v[92:93]
	v_pk_mul_f32 v[80:81], v[82:83], v[96:97] op_sel_hi:[1,0]
	v_pk_mul_f32 v[88:89], v[88:89], v[98:99]
	v_pk_mul_f32 v[84:85], v[80:81], v[84:85]
	v_cvt_pk_bf16_f32 v80, v88, v89
	v_cvt_pk_bf16_f32 v83, v84, v85
	v_mad_i64_i32 v[84:85], s[4:5], v148, s58, v[120:121]
	v_cvt_pk_bf16_f32 v81, v90, v91
	v_cvt_pk_bf16_f32 v82, v86, v87
	v_lshl_add_u64 v[84:85], v[84:85], 0, v[142:143]
	global_store_dwordx4 v[84:85], v[80:83], off
	s_nop 1
	v_mul_f32_e32 v81, 0xbfb8aa3b, v151
	v_mul_f32_e32 v80, v76, v81
	v_exp_f32_e32 v82, v80
	v_mul_f32_e32 v80, v77, v81
	v_mul_f32_e32 v76, v78, v81
	v_mul_f32_e32 v77, v79, v81
	v_exp_f32_e32 v76, v76
	v_exp_f32_e32 v77, v77
	v_mul_f32_e32 v78, v68, v81
	v_mul_f32_e32 v79, v69, v81
	v_add_f32_e32 v76, 1.0, v76
	v_add_f32_e32 v77, 1.0, v77
	v_rcp_f32_e32 v76, v76
	v_rcp_f32_e32 v77, v77
	v_exp_f32_e32 v78, v78
	v_exp_f32_e32 v79, v79
	v_mul_f32_e32 v70, v70, v81
	v_mul_f32_e32 v71, v71, v81
	v_exp_f32_e32 v70, v70
	v_exp_f32_e32 v71, v71
	v_exp_f32_e32 v83, v80
	v_mul_f32_e32 v80, v151, v151
	v_pk_mul_f32 v[74:75], v[74:75], v[80:81] op_sel_hi:[1,0]
	v_add_f32_e32 v68, 1.0, v70
	v_pk_mul_f32 v[74:75], v[74:75], v[76:77]
	v_add_f32_e32 v76, 1.0, v78
	v_add_f32_e32 v77, 1.0, v79
	v_rcp_f32_e32 v76, v76
	v_rcp_f32_e32 v77, v77
	v_add_f32_e32 v69, 1.0, v71
	v_add_f32_e32 v82, 1.0, v82
	v_add_f32_e32 v83, 1.0, v83
	v_rcp_f32_e32 v68, v68
	v_rcp_f32_e32 v69, v69
	v_rcp_f32_e32 v82, v82
	v_rcp_f32_e32 v83, v83
	v_pk_mul_f32 v[64:65], v[64:65], v[80:81] op_sel_hi:[1,0]
	v_pk_mul_f32 v[72:73], v[72:73], v[80:81] op_sel_hi:[1,0]
	v_pk_mul_f32 v[70:71], v[64:65], v[76:77]
	v_pk_mul_f32 v[64:65], v[66:67], v[80:81] op_sel_hi:[1,0]
	v_pk_mul_f32 v[72:73], v[72:73], v[82:83]
	v_pk_mul_f32 v[68:69], v[64:65], v[68:69]
	v_cvt_pk_bf16_f32 v64, v72, v73
	v_cvt_pk_bf16_f32 v67, v68, v69
	v_mad_i64_i32 v[68:69], s[4:5], v146, s58, v[120:121]
	v_cvt_pk_bf16_f32 v65, v74, v75
	v_cvt_pk_bf16_f32 v66, v70, v71
	v_lshl_add_u64 v[68:69], v[68:69], 0, v[142:143]
	global_store_dwordx4 v[68:69], v[64:67], off

; #define PG8_STAGE(bufoff, gbase, voff) do { _Pragma("unroll") for (int _i = 0; _i < 2; ++_i) \
;     __builtin_amdgcn_global_load_lds((const unsigned*)((const char*)(gbase) + (voff)[_i]), (PG8_LAS unsigned*)(lds + (bufoff) + ldsw + _i * 8192), 16, 0, 0); } while (0)
; #define PG8_LDA(dst, b, h) do { _Pragma("unroll") for (int m = 0; m < 4; ++m) _Pragma("unroll") for (int k = 0; k < 2; ++k) dst[m][k] = *(const PG8_LAS bf16x8*)(lds + PG8_SA(b, h) + aoff + m * 2048 + k * 1024); } while (0)
; #define PG8_LDB(dst, b, h) do { _Pragma("unroll") for (int n = 0; n < 2; ++n) _Pragma("unroll") for (int k = 0; k < 2; ++k) dst[n][k] = *(const PG8_LAS bf16x8*)(lds + PG8_SB(b, h) + boff + n * 2048 + k * 1024); } while (0)
; #define PG8_MMA(ai, bj, At, Bt) do { __builtin_amdgcn_s_setprio(1); _Pragma("unroll") for (int m = 0; m < 4; ++m) _Pragma("unroll") for (int n = 0; n < 2; ++n) _Pragma("unroll") for (int k = 0; k < 2; ++k) \
;     acc[ai][bj][m][n] = __builtin_amdgcn_mfma_f32_16x16x32_bf16(Bt[n][k], At[m][k], acc[ai][bj][m][n], 0, 0, 0); __builtin_amdgcn_s_setprio(0); } while (0)
; #define PG8_WAIT_L(n) asm volatile("s_waitcnt lgkmcnt(" #n ")" ::: "memory")
; #define PG8_BAR __builtin_amdgcn_s_barrier()
; template <class Epi>
; DI void gemm_phase(PG8_LAS unsigned char* lds, const Gemm g, const StaticOrder& S, const Epi& E, const int wv) {
;     ...
;   for (;;) {
;     const bool has_next = S.next(ui + 1, nxt);
;     const char* nA = has_next ? (const char*)g.A + (size_t)nxt.pm * tstep : cA; const char* nB = has_next ? (const char*)g.Bt + (size_t)nxt.pn * tstep : cB;
; #pragma nounroll
;     for (int t = 0; t < nt; t += 2) {
;       const bool last = (t == nt - 2);
;       const char* a1 = cA + (size_t)(t + 1) * kstep;
;       const char* a2 = last ? nA : cA + (size_t)(t + 2) * kstep; const char* b2 = last ? nB : cB + (size_t)(t + 2) * kstep;
;       const char* a3 = a2 + kstep; const char* b3 = b2 + kstep;
;       PG8_LDB(B0, 0, 0); PG8_SCHED; PG8_LDA(At, 0, 0); PG8_STAGE(PG8_SA(1, 1), a1 + hstep, voffA);
;       PG8_WAIT_L(8); PG8_BAR; PG8_WAIT_L(0); PG8_MMA(0, 0, At, B0); PG8_BAR; PG8_SCHED;
;       PG8_LDB(B1, 0, 1); PG8_STAGE(PG8_SB(0, 0), b2, voffB);
;       PG8_BAR; PG8_WAIT_L(0); PG8_MMA(0, 1, At, B1); PG8_BAR;
;       PG8_LDA(At, 0, 1); PG8_STAGE(PG8_SA(0, 0), a2, voffA);
;       PG8_BAR; PG8_WAIT_L(0); PG8_MMA(1, 0, At, B0); PG8_BAR; PG8_SCHED;
.LBB0_968:
	ds_read_b128 v[128:131], v189
	ds_read_b128 v[132:135], v189 offset:1024
	ds_read_b128 v[136:139], v189 offset:2048
	ds_read_b128 v[140:143], v189 offset:3072
	s_add_u32 s28, s26, 0x100
	s_addc_u32 s29, s27, 0
	s_cmp_eq_u32 s63, 40
	s_cselect_b32 s35, s25, s29
	s_cselect_b32 s34, s24, s28
	s_cselect_b32 s31, s7, s62
	s_cselect_b32 s30, s6, s61
	v_lshl_add_u64 v[198:199], s[26:27], 0, v[160:161]
	s_add_i32 m0, s43, 0xc000
	ds_read_b128 v[144:147], v190
	ds_read_b128 v[148:151], v190 offset:1024
	ds_read_b128 v[166:169], v190 offset:2048
	ds_read_b128 v[170:173], v190 offset:3072
	ds_read_b128 v[174:177], v190 offset:4096
	ds_read_b128 v[178:181], v190 offset:5120
	ds_read_b128 v[182:185], v190 offset:6144
	ds_read_b128 v[194:197], v190 offset:7168
	global_load_lds_dwordx4 v[198:199], off
	v_lshl_add_u64 v[198:199], s[26:27], 0, v[162:163]
	s_add_i32 m0, s43, 0xe000
	s_nop 0
	global_load_lds_dwordx4 v[198:199], off
	s_waitcnt lgkmcnt(8)
	s_barrier
	s_waitcnt lgkmcnt(0)
	s_setprio 1
	s_waitcnt lgkmcnt(0)
	v_mfma_f32_16x16x32_bf16 v[124:127], v[128:131], v[144:147], v[124:127]
	v_mfma_f32_16x16x32_bf16 v[120:123], v[136:139], v[144:147], v[120:123]
	v_mfma_f32_16x16x32_bf16 v[108:111], v[128:131], v[166:169], v[108:111]
	v_mfma_f32_16x16x32_bf16 v[104:107], v[136:139], v[166:169], v[104:107]
	v_mfma_f32_16x16x32_bf16 v[92:95], v[128:131], v[174:177], v[92:95]
	v_mfma_f32_16x16x32_bf16 v[88:91], v[136:139], v[174:177], v[88:91]
	v_mfma_f32_16x16x32_bf16 v[76:79], v[128:131], v[182:185], v[76:79]
	v_mfma_f32_16x16x32_bf16 v[72:75], v[136:139], v[182:185], v[72:75]
	v_mfma_f32_16x16x32_bf16 v[124:127], v[132:135], v[148:151], v[124:127]
	v_mfma_f32_16x16x32_bf16 v[120:123], v[140:143], v[148:151], v[120:123]
	v_mfma_f32_16x16x32_bf16 v[108:111], v[132:135], v[170:173], v[108:111]
	v_mfma_f32_16x16x32_bf16 v[104:107], v[140:143], v[170:173], v[104:107]
	v_mfma_f32_16x16x32_bf16 v[92:95], v[132:135], v[178:181], v[92:95]
	v_mfma_f32_16x16x32_bf16 v[88:91], v[140:143], v[178:181], v[88:91]
	v_mfma_f32_16x16x32_bf16 v[76:79], v[132:135], v[194:197], v[76:79]
	v_mfma_f32_16x16x32_bf16 v[72:75], v[140:143], v[194:197], v[72:75]
	s_setprio 0
	s_barrier
	s_add_i32 s26, s54, s42
	v_lshl_add_u64 v[214:215], s[30:31], 0, v[154:155]
	s_mov_b32 m0, s26
	ds_read_b128 v[198:201], v191
	ds_read_b128 v[202:205], v191 offset:1024
	ds_read_b128 v[206:209], v191 offset:2048
	ds_read_b128 v[210:213], v191 offset:3072
	global_load_lds_dwordx4 v[214:215], off
	v_lshl_add_u64 v[216:217], s[30:31], 0, v[158:159]
	s_add_i32 m0, s26, 0x2000
	s_nop 0
	global_load_lds_dwordx4 v[216:217], off
	s_barrier
	s_waitcnt lgkmcnt(0)
	s_setprio 1
	v_mfma_f32_16x16x32_bf16 v[116:119], v[198:201], v[144:147], v[116:119]
	v_mfma_f32_16x16x32_bf16 v[112:115], v[206:209], v[144:147], v[112:115]
	v_mfma_f32_16x16x32_bf16 v[100:103], v[198:201], v[166:169], v[100:103]
	v_mfma_f32_16x16x32_bf16 v[96:99], v[206:209], v[166:169], v[96:99]
	v_mfma_f32_16x16x32_bf16 v[84:87], v[198:201], v[174:177], v[84:87]
	v_mfma_f32_16x16x32_bf16 v[80:83], v[206:209], v[174:177], v[80:83]
	v_mfma_f32_16x16x32_bf16 v[68:71], v[198:201], v[182:185], v[68:71]
	v_mfma_f32_16x16x32_bf16 v[64:67], v[206:209], v[182:185], v[64:67]
	v_mfma_f32_16x16x32_bf16 v[116:119], v[202:205], v[148:151], v[116:119]
	v_mfma_f32_16x16x32_bf16 v[112:115], v[210:213], v[148:151], v[112:115]
	v_mfma_f32_16x16x32_bf16 v[100:103], v[202:205], v[170:173], v[100:103]
	v_mfma_f32_16x16x32_bf16 v[96:99], v[210:213], v[170:173], v[96:99]
	v_mfma_f32_16x16x32_bf16 v[84:87], v[202:205], v[178:181], v[84:87]
	v_mfma_f32_16x16x32_bf16 v[80:83], v[210:213], v[178:181], v[80:83]
	v_mfma_f32_16x16x32_bf16 v[68:71], v[202:205], v[194:197], v[68:71]
	v_mfma_f32_16x16x32_bf16 v[64:67], v[210:213], v[194:197], v[64:67]
	s_setprio 0
	s_mov_b32 m0, s43
	v_lshl_add_u64 v[220:221], s[34:35], 0, v[152:153]
	s_barrier
	ds_read_b128 v[144:147], v190 offset:16384
	ds_read_b128 v[148:151], v190 offset:17408
	ds_read_b128 v[166:169], v190 offset:18432
	ds_read_b128 v[170:173], v190 offset:19456
	ds_read_b128 v[174:177], v190 offset:20480
	ds_read_b128 v[178:181], v190 offset:21504
	ds_read_b128 v[182:185], v190 offset:22528
	ds_read_b128 v[194:197], v190 offset:23552
	global_load_lds_dwordx4 v[220:221], off
	v_lshl_add_u64 v[222:223], s[34:35], 0, v[156:157]
	s_mov_b32 m0, s44
	s_nop 0
	global_load_lds_dwordx4 v[222:223], off
	s_barrier
	s_waitcnt lgkmcnt(0)
	s_setprio 1
	v_mfma_f32_16x16x32_bf16 v[60:63], v[128:131], v[144:147], v[60:63]
	v_mfma_f32_16x16x32_bf16 v[56:59], v[136:139], v[144:147], v[56:59]
	v_mfma_f32_16x16x32_bf16 v[44:47], v[128:131], v[166:169], v[44:47]
	v_mfma_f32_16x16x32_bf16 v[40:43], v[136:139], v[166:169], v[40:43]
	v_mfma_f32_16x16x32_bf16 v[28:31], v[128:131], v[174:177], v[28:31]
	v_mfma_f32_16x16x32_bf16 v[24:27], v[136:139], v[174:177], v[24:27]
	v_mfma_f32_16x16x32_bf16 v[12:15], v[128:131], v[182:185], v[12:15]
	v_mfma_f32_16x16x32_bf16 v[8:11], v[136:139], v[182:185], v[8:11]
	v_mfma_f32_16x16x32_bf16 v[60:63], v[132:135], v[148:151], v[60:63]
	v_mfma_f32_16x16x32_bf16 v[56:59], v[140:143], v[148:151], v[56:59]
	v_mfma_f32_16x16x32_bf16 v[44:47], v[132:135], v[170:173], v[44:47]
	v_mfma_f32_16x16x32_bf16 v[40:43], v[140:143], v[170:173], v[40:43]
	v_mfma_f32_16x16x32_bf16 v[28:31], v[132:135], v[178:181], v[28:31]
	v_mfma_f32_16x16x32_bf16 v[24:27], v[140:143], v[178:181], v[24:27]
	v_mfma_f32_16x16x32_bf16 v[12:15], v[132:135], v[194:197], v[12:15]
	v_mfma_f32_16x16x32_bf16 v[8:11], v[140:143], v[194:197], v[8:11]
	s_setprio 0
	s_barrier
; #define PG8_STAGE(bufoff, gbase, voff) do { _Pragma("unroll") for (int _i = 0; _i < 2; ++_i) \
;     __builtin_amdgcn_global_load_lds((const unsigned*)((const char*)(gbase) + (voff)[_i]), (PG8_LAS unsigned*)(lds + (bufoff) + ldsw + _i * 8192), 16, 0, 0); } while (0)
; #define PG8_LDA(dst, b, h) do { _Pragma("unroll") for (int m = 0; m < 4; ++m) _Pragma("unroll") for (int k = 0; k < 2; ++k) dst[m][k] = *(const PG8_LAS bf16x8*)(lds + PG8_SA(b, h) + aoff + m * 2048 + k * 1024); } while (0)
; #define PG8_LDB(dst, b, h) do { _Pragma("unroll") for (int n = 0; n < 2; ++n) _Pragma("unroll") for (int k = 0; k < 2; ++k) dst[n][k] = *(const PG8_LAS bf16x8*)(lds + PG8_SB(b, h) + boff + n * 2048 + k * 1024); } while (0)
; #define PG8_MMA(ai, bj, At, Bt) do { __builtin_amdgcn_s_setprio(1); _Pragma("unroll") for (int m = 0; m < 4; ++m) _Pragma("unroll") for (int n = 0; n < 2; ++n) _Pragma("unroll") for (int k = 0; k < 2; ++k) \
;     acc[ai][bj][m][n] = __builtin_amdgcn_mfma_f32_16x16x32_bf16(Bt[n][k], At[m][k], acc[ai][bj][m][n], 0, 0, 0); __builtin_amdgcn_s_setprio(0); } while (0)
; #define PG8_WAIT_V(n) asm volatile("s_waitcnt vmcnt(" #n ")" ::: "memory")
; #define PG8_WAIT_L(n) asm volatile("s_waitcnt lgkmcnt(" #n ")" ::: "memory")
; #define PG8_BAR __builtin_amdgcn_s_barrier()
; #define PG8_SCHED __builtin_amdgcn_sched_barrier(0)
; template <class Epi>
; DI void gemm_phase(PG8_LAS unsigned char* lds, const Gemm g, const StaticOrder& S, const Epi& E, const int wv) {
;     ...
;       PG8_STAGE(PG8_SB(0, 1), b2 + hstep, voffB);
;       PG8_WAIT_V(6); PG8_BAR; PG8_MMA(1, 1, At, B1); PG8_BAR;
;       PG8_LDB(B0, 1, 0); PG8_SCHED; PG8_LDA(At, 1, 0); PG8_STAGE(PG8_SA(0, 1), a2 + hstep, voffA);
;       PG8_WAIT_L(8); PG8_BAR; PG8_WAIT_L(0); PG8_MMA(0, 0, At, B0); PG8_BAR; PG8_SCHED;
;       PG8_LDB(B1, 1, 1); PG8_STAGE(PG8_SB(1, 0), b3, voffB);
;       PG8_BAR; PG8_WAIT_L(0); PG8_MMA(0, 1, At, B1); PG8_BAR;
;       PG8_LDA(At, 1, 1); PG8_STAGE(PG8_SA(1, 0), a3, voffA);
	s_add_u32 s26, s30, 0xb0000
	s_addc_u32 s27, s31, 0
	s_add_i32 s64, s55, s42
	v_lshl_add_u64 v[128:129], s[26:27], 0, v[154:155]
	s_mov_b32 m0, s64
	s_nop 0
	global_load_lds_dwordx4 v[128:129], off
	v_lshl_add_u64 v[128:129], s[26:27], 0, v[158:159]
	s_add_i32 m0, s64, 0x2000
	s_nop 0
	global_load_lds_dwordx4 v[128:129], off
	s_waitcnt vmcnt(6)
	s_barrier
	s_setprio 1
	v_mfma_f32_16x16x32_bf16 v[52:55], v[198:201], v[144:147], v[52:55]
	v_mfma_f32_16x16x32_bf16 v[48:51], v[206:209], v[144:147], v[48:51]
	v_mfma_f32_16x16x32_bf16 v[36:39], v[198:201], v[166:169], v[36:39]
	v_mfma_f32_16x16x32_bf16 v[32:35], v[206:209], v[166:169], v[32:35]
	v_mfma_f32_16x16x32_bf16 v[20:23], v[198:201], v[174:177], v[20:23]
	v_mfma_f32_16x16x32_bf16 v[16:19], v[206:209], v[174:177], v[16:19]
	v_mfma_f32_16x16x32_bf16 v[4:7], v[198:201], v[182:185], v[4:7]
	v_mfma_f32_16x16x32_bf16 v[0:3], v[206:209], v[182:185], v[0:3]
	v_mfma_f32_16x16x32_bf16 v[52:55], v[202:205], v[148:151], v[52:55]
	v_mfma_f32_16x16x32_bf16 v[48:51], v[210:213], v[148:151], v[48:51]
	v_mfma_f32_16x16x32_bf16 v[36:39], v[202:205], v[170:173], v[36:39]
	v_mfma_f32_16x16x32_bf16 v[32:35], v[210:213], v[170:173], v[32:35]
	v_mfma_f32_16x16x32_bf16 v[20:23], v[202:205], v[178:181], v[20:23]
	v_mfma_f32_16x16x32_bf16 v[16:19], v[210:213], v[178:181], v[16:19]
	v_mfma_f32_16x16x32_bf16 v[4:7], v[202:205], v[194:197], v[4:7]
	v_mfma_f32_16x16x32_bf16 v[0:3], v[210:213], v[194:197], v[0:3]
	s_setprio 0
	s_add_i32 s64, 0, 0x18000
	v_add_u32_e32 v140, s64, v187
	s_barrier
	ds_read_b128 v[128:131], v140
	ds_read_b128 v[132:135], v140 offset:1024
	ds_read_b128 v[136:139], v140 offset:2048
	ds_read_b128 v[140:143], v140 offset:3072
	s_add_u32 s26, s34, 0xb0000
	s_addc_u32 s27, s35, 0
	s_mov_b32 m0, s45
	v_lshl_add_u64 v[198:199], s[26:27], 0, v[152:153]
	ds_read_b128 v[144:147], v190 offset:32768
	ds_read_b128 v[148:151], v190 offset:33792
	ds_read_b128 v[166:169], v190 offset:34816
	ds_read_b128 v[170:173], v190 offset:35840
	ds_read_b128 v[174:177], v190 offset:36864
	ds_read_b128 v[178:181], v190 offset:37888
	ds_read_b128 v[182:185], v190 offset:38912
	ds_read_b128 v[194:197], v190 offset:39936
	global_load_lds_dwordx4 v[198:199], off
	v_lshl_add_u64 v[198:199], s[26:27], 0, v[156:157]
	s_mov_b32 m0, s46
	s_nop 0
	global_load_lds_dwordx4 v[198:199], off
	s_waitcnt lgkmcnt(8)
	s_barrier
	s_waitcnt lgkmcnt(0)
	s_setprio 1
	s_waitcnt lgkmcnt(0)
	v_mfma_f32_16x16x32_bf16 v[124:127], v[128:131], v[144:147], v[124:127]
	v_mfma_f32_16x16x32_bf16 v[120:123], v[136:139], v[144:147], v[120:123]
	v_mfma_f32_16x16x32_bf16 v[108:111], v[128:131], v[166:169], v[108:111]
	v_mfma_f32_16x16x32_bf16 v[104:107], v[136:139], v[166:169], v[104:107]
	v_mfma_f32_16x16x32_bf16 v[92:95], v[128:131], v[174:177], v[92:95]
	v_mfma_f32_16x16x32_bf16 v[88:91], v[136:139], v[174:177], v[88:91]
	v_mfma_f32_16x16x32_bf16 v[76:79], v[128:131], v[182:185], v[76:79]
	v_mfma_f32_16x16x32_bf16 v[72:75], v[136:139], v[182:185], v[72:75]
	v_mfma_f32_16x16x32_bf16 v[124:127], v[132:135], v[148:151], v[124:127]
	v_mfma_f32_16x16x32_bf16 v[120:123], v[140:143], v[148:151], v[120:123]
	v_mfma_f32_16x16x32_bf16 v[108:111], v[132:135], v[170:173], v[108:111]
	v_mfma_f32_16x16x32_bf16 v[104:107], v[140:143], v[170:173], v[104:107]
	v_mfma_f32_16x16x32_bf16 v[92:95], v[132:135], v[178:181], v[92:95]
	v_mfma_f32_16x16x32_bf16 v[88:91], v[140:143], v[178:181], v[88:91]
	v_mfma_f32_16x16x32_bf16 v[76:79], v[132:135], v[194:197], v[76:79]
	v_mfma_f32_16x16x32_bf16 v[72:75], v[140:143], v[194:197], v[72:75]
	s_setprio 0
	s_barrier
	s_add_i32 s34, 0, 0x1c000
	s_add_i32 s26, s64, s42
	v_add_u32_e32 v193, s34, v187
	v_lshl_add_u64 v[214:215], v[214:215], 0, s[20:21]
	s_mov_b32 m0, s26
	ds_read_b128 v[198:201], v193
	ds_read_b128 v[202:205], v193 offset:1024
	ds_read_b128 v[206:209], v193 offset:2048
	ds_read_b128 v[210:213], v193 offset:3072
	global_load_lds_dwordx4 v[214:215], off
	v_lshl_add_u64 v[214:215], v[216:217], 0, s[20:21]
	s_add_i32 m0, s26, 0x2000
	s_nop 0
	global_load_lds_dwordx4 v[214:215], off
	s_barrier
	s_waitcnt lgkmcnt(0)
	s_setprio 1
	s_waitcnt lgkmcnt(0)
	v_mfma_f32_16x16x32_bf16 v[116:119], v[198:201], v[144:147], v[116:119]
	v_mfma_f32_16x16x32_bf16 v[112:115], v[206:209], v[144:147], v[112:115]
	v_mfma_f32_16x16x32_bf16 v[100:103], v[198:201], v[166:169], v[100:103]
	v_mfma_f32_16x16x32_bf16 v[96:99], v[206:209], v[166:169], v[96:99]
	v_mfma_f32_16x16x32_bf16 v[84:87], v[198:201], v[174:177], v[84:87]
	v_mfma_f32_16x16x32_bf16 v[80:83], v[206:209], v[174:177], v[80:83]
	v_mfma_f32_16x16x32_bf16 v[68:71], v[198:201], v[182:185], v[68:71]
	v_mfma_f32_16x16x32_bf16 v[64:67], v[206:209], v[182:185], v[64:67]
	v_mfma_f32_16x16x32_bf16 v[116:119], v[202:205], v[148:151], v[116:119]
	v_mfma_f32_16x16x32_bf16 v[112:115], v[210:213], v[148:151], v[112:115]
	v_mfma_f32_16x16x32_bf16 v[100:103], v[202:205], v[170:173], v[100:103]
	v_mfma_f32_16x16x32_bf16 v[96:99], v[210:213], v[170:173], v[96:99]
	v_mfma_f32_16x16x32_bf16 v[84:87], v[202:205], v[178:181], v[84:87]
	v_mfma_f32_16x16x32_bf16 v[80:83], v[210:213], v[178:181], v[80:83]
	v_mfma_f32_16x16x32_bf16 v[68:71], v[202:205], v[194:197], v[68:71]
	v_mfma_f32_16x16x32_bf16 v[64:67], v[210:213], v[194:197], v[64:67]
	s_setprio 0
	s_mov_b32 m0, s48
	v_lshl_add_u64 v[214:215], v[220:221], 0, s[20:21]
	s_barrier
	ds_read_b128 v[144:147], v190 offset:49152
	ds_read_b128 v[148:151], v190 offset:50176
	ds_read_b128 v[166:169], v190 offset:51200
	ds_read_b128 v[170:173], v190 offset:52224
	ds_read_b128 v[174:177], v190 offset:53248
	ds_read_b128 v[178:181], v190 offset:54272
	ds_read_b128 v[182:185], v190 offset:55296
	ds_read_b128 v[194:197], v190 offset:56320
	global_load_lds_dwordx4 v[214:215], off
	v_lshl_add_u64 v[214:215], v[222:223], 0, s[20:21]
	s_mov_b32 m0, s49
	s_nop 0
	global_load_lds_dwordx4 v[214:215], off
	s_barrier
; template <class Epi>
; DI void gemm_phase(PG8_LAS unsigned char* lds, const Gemm g, const StaticOrder& S, const Epi& E, const int wv) {
;     ...
;       PG8_BAR; PG8_WAIT_L(0); PG8_MMA(1, 0, At, B0); PG8_BAR; PG8_SCHED;
;       PG8_STAGE(PG8_SB(1, 1), b3 + hstep, voffB);
;       PG8_WAIT_V(6); PG8_BAR; PG8_MMA(1, 1, At, B1); PG8_BAR;
;   DI void operator()(AccRef acc, const pg8::Unit& u, int wr, int wc, int fr, int fq) const {
;     ...
;         u32x4 rb[4][2];
; #pragma unroll
;         for (int m = 0; m < 4; ++m)
; #pragma unroll
;           for (int bj = 0; bj < 2; ++bj) {
;             const int rr = row0 + ai * 128 + m * 16;
;             const int sr = (MODE == 3) ? rr + NMETA * ((rr >> 12) + 1) : rr;
;             rb[m][bj] = *(const u32x4*)(hsrc + (size_t)sr * DM + col0 + bj * 128);
;           }
; #pragma unroll
;         for (int m = 0; m < 4; ++m)
; #pragma unroll
;           for (int bj = 0; bj < 2; ++bj) {
;             r[m][bj][0] = f32x4{bf_lo(rb[m][bj][0]), bf_hi(rb[m][bj][0]), bf_lo(rb[m][bj][1]), bf_hi(rb[m][bj][1])};
;             r[m][bj][1] = f32x4{bf_lo(rb[m][bj][2]), bf_hi(rb[m][bj][2]), bf_lo(rb[m][bj][3]), bf_hi(rb[m][bj][3])};
;           }
;       }
; #pragma unroll
;       for (int m = 0; m < 4; ++m) {
;         const int row = row0 + ai * 128 + m * 16;
;         if constexpr (MODE == 4) {
;           float* dst = P.out + (size_t)row * DM + col0;
; #pragma unroll
;           for (int bj = 0; bj < 2; ++bj) {
;             *(f32x4*)(dst + bj * 128) = r[m][bj][0] + acc[ai][bj][m][0];
;             *(f32x4*)(dst + bj * 128 + 4) = r[m][bj][1] + acc[ai][bj][m][1];
;           }
;         } else if constexpr (MODE == 2) {
;           const int s = row / L, p = row - s * L;
;           if (p >= NMETA) {
;             float* dst = P.out + ((size_t)s * SEQ + (p - NMETA)) * DM + col0;
; #pragma unroll
;             for (int bj = 0; bj < 2; ++bj) {
;               *(f32x4*)(dst + bj * 128) = r[m][bj][0] + acc[ai][bj][m][0];
;               *(f32x4*)(dst + bj * 128 + 4) = r[m][bj][1] + acc[ai][bj][m][1];
;             }
;           }
;         } else {
;           float s2 = 0.f;
; #pragma unroll
;           for (int bj = 0; bj < 2; ++bj) {
;             const f32x4 r0 = r[m][bj][0] + acc[ai][bj][m][0], r1 = r[m][bj][1] + acc[ai][bj][m][1];
;             *(u32x4*)(hdst + (size_t)row * DM + col0 + bj * 128) = pack8v(r0, r1);
	s_waitcnt lgkmcnt(0)
	s_setprio 1
	v_mfma_f32_16x16x32_bf16 v[60:63], v[128:131], v[144:147], v[60:63]
	v_mfma_f32_16x16x32_bf16 v[56:59], v[136:139], v[144:147], v[56:59]
	v_mfma_f32_16x16x32_bf16 v[44:47], v[128:131], v[166:169], v[44:47]
	v_mfma_f32_16x16x32_bf16 v[40:43], v[136:139], v[166:169], v[40:43]
	v_mfma_f32_16x16x32_bf16 v[28:31], v[128:131], v[174:177], v[28:31]
	v_mfma_f32_16x16x32_bf16 v[24:27], v[136:139], v[174:177], v[24:27]
	v_mfma_f32_16x16x32_bf16 v[12:15], v[128:131], v[182:185], v[12:15]
	v_mfma_f32_16x16x32_bf16 v[8:11], v[136:139], v[182:185], v[8:11]
	v_mfma_f32_16x16x32_bf16 v[60:63], v[132:135], v[148:151], v[60:63]
	v_mfma_f32_16x16x32_bf16 v[56:59], v[140:143], v[148:151], v[56:59]
	v_mfma_f32_16x16x32_bf16 v[44:47], v[132:135], v[170:173], v[44:47]
	v_mfma_f32_16x16x32_bf16 v[40:43], v[140:143], v[170:173], v[40:43]
	v_mfma_f32_16x16x32_bf16 v[28:31], v[132:135], v[178:181], v[28:31]
	v_mfma_f32_16x16x32_bf16 v[24:27], v[140:143], v[178:181], v[24:27]
	v_mfma_f32_16x16x32_bf16 v[12:15], v[132:135], v[194:197], v[12:15]
	v_mfma_f32_16x16x32_bf16 v[8:11], v[140:143], v[194:197], v[8:11]
	s_setprio 0
	s_barrier
	s_add_u32 s26, s30, 0xb0080
	s_addc_u32 s27, s31, 0
	s_add_i32 s30, s34, s42
	v_lshl_add_u64 v[128:129], s[26:27], 0, v[154:155]
	s_mov_b32 m0, s30
	s_nop 0
	global_load_lds_dwordx4 v[128:129], off
	v_lshl_add_u64 v[128:129], s[26:27], 0, v[158:159]
	s_add_i32 m0, s30, 0x2000
	s_nop 0
	global_load_lds_dwordx4 v[128:129], off
	s_waitcnt vmcnt(6)
	s_barrier
	s_setprio 1
	v_mfma_f32_16x16x32_bf16 v[52:55], v[198:201], v[144:147], v[52:55]
	v_mfma_f32_16x16x32_bf16 v[48:51], v[206:209], v[144:147], v[48:51]
	v_mfma_f32_16x16x32_bf16 v[36:39], v[198:201], v[166:169], v[36:39]
	v_mfma_f32_16x16x32_bf16 v[32:35], v[206:209], v[166:169], v[32:35]
	v_mfma_f32_16x16x32_bf16 v[20:23], v[198:201], v[174:177], v[20:23]
	v_mfma_f32_16x16x32_bf16 v[16:19], v[206:209], v[174:177], v[16:19]
	v_mfma_f32_16x16x32_bf16 v[4:7], v[198:201], v[182:185], v[4:7]
	v_mfma_f32_16x16x32_bf16 v[0:3], v[206:209], v[182:185], v[0:3]
	v_mfma_f32_16x16x32_bf16 v[52:55], v[202:205], v[148:151], v[52:55]
	v_mfma_f32_16x16x32_bf16 v[48:51], v[210:213], v[148:151], v[48:51]
	v_mfma_f32_16x16x32_bf16 v[36:39], v[202:205], v[170:173], v[36:39]
	v_mfma_f32_16x16x32_bf16 v[32:35], v[210:213], v[170:173], v[32:35]
	v_mfma_f32_16x16x32_bf16 v[20:23], v[202:205], v[178:181], v[20:23]
	v_mfma_f32_16x16x32_bf16 v[16:19], v[210:213], v[178:181], v[16:19]
	v_mfma_f32_16x16x32_bf16 v[4:7], v[202:205], v[194:197], v[4:7]
	v_mfma_f32_16x16x32_bf16 v[0:3], v[210:213], v[194:197], v[0:3]
	s_setprio 0
	s_add_i32 s63, s63, 2
	s_add_u32 s61, s61, 0x100
	s_addc_u32 s62, s62, 0
	s_cmp_gt_u32 s63, 41
	s_mov_b64 s[26:27], s[28:29]
	s_barrier
	s_cbranch_scc0 .LBB0_968
	v_lshl_or_b32 v166, s60, 8, v188
	v_ashrrev_i32_e32 v167, 31, v166
	v_lshlrev_b64 v[168:169], 1, v[166:167]
	v_lshl_add_u32 v172, s59, 8, v186
	s_cmpk_gt_i32 s59, 0x181
	v_lshl_add_u64 v[170:171], s[8:9], 0, v[168:169]
	s_cbranch_scc1 .LBB0_979
	v_ashrrev_i32_e32 v173, 31, v172
	v_lshlrev_b64 v[204:205], 11, v[172:173]
	v_lshl_add_u64 v[128:129], v[170:171], 0, v[204:205]
	global_load_dwordx4 v[196:199], v[128:129], off
	global_load_dwordx4 v[200:203], v[128:129], off offset:256
	v_or_b32_e32 v182, 16, v172
	v_or_b32_e32 v178, 32, v172
	v_or_b32_e32 v174, 48, v172
	v_ashrrev_i32_e32 v183, 31, v182
	v_ashrrev_i32_e32 v179, 31, v178
	v_ashrrev_i32_e32 v175, 31, v174
	v_lshlrev_b64 v[184:185], 11, v[182:183]
	v_lshlrev_b64 v[180:181], 11, v[178:179]
	v_lshlrev_b64 v[176:177], 11, v[174:175]
	v_lshl_add_u64 v[128:129], v[170:171], 0, v[184:185]
	v_lshl_add_u64 v[130:131], v[170:171], 0, v[180:181]
	v_lshl_add_u64 v[194:195], v[170:171], 0, v[176:177]
	global_load_dwordx4 v[148:151], v[128:129], off
	global_load_dwordx4 v[144:147], v[128:129], off offset:256
	global_load_dwordx4 v[140:143], v[130:131], off
	global_load_dwordx4 v[136:139], v[130:131], off offset:256
	global_load_dwordx4 v[132:135], v[194:195], off
	s_nop 0
	global_load_dwordx4 v[128:131], v[194:195], off offset:256
	v_and_b32_e32 v194, 64, v192
	v_xor_b32_e32 v193, 16, v192
	v_add_u32_e32 v194, 64, v194
	v_xor_b32_e32 v195, 32, v192
	v_cmp_lt_i32_e32 vcc, v193, v194
	s_waitcnt vmcnt(0)
	v_lshlrev_b32_e32 v206, 16, v196
	v_cndmask_b32_e32 v193, v192, v193, vcc
	v_cmp_lt_i32_e32 vcc, v195, v194
	v_and_b32_e32 v207, 0xffff0000, v196
	v_lshlrev_b32_e32 v210, 16, v200
	v_and_b32_e32 v211, 0xffff0000, v200
	v_cndmask_b32_e32 v195, v192, v195, vcc
	v_lshlrev_b32_e32 v208, 16, v198
	v_and_b32_e32 v209, 0xffff0000, v198
	v_lshlrev_b32_e32 v198, 16, v199
	v_and_b32_e32 v199, 0xffff0000, v199
	v_lshlrev_b32_e32 v212, 16, v202
	v_and_b32_e32 v213, 0xffff0000, v202
	v_pk_add_f32 v[124:125], v[124:125], v[206:207]
	v_pk_add_f32 v[116:117], v[116:117], v[210:211]
	v_lshlrev_b32_e32 v194, 2, v193
	v_lshlrev_b32_e32 v193, 2, v195
	v_lshlrev_b32_e32 v196, 16, v197
	v_and_b32_e32 v197, 0xffff0000, v197
	v_lshlrev_b32_e32 v200, 16, v201
	v_and_b32_e32 v201, 0xffff0000, v201
	v_pk_add_f32 v[122:123], v[122:123], v[198:199]
	v_pk_add_f32 v[198:199], v[112:113], v[212:213]
	v_cvt_pk_bf16_f32 v112, v124, v125
	v_mul_f32_e32 v125, v125, v125
	v_mul_f32_e32 v195, v117, v117
	v_pk_add_f32 v[126:127], v[126:127], v[196:197]
	v_pk_add_f32 v[118:119], v[118:119], v[200:201]
	v_fmac_f32_e32 v125, v124, v124
	v_fmac_f32_e32 v195, v116, v116
	v_fmac_f32_e32 v125, v126, v126
	v_fmac_f32_e32 v195, v118, v118
	v_pk_add_f32 v[120:121], v[120:121], v[208:209]
	v_fmac_f32_e32 v125, v127, v127
	v_fmac_f32_e32 v195, v119, v119
	v_lshlrev_b32_e32 v202, 16, v203
	v_and_b32_e32 v203, 0xffff0000, v203
	v_fmac_f32_e32 v125, v120, v120
	v_fmac_f32_e32 v195, v198, v198
	v_pk_add_f32 v[196:197], v[114:115], v[202:203]
	v_fmac_f32_e32 v125, v121, v121
	v_fmac_f32_e32 v195, v199, v199
	v_fmac_f32_e32 v125, v122, v122
	v_fmac_f32_e32 v195, v196, v196
	v_fmac_f32_e32 v125, v123, v123
	v_fmac_f32_e32 v195, v197, v197
	v_cvt_pk_bf16_f32 v115, v122, v123
	v_add_f32_e32 v122, v125, v195
	ds_bpermute_b32 v123, v194, v122
	v_cvt_pk_bf16_f32 v114, v120, v121
	v_lshl_add_u64 v[120:121], s[16:17], 0, v[204:205]
	v_cvt_pk_bf16_f32 v113, v126, v127
	v_lshl_add_u64 v[120:121], v[120:121], 0, v[168:169]
	global_store_dwordx4 v[120:121], v[112:115], off
	s_waitcnt lgkmcnt(0)
	s_nop 0
	v_add_f32_e32 v112, v122, v123
	ds_bpermute_b32 v113, v193, v112
	v_cvt_pk_bf16_f32 v114, v116, v117
	v_cvt_pk_bf16_f32 v115, v118, v119
	v_cvt_pk_bf16_f32 v116, v198, v199
	v_cvt_pk_bf16_f32 v117, v196, v197
	global_store_dwordx4 v[120:121], v[114:117], off offset:256
	s_and_saveexec_b64 s[26:27], s[4:5]
	s_cbranch_execz .LBB0_972
	v_lshl_add_u64 v[114:115], v[172:173], 2, s[18:19]
	s_waitcnt lgkmcnt(0)
	v_add_f32_e32 v112, v112, v113
	global_atomic_add_f32 v[114:115], v112, off

; #define PG8_STAGE(bufoff, gbase, voff) do { _Pragma("unroll") for (int _i = 0; _i < 2; ++_i) \
;     __builtin_amdgcn_global_load_lds((const unsigned*)((const char*)(gbase) + (voff)[_i]), (PG8_LAS unsigned*)(lds + (bufoff) + ldsw + _i * 8192), 16, 0, 0); } while (0)
; #define PG8_LDA(dst, b, h) do { _Pragma("unroll") for (int m = 0; m < 4; ++m) _Pragma("unroll") for (int k = 0; k < 2; ++k) dst[m][k] = *(const PG8_LAS bf16x8*)(lds + PG8_SA(b, h) + aoff + m * 2048 + k * 1024); } while (0)
; #define PG8_LDB(dst, b, h) do { _Pragma("unroll") for (int n = 0; n < 2; ++n) _Pragma("unroll") for (int k = 0; k < 2; ++k) dst[n][k] = *(const PG8_LAS bf16x8*)(lds + PG8_SB(b, h) + boff + n * 2048 + k * 1024); } while (0)
; #define PG8_MMA(ai, bj, At, Bt) do { __builtin_amdgcn_s_setprio(1); _Pragma("unroll") for (int m = 0; m < 4; ++m) _Pragma("unroll") for (int n = 0; n < 2; ++n) _Pragma("unroll") for (int k = 0; k < 2; ++k) \
;     acc[ai][bj][m][n] = __builtin_amdgcn_mfma_f32_16x16x32_bf16(Bt[n][k], At[m][k], acc[ai][bj][m][n], 0, 0, 0); __builtin_amdgcn_s_setprio(0); } while (0)
; #define PG8_WAIT_L(n) asm volatile("s_waitcnt lgkmcnt(" #n ")" ::: "memory")
; #define PG8_BAR __builtin_amdgcn_s_barrier()
; template <class Epi>
; DI void gemm_phase(PG8_LAS unsigned char* lds, const Gemm g, const StaticOrder& S, const Epi& E, const int wv) {
;     ...
;   for (;;) {
;     const bool has_next = S.next(ui + 1, nxt);
;     const char* nA = has_next ? (const char*)g.A + (size_t)nxt.pm * tstep : cA; const char* nB = has_next ? (const char*)g.Bt + (size_t)nxt.pn * tstep : cB;
; #pragma nounroll
;     for (int t = 0; t < nt; t += 2) {
;       const bool last = (t == nt - 2);
;       const char* a1 = cA + (size_t)(t + 1) * kstep;
;       const char* a2 = last ? nA : cA + (size_t)(t + 2) * kstep; const char* b2 = last ? nB : cB + (size_t)(t + 2) * kstep;
;       const char* a3 = a2 + kstep; const char* b3 = b2 + kstep;
;       PG8_LDB(B0, 0, 0); PG8_SCHED; PG8_LDA(At, 0, 0); PG8_STAGE(PG8_SA(1, 1), a1 + hstep, voffA);
;       PG8_WAIT_L(8); PG8_BAR; PG8_WAIT_L(0); PG8_MMA(0, 0, At, B0); PG8_BAR; PG8_SCHED;
;       PG8_LDB(B1, 0, 1); PG8_STAGE(PG8_SB(0, 0), b2, voffB);
;       PG8_BAR; PG8_WAIT_L(0); PG8_MMA(0, 1, At, B1); PG8_BAR;
;       PG8_LDA(At, 0, 1); PG8_STAGE(PG8_SA(0, 0), a2, voffA);
;       PG8_BAR; PG8_WAIT_L(0); PG8_MMA(1, 0, At, B0); PG8_BAR; PG8_SCHED;
.LBB0_1061:
	ds_read_b128 v[146:149], v157
	ds_read_b128 v[150:153], v157 offset:1024
	ds_read_b128 v[162:165], v157 offset:2048
	ds_read_b128 v[166:169], v157 offset:3072
	s_add_u32 s36, s6, 0xfffc0080
	s_addc_u32 s37, s7, -1
	s_cmp_eq_u32 s74, 12
	s_cselect_b32 s39, s5, s37
	s_cselect_b32 s38, s27, s36
	s_cselect_b32 s37, s25, s73
	s_cselect_b32 s36, s71, s72
	v_lshl_add_u64 v[202:203], s[6:7], 0, v[140:141]
	s_add_i32 m0, s35, 0xc000
	ds_read_b128 v[170:173], v158
	ds_read_b128 v[174:177], v158 offset:1024
	ds_read_b128 v[178:181], v158 offset:2048
	ds_read_b128 v[182:185], v158 offset:3072
	ds_read_b128 v[186:189], v158 offset:4096
	ds_read_b128 v[190:193], v158 offset:5120
	ds_read_b128 v[194:197], v158 offset:6144
	ds_read_b128 v[198:201], v158 offset:7168
	global_load_lds_dwordx4 v[202:203], off
	v_lshl_add_u64 v[202:203], s[6:7], 0, v[142:143]
	s_add_i32 m0, s35, 0xe000
	s_nop 0
	global_load_lds_dwordx4 v[202:203], off
	s_waitcnt lgkmcnt(8)
	s_barrier
	s_waitcnt lgkmcnt(0)
	s_setprio 1
	s_waitcnt lgkmcnt(0)
	v_mfma_f32_16x16x32_bf16 v[124:127], v[146:149], v[170:173], v[124:127]
	v_mfma_f32_16x16x32_bf16 v[120:123], v[162:165], v[170:173], v[120:123]
	v_mfma_f32_16x16x32_bf16 v[108:111], v[146:149], v[178:181], v[108:111]
	v_mfma_f32_16x16x32_bf16 v[104:107], v[162:165], v[178:181], v[104:107]
	v_mfma_f32_16x16x32_bf16 v[92:95], v[146:149], v[186:189], v[92:95]
	v_mfma_f32_16x16x32_bf16 v[88:91], v[162:165], v[186:189], v[88:91]
	v_mfma_f32_16x16x32_bf16 v[76:79], v[146:149], v[194:197], v[76:79]
	v_mfma_f32_16x16x32_bf16 v[72:75], v[162:165], v[194:197], v[72:75]
	v_mfma_f32_16x16x32_bf16 v[124:127], v[150:153], v[174:177], v[124:127]
	v_mfma_f32_16x16x32_bf16 v[120:123], v[166:169], v[174:177], v[120:123]
	v_mfma_f32_16x16x32_bf16 v[108:111], v[150:153], v[182:185], v[108:111]
	v_mfma_f32_16x16x32_bf16 v[104:107], v[166:169], v[182:185], v[104:107]
	v_mfma_f32_16x16x32_bf16 v[92:95], v[150:153], v[190:193], v[92:95]
	v_mfma_f32_16x16x32_bf16 v[88:91], v[166:169], v[190:193], v[88:91]
	v_mfma_f32_16x16x32_bf16 v[76:79], v[150:153], v[198:201], v[76:79]
	v_mfma_f32_16x16x32_bf16 v[72:75], v[166:169], v[198:201], v[72:75]
	s_setprio 0
	s_barrier
	s_add_i32 s75, s62, s46
	v_lshl_add_u64 v[220:221], s[36:37], 0, v[130:131]
	s_mov_b32 m0, s75
	ds_read_b128 v[202:205], v159
	ds_read_b128 v[206:209], v159 offset:1024
	ds_read_b128 v[210:213], v159 offset:2048
	ds_read_b128 v[214:217], v159 offset:3072
	global_load_lds_dwordx4 v[220:221], off
	v_lshl_add_u64 v[222:223], s[36:37], 0, v[134:135]
	s_add_i32 m0, s75, 0x2000
	s_nop 0
	global_load_lds_dwordx4 v[222:223], off
	s_barrier
	s_waitcnt lgkmcnt(0)
	s_setprio 1
	v_mfma_f32_16x16x32_bf16 v[116:119], v[202:205], v[170:173], v[116:119]
	v_mfma_f32_16x16x32_bf16 v[112:115], v[210:213], v[170:173], v[112:115]
	v_mfma_f32_16x16x32_bf16 v[100:103], v[202:205], v[178:181], v[100:103]
	v_mfma_f32_16x16x32_bf16 v[96:99], v[210:213], v[178:181], v[96:99]
	v_mfma_f32_16x16x32_bf16 v[84:87], v[202:205], v[186:189], v[84:87]
	v_mfma_f32_16x16x32_bf16 v[80:83], v[210:213], v[186:189], v[80:83]
	v_mfma_f32_16x16x32_bf16 v[68:71], v[202:205], v[194:197], v[68:71]
	v_mfma_f32_16x16x32_bf16 v[64:67], v[210:213], v[194:197], v[64:67]
	v_mfma_f32_16x16x32_bf16 v[116:119], v[206:209], v[174:177], v[116:119]
	v_mfma_f32_16x16x32_bf16 v[112:115], v[214:217], v[174:177], v[112:115]
	v_mfma_f32_16x16x32_bf16 v[100:103], v[206:209], v[182:185], v[100:103]
	v_mfma_f32_16x16x32_bf16 v[96:99], v[214:217], v[182:185], v[96:99]
	v_mfma_f32_16x16x32_bf16 v[84:87], v[206:209], v[190:193], v[84:87]
	v_mfma_f32_16x16x32_bf16 v[80:83], v[214:217], v[190:193], v[80:83]
	v_mfma_f32_16x16x32_bf16 v[68:71], v[206:209], v[198:201], v[68:71]
	v_mfma_f32_16x16x32_bf16 v[64:67], v[214:217], v[198:201], v[64:67]
	s_setprio 0
	s_mov_b32 m0, s35
	v_lshl_add_u64 v[224:225], s[38:39], 0, v[128:129]
	s_barrier
	ds_read_b128 v[170:173], v158 offset:16384
	ds_read_b128 v[174:177], v158 offset:17408
	ds_read_b128 v[178:181], v158 offset:18432
	ds_read_b128 v[182:185], v158 offset:19456
	ds_read_b128 v[186:189], v158 offset:20480
	ds_read_b128 v[190:193], v158 offset:21504
	ds_read_b128 v[194:197], v158 offset:22528
	ds_read_b128 v[198:201], v158 offset:23552
	global_load_lds_dwordx4 v[224:225], off
	v_lshl_add_u64 v[226:227], s[38:39], 0, v[132:133]
	s_mov_b32 m0, s47
	s_nop 0
	global_load_lds_dwordx4 v[226:227], off
	s_barrier
	s_waitcnt lgkmcnt(0)
	s_setprio 1
	v_mfma_f32_16x16x32_bf16 v[60:63], v[146:149], v[170:173], v[60:63]
	v_mfma_f32_16x16x32_bf16 v[56:59], v[162:165], v[170:173], v[56:59]
	v_mfma_f32_16x16x32_bf16 v[44:47], v[146:149], v[178:181], v[44:47]
	v_mfma_f32_16x16x32_bf16 v[40:43], v[162:165], v[178:181], v[40:43]
	v_mfma_f32_16x16x32_bf16 v[28:31], v[146:149], v[186:189], v[28:31]
	v_mfma_f32_16x16x32_bf16 v[24:27], v[162:165], v[186:189], v[24:27]
	v_mfma_f32_16x16x32_bf16 v[12:15], v[146:149], v[194:197], v[12:15]
	v_mfma_f32_16x16x32_bf16 v[8:11], v[162:165], v[194:197], v[8:11]
	v_mfma_f32_16x16x32_bf16 v[60:63], v[150:153], v[174:177], v[60:63]
	v_mfma_f32_16x16x32_bf16 v[56:59], v[166:169], v[174:177], v[56:59]
	v_mfma_f32_16x16x32_bf16 v[44:47], v[150:153], v[182:185], v[44:47]
	v_mfma_f32_16x16x32_bf16 v[40:43], v[166:169], v[182:185], v[40:43]
	v_mfma_f32_16x16x32_bf16 v[28:31], v[150:153], v[190:193], v[28:31]
	v_mfma_f32_16x16x32_bf16 v[24:27], v[166:169], v[190:193], v[24:27]
	v_mfma_f32_16x16x32_bf16 v[12:15], v[150:153], v[198:201], v[12:15]
	v_mfma_f32_16x16x32_bf16 v[8:11], v[166:169], v[198:201], v[8:11]
	s_setprio 0
	s_barrier
; #define PG8_STAGE(bufoff, gbase, voff) do { _Pragma("unroll") for (int _i = 0; _i < 2; ++_i) \
;     __builtin_amdgcn_global_load_lds((const unsigned*)((const char*)(gbase) + (voff)[_i]), (PG8_LAS unsigned*)(lds + (bufoff) + ldsw + _i * 8192), 16, 0, 0); } while (0)
; #define PG8_LDA(dst, b, h) do { _Pragma("unroll") for (int m = 0; m < 4; ++m) _Pragma("unroll") for (int k = 0; k < 2; ++k) dst[m][k] = *(const PG8_LAS bf16x8*)(lds + PG8_SA(b, h) + aoff + m * 2048 + k * 1024); } while (0)
; #define PG8_LDB(dst, b, h) do { _Pragma("unroll") for (int n = 0; n < 2; ++n) _Pragma("unroll") for (int k = 0; k < 2; ++k) dst[n][k] = *(const PG8_LAS bf16x8*)(lds + PG8_SB(b, h) + boff + n * 2048 + k * 1024); } while (0)
; #define PG8_MMA(ai, bj, At, Bt) do { __builtin_amdgcn_s_setprio(1); _Pragma("unroll") for (int m = 0; m < 4; ++m) _Pragma("unroll") for (int n = 0; n < 2; ++n) _Pragma("unroll") for (int k = 0; k < 2; ++k) \
;     acc[ai][bj][m][n] = __builtin_amdgcn_mfma_f32_16x16x32_bf16(Bt[n][k], At[m][k], acc[ai][bj][m][n], 0, 0, 0); __builtin_amdgcn_s_setprio(0); } while (0)
; #define PG8_WAIT_V(n) asm volatile("s_waitcnt vmcnt(" #n ")" ::: "memory")
; #define PG8_WAIT_L(n) asm volatile("s_waitcnt lgkmcnt(" #n ")" ::: "memory")
; #define PG8_BAR __builtin_amdgcn_s_barrier()
; #define PG8_SCHED __builtin_amdgcn_sched_barrier(0)
; template <class Epi>
; DI void gemm_phase(PG8_LAS unsigned char* lds, const Gemm g, const StaticOrder& S, const Epi& E, const int wv) {
;     ...
;       PG8_STAGE(PG8_SB(0, 1), b2 + hstep, voffB);
;       PG8_WAIT_V(6); PG8_BAR; PG8_MMA(1, 1, At, B1); PG8_BAR;
;       PG8_LDB(B0, 1, 0); PG8_SCHED; PG8_LDA(At, 1, 0); PG8_STAGE(PG8_SA(0, 1), a2 + hstep, voffA);
;       PG8_WAIT_L(8); PG8_BAR; PG8_WAIT_L(0); PG8_MMA(0, 0, At, B0); PG8_BAR; PG8_SCHED;
;       PG8_LDB(B1, 1, 1); PG8_STAGE(PG8_SB(1, 0), b3, voffB);
;       PG8_BAR; PG8_WAIT_L(0); PG8_MMA(0, 1, At, B1); PG8_BAR;
;       PG8_LDA(At, 1, 1); PG8_STAGE(PG8_SA(1, 0), a3, voffA);
	s_add_u32 s76, s36, 0x40000
	s_addc_u32 s77, s37, 0
	s_add_i32 s75, s65, s46
	v_lshl_add_u64 v[146:147], s[76:77], 0, v[130:131]
	s_mov_b32 m0, s75
	s_nop 0
	global_load_lds_dwordx4 v[146:147], off
	v_lshl_add_u64 v[146:147], s[76:77], 0, v[134:135]
	s_add_i32 m0, s75, 0x2000
	s_nop 0
	global_load_lds_dwordx4 v[146:147], off
	s_waitcnt vmcnt(6)
	s_barrier
	s_setprio 1
	v_mfma_f32_16x16x32_bf16 v[52:55], v[202:205], v[170:173], v[52:55]
	v_mfma_f32_16x16x32_bf16 v[48:51], v[210:213], v[170:173], v[48:51]
	v_mfma_f32_16x16x32_bf16 v[36:39], v[202:205], v[178:181], v[36:39]
	v_mfma_f32_16x16x32_bf16 v[32:35], v[210:213], v[178:181], v[32:35]
	v_mfma_f32_16x16x32_bf16 v[20:23], v[202:205], v[186:189], v[20:23]
	v_mfma_f32_16x16x32_bf16 v[16:19], v[210:213], v[186:189], v[16:19]
	v_mfma_f32_16x16x32_bf16 v[4:7], v[202:205], v[194:197], v[4:7]
	v_mfma_f32_16x16x32_bf16 v[0:3], v[210:213], v[194:197], v[0:3]
	v_mfma_f32_16x16x32_bf16 v[52:55], v[206:209], v[174:177], v[52:55]
	v_mfma_f32_16x16x32_bf16 v[48:51], v[214:217], v[174:177], v[48:51]
	v_mfma_f32_16x16x32_bf16 v[36:39], v[206:209], v[182:185], v[36:39]
	v_mfma_f32_16x16x32_bf16 v[32:35], v[214:217], v[182:185], v[32:35]
	v_mfma_f32_16x16x32_bf16 v[20:23], v[206:209], v[190:193], v[20:23]
	v_mfma_f32_16x16x32_bf16 v[16:19], v[214:217], v[190:193], v[16:19]
	v_mfma_f32_16x16x32_bf16 v[4:7], v[206:209], v[198:201], v[4:7]
	v_mfma_f32_16x16x32_bf16 v[0:3], v[214:217], v[198:201], v[0:3]
	s_setprio 0
	s_add_i32 s75, 0, 0x18000
	v_add_u32_e32 v136, s75, v155
	s_barrier
	ds_read_b128 v[146:149], v136
	ds_read_b128 v[150:153], v136 offset:1024
	ds_read_b128 v[162:165], v136 offset:2048
	ds_read_b128 v[166:169], v136 offset:3072
	s_add_u32 s38, s38, 0x40000
	s_addc_u32 s39, s39, 0
	s_mov_b32 m0, s48
	v_lshl_add_u64 v[202:203], s[38:39], 0, v[128:129]
	ds_read_b128 v[170:173], v158 offset:32768
	ds_read_b128 v[174:177], v158 offset:33792
	ds_read_b128 v[178:181], v158 offset:34816
	ds_read_b128 v[182:185], v158 offset:35840
	ds_read_b128 v[186:189], v158 offset:36864
	ds_read_b128 v[190:193], v158 offset:37888
	ds_read_b128 v[194:197], v158 offset:38912
	ds_read_b128 v[198:201], v158 offset:39936
	global_load_lds_dwordx4 v[202:203], off
	v_lshl_add_u64 v[202:203], s[38:39], 0, v[132:133]
	s_mov_b32 m0, s49
	s_nop 0
	global_load_lds_dwordx4 v[202:203], off
	s_waitcnt lgkmcnt(8)
	s_barrier
	s_waitcnt lgkmcnt(0)
	s_setprio 1
	s_waitcnt lgkmcnt(0)
	v_mfma_f32_16x16x32_bf16 v[124:127], v[146:149], v[170:173], v[124:127]
	v_mfma_f32_16x16x32_bf16 v[120:123], v[162:165], v[170:173], v[120:123]
	v_mfma_f32_16x16x32_bf16 v[108:111], v[146:149], v[178:181], v[108:111]
	v_mfma_f32_16x16x32_bf16 v[104:107], v[162:165], v[178:181], v[104:107]
	v_mfma_f32_16x16x32_bf16 v[92:95], v[146:149], v[186:189], v[92:95]
	v_mfma_f32_16x16x32_bf16 v[88:91], v[162:165], v[186:189], v[88:91]
	v_mfma_f32_16x16x32_bf16 v[76:79], v[146:149], v[194:197], v[76:79]
	v_mfma_f32_16x16x32_bf16 v[72:75], v[162:165], v[194:197], v[72:75]
	v_mfma_f32_16x16x32_bf16 v[124:127], v[150:153], v[174:177], v[124:127]
	v_mfma_f32_16x16x32_bf16 v[120:123], v[166:169], v[174:177], v[120:123]
	v_mfma_f32_16x16x32_bf16 v[108:111], v[150:153], v[182:185], v[108:111]
	v_mfma_f32_16x16x32_bf16 v[104:107], v[166:169], v[182:185], v[104:107]
	v_mfma_f32_16x16x32_bf16 v[92:95], v[150:153], v[190:193], v[92:95]
	v_mfma_f32_16x16x32_bf16 v[88:91], v[166:169], v[190:193], v[88:91]
	v_mfma_f32_16x16x32_bf16 v[76:79], v[150:153], v[198:201], v[76:79]
	v_mfma_f32_16x16x32_bf16 v[72:75], v[166:169], v[198:201], v[72:75]
	s_setprio 0
	s_barrier
	s_add_i32 s38, 0, 0x1c000
	s_add_i32 s39, s75, s46
	v_add_u32_e32 v136, s38, v155
	v_lshl_add_u64 v[220:221], v[220:221], 0, s[20:21]
	s_mov_b32 m0, s39
	ds_read_b128 v[202:205], v136
	ds_read_b128 v[206:209], v136 offset:1024
	ds_read_b128 v[210:213], v136 offset:2048
	ds_read_b128 v[214:217], v136 offset:3072
	global_load_lds_dwordx4 v[220:221], off
	v_lshl_add_u64 v[220:221], v[222:223], 0, s[20:21]
	s_add_i32 m0, s39, 0x2000
	s_nop 0
	global_load_lds_dwordx4 v[220:221], off
	s_barrier
	s_waitcnt lgkmcnt(0)
	s_setprio 1
	s_waitcnt lgkmcnt(0)
	v_mfma_f32_16x16x32_bf16 v[116:119], v[202:205], v[170:173], v[116:119]
	v_mfma_f32_16x16x32_bf16 v[112:115], v[210:213], v[170:173], v[112:115]
	v_mfma_f32_16x16x32_bf16 v[100:103], v[202:205], v[178:181], v[100:103]
	v_mfma_f32_16x16x32_bf16 v[96:99], v[210:213], v[178:181], v[96:99]
	v_mfma_f32_16x16x32_bf16 v[84:87], v[202:205], v[186:189], v[84:87]
	v_mfma_f32_16x16x32_bf16 v[80:83], v[210:213], v[186:189], v[80:83]
	v_mfma_f32_16x16x32_bf16 v[68:71], v[202:205], v[194:197], v[68:71]
	v_mfma_f32_16x16x32_bf16 v[64:67], v[210:213], v[194:197], v[64:67]
	v_mfma_f32_16x16x32_bf16 v[116:119], v[206:209], v[174:177], v[116:119]
	v_mfma_f32_16x16x32_bf16 v[112:115], v[214:217], v[174:177], v[112:115]
	v_mfma_f32_16x16x32_bf16 v[100:103], v[206:209], v[182:185], v[100:103]
	v_mfma_f32_16x16x32_bf16 v[96:99], v[214:217], v[182:185], v[96:99]
	v_mfma_f32_16x16x32_bf16 v[84:87], v[206:209], v[190:193], v[84:87]
	v_mfma_f32_16x16x32_bf16 v[80:83], v[214:217], v[190:193], v[80:83]
	v_mfma_f32_16x16x32_bf16 v[68:71], v[206:209], v[198:201], v[68:71]
	v_mfma_f32_16x16x32_bf16 v[64:67], v[214:217], v[198:201], v[64:67]
	s_setprio 0
	s_mov_b32 m0, s54
	v_lshl_add_u64 v[220:221], v[224:225], 0, s[20:21]
	s_barrier
	ds_read_b128 v[170:173], v158 offset:49152
	ds_read_b128 v[174:177], v158 offset:50176
	ds_read_b128 v[178:181], v158 offset:51200
	ds_read_b128 v[182:185], v158 offset:52224
	ds_read_b128 v[186:189], v158 offset:53248
	ds_read_b128 v[190:193], v158 offset:54272
	ds_read_b128 v[194:197], v158 offset:55296
	ds_read_b128 v[198:201], v158 offset:56320
	global_load_lds_dwordx4 v[220:221], off
	v_lshl_add_u64 v[220:221], v[226:227], 0, s[20:21]
	s_mov_b32 m0, s55
	s_nop 0
	global_load_lds_dwordx4 v[220:221], off
	s_barrier
; #define PG8_STAGE(bufoff, gbase, voff) do { _Pragma("unroll") for (int _i = 0; _i < 2; ++_i) \
;     __builtin_amdgcn_global_load_lds((const unsigned*)((const char*)(gbase) + (voff)[_i]), (PG8_LAS unsigned*)(lds + (bufoff) + ldsw + _i * 8192), 16, 0, 0); } while (0)
; #define PG8_MMA(ai, bj, At, Bt) do { __builtin_amdgcn_s_setprio(1); _Pragma("unroll") for (int m = 0; m < 4; ++m) _Pragma("unroll") for (int n = 0; n < 2; ++n) _Pragma("unroll") for (int k = 0; k < 2; ++k) \
;     acc[ai][bj][m][n] = __builtin_amdgcn_mfma_f32_16x16x32_bf16(Bt[n][k], At[m][k], acc[ai][bj][m][n], 0, 0, 0); __builtin_amdgcn_s_setprio(0); } while (0)
; #define PG8_WAIT_V(n) asm volatile("s_waitcnt vmcnt(" #n ")" ::: "memory")
; #define PG8_WAIT_L(n) asm volatile("s_waitcnt lgkmcnt(" #n ")" ::: "memory")
; #define PG8_BAR __builtin_amdgcn_s_barrier()
; #define PG8_SCHED __builtin_amdgcn_sched_barrier(0)
; #define EPI_ROWS_BEGIN() \
;   _Pragma("unroll") for (int ai = 0; ai < 2; ++ai) { if (u.pm * 256 + ai * 128 >= T) continue;
; template <class Epi>
; DI void gemm_phase(PG8_LAS unsigned char* lds, const Gemm g, const StaticOrder& S, const Epi& E, const int wv) {
;     ...
;       PG8_BAR; PG8_WAIT_L(0); PG8_MMA(1, 0, At, B0); PG8_BAR; PG8_SCHED;
;       PG8_STAGE(PG8_SB(1, 1), b3 + hstep, voffB);
;       PG8_WAIT_V(6); PG8_BAR; PG8_MMA(1, 1, At, B1); PG8_BAR;
;   DI void operator()(AccRef acc, const pg8::Unit& u, int wr, int wc, int fr, int fq) const {
;     const int row0 = u.pm * 256 + wr * 64 + fr, w0 = wc * 32 + 8 * fq;
;     EPI_ROWS_BEGIN()
;       float rs[4];
; #pragma unroll
;       for (int m = 0; m < 4; ++m) rs[m] = ss[row0 + ai * 128 + m * 16];
; #pragma unroll
;       for (int m = 0; m < 4; ++m) rs[m] = rsqrtf(rs[m] * (1.f / DM) + EPS);
; #pragma unroll
;       for (int m = 0; m < 4; ++m) {
;         const int row = row0 + ai * 128 + m * 16;
;         if (u.pn < 5) {
	s_waitcnt lgkmcnt(0)
	s_setprio 1
	v_mfma_f32_16x16x32_bf16 v[60:63], v[146:149], v[170:173], v[60:63]
	v_mfma_f32_16x16x32_bf16 v[56:59], v[162:165], v[170:173], v[56:59]
	v_mfma_f32_16x16x32_bf16 v[44:47], v[146:149], v[178:181], v[44:47]
	v_mfma_f32_16x16x32_bf16 v[40:43], v[162:165], v[178:181], v[40:43]
	v_mfma_f32_16x16x32_bf16 v[28:31], v[146:149], v[186:189], v[28:31]
	v_mfma_f32_16x16x32_bf16 v[24:27], v[162:165], v[186:189], v[24:27]
	v_mfma_f32_16x16x32_bf16 v[12:15], v[146:149], v[194:197], v[12:15]
	v_mfma_f32_16x16x32_bf16 v[8:11], v[162:165], v[194:197], v[8:11]
	v_mfma_f32_16x16x32_bf16 v[60:63], v[150:153], v[174:177], v[60:63]
	v_mfma_f32_16x16x32_bf16 v[56:59], v[166:169], v[174:177], v[56:59]
	v_mfma_f32_16x16x32_bf16 v[44:47], v[150:153], v[182:185], v[44:47]
	v_mfma_f32_16x16x32_bf16 v[40:43], v[166:169], v[182:185], v[40:43]
	v_mfma_f32_16x16x32_bf16 v[28:31], v[150:153], v[190:193], v[28:31]
	v_mfma_f32_16x16x32_bf16 v[24:27], v[166:169], v[190:193], v[24:27]
	v_mfma_f32_16x16x32_bf16 v[12:15], v[150:153], v[198:201], v[12:15]
	v_mfma_f32_16x16x32_bf16 v[8:11], v[166:169], v[198:201], v[8:11]
	s_setprio 0
	s_barrier
	s_add_u32 s36, s36, 0x40080
	s_addc_u32 s37, s37, 0
	s_add_i32 s38, s38, s46
	v_lshl_add_u64 v[146:147], s[36:37], 0, v[130:131]
	s_mov_b32 m0, s38
	s_nop 0
	global_load_lds_dwordx4 v[146:147], off
	v_lshl_add_u64 v[146:147], s[36:37], 0, v[134:135]
	s_add_i32 m0, s38, 0x2000
	s_nop 0
	global_load_lds_dwordx4 v[146:147], off
	s_waitcnt vmcnt(6)
	s_barrier
	s_setprio 1
	v_mfma_f32_16x16x32_bf16 v[52:55], v[202:205], v[170:173], v[52:55]
	v_mfma_f32_16x16x32_bf16 v[48:51], v[210:213], v[170:173], v[48:51]
	v_mfma_f32_16x16x32_bf16 v[36:39], v[202:205], v[178:181], v[36:39]
	v_mfma_f32_16x16x32_bf16 v[32:35], v[210:213], v[178:181], v[32:35]
	v_mfma_f32_16x16x32_bf16 v[20:23], v[202:205], v[186:189], v[20:23]
	v_mfma_f32_16x16x32_bf16 v[16:19], v[210:213], v[186:189], v[16:19]
	v_mfma_f32_16x16x32_bf16 v[4:7], v[202:205], v[194:197], v[4:7]
	v_mfma_f32_16x16x32_bf16 v[0:3], v[210:213], v[194:197], v[0:3]
	v_mfma_f32_16x16x32_bf16 v[52:55], v[206:209], v[174:177], v[52:55]
	v_mfma_f32_16x16x32_bf16 v[48:51], v[214:217], v[174:177], v[48:51]
	v_mfma_f32_16x16x32_bf16 v[36:39], v[206:209], v[182:185], v[36:39]
	v_mfma_f32_16x16x32_bf16 v[32:35], v[214:217], v[182:185], v[32:35]
	v_mfma_f32_16x16x32_bf16 v[20:23], v[206:209], v[190:193], v[20:23]
	v_mfma_f32_16x16x32_bf16 v[16:19], v[214:217], v[190:193], v[16:19]
	v_mfma_f32_16x16x32_bf16 v[4:7], v[206:209], v[198:201], v[4:7]
	v_mfma_f32_16x16x32_bf16 v[0:3], v[214:217], v[198:201], v[0:3]
	s_setprio 0
	s_add_i32 s74, s74, 2
	s_add_u32 s6, s6, 0x100
	s_addc_u32 s7, s7, 0
	s_add_u32 s72, s72, 0x100
	s_addc_u32 s73, s73, 0
	s_cmp_gt_u32 s74, 13
	s_barrier
	s_cbranch_scc0 .LBB0_1061
	s_cmp_gt_i32 s4, 4
	s_cselect_b64 s[38:39], -1, 0
	s_lshl_b32 s36, s4, 8
	s_ashr_i32 s37, s36, 31
	s_cmpk_gt_i32 s34, 0x181
	v_lshl_add_u32 v146, s34, 8, v139
	s_cbranch_scc1 .LBB0_1079
	v_ashrrev_i32_e32 v147, 31, v146
	v_lshl_add_u64 v[148:149], v[146:147], 2, s[18:19]
	global_load_dword v136, v[148:149], off
	v_or_b32_e32 v152, 16, v146
	v_or_b32_e32 v150, 32, v146
	v_or_b32_e32 v148, 48, v146
	v_ashrrev_i32_e32 v153, 31, v152
	v_ashrrev_i32_e32 v151, 31, v150
	v_ashrrev_i32_e32 v149, 31, v148
	v_lshl_add_u64 v[162:163], v[152:153], 2, s[18:19]
	v_lshl_add_u64 v[164:165], v[150:151], 2, s[18:19]
	v_lshl_add_u64 v[166:167], v[148:149], 2, s[18:19]
	global_load_dword v151, v[162:163], off
	global_load_dword v149, v[164:165], off
	global_load_dword v147, v[166:167], off
	s_and_b64 s[4:5], exec, s[38:39]
	s_mov_b64 s[6:7], -1
	s_waitcnt vmcnt(0)
	v_fmamk_f32 v136, v136, 0x3a800000, v160
	v_mul_f32_e32 v153, 0x4b800000, v136
	v_cmp_gt_f32_e32 vcc, s66, v136
	s_nop 1
	v_cndmask_b32_e32 v136, v136, v153, vcc
	v_rsq_f32_e32 v136, v136
	s_nop 0
	v_mul_f32_e32 v153, 0x45800000, v136
	v_cndmask_b32_e32 v154, v136, v153, vcc
	s_mov_b64 vcc, s[4:5]
	s_cbranch_vccz .LBB0_1065
; DI u16 f2bf(float x) { return (u16)(cvtpk(x, 0.f) & 0xffffu); }
; DI int vt_pos(int p) { return (p & ~12) | ((p & 4) << 1) | ((p & 8) >> 1); }
;   DI void operator()(AccRef acc, const pg8::Unit& u, int wr, int wc, int fr, int fq) const {
;     ...
;           const int s = row / L, p = row - s * L;
; #pragma unroll
;           for (int bj = 0; bj < 2; ++bj) {
;             u16* vp = vt + (size_t)((s * 2 + bj) * 128 + w0) * LP + vt_pos(p);
; #pragma unroll
;             for (int n = 0; n < 2; ++n)
; #pragma unroll
;               for (int e = 0; e < 4; ++e) vp[(size_t)(4 * n + e) * LP] = f2bf(acc[ai][bj][m][n][e] * rs[m]);
;           }
	v_mul_hi_i32 v136, v146, s67
	v_lshrrev_b32_e32 v153, 31, v136
	v_ashrrev_i32_e32 v136, 11, v136
	v_add_u32_e32 v136, v136, v153
	v_mad_i32_i24 v153, v136, s68, v146
	v_and_or_b32 v162, v153, -13, v156
	v_ashrrev_i32_e32 v163, 31, v162
	v_lshl_or_b32 v136, v136, 8, v138
	v_lshl_add_u64 v[162:163], v[162:163], 1, s[16:17]
	v_mul_f32_e32 v153, v124, v154
	v_mad_i64_i32 v[164:165], s[4:5], v136, s69, v[162:163]
	v_cvt_pk_bf16_f32 v153, v153, s0
	global_store_short v[164:165], v153, off
	v_mul_f32_e32 v153, v125, v154
	v_add_co_u32_e32 v166, vcc, s50, v164
	v_cvt_pk_bf16_f32 v153, v153, s0
	s_nop 0
	v_addc_co_u32_e32 v167, vcc, 0, v165, vcc
	global_store_short v[166:167], v153, off offset:128
	v_mul_f32_e32 v153, v126, v154
	v_add_co_u32_e32 v166, vcc, s52, v164
	v_cvt_pk_bf16_f32 v153, v153, s0
	s_nop 0
	v_addc_co_u32_e32 v167, vcc, 0, v165, vcc
	global_store_short v[166:167], v153, off offset:256
	v_mul_f32_e32 v153, v127, v154
	v_add_co_u32_e32 v166, vcc, s53, v164
	v_cvt_pk_bf16_f32 v153, v153, s0
	s_nop 0
	v_addc_co_u32_e32 v167, vcc, 0, v165, vcc
	global_store_short v[166:167], v153, off offset:384
	v_mul_f32_e32 v153, v120, v154
	v_add_co_u32_e32 v166, vcc, s57, v164
	v_cvt_pk_bf16_f32 v153, v153, s0
	s_nop 0
	v_addc_co_u32_e32 v167, vcc, 0, v165, vcc
	global_store_short v[166:167], v153, off offset:512
	v_mul_f32_e32 v153, v121, v154
	v_add_co_u32_e32 v166, vcc, s58, v164
	v_cvt_pk_bf16_f32 v153, v153, s0
	s_nop 0
	v_addc_co_u32_e32 v167, vcc, 0, v165, vcc
	global_store_short v[166:167], v153, off offset:640
	v_mul_f32_e32 v153, v122, v154
	v_add_co_u32_e32 v166, vcc, s63, v164
	v_cvt_pk_bf16_f32 v153, v153, s0
	s_nop 0
	v_addc_co_u32_e32 v167, vcc, 0, v165, vcc
	v_or_b32_e32 v136, 0x80, v136
	global_store_short v[166:167], v153, off offset:768
	v_mul_f32_e32 v153, v123, v154
	v_add_co_u32_e32 v164, vcc, s64, v164
	v_mad_i64_i32 v[162:163], s[4:5], v136, s69, v[162:163]
	v_mul_f32_e32 v136, v116, v154
	v_cvt_pk_bf16_f32 v153, v153, s0
	v_addc_co_u32_e32 v165, vcc, 0, v165, vcc
	v_cvt_pk_bf16_f32 v136, v136, s0
	global_store_short v[164:165], v153, off offset:896
	global_store_short v[162:163], v136, off
	v_mul_f32_e32 v136, v117, v154
	v_add_co_u32_e32 v164, vcc, s50, v162
	v_cvt_pk_bf16_f32 v136, v136, s0
	s_nop 0
	v_addc_co_u32_e32 v165, vcc, 0, v163, vcc
	global_store_short v[164:165], v136, off offset:128
	v_mul_f32_e32 v136, v118, v154
	v_add_co_u32_e32 v164, vcc, s52, v162
	v_cvt_pk_bf16_f32 v136, v136, s0
	s_nop 0
	v_addc_co_u32_e32 v165, vcc, 0, v163, vcc
	global_store_short v[164:165], v136, off offset:256
	v_mul_f32_e32 v136, v119, v154
	v_add_co_u32_e32 v164, vcc, s53, v162
	v_cvt_pk_bf16_f32 v136, v136, s0
	s_nop 0
	v_addc_co_u32_e32 v165, vcc, 0, v163, vcc
	global_store_short v[164:165], v136, off offset:384
	v_mul_f32_e32 v136, v112, v154
	v_add_co_u32_e32 v164, vcc, s57, v162
	v_cvt_pk_bf16_f32 v136, v136, s0
	s_nop 0
	v_addc_co_u32_e32 v165, vcc, 0, v163, vcc
	global_store_short v[164:165], v136, off offset:512
	v_mul_f32_e32 v136, v113, v154
	v_add_co_u32_e32 v164, vcc, s58, v162
	v_cvt_pk_bf16_f32 v136, v136, s0
	s_nop 0
	v_addc_co_u32_e32 v165, vcc, 0, v163, vcc
	global_store_short v[164:165], v136, off offset:640
	v_mul_f32_e32 v136, v114, v154
	v_add_co_u32_e32 v164, vcc, 0xc000, v162
	v_cvt_pk_bf16_f32 v136, v136, s0
	s_nop 0
	v_addc_co_u32_e32 v165, vcc, 0, v163, vcc
	global_store_short v[164:165], v136, off offset:768
	v_mul_f32_e32 v136, v115, v154
	v_add_co_u32_e32 v162, vcc, 0xe000, v162
	v_cvt_pk_bf16_f32 v136, v136, s0
	s_nop 0
	v_addc_co_u32_e32 v163, vcc, 0, v163, vcc
	global_store_short v[162:163], v136, off offset:896
	s_mov_b64 s[6:7], 0

; #define PG8_STAGE(bufoff, gbase, voff) do { _Pragma("unroll") for (int _i = 0; _i < 2; ++_i) \
;     __builtin_amdgcn_global_load_lds((const unsigned*)((const char*)(gbase) + (voff)[_i]), (PG8_LAS unsigned*)(lds + (bufoff) + ldsw + _i * 8192), 16, 0, 0); } while (0)
; #define PG8_LDA(dst, b, h) do { _Pragma("unroll") for (int m = 0; m < 4; ++m) _Pragma("unroll") for (int k = 0; k < 2; ++k) dst[m][k] = *(const PG8_LAS bf16x8*)(lds + PG8_SA(b, h) + aoff + m * 2048 + k * 1024); } while (0)
; #define PG8_LDB(dst, b, h) do { _Pragma("unroll") for (int n = 0; n < 2; ++n) _Pragma("unroll") for (int k = 0; k < 2; ++k) dst[n][k] = *(const PG8_LAS bf16x8*)(lds + PG8_SB(b, h) + boff + n * 2048 + k * 1024); } while (0)
; #define PG8_MMA(ai, bj, At, Bt) do { __builtin_amdgcn_s_setprio(1); _Pragma("unroll") for (int m = 0; m < 4; ++m) _Pragma("unroll") for (int n = 0; n < 2; ++n) _Pragma("unroll") for (int k = 0; k < 2; ++k) \
;     acc[ai][bj][m][n] = __builtin_amdgcn_mfma_f32_16x16x32_bf16(Bt[n][k], At[m][k], acc[ai][bj][m][n], 0, 0, 0); __builtin_amdgcn_s_setprio(0); } while (0)
; #define PG8_WAIT_L(n) asm volatile("s_waitcnt lgkmcnt(" #n ")" ::: "memory")
; #define PG8_BAR __builtin_amdgcn_s_barrier()
; template <class Epi>
; DI void gemm_phase(PG8_LAS unsigned char* lds, const Gemm g, const StaticOrder& S, const Epi& E, const int wv) {
;     ...
;   for (;;) {
;     const bool has_next = S.next(ui + 1, nxt);
;     const char* nA = has_next ? (const char*)g.A + (size_t)nxt.pm * tstep : cA; const char* nB = has_next ? (const char*)g.Bt + (size_t)nxt.pn * tstep : cB;
; #pragma nounroll
;     for (int t = 0; t < nt; t += 2) {
;       const bool last = (t == nt - 2);
;       const char* a1 = cA + (size_t)(t + 1) * kstep;
;       const char* a2 = last ? nA : cA + (size_t)(t + 2) * kstep; const char* b2 = last ? nB : cB + (size_t)(t + 2) * kstep;
;       const char* a3 = a2 + kstep; const char* b3 = b2 + kstep;
;       PG8_LDB(B0, 0, 0); PG8_SCHED; PG8_LDA(At, 0, 0); PG8_STAGE(PG8_SA(1, 1), a1 + hstep, voffA);
;       PG8_WAIT_L(8); PG8_BAR; PG8_WAIT_L(0); PG8_MMA(0, 0, At, B0); PG8_BAR; PG8_SCHED;
;       PG8_LDB(B1, 0, 1); PG8_STAGE(PG8_SB(0, 0), b2, voffB);
;       PG8_BAR; PG8_WAIT_L(0); PG8_MMA(0, 1, At, B1); PG8_BAR;
;       PG8_LDA(At, 0, 1); PG8_STAGE(PG8_SA(0, 0), a2, voffA);
;       PG8_BAR; PG8_WAIT_L(0); PG8_MMA(1, 0, At, B0); PG8_BAR; PG8_SCHED;
.LBB0_1284:
	ds_read_b128 v[128:131], v179
	ds_read_b128 v[132:135], v179 offset:1024
	ds_read_b128 v[136:139], v179 offset:2048
	ds_read_b128 v[140:143], v179 offset:3072
	s_add_u32 s38, s36, 0xfffc0080
	s_addc_u32 s39, s37, -1
	s_cmp_eq_u32 s64, 12
	s_cselect_b32 s41, s25, s39
	s_cselect_b32 s40, s31, s38
	s_cselect_b32 s39, s23, s63
	s_cselect_b32 s38, s35, s62
	v_lshl_add_u64 v[174:175], s[36:37], 0, v[160:161]
	s_add_i32 m0, s47, 0xc000
	ds_read_b128 v[144:147], v180
	ds_read_b128 v[148:151], v180 offset:1024
	ds_read_b128 v[166:169], v180 offset:2048
	ds_read_b128 v[170:173], v180 offset:3072
	ds_read_b128 v[184:187], v180 offset:4096
	ds_read_b128 v[188:191], v180 offset:5120
	ds_read_b128 v[192:195], v180 offset:6144
	ds_read_b128 v[196:199], v180 offset:7168
	global_load_lds_dwordx4 v[174:175], off
	v_lshl_add_u64 v[174:175], s[36:37], 0, v[162:163]
	s_add_i32 m0, s47, 0xe000
	s_nop 0
	global_load_lds_dwordx4 v[174:175], off
	s_waitcnt lgkmcnt(8)
	s_barrier
	s_waitcnt lgkmcnt(0)
	s_setprio 1
	s_waitcnt lgkmcnt(0)
	v_mfma_f32_16x16x32_bf16 v[124:127], v[128:131], v[144:147], v[124:127]
	v_mfma_f32_16x16x32_bf16 v[120:123], v[136:139], v[144:147], v[120:123]
	v_mfma_f32_16x16x32_bf16 v[108:111], v[128:131], v[166:169], v[108:111]
	v_mfma_f32_16x16x32_bf16 v[104:107], v[136:139], v[166:169], v[104:107]
	v_mfma_f32_16x16x32_bf16 v[92:95], v[128:131], v[184:187], v[92:95]
	v_mfma_f32_16x16x32_bf16 v[88:91], v[136:139], v[184:187], v[88:91]
	v_mfma_f32_16x16x32_bf16 v[76:79], v[128:131], v[192:195], v[76:79]
	v_mfma_f32_16x16x32_bf16 v[72:75], v[136:139], v[192:195], v[72:75]
	v_mfma_f32_16x16x32_bf16 v[124:127], v[132:135], v[148:151], v[124:127]
	v_mfma_f32_16x16x32_bf16 v[120:123], v[140:143], v[148:151], v[120:123]
	v_mfma_f32_16x16x32_bf16 v[108:111], v[132:135], v[170:173], v[108:111]
	v_mfma_f32_16x16x32_bf16 v[104:107], v[140:143], v[170:173], v[104:107]
	v_mfma_f32_16x16x32_bf16 v[92:95], v[132:135], v[188:191], v[92:95]
	v_mfma_f32_16x16x32_bf16 v[88:91], v[140:143], v[188:191], v[88:91]
	v_mfma_f32_16x16x32_bf16 v[76:79], v[132:135], v[196:199], v[76:79]
	v_mfma_f32_16x16x32_bf16 v[72:75], v[140:143], v[196:199], v[72:75]
	s_setprio 0
	s_barrier
	s_add_i32 s65, s60, s46
	v_lshl_add_u64 v[174:175], s[38:39], 0, v[154:155]
	s_mov_b32 m0, s65
	ds_read_b128 v[200:203], v181
	ds_read_b128 v[204:207], v181 offset:1024
	ds_read_b128 v[208:211], v181 offset:2048
	ds_read_b128 v[212:215], v181 offset:3072
	global_load_lds_dwordx4 v[174:175], off
	v_lshl_add_u64 v[216:217], s[38:39], 0, v[158:159]
	s_add_i32 m0, s65, 0x2000
	s_nop 0
	global_load_lds_dwordx4 v[216:217], off
	s_barrier
	s_waitcnt lgkmcnt(0)
	s_setprio 1
	v_mfma_f32_16x16x32_bf16 v[116:119], v[200:203], v[144:147], v[116:119]
	v_mfma_f32_16x16x32_bf16 v[112:115], v[208:211], v[144:147], v[112:115]
	v_mfma_f32_16x16x32_bf16 v[100:103], v[200:203], v[166:169], v[100:103]
	v_mfma_f32_16x16x32_bf16 v[96:99], v[208:211], v[166:169], v[96:99]
	v_mfma_f32_16x16x32_bf16 v[84:87], v[200:203], v[184:187], v[84:87]
	v_mfma_f32_16x16x32_bf16 v[80:83], v[208:211], v[184:187], v[80:83]
	v_mfma_f32_16x16x32_bf16 v[68:71], v[200:203], v[192:195], v[68:71]
	v_mfma_f32_16x16x32_bf16 v[64:67], v[208:211], v[192:195], v[64:67]
	v_mfma_f32_16x16x32_bf16 v[116:119], v[204:207], v[148:151], v[116:119]
	v_mfma_f32_16x16x32_bf16 v[112:115], v[212:215], v[148:151], v[112:115]
	v_mfma_f32_16x16x32_bf16 v[100:103], v[204:207], v[170:173], v[100:103]
	v_mfma_f32_16x16x32_bf16 v[96:99], v[212:215], v[170:173], v[96:99]
	v_mfma_f32_16x16x32_bf16 v[84:87], v[204:207], v[188:191], v[84:87]
	v_mfma_f32_16x16x32_bf16 v[80:83], v[212:215], v[188:191], v[80:83]
	v_mfma_f32_16x16x32_bf16 v[68:71], v[204:207], v[196:199], v[68:71]
	v_mfma_f32_16x16x32_bf16 v[64:67], v[212:215], v[196:199], v[64:67]
	s_setprio 0
	s_mov_b32 m0, s47
	v_lshl_add_u64 v[218:219], s[40:41], 0, v[152:153]
	s_barrier
	ds_read_b128 v[144:147], v180 offset:16384
	ds_read_b128 v[148:151], v180 offset:17408
	ds_read_b128 v[166:169], v180 offset:18432
	ds_read_b128 v[170:173], v180 offset:19456
	ds_read_b128 v[184:187], v180 offset:20480
	ds_read_b128 v[188:191], v180 offset:21504
	ds_read_b128 v[192:195], v180 offset:22528
	ds_read_b128 v[196:199], v180 offset:23552
	global_load_lds_dwordx4 v[218:219], off
	v_lshl_add_u64 v[220:221], s[40:41], 0, v[156:157]
	s_mov_b32 m0, s48
	s_nop 0
	global_load_lds_dwordx4 v[220:221], off
	s_barrier
	s_waitcnt lgkmcnt(0)
	s_setprio 1
	v_mfma_f32_16x16x32_bf16 v[60:63], v[128:131], v[144:147], v[60:63]
	v_mfma_f32_16x16x32_bf16 v[56:59], v[136:139], v[144:147], v[56:59]
	v_mfma_f32_16x16x32_bf16 v[44:47], v[128:131], v[166:169], v[44:47]
	v_mfma_f32_16x16x32_bf16 v[40:43], v[136:139], v[166:169], v[40:43]
	v_mfma_f32_16x16x32_bf16 v[28:31], v[128:131], v[184:187], v[28:31]
	v_mfma_f32_16x16x32_bf16 v[24:27], v[136:139], v[184:187], v[24:27]
	v_mfma_f32_16x16x32_bf16 v[12:15], v[128:131], v[192:195], v[12:15]
	v_mfma_f32_16x16x32_bf16 v[8:11], v[136:139], v[192:195], v[8:11]
	v_mfma_f32_16x16x32_bf16 v[60:63], v[132:135], v[148:151], v[60:63]
	v_mfma_f32_16x16x32_bf16 v[56:59], v[140:143], v[148:151], v[56:59]
	v_mfma_f32_16x16x32_bf16 v[44:47], v[132:135], v[170:173], v[44:47]
	v_mfma_f32_16x16x32_bf16 v[40:43], v[140:143], v[170:173], v[40:43]
	v_mfma_f32_16x16x32_bf16 v[28:31], v[132:135], v[188:191], v[28:31]
	v_mfma_f32_16x16x32_bf16 v[24:27], v[140:143], v[188:191], v[24:27]
	v_mfma_f32_16x16x32_bf16 v[12:15], v[132:135], v[196:199], v[12:15]
	v_mfma_f32_16x16x32_bf16 v[8:11], v[140:143], v[196:199], v[8:11]
	s_setprio 0
	s_barrier
; #define PG8_STAGE(bufoff, gbase, voff) do { _Pragma("unroll") for (int _i = 0; _i < 2; ++_i) \
;     __builtin_amdgcn_global_load_lds((const unsigned*)((const char*)(gbase) + (voff)[_i]), (PG8_LAS unsigned*)(lds + (bufoff) + ldsw + _i * 8192), 16, 0, 0); } while (0)
; #define PG8_LDA(dst, b, h) do { _Pragma("unroll") for (int m = 0; m < 4; ++m) _Pragma("unroll") for (int k = 0; k < 2; ++k) dst[m][k] = *(const PG8_LAS bf16x8*)(lds + PG8_SA(b, h) + aoff + m * 2048 + k * 1024); } while (0)
; #define PG8_LDB(dst, b, h) do { _Pragma("unroll") for (int n = 0; n < 2; ++n) _Pragma("unroll") for (int k = 0; k < 2; ++k) dst[n][k] = *(const PG8_LAS bf16x8*)(lds + PG8_SB(b, h) + boff + n * 2048 + k * 1024); } while (0)
; #define PG8_MMA(ai, bj, At, Bt) do { __builtin_amdgcn_s_setprio(1); _Pragma("unroll") for (int m = 0; m < 4; ++m) _Pragma("unroll") for (int n = 0; n < 2; ++n) _Pragma("unroll") for (int k = 0; k < 2; ++k) \
;     acc[ai][bj][m][n] = __builtin_amdgcn_mfma_f32_16x16x32_bf16(Bt[n][k], At[m][k], acc[ai][bj][m][n], 0, 0, 0); __builtin_amdgcn_s_setprio(0); } while (0)
; #define PG8_WAIT_V(n) asm volatile("s_waitcnt vmcnt(" #n ")" ::: "memory")
; #define PG8_WAIT_L(n) asm volatile("s_waitcnt lgkmcnt(" #n ")" ::: "memory")
; #define PG8_BAR __builtin_amdgcn_s_barrier()
; #define PG8_SCHED __builtin_amdgcn_sched_barrier(0)
; template <class Epi>
; DI void gemm_phase(PG8_LAS unsigned char* lds, const Gemm g, const StaticOrder& S, const Epi& E, const int wv) {
;     ...
;       PG8_STAGE(PG8_SB(0, 1), b2 + hstep, voffB);
;       PG8_WAIT_V(6); PG8_BAR; PG8_MMA(1, 1, At, B1); PG8_BAR;
;       PG8_LDB(B0, 1, 0); PG8_SCHED; PG8_LDA(At, 1, 0); PG8_STAGE(PG8_SA(0, 1), a2 + hstep, voffA);
;       PG8_WAIT_L(8); PG8_BAR; PG8_WAIT_L(0); PG8_MMA(0, 0, At, B0); PG8_BAR; PG8_SCHED;
;       PG8_LDB(B1, 1, 1); PG8_STAGE(PG8_SB(1, 0), b3, voffB);
;       PG8_BAR; PG8_WAIT_L(0); PG8_MMA(0, 1, At, B1); PG8_BAR;
;       PG8_LDA(At, 1, 1); PG8_STAGE(PG8_SA(1, 0), a3, voffA);
;       PG8_BAR; PG8_WAIT_L(0); PG8_MMA(1, 0, At, B0); PG8_BAR; PG8_SCHED;
;       PG8_STAGE(PG8_SB(1, 1), b3 + hstep, voffB);
	s_add_u32 s66, s38, 0x40000
	s_addc_u32 s67, s39, 0
	s_add_i32 s65, s61, s46
	v_lshl_add_u64 v[128:129], s[66:67], 0, v[154:155]
	s_mov_b32 m0, s65
	s_nop 0
	global_load_lds_dwordx4 v[128:129], off
	v_lshl_add_u64 v[128:129], s[66:67], 0, v[158:159]
	s_add_i32 m0, s65, 0x2000
	s_nop 0
	global_load_lds_dwordx4 v[128:129], off
	s_waitcnt vmcnt(6)
	s_barrier
	s_setprio 1
	v_mfma_f32_16x16x32_bf16 v[52:55], v[200:203], v[144:147], v[52:55]
	v_mfma_f32_16x16x32_bf16 v[48:51], v[208:211], v[144:147], v[48:51]
	v_mfma_f32_16x16x32_bf16 v[36:39], v[200:203], v[166:169], v[36:39]
	v_mfma_f32_16x16x32_bf16 v[32:35], v[208:211], v[166:169], v[32:35]
	v_mfma_f32_16x16x32_bf16 v[20:23], v[200:203], v[184:187], v[20:23]
	v_mfma_f32_16x16x32_bf16 v[16:19], v[208:211], v[184:187], v[16:19]
	v_mfma_f32_16x16x32_bf16 v[4:7], v[200:203], v[192:195], v[4:7]
	v_mfma_f32_16x16x32_bf16 v[0:3], v[208:211], v[192:195], v[0:3]
	v_mfma_f32_16x16x32_bf16 v[52:55], v[204:207], v[148:151], v[52:55]
	v_mfma_f32_16x16x32_bf16 v[48:51], v[212:215], v[148:151], v[48:51]
	v_mfma_f32_16x16x32_bf16 v[36:39], v[204:207], v[170:173], v[36:39]
	v_mfma_f32_16x16x32_bf16 v[32:35], v[212:215], v[170:173], v[32:35]
	v_mfma_f32_16x16x32_bf16 v[20:23], v[204:207], v[188:191], v[20:23]
	v_mfma_f32_16x16x32_bf16 v[16:19], v[212:215], v[188:191], v[16:19]
	v_mfma_f32_16x16x32_bf16 v[4:7], v[204:207], v[196:199], v[4:7]
	v_mfma_f32_16x16x32_bf16 v[0:3], v[212:215], v[196:199], v[0:3]
	s_setprio 0
	s_add_i32 s65, 0, 0x18000
	v_add_u32_e32 v140, s65, v177
	s_barrier
	ds_read_b128 v[128:131], v140
	ds_read_b128 v[132:135], v140 offset:1024
	ds_read_b128 v[136:139], v140 offset:2048
	ds_read_b128 v[140:143], v140 offset:3072
	s_add_u32 s40, s40, 0x40000
	s_addc_u32 s41, s41, 0
	s_mov_b32 m0, s49
	v_lshl_add_u64 v[200:201], s[40:41], 0, v[152:153]
	ds_read_b128 v[144:147], v180 offset:32768
	ds_read_b128 v[148:151], v180 offset:33792
	ds_read_b128 v[166:169], v180 offset:34816
	ds_read_b128 v[170:173], v180 offset:35840
	ds_read_b128 v[184:187], v180 offset:36864
	ds_read_b128 v[188:191], v180 offset:37888
	ds_read_b128 v[192:195], v180 offset:38912
	ds_read_b128 v[196:199], v180 offset:39936
	global_load_lds_dwordx4 v[200:201], off
	v_lshl_add_u64 v[200:201], s[40:41], 0, v[156:157]
	s_mov_b32 m0, s50
	s_nop 0
	global_load_lds_dwordx4 v[200:201], off
	s_waitcnt lgkmcnt(8)
	s_barrier
	s_waitcnt lgkmcnt(0)
	s_setprio 1
	s_waitcnt lgkmcnt(0)
	v_mfma_f32_16x16x32_bf16 v[124:127], v[128:131], v[144:147], v[124:127]
	v_mfma_f32_16x16x32_bf16 v[120:123], v[136:139], v[144:147], v[120:123]
	v_mfma_f32_16x16x32_bf16 v[108:111], v[128:131], v[166:169], v[108:111]
	v_mfma_f32_16x16x32_bf16 v[104:107], v[136:139], v[166:169], v[104:107]
	v_mfma_f32_16x16x32_bf16 v[92:95], v[128:131], v[184:187], v[92:95]
	v_mfma_f32_16x16x32_bf16 v[88:91], v[136:139], v[184:187], v[88:91]
	v_mfma_f32_16x16x32_bf16 v[76:79], v[128:131], v[192:195], v[76:79]
	v_mfma_f32_16x16x32_bf16 v[72:75], v[136:139], v[192:195], v[72:75]
	v_mfma_f32_16x16x32_bf16 v[124:127], v[132:135], v[148:151], v[124:127]
	v_mfma_f32_16x16x32_bf16 v[120:123], v[140:143], v[148:151], v[120:123]
	v_mfma_f32_16x16x32_bf16 v[108:111], v[132:135], v[170:173], v[108:111]
	v_mfma_f32_16x16x32_bf16 v[104:107], v[140:143], v[170:173], v[104:107]
	v_mfma_f32_16x16x32_bf16 v[92:95], v[132:135], v[188:191], v[92:95]
	v_mfma_f32_16x16x32_bf16 v[88:91], v[140:143], v[188:191], v[88:91]
	v_mfma_f32_16x16x32_bf16 v[76:79], v[132:135], v[196:199], v[76:79]
	v_mfma_f32_16x16x32_bf16 v[72:75], v[140:143], v[196:199], v[72:75]
	s_setprio 0
	s_barrier
	s_add_i32 s40, 0, 0x1c000
	s_add_i32 s41, s65, s46
	v_add_u32_e32 v183, s40, v177
	v_lshl_add_u64 v[174:175], v[174:175], 0, s[18:19]
	s_mov_b32 m0, s41
	ds_read_b128 v[200:203], v183
	ds_read_b128 v[204:207], v183 offset:1024
	ds_read_b128 v[208:211], v183 offset:2048
	ds_read_b128 v[212:215], v183 offset:3072
	global_load_lds_dwordx4 v[174:175], off
	v_lshl_add_u64 v[174:175], v[216:217], 0, s[18:19]
	s_add_i32 m0, s41, 0x2000
	s_nop 0
	global_load_lds_dwordx4 v[174:175], off
	s_barrier
	s_waitcnt lgkmcnt(0)
	s_setprio 1
	s_waitcnt lgkmcnt(0)
	v_mfma_f32_16x16x32_bf16 v[116:119], v[200:203], v[144:147], v[116:119]
	v_mfma_f32_16x16x32_bf16 v[112:115], v[208:211], v[144:147], v[112:115]
	v_mfma_f32_16x16x32_bf16 v[100:103], v[200:203], v[166:169], v[100:103]
	v_mfma_f32_16x16x32_bf16 v[96:99], v[208:211], v[166:169], v[96:99]
	v_mfma_f32_16x16x32_bf16 v[84:87], v[200:203], v[184:187], v[84:87]
	v_mfma_f32_16x16x32_bf16 v[80:83], v[208:211], v[184:187], v[80:83]
	v_mfma_f32_16x16x32_bf16 v[68:71], v[200:203], v[192:195], v[68:71]
	v_mfma_f32_16x16x32_bf16 v[64:67], v[208:211], v[192:195], v[64:67]
	v_mfma_f32_16x16x32_bf16 v[116:119], v[204:207], v[148:151], v[116:119]
	v_mfma_f32_16x16x32_bf16 v[112:115], v[212:215], v[148:151], v[112:115]
	v_mfma_f32_16x16x32_bf16 v[100:103], v[204:207], v[170:173], v[100:103]
	v_mfma_f32_16x16x32_bf16 v[96:99], v[212:215], v[170:173], v[96:99]
	v_mfma_f32_16x16x32_bf16 v[84:87], v[204:207], v[188:191], v[84:87]
	v_mfma_f32_16x16x32_bf16 v[80:83], v[212:215], v[188:191], v[80:83]
	v_mfma_f32_16x16x32_bf16 v[68:71], v[204:207], v[196:199], v[68:71]
	v_mfma_f32_16x16x32_bf16 v[64:67], v[212:215], v[196:199], v[64:67]
	s_setprio 0
	s_mov_b32 m0, s53
	v_lshl_add_u64 v[174:175], v[218:219], 0, s[18:19]
	s_barrier
	ds_read_b128 v[144:147], v180 offset:49152
	ds_read_b128 v[148:151], v180 offset:50176
	ds_read_b128 v[166:169], v180 offset:51200
	ds_read_b128 v[170:173], v180 offset:52224
	ds_read_b128 v[184:187], v180 offset:53248
	ds_read_b128 v[188:191], v180 offset:54272
	ds_read_b128 v[192:195], v180 offset:55296
	ds_read_b128 v[196:199], v180 offset:56320
	global_load_lds_dwordx4 v[174:175], off
	v_lshl_add_u64 v[174:175], v[220:221], 0, s[18:19]
	s_mov_b32 m0, s54
	s_nop 0
	global_load_lds_dwordx4 v[174:175], off
	s_barrier
; #define PG8_STAGE(bufoff, gbase, voff) do { _Pragma("unroll") for (int _i = 0; _i < 2; ++_i) \
;     __builtin_amdgcn_global_load_lds((const unsigned*)((const char*)(gbase) + (voff)[_i]), (PG8_LAS unsigned*)(lds + (bufoff) + ldsw + _i * 8192), 16, 0, 0); } while (0)
; #define PG8_MMA(ai, bj, At, Bt) do { __builtin_amdgcn_s_setprio(1); _Pragma("unroll") for (int m = 0; m < 4; ++m) _Pragma("unroll") for (int n = 0; n < 2; ++n) _Pragma("unroll") for (int k = 0; k < 2; ++k) \
;     acc[ai][bj][m][n] = __builtin_amdgcn_mfma_f32_16x16x32_bf16(Bt[n][k], At[m][k], acc[ai][bj][m][n], 0, 0, 0); __builtin_amdgcn_s_setprio(0); } while (0)
; #define PG8_WAIT_V(n) asm volatile("s_waitcnt vmcnt(" #n ")" ::: "memory")
; #define PG8_WAIT_L(n) asm volatile("s_waitcnt lgkmcnt(" #n ")" ::: "memory")
; #define PG8_BAR __builtin_amdgcn_s_barrier()
; #define PG8_SCHED __builtin_amdgcn_sched_barrier(0)
; #define EPI_ROWS_BEGIN() \
;   _Pragma("unroll") for (int ai = 0; ai < 2; ++ai) { if (u.pm * 256 + ai * 128 >= T) continue;
; template <class Epi>
; DI void gemm_phase(PG8_LAS unsigned char* lds, const Gemm g, const StaticOrder& S, const Epi& E, const int wv) {
;     ...
;       PG8_BAR; PG8_WAIT_L(0); PG8_MMA(1, 0, At, B0); PG8_BAR; PG8_SCHED;
;       PG8_STAGE(PG8_SB(1, 1), b3 + hstep, voffB);
;       PG8_WAIT_V(6); PG8_BAR; PG8_MMA(1, 1, At, B1); PG8_BAR;
;     }
;   DI void operator()(AccRef acc, const pg8::Unit& u, int wr, int wc, int fr, int fq) const {
;     const int row0 = u.pm * 256 + wr * 64 + fr, col0 = u.pn * 256 + wc * 32 + 8 * fq;
;     EPI_ROWS_BEGIN()
;       f32x4 r[4][2][2];
;       if constexpr (MODE == 0) {
; #pragma unroll
;         for (int m = 0; m < 4; ++m) {
;           const float* src = xrow(P, row0 + ai * 128 + m * 16) + col0;
; #pragma unroll
;           for (int bj = 0; bj < 2; ++bj) { r[m][bj][0] = *(const f32x4*)(src + bj * 128); r[m][bj][1] = *(const f32x4*)(src + bj * 128 + 4); }
;         }
;       } else {
;         u32x4 rb[4][2];
; #pragma unroll
;         for (int m = 0; m < 4; ++m)
; #pragma unroll
;           for (int bj = 0; bj < 2; ++bj) {
;             const int rr = row0 + ai * 128 + m * 16;
;             const int sr = (MODE == 3) ? rr + NMETA * ((rr >> 12) + 1) : rr;
;             rb[m][bj] = *(const u32x4*)(hsrc + (size_t)sr * DM + col0 + bj * 128);
	s_waitcnt lgkmcnt(0)
	s_setprio 1
	v_mfma_f32_16x16x32_bf16 v[60:63], v[128:131], v[144:147], v[60:63]
	v_mfma_f32_16x16x32_bf16 v[56:59], v[136:139], v[144:147], v[56:59]
	v_mfma_f32_16x16x32_bf16 v[44:47], v[128:131], v[166:169], v[44:47]
	v_mfma_f32_16x16x32_bf16 v[40:43], v[136:139], v[166:169], v[40:43]
	v_mfma_f32_16x16x32_bf16 v[28:31], v[128:131], v[184:187], v[28:31]
	v_mfma_f32_16x16x32_bf16 v[24:27], v[136:139], v[184:187], v[24:27]
	v_mfma_f32_16x16x32_bf16 v[12:15], v[128:131], v[192:195], v[12:15]
	v_mfma_f32_16x16x32_bf16 v[8:11], v[136:139], v[192:195], v[8:11]
	v_mfma_f32_16x16x32_bf16 v[60:63], v[132:135], v[148:151], v[60:63]
	v_mfma_f32_16x16x32_bf16 v[56:59], v[140:143], v[148:151], v[56:59]
	v_mfma_f32_16x16x32_bf16 v[44:47], v[132:135], v[170:173], v[44:47]
	v_mfma_f32_16x16x32_bf16 v[40:43], v[140:143], v[170:173], v[40:43]
	v_mfma_f32_16x16x32_bf16 v[28:31], v[132:135], v[188:191], v[28:31]
	v_mfma_f32_16x16x32_bf16 v[24:27], v[140:143], v[188:191], v[24:27]
	v_mfma_f32_16x16x32_bf16 v[12:15], v[132:135], v[196:199], v[12:15]
	v_mfma_f32_16x16x32_bf16 v[8:11], v[140:143], v[196:199], v[8:11]
	s_setprio 0
	s_barrier
	s_add_u32 s38, s38, 0x40080
	s_addc_u32 s39, s39, 0
	s_add_i32 s40, s40, s46
	v_lshl_add_u64 v[128:129], s[38:39], 0, v[154:155]
	s_mov_b32 m0, s40
	s_nop 0
	global_load_lds_dwordx4 v[128:129], off
	v_lshl_add_u64 v[128:129], s[38:39], 0, v[158:159]
	s_add_i32 m0, s40, 0x2000
	s_nop 0
	global_load_lds_dwordx4 v[128:129], off
	s_waitcnt vmcnt(6)
	s_barrier
	s_setprio 1
	v_mfma_f32_16x16x32_bf16 v[52:55], v[200:203], v[144:147], v[52:55]
	v_mfma_f32_16x16x32_bf16 v[48:51], v[208:211], v[144:147], v[48:51]
	v_mfma_f32_16x16x32_bf16 v[36:39], v[200:203], v[166:169], v[36:39]
	v_mfma_f32_16x16x32_bf16 v[32:35], v[208:211], v[166:169], v[32:35]
	v_mfma_f32_16x16x32_bf16 v[20:23], v[200:203], v[184:187], v[20:23]
	v_mfma_f32_16x16x32_bf16 v[16:19], v[208:211], v[184:187], v[16:19]
	v_mfma_f32_16x16x32_bf16 v[4:7], v[200:203], v[192:195], v[4:7]
	v_mfma_f32_16x16x32_bf16 v[0:3], v[208:211], v[192:195], v[0:3]
	v_mfma_f32_16x16x32_bf16 v[52:55], v[204:207], v[148:151], v[52:55]
	v_mfma_f32_16x16x32_bf16 v[48:51], v[212:215], v[148:151], v[48:51]
	v_mfma_f32_16x16x32_bf16 v[36:39], v[204:207], v[170:173], v[36:39]
	v_mfma_f32_16x16x32_bf16 v[32:35], v[212:215], v[170:173], v[32:35]
	v_mfma_f32_16x16x32_bf16 v[20:23], v[204:207], v[188:191], v[20:23]
	v_mfma_f32_16x16x32_bf16 v[16:19], v[212:215], v[188:191], v[16:19]
	v_mfma_f32_16x16x32_bf16 v[4:7], v[204:207], v[196:199], v[4:7]
	v_mfma_f32_16x16x32_bf16 v[0:3], v[212:215], v[196:199], v[0:3]
	s_setprio 0
	s_add_i32 s64, s64, 2
	s_add_u32 s36, s36, 0x100
	s_addc_u32 s37, s37, 0
	s_add_u32 s62, s62, 0x100
	s_addc_u32 s63, s63, 0
	s_cmp_gt_u32 s64, 13
	s_barrier
	s_cbranch_scc0 .LBB0_1284
	v_lshl_or_b32 v166, s34, 8, v178
	s_lshl_b32 s23, s30, 8
	v_ashrrev_i32_e32 v167, 31, v166
	s_add_i32 s23, s23, s52
	v_lshlrev_b64 v[170:171], 1, v[166:167]
	v_or_b32_e32 v168, s23, v176
	s_cmpk_gt_i32 s30, 0x181
	v_lshl_add_u64 v[172:173], s[8:9], 0, v[170:171]
	s_cbranch_scc1 .LBB0_1295
; DI float bf_lo(unsigned u) { return __uint_as_float(u << 16); }
;   DI void operator()(AccRef acc, const pg8::Unit& u, int wr, int wc, int fr, int fq) const {
;     ...
;         u32x4 rb[4][2];
; #pragma unroll
;         for (int m = 0; m < 4; ++m)
; #pragma unroll
;           for (int bj = 0; bj < 2; ++bj) {
;             const int rr = row0 + ai * 128 + m * 16;
;             const int sr = (MODE == 3) ? rr + NMETA * ((rr >> 12) + 1) : rr;
;             rb[m][bj] = *(const u32x4*)(hsrc + (size_t)sr * DM + col0 + bj * 128);
;           }
; #pragma unroll
;         for (int m = 0; m < 4; ++m)
; #pragma unroll
;           for (int bj = 0; bj < 2; ++bj) {
;             r[m][bj][0] = f32x4{bf_lo(rb[m][bj][0]), bf_hi(rb[m][bj][0]), bf_lo(rb[m][bj][1]), bf_hi(rb[m][bj][1])};
;             r[m][bj][1] = f32x4{bf_lo(rb[m][bj][2]), bf_hi(rb[m][bj][2]), bf_lo(rb[m][bj][3]), bf_hi(rb[m][bj][3])};
;           }
;       }
; #pragma unroll
;       for (int m = 0; m < 4; ++m) {
;         const int row = row0 + ai * 128 + m * 16;
;         if constexpr (MODE == 4) {
;           float* dst = P.out + (size_t)row * DM + col0;
; #pragma unroll
;           for (int bj = 0; bj < 2; ++bj) {
;             *(f32x4*)(dst + bj * 128) = r[m][bj][0] + acc[ai][bj][m][0];
;             *(f32x4*)(dst + bj * 128 + 4) = r[m][bj][1] + acc[ai][bj][m][1];
;           }
;         } else if constexpr (MODE == 2) {
;           const int s = row / L, p = row - s * L;
;           if (p >= NMETA) {
;             float* dst = P.out + ((size_t)s * SEQ + (p - NMETA)) * DM + col0;
; #pragma unroll
;             for (int bj = 0; bj < 2; ++bj) {
;               *(f32x4*)(dst + bj * 128) = r[m][bj][0] + acc[ai][bj][m][0];
;               *(f32x4*)(dst + bj * 128 + 4) = r[m][bj][1] + acc[ai][bj][m][1];
;             }
;           }
;         } else {
;           float s2 = 0.f;
; #pragma unroll
;           for (int bj = 0; bj < 2; ++bj) {
;             const f32x4 r0 = r[m][bj][0] + acc[ai][bj][m][0], r1 = r[m][bj][1] + acc[ai][bj][m][1];
;             *(u32x4*)(hdst + (size_t)row * DM + col0 + bj * 128) = pack8v(r0, r1);
;             s2 += r0[0] * r0[0] + r0[1] * r0[1] + r0[2] * r0[2] + r0[3] * r0[3] + r1[0] * r1[0] + r1[1] * r1[1] + r1[2] * r1[2] + r1[3] * r1[3];
;           }
;           s2 += __shfl_xor(s2, 16);
;           s2 += __shfl_xor(s2, 32);
;           if (fq == 0) atomicAdd(ss + row, s2);
	s_ashr_i32 s23, s23, 8
	s_and_b32 s23, s23, -16
	v_or_b32_e32 v174, 16, v168
	v_add_u32_e32 v128, s23, v174
	v_ashrrev_i32_e32 v129, 31, v128
	v_lshlrev_b64 v[130:131], 11, v[128:129]
	v_lshl_add_u64 v[130:131], v[172:173], 0, v[130:131]
	global_load_dwordx4 v[186:189], v[130:131], off
	global_load_dwordx4 v[190:193], v[130:131], off offset:256
	v_add_u32_e32 v130, 16, v128
	v_add_u32_e32 v132, 32, v128
	v_add_u32_e32 v128, 48, v128
	v_ashrrev_i32_e32 v131, 31, v130
	v_ashrrev_i32_e32 v133, 31, v132
	v_ashrrev_i32_e32 v129, 31, v128
	v_lshlrev_b64 v[130:131], 11, v[130:131]
	v_lshlrev_b64 v[132:133], 11, v[132:133]
	v_lshlrev_b64 v[128:129], 11, v[128:129]
	v_lshl_add_u64 v[130:131], v[172:173], 0, v[130:131]
	v_lshl_add_u64 v[132:133], v[172:173], 0, v[132:133]
	v_lshl_add_u64 v[128:129], v[172:173], 0, v[128:129]
	global_load_dwordx4 v[148:151], v[130:131], off
	global_load_dwordx4 v[144:147], v[130:131], off offset:256
	global_load_dwordx4 v[140:143], v[132:133], off
	global_load_dwordx4 v[136:139], v[132:133], off offset:256
	s_nop 0
	global_load_dwordx4 v[132:135], v[128:129], off
	s_nop 0
	global_load_dwordx4 v[128:131], v[128:129], off offset:256
	v_and_b32_e32 v183, 64, v182
	v_xor_b32_e32 v175, 16, v182
	v_add_u32_e32 v183, 64, v183
	v_xor_b32_e32 v184, 32, v182
	v_cmp_lt_i32_e32 vcc, v175, v183
	v_ashrrev_i32_e32 v169, 31, v168
	v_lshlrev_b64 v[194:195], 11, v[168:169]
	v_cndmask_b32_e32 v175, v182, v175, vcc
	v_cmp_lt_i32_e32 vcc, v184, v183
	s_waitcnt vmcnt(0)
	v_lshlrev_b32_e32 v196, 16, v186
	v_and_b32_e32 v197, 0xffff0000, v186
	v_lshlrev_b32_e32 v200, 16, v190
	v_and_b32_e32 v201, 0xffff0000, v190
	v_lshlrev_b32_e32 v198, 16, v188
	v_and_b32_e32 v199, 0xffff0000, v188
	v_lshlrev_b32_e32 v188, 16, v189
	v_and_b32_e32 v189, 0xffff0000, v189
	v_lshlrev_b32_e32 v202, 16, v192
	v_and_b32_e32 v203, 0xffff0000, v192
	v_pk_add_f32 v[124:125], v[124:125], v[196:197]
	v_pk_add_f32 v[116:117], v[116:117], v[200:201]
	v_cndmask_b32_e32 v183, v182, v184, vcc
	v_lshlrev_b32_e32 v184, 2, v175
	v_lshlrev_b32_e32 v186, 16, v187
	v_and_b32_e32 v187, 0xffff0000, v187
	v_lshlrev_b32_e32 v190, 16, v191
	v_and_b32_e32 v191, 0xffff0000, v191
	v_pk_add_f32 v[122:123], v[122:123], v[188:189]
	v_pk_add_f32 v[188:189], v[112:113], v[202:203]
	v_cvt_pk_bf16_f32 v112, v124, v125
	v_mul_f32_e32 v125, v125, v125
	v_mul_f32_e32 v175, v117, v117
	v_pk_add_f32 v[126:127], v[126:127], v[186:187]
	v_pk_add_f32 v[118:119], v[118:119], v[190:191]
	v_fmac_f32_e32 v125, v124, v124
	v_fmac_f32_e32 v175, v116, v116
	v_fmac_f32_e32 v125, v126, v126
	v_fmac_f32_e32 v175, v118, v118
	v_pk_add_f32 v[120:121], v[120:121], v[198:199]
	v_fmac_f32_e32 v125, v127, v127
	v_fmac_f32_e32 v175, v119, v119
	v_lshlrev_b32_e32 v192, 16, v193
	v_and_b32_e32 v193, 0xffff0000, v193
	v_fmac_f32_e32 v125, v120, v120
	v_fmac_f32_e32 v175, v188, v188
	v_pk_add_f32 v[186:187], v[114:115], v[192:193]
	v_fmac_f32_e32 v125, v121, v121
	v_fmac_f32_e32 v175, v189, v189
	v_fmac_f32_e32 v125, v122, v122
	v_fmac_f32_e32 v175, v186, v186
	v_fmac_f32_e32 v125, v123, v123
	v_fmac_f32_e32 v175, v187, v187
	v_cvt_pk_bf16_f32 v115, v122, v123
	v_add_f32_e32 v122, v125, v175
	ds_bpermute_b32 v123, v184, v122
	v_cvt_pk_bf16_f32 v114, v120, v121
	v_lshl_add_u64 v[120:121], s[14:15], 0, v[194:195]
	v_cvt_pk_bf16_f32 v113, v126, v127
	v_lshl_add_u64 v[120:121], v[120:121], 0, v[170:171]
	v_lshlrev_b32_e32 v183, 2, v183
	global_store_dwordx4 v[120:121], v[112:115], off
	s_waitcnt lgkmcnt(0)
	s_nop 0
	v_add_f32_e32 v112, v122, v123
	ds_bpermute_b32 v113, v183, v112
	v_cvt_pk_bf16_f32 v114, v116, v117
	v_cvt_pk_bf16_f32 v115, v118, v119
	v_cvt_pk_bf16_f32 v116, v188, v189
	v_cvt_pk_bf16_f32 v117, v186, v187
	global_store_dwordx4 v[120:121], v[114:117], off offset:256
	s_and_saveexec_b64 s[34:35], s[4:5]
	s_cbranch_execz .LBB0_1288
	v_lshl_add_u64 v[114:115], v[168:169], 2, s[16:17]
	s_waitcnt lgkmcnt(0)
	v_add_f32_e32 v112, v112, v113
	global_atomic_add_f32 v[114:115], v112, off

; #define PG8_STAGE(bufoff, gbase, voff) do { _Pragma("unroll") for (int _i = 0; _i < 2; ++_i) \
;     __builtin_amdgcn_global_load_lds((const unsigned*)((const char*)(gbase) + (voff)[_i]), (PG8_LAS unsigned*)(lds + (bufoff) + ldsw + _i * 8192), 16, 0, 0); } while (0)
; #define PG8_LDA(dst, b, h) do { _Pragma("unroll") for (int m = 0; m < 4; ++m) _Pragma("unroll") for (int k = 0; k < 2; ++k) dst[m][k] = *(const PG8_LAS bf16x8*)(lds + PG8_SA(b, h) + aoff + m * 2048 + k * 1024); } while (0)
; #define PG8_LDB(dst, b, h) do { _Pragma("unroll") for (int n = 0; n < 2; ++n) _Pragma("unroll") for (int k = 0; k < 2; ++k) dst[n][k] = *(const PG8_LAS bf16x8*)(lds + PG8_SB(b, h) + boff + n * 2048 + k * 1024); } while (0)
; #define PG8_MMA(ai, bj, At, Bt) do { __builtin_amdgcn_s_setprio(1); _Pragma("unroll") for (int m = 0; m < 4; ++m) _Pragma("unroll") for (int n = 0; n < 2; ++n) _Pragma("unroll") for (int k = 0; k < 2; ++k) \
;     acc[ai][bj][m][n] = __builtin_amdgcn_mfma_f32_16x16x32_bf16(Bt[n][k], At[m][k], acc[ai][bj][m][n], 0, 0, 0); __builtin_amdgcn_s_setprio(0); } while (0)
; #define PG8_WAIT_V(n) asm volatile("s_waitcnt vmcnt(" #n ")" ::: "memory")
; #define PG8_WAIT_L(n) asm volatile("s_waitcnt lgkmcnt(" #n ")" ::: "memory")
; #define PG8_BAR __builtin_amdgcn_s_barrier()
; #define PG8_SCHED __builtin_amdgcn_sched_barrier(0)
; template <class Epi>
; DI void gemm_phase(PG8_LAS unsigned char* lds, const Gemm g, const StaticOrder& S, const Epi& E, const int wv) {
;     ...
;     for (int t = 0; t < nt; t += 2) {
;       const bool last = (t == nt - 2);
;       const char* a1 = cA + (size_t)(t + 1) * kstep;
;       const char* a2 = last ? nA : cA + (size_t)(t + 2) * kstep; const char* b2 = last ? nB : cB + (size_t)(t + 2) * kstep;
;       const char* a3 = a2 + kstep; const char* b3 = b2 + kstep;
;       PG8_LDB(B0, 0, 0); PG8_SCHED; PG8_LDA(At, 0, 0); PG8_STAGE(PG8_SA(1, 1), a1 + hstep, voffA);
;       PG8_WAIT_L(8); PG8_BAR; PG8_WAIT_L(0); PG8_MMA(0, 0, At, B0); PG8_BAR; PG8_SCHED;
;       PG8_LDB(B1, 0, 1); PG8_STAGE(PG8_SB(0, 0), b2, voffB);
;       PG8_BAR; PG8_WAIT_L(0); PG8_MMA(0, 1, At, B1); PG8_BAR;
;       PG8_LDA(At, 0, 1); PG8_STAGE(PG8_SA(0, 0), a2, voffA);
;       PG8_BAR; PG8_WAIT_L(0); PG8_MMA(1, 0, At, B0); PG8_BAR; PG8_SCHED;
;       PG8_STAGE(PG8_SB(0, 1), b2 + hstep, voffB);
;       PG8_WAIT_V(6); PG8_BAR; PG8_MMA(1, 1, At, B1); PG8_BAR;
.LBB0_1367:
	ds_read_b128 v[142:145], v155
	ds_read_b128 v[146:149], v155 offset:1024
	ds_read_b128 v[160:163], v155 offset:2048
	ds_read_b128 v[164:167], v155 offset:3072
	s_add_u32 s8, s6, 0xfffc0080
	s_addc_u32 s9, s7, -1
	s_cmp_eq_u32 s61, 12
	s_cselect_b32 s35, s5, s9
	s_cselect_b32 s34, s25, s8
	s_cselect_b32 s9, s23, s60
	s_cselect_b32 s8, s58, s59
	v_lshl_add_u64 v[150:151], s[6:7], 0, v[136:137]
	s_add_i32 m0, s31, 0xc000
	ds_read_b128 v[168:171], v156
	ds_read_b128 v[172:175], v156 offset:1024
	ds_read_b128 v[176:179], v156 offset:2048
	ds_read_b128 v[180:183], v156 offset:3072
	ds_read_b128 v[184:187], v156 offset:4096
	ds_read_b128 v[188:191], v156 offset:5120
	ds_read_b128 v[192:195], v156 offset:6144
	ds_read_b128 v[196:199], v156 offset:7168
	global_load_lds_dwordx4 v[150:151], off
	v_lshl_add_u64 v[150:151], s[6:7], 0, v[138:139]
	s_add_i32 m0, s31, 0xe000
	s_nop 0
	global_load_lds_dwordx4 v[150:151], off
	s_waitcnt lgkmcnt(8)
	s_barrier
	s_waitcnt lgkmcnt(0)
	s_setprio 1
	s_waitcnt lgkmcnt(0)
	v_mfma_f32_16x16x32_bf16 v[116:119], v[142:145], v[168:171], v[116:119]
	v_mfma_f32_16x16x32_bf16 v[112:115], v[160:163], v[168:171], v[112:115]
	v_mfma_f32_16x16x32_bf16 v[108:111], v[142:145], v[176:179], v[108:111]
	v_mfma_f32_16x16x32_bf16 v[100:103], v[160:163], v[176:179], v[100:103]
	v_mfma_f32_16x16x32_bf16 v[92:95], v[142:145], v[184:187], v[92:95]
	v_mfma_f32_16x16x32_bf16 v[84:87], v[160:163], v[184:187], v[84:87]
	v_mfma_f32_16x16x32_bf16 v[76:79], v[142:145], v[192:195], v[76:79]
	v_mfma_f32_16x16x32_bf16 v[68:71], v[160:163], v[192:195], v[68:71]
	v_mfma_f32_16x16x32_bf16 v[116:119], v[146:149], v[172:175], v[116:119]
	v_mfma_f32_16x16x32_bf16 v[112:115], v[164:167], v[172:175], v[112:115]
	v_mfma_f32_16x16x32_bf16 v[108:111], v[146:149], v[180:183], v[108:111]
	v_mfma_f32_16x16x32_bf16 v[100:103], v[164:167], v[180:183], v[100:103]
	v_mfma_f32_16x16x32_bf16 v[92:95], v[146:149], v[188:191], v[92:95]
	v_mfma_f32_16x16x32_bf16 v[84:87], v[164:167], v[188:191], v[84:87]
	v_mfma_f32_16x16x32_bf16 v[76:79], v[146:149], v[196:199], v[76:79]
	v_mfma_f32_16x16x32_bf16 v[68:71], v[164:167], v[196:199], v[68:71]
	s_setprio 0
	s_barrier
	s_add_i32 s62, s53, s42
	v_lshl_add_u64 v[150:151], s[8:9], 0, v[132:133]
	s_mov_b32 m0, s62
	ds_read_b128 v[200:203], v157
	ds_read_b128 v[204:207], v157 offset:1024
	ds_read_b128 v[208:211], v157 offset:2048
	ds_read_b128 v[212:215], v157 offset:3072
	global_load_lds_dwordx4 v[150:151], off
	v_lshl_add_u64 v[216:217], s[8:9], 0, v[128:129]
	s_add_i32 m0, s62, 0x2000
	s_nop 0
	global_load_lds_dwordx4 v[216:217], off
	s_barrier
	s_waitcnt lgkmcnt(0)
	s_setprio 1
	v_mfma_f32_16x16x32_bf16 v[124:127], v[200:203], v[168:171], v[124:127]
	v_mfma_f32_16x16x32_bf16 v[120:123], v[208:211], v[168:171], v[120:123]
	v_mfma_f32_16x16x32_bf16 v[104:107], v[200:203], v[176:179], v[104:107]
	v_mfma_f32_16x16x32_bf16 v[96:99], v[208:211], v[176:179], v[96:99]
	v_mfma_f32_16x16x32_bf16 v[88:91], v[200:203], v[184:187], v[88:91]
	v_mfma_f32_16x16x32_bf16 v[80:83], v[208:211], v[184:187], v[80:83]
	v_mfma_f32_16x16x32_bf16 v[72:75], v[200:203], v[192:195], v[72:75]
	v_mfma_f32_16x16x32_bf16 v[64:67], v[208:211], v[192:195], v[64:67]
	v_mfma_f32_16x16x32_bf16 v[124:127], v[204:207], v[172:175], v[124:127]
	v_mfma_f32_16x16x32_bf16 v[120:123], v[212:215], v[172:175], v[120:123]
	v_mfma_f32_16x16x32_bf16 v[104:107], v[204:207], v[180:183], v[104:107]
	v_mfma_f32_16x16x32_bf16 v[96:99], v[212:215], v[180:183], v[96:99]
	v_mfma_f32_16x16x32_bf16 v[88:91], v[204:207], v[188:191], v[88:91]
	v_mfma_f32_16x16x32_bf16 v[80:83], v[212:215], v[188:191], v[80:83]
	v_mfma_f32_16x16x32_bf16 v[72:75], v[204:207], v[196:199], v[72:75]
	v_mfma_f32_16x16x32_bf16 v[64:67], v[212:215], v[196:199], v[64:67]
	s_setprio 0
	s_mov_b32 m0, s31
	v_lshl_add_u64 v[218:219], s[34:35], 0, v[134:135]
	s_barrier
	ds_read_b128 v[168:171], v156 offset:16384
	ds_read_b128 v[172:175], v156 offset:17408
	ds_read_b128 v[176:179], v156 offset:18432
	ds_read_b128 v[180:183], v156 offset:19456
	ds_read_b128 v[184:187], v156 offset:20480
	ds_read_b128 v[188:191], v156 offset:21504
	ds_read_b128 v[192:195], v156 offset:22528
	ds_read_b128 v[196:199], v156 offset:23552
	global_load_lds_dwordx4 v[218:219], off
	v_lshl_add_u64 v[220:221], s[34:35], 0, v[130:131]
	s_mov_b32 m0, s45
	s_nop 0
	global_load_lds_dwordx4 v[220:221], off
	s_barrier
	s_waitcnt lgkmcnt(0)
	s_setprio 1
	v_mfma_f32_16x16x32_bf16 v[52:55], v[142:145], v[168:171], v[52:55]
	v_mfma_f32_16x16x32_bf16 v[48:51], v[160:163], v[168:171], v[48:51]
	v_mfma_f32_16x16x32_bf16 v[44:47], v[142:145], v[176:179], v[44:47]
	v_mfma_f32_16x16x32_bf16 v[36:39], v[160:163], v[176:179], v[36:39]
	v_mfma_f32_16x16x32_bf16 v[28:31], v[142:145], v[184:187], v[28:31]
	v_mfma_f32_16x16x32_bf16 v[20:23], v[160:163], v[184:187], v[20:23]
	v_mfma_f32_16x16x32_bf16 v[12:15], v[142:145], v[192:195], v[12:15]
	v_mfma_f32_16x16x32_bf16 v[4:7], v[160:163], v[192:195], v[4:7]
	v_mfma_f32_16x16x32_bf16 v[52:55], v[146:149], v[172:175], v[52:55]
	v_mfma_f32_16x16x32_bf16 v[48:51], v[164:167], v[172:175], v[48:51]
	v_mfma_f32_16x16x32_bf16 v[44:47], v[146:149], v[180:183], v[44:47]
	v_mfma_f32_16x16x32_bf16 v[36:39], v[164:167], v[180:183], v[36:39]
	v_mfma_f32_16x16x32_bf16 v[28:31], v[146:149], v[188:191], v[28:31]
	v_mfma_f32_16x16x32_bf16 v[20:23], v[164:167], v[188:191], v[20:23]
	v_mfma_f32_16x16x32_bf16 v[12:15], v[146:149], v[196:199], v[12:15]
	v_mfma_f32_16x16x32_bf16 v[4:7], v[164:167], v[196:199], v[4:7]
	s_setprio 0
	s_barrier
; #define PG8_STAGE(bufoff, gbase, voff) do { _Pragma("unroll") for (int _i = 0; _i < 2; ++_i) \
;     __builtin_amdgcn_global_load_lds((const unsigned*)((const char*)(gbase) + (voff)[_i]), (PG8_LAS unsigned*)(lds + (bufoff) + ldsw + _i * 8192), 16, 0, 0); } while (0)
; #define PG8_LDA(dst, b, h) do { _Pragma("unroll") for (int m = 0; m < 4; ++m) _Pragma("unroll") for (int k = 0; k < 2; ++k) dst[m][k] = *(const PG8_LAS bf16x8*)(lds + PG8_SA(b, h) + aoff + m * 2048 + k * 1024); } while (0)
; #define PG8_LDB(dst, b, h) do { _Pragma("unroll") for (int n = 0; n < 2; ++n) _Pragma("unroll") for (int k = 0; k < 2; ++k) dst[n][k] = *(const PG8_LAS bf16x8*)(lds + PG8_SB(b, h) + boff + n * 2048 + k * 1024); } while (0)
; #define PG8_MMA(ai, bj, At, Bt) do { __builtin_amdgcn_s_setprio(1); _Pragma("unroll") for (int m = 0; m < 4; ++m) _Pragma("unroll") for (int n = 0; n < 2; ++n) _Pragma("unroll") for (int k = 0; k < 2; ++k) \
;     acc[ai][bj][m][n] = __builtin_amdgcn_mfma_f32_16x16x32_bf16(Bt[n][k], At[m][k], acc[ai][bj][m][n], 0, 0, 0); __builtin_amdgcn_s_setprio(0); } while (0)
; #define PG8_WAIT_V(n) asm volatile("s_waitcnt vmcnt(" #n ")" ::: "memory")
; #define PG8_WAIT_L(n) asm volatile("s_waitcnt lgkmcnt(" #n ")" ::: "memory")
; #define PG8_BAR __builtin_amdgcn_s_barrier()
; #define PG8_SCHED __builtin_amdgcn_sched_barrier(0)
; template <class Epi>
; DI void gemm_phase(PG8_LAS unsigned char* lds, const Gemm g, const StaticOrder& S, const Epi& E, const int wv) {
;     ...
;       PG8_WAIT_V(6); PG8_BAR; PG8_MMA(1, 1, At, B1); PG8_BAR;
;       PG8_LDB(B0, 1, 0); PG8_SCHED; PG8_LDA(At, 1, 0); PG8_STAGE(PG8_SA(0, 1), a2 + hstep, voffA);
;       PG8_WAIT_L(8); PG8_BAR; PG8_WAIT_L(0); PG8_MMA(0, 0, At, B0); PG8_BAR; PG8_SCHED;
;       PG8_LDB(B1, 1, 1); PG8_STAGE(PG8_SB(1, 0), b3, voffB);
;       PG8_BAR; PG8_WAIT_L(0); PG8_MMA(0, 1, At, B1); PG8_BAR;
;       PG8_LDA(At, 1, 1); PG8_STAGE(PG8_SA(1, 0), a3, voffA);
	s_add_u32 s62, s8, 0x40000
	s_addc_u32 s63, s9, 0
	s_add_i32 s64, s54, s42
	v_lshl_add_u64 v[142:143], s[62:63], 0, v[132:133]
	s_mov_b32 m0, s64
	s_nop 0
	global_load_lds_dwordx4 v[142:143], off
	v_lshl_add_u64 v[142:143], s[62:63], 0, v[128:129]
	s_add_i32 m0, s64, 0x2000
	s_nop 0
	global_load_lds_dwordx4 v[142:143], off
	s_waitcnt vmcnt(6)
	s_barrier
	s_setprio 1
	v_mfma_f32_16x16x32_bf16 v[60:63], v[200:203], v[168:171], v[60:63]
	v_mfma_f32_16x16x32_bf16 v[56:59], v[208:211], v[168:171], v[56:59]
	v_mfma_f32_16x16x32_bf16 v[40:43], v[200:203], v[176:179], v[40:43]
	v_mfma_f32_16x16x32_bf16 v[32:35], v[208:211], v[176:179], v[32:35]
	v_mfma_f32_16x16x32_bf16 v[24:27], v[200:203], v[184:187], v[24:27]
	v_mfma_f32_16x16x32_bf16 v[16:19], v[208:211], v[184:187], v[16:19]
	v_mfma_f32_16x16x32_bf16 v[8:11], v[200:203], v[192:195], v[8:11]
	v_mfma_f32_16x16x32_bf16 v[0:3], v[208:211], v[192:195], v[0:3]
	v_mfma_f32_16x16x32_bf16 v[60:63], v[204:207], v[172:175], v[60:63]
	v_mfma_f32_16x16x32_bf16 v[56:59], v[212:215], v[172:175], v[56:59]
	v_mfma_f32_16x16x32_bf16 v[40:43], v[204:207], v[180:183], v[40:43]
	v_mfma_f32_16x16x32_bf16 v[32:35], v[212:215], v[180:183], v[32:35]
	v_mfma_f32_16x16x32_bf16 v[24:27], v[204:207], v[188:191], v[24:27]
	v_mfma_f32_16x16x32_bf16 v[16:19], v[212:215], v[188:191], v[16:19]
	v_mfma_f32_16x16x32_bf16 v[8:11], v[204:207], v[196:199], v[8:11]
	v_mfma_f32_16x16x32_bf16 v[0:3], v[212:215], v[196:199], v[0:3]
	s_setprio 0
	s_add_i32 s62, 0, 0x18000
	v_add_u32_e32 v159, s62, v153
	s_barrier
	ds_read_b128 v[142:145], v159
	ds_read_b128 v[146:149], v159 offset:1024
	ds_read_b128 v[160:163], v159 offset:2048
	ds_read_b128 v[164:167], v159 offset:3072
	s_add_u32 s34, s34, 0x40000
	s_addc_u32 s35, s35, 0
	s_mov_b32 m0, s46
	v_lshl_add_u64 v[200:201], s[34:35], 0, v[134:135]
	ds_read_b128 v[168:171], v156 offset:32768
	ds_read_b128 v[172:175], v156 offset:33792
	ds_read_b128 v[176:179], v156 offset:34816
	ds_read_b128 v[180:183], v156 offset:35840
	ds_read_b128 v[184:187], v156 offset:36864
	ds_read_b128 v[188:191], v156 offset:37888
	ds_read_b128 v[192:195], v156 offset:38912
	ds_read_b128 v[196:199], v156 offset:39936
	global_load_lds_dwordx4 v[200:201], off
	v_lshl_add_u64 v[200:201], s[34:35], 0, v[130:131]
	s_mov_b32 m0, s47
	s_nop 0
	global_load_lds_dwordx4 v[200:201], off
	s_waitcnt lgkmcnt(8)
	s_barrier
	s_waitcnt lgkmcnt(0)
	s_setprio 1
	s_waitcnt lgkmcnt(0)
	v_mfma_f32_16x16x32_bf16 v[116:119], v[142:145], v[168:171], v[116:119]
	v_mfma_f32_16x16x32_bf16 v[112:115], v[160:163], v[168:171], v[112:115]
	v_mfma_f32_16x16x32_bf16 v[108:111], v[142:145], v[176:179], v[108:111]
	v_mfma_f32_16x16x32_bf16 v[100:103], v[160:163], v[176:179], v[100:103]
	v_mfma_f32_16x16x32_bf16 v[92:95], v[142:145], v[184:187], v[92:95]
	v_mfma_f32_16x16x32_bf16 v[84:87], v[160:163], v[184:187], v[84:87]
	v_mfma_f32_16x16x32_bf16 v[76:79], v[142:145], v[192:195], v[76:79]
	v_mfma_f32_16x16x32_bf16 v[68:71], v[160:163], v[192:195], v[68:71]
	v_mfma_f32_16x16x32_bf16 v[116:119], v[146:149], v[172:175], v[116:119]
	v_mfma_f32_16x16x32_bf16 v[112:115], v[164:167], v[172:175], v[112:115]
	v_mfma_f32_16x16x32_bf16 v[108:111], v[146:149], v[180:183], v[108:111]
	v_mfma_f32_16x16x32_bf16 v[100:103], v[164:167], v[180:183], v[100:103]
	v_mfma_f32_16x16x32_bf16 v[92:95], v[146:149], v[188:191], v[92:95]
	v_mfma_f32_16x16x32_bf16 v[84:87], v[164:167], v[188:191], v[84:87]
	v_mfma_f32_16x16x32_bf16 v[76:79], v[146:149], v[196:199], v[76:79]
	v_mfma_f32_16x16x32_bf16 v[68:71], v[164:167], v[196:199], v[68:71]
	s_setprio 0
	s_barrier
	s_add_i32 s34, 0, 0x1c000
	s_add_i32 s35, s62, s42
	v_add_u32_e32 v159, s34, v153
	v_lshl_add_u64 v[150:151], v[150:151], 0, s[18:19]
	s_mov_b32 m0, s35
	ds_read_b128 v[200:203], v159
	ds_read_b128 v[204:207], v159 offset:1024
	ds_read_b128 v[208:211], v159 offset:2048
	ds_read_b128 v[212:215], v159 offset:3072
	global_load_lds_dwordx4 v[150:151], off
	v_lshl_add_u64 v[150:151], v[216:217], 0, s[18:19]
	s_add_i32 m0, s35, 0x2000
	s_nop 0
	global_load_lds_dwordx4 v[150:151], off
	s_barrier
	s_waitcnt lgkmcnt(0)
	s_setprio 1
	s_waitcnt lgkmcnt(0)
	v_mfma_f32_16x16x32_bf16 v[124:127], v[200:203], v[168:171], v[124:127]
	v_mfma_f32_16x16x32_bf16 v[120:123], v[208:211], v[168:171], v[120:123]
	v_mfma_f32_16x16x32_bf16 v[104:107], v[200:203], v[176:179], v[104:107]
	v_mfma_f32_16x16x32_bf16 v[96:99], v[208:211], v[176:179], v[96:99]
	v_mfma_f32_16x16x32_bf16 v[88:91], v[200:203], v[184:187], v[88:91]
	v_mfma_f32_16x16x32_bf16 v[80:83], v[208:211], v[184:187], v[80:83]
	v_mfma_f32_16x16x32_bf16 v[72:75], v[200:203], v[192:195], v[72:75]
	v_mfma_f32_16x16x32_bf16 v[64:67], v[208:211], v[192:195], v[64:67]
	v_mfma_f32_16x16x32_bf16 v[124:127], v[204:207], v[172:175], v[124:127]
	v_mfma_f32_16x16x32_bf16 v[120:123], v[212:215], v[172:175], v[120:123]
	v_mfma_f32_16x16x32_bf16 v[104:107], v[204:207], v[180:183], v[104:107]
	v_mfma_f32_16x16x32_bf16 v[96:99], v[212:215], v[180:183], v[96:99]
	v_mfma_f32_16x16x32_bf16 v[88:91], v[204:207], v[188:191], v[88:91]
	v_mfma_f32_16x16x32_bf16 v[80:83], v[212:215], v[188:191], v[80:83]
	v_mfma_f32_16x16x32_bf16 v[72:75], v[204:207], v[196:199], v[72:75]
	v_mfma_f32_16x16x32_bf16 v[64:67], v[212:215], v[196:199], v[64:67]
	s_setprio 0
	s_mov_b32 m0, s49
	v_lshl_add_u64 v[150:151], v[218:219], 0, s[18:19]
	s_barrier
	ds_read_b128 v[168:171], v156 offset:49152
	ds_read_b128 v[172:175], v156 offset:50176
	ds_read_b128 v[176:179], v156 offset:51200
	ds_read_b128 v[180:183], v156 offset:52224
	ds_read_b128 v[184:187], v156 offset:53248
	ds_read_b128 v[188:191], v156 offset:54272
	ds_read_b128 v[192:195], v156 offset:55296
	ds_read_b128 v[196:199], v156 offset:56320
	global_load_lds_dwordx4 v[150:151], off
	v_lshl_add_u64 v[150:151], v[220:221], 0, s[18:19]
	s_mov_b32 m0, s50
	s_nop 0
	global_load_lds_dwordx4 v[150:151], off
	s_barrier
; #define PG8_STAGE(bufoff, gbase, voff) do { _Pragma("unroll") for (int _i = 0; _i < 2; ++_i) \
;     __builtin_amdgcn_global_load_lds((const unsigned*)((const char*)(gbase) + (voff)[_i]), (PG8_LAS unsigned*)(lds + (bufoff) + ldsw + _i * 8192), 16, 0, 0); } while (0)
; #define PG8_MMA(ai, bj, At, Bt) do { __builtin_amdgcn_s_setprio(1); _Pragma("unroll") for (int m = 0; m < 4; ++m) _Pragma("unroll") for (int n = 0; n < 2; ++n) _Pragma("unroll") for (int k = 0; k < 2; ++k) \
;     acc[ai][bj][m][n] = __builtin_amdgcn_mfma_f32_16x16x32_bf16(Bt[n][k], At[m][k], acc[ai][bj][m][n], 0, 0, 0); __builtin_amdgcn_s_setprio(0); } while (0)
; #define PG8_WAIT_V(n) asm volatile("s_waitcnt vmcnt(" #n ")" ::: "memory")
; #define PG8_WAIT_L(n) asm volatile("s_waitcnt lgkmcnt(" #n ")" ::: "memory")
; #define PG8_BAR __builtin_amdgcn_s_barrier()
; #define PG8_SCHED __builtin_amdgcn_sched_barrier(0)
; #define EPI_ROWS_BEGIN() \
;   _Pragma("unroll") for (int ai = 0; ai < 2; ++ai) { if (u.pm * 256 + ai * 128 >= T) continue;
; template <class Epi>
; DI void gemm_phase(PG8_LAS unsigned char* lds, const Gemm g, const StaticOrder& S, const Epi& E, const int wv) {
;     ...
;       PG8_BAR; PG8_WAIT_L(0); PG8_MMA(1, 0, At, B0); PG8_BAR; PG8_SCHED;
;       PG8_STAGE(PG8_SB(1, 1), b3 + hstep, voffB);
;       PG8_WAIT_V(6); PG8_BAR; PG8_MMA(1, 1, At, B1); PG8_BAR;
;     }
;   DI void operator()(AccRef acc, const pg8::Unit& u, int wr, int wc, int fr, int fq) const {
;     const int row0 = u.pm * 256 + wr * 64 + fr, col0 = u.pn * 128 + wc * 32 + 8 * fq;
;     EPI_ROWS_BEGIN()
;       float rs[4];
; #pragma unroll
;       for (int m = 0; m < 4; ++m) rs[m] = ss[row0 + ai * 128 + m * 16];
; #pragma unroll
;       for (int m = 0; m < 4; ++m) rs[m] = rsqrtf(rs[m] * (1.f / DM) + EPS);
; #pragma unroll
;       for (int m = 0; m < 4; ++m) {
;         const int row = row0 + ai * 128 + m * 16;
;         const float ne = rs[m] * -1.4426950408889634f, r2 = rs[m] * rs[m];
	s_waitcnt lgkmcnt(0)
	s_setprio 1
	v_mfma_f32_16x16x32_bf16 v[52:55], v[142:145], v[168:171], v[52:55]
	v_mfma_f32_16x16x32_bf16 v[48:51], v[160:163], v[168:171], v[48:51]
	v_mfma_f32_16x16x32_bf16 v[44:47], v[142:145], v[176:179], v[44:47]
	v_mfma_f32_16x16x32_bf16 v[36:39], v[160:163], v[176:179], v[36:39]
	v_mfma_f32_16x16x32_bf16 v[28:31], v[142:145], v[184:187], v[28:31]
	v_mfma_f32_16x16x32_bf16 v[20:23], v[160:163], v[184:187], v[20:23]
	v_mfma_f32_16x16x32_bf16 v[12:15], v[142:145], v[192:195], v[12:15]
	v_mfma_f32_16x16x32_bf16 v[4:7], v[160:163], v[192:195], v[4:7]
	v_mfma_f32_16x16x32_bf16 v[52:55], v[146:149], v[172:175], v[52:55]
	v_mfma_f32_16x16x32_bf16 v[48:51], v[164:167], v[172:175], v[48:51]
	v_mfma_f32_16x16x32_bf16 v[44:47], v[146:149], v[180:183], v[44:47]
	v_mfma_f32_16x16x32_bf16 v[36:39], v[164:167], v[180:183], v[36:39]
	v_mfma_f32_16x16x32_bf16 v[28:31], v[146:149], v[188:191], v[28:31]
	v_mfma_f32_16x16x32_bf16 v[20:23], v[164:167], v[188:191], v[20:23]
	v_mfma_f32_16x16x32_bf16 v[12:15], v[146:149], v[196:199], v[12:15]
	v_mfma_f32_16x16x32_bf16 v[4:7], v[164:167], v[196:199], v[4:7]
	s_setprio 0
	s_barrier
	s_add_u32 s8, s8, 0x40080
	s_addc_u32 s9, s9, 0
	s_add_i32 s34, s34, s42
	v_lshl_add_u64 v[142:143], s[8:9], 0, v[132:133]
	s_mov_b32 m0, s34
	s_nop 0
	global_load_lds_dwordx4 v[142:143], off
	v_lshl_add_u64 v[142:143], s[8:9], 0, v[128:129]
	s_add_i32 m0, s34, 0x2000
	s_nop 0
	global_load_lds_dwordx4 v[142:143], off
	s_waitcnt vmcnt(6)
	s_barrier
	s_setprio 1
	v_mfma_f32_16x16x32_bf16 v[60:63], v[200:203], v[168:171], v[60:63]
	v_mfma_f32_16x16x32_bf16 v[56:59], v[208:211], v[168:171], v[56:59]
	v_mfma_f32_16x16x32_bf16 v[40:43], v[200:203], v[176:179], v[40:43]
	v_mfma_f32_16x16x32_bf16 v[32:35], v[208:211], v[176:179], v[32:35]
	v_mfma_f32_16x16x32_bf16 v[24:27], v[200:203], v[184:187], v[24:27]
	v_mfma_f32_16x16x32_bf16 v[16:19], v[208:211], v[184:187], v[16:19]
	v_mfma_f32_16x16x32_bf16 v[8:11], v[200:203], v[192:195], v[8:11]
	v_mfma_f32_16x16x32_bf16 v[0:3], v[208:211], v[192:195], v[0:3]
	v_mfma_f32_16x16x32_bf16 v[60:63], v[204:207], v[172:175], v[60:63]
	v_mfma_f32_16x16x32_bf16 v[56:59], v[212:215], v[172:175], v[56:59]
	v_mfma_f32_16x16x32_bf16 v[40:43], v[204:207], v[180:183], v[40:43]
	v_mfma_f32_16x16x32_bf16 v[32:35], v[212:215], v[180:183], v[32:35]
	v_mfma_f32_16x16x32_bf16 v[24:27], v[204:207], v[188:191], v[24:27]
	v_mfma_f32_16x16x32_bf16 v[16:19], v[212:215], v[188:191], v[16:19]
	v_mfma_f32_16x16x32_bf16 v[8:11], v[204:207], v[196:199], v[8:11]
	v_mfma_f32_16x16x32_bf16 v[0:3], v[212:215], v[196:199], v[0:3]
	s_setprio 0
	s_add_i32 s61, s61, 2
	s_add_u32 s6, s6, 0x100
	s_addc_u32 s7, s7, 0
	s_add_u32 s59, s59, 0x100
	s_addc_u32 s60, s60, 0
	s_cmp_gt_u32 s61, 13
	s_barrier
	s_cbranch_scc0 .LBB0_1367
	v_lshl_or_b32 v142, s4, 7, v154
	v_ashrrev_i32_e32 v143, 31, v142
	v_lshl_add_u32 v144, s30, 8, v152
	s_cmpk_gt_i32 s30, 0x181
	v_lshlrev_b64 v[142:143], 1, v[142:143]
	s_cbranch_scc1 .LBB0_1370
	v_ashrrev_i32_e32 v145, 31, v144
	v_lshl_add_u64 v[146:147], v[144:145], 2, s[16:17]
	v_or_b32_e32 v150, 16, v144
	global_load_dword v145, v[146:147], off
	v_ashrrev_i32_e32 v151, 31, v150
	v_or_b32_e32 v148, 32, v144
	v_or_b32_e32 v146, 48, v144
	v_lshl_add_u64 v[160:161], v[150:151], 2, s[16:17]
	v_ashrrev_i32_e32 v149, 31, v148
	v_ashrrev_i32_e32 v147, 31, v146
	v_lshl_add_u64 v[162:163], v[148:149], 2, s[16:17]
	v_lshl_add_u64 v[164:165], v[146:147], 2, s[16:17]
	global_load_dword v147, v[160:161], off
	global_load_dword v149, v[162:163], off
	global_load_dword v151, v[164:165], off
	v_add_u32_e32 v224, 0x80, v144
	v_ashrrev_i32_e32 v225, 31, v224
	v_lshl_add_u64 v[226:227], v[224:225], 2, s[16:17]
	global_load_dword v250, v[226:227], off
	global_load_dword v251, v[226:227], off offset:64
	global_load_dword v252, v[226:227], off offset:128
	global_load_dword v253, v[226:227], off offset:192
	v_pk_mul_f32 v[160:161], v[112:113], v[120:121]
	v_mov_b64_e32 v[120:121], s[14:15]
	v_mad_i64_i32 v[162:163], s[4:5], v144, s57, v[120:121]
	v_pk_mul_f32 v[126:127], v[118:119], v[126:127]
	v_pk_mul_f32 v[124:125], v[116:117], v[124:125]
	v_pk_mul_f32 v[122:123], v[114:115], v[122:123]
	v_pk_mul_f32 v[104:105], v[108:109], v[104:105]
	v_pk_mul_f32 v[106:107], v[110:111], v[106:107]
	v_pk_mul_f32 v[98:99], v[102:103], v[98:99]
	v_lshl_add_u64 v[162:163], v[162:163], 0, v[142:143]
	v_pk_mul_f32 v[96:97], v[100:101], v[96:97]
	v_pk_mul_f32 v[88:89], v[92:93], v[88:89]
	v_pk_mul_f32 v[90:91], v[94:95], v[90:91]
	v_pk_mul_f32 v[82:83], v[86:87], v[82:83]
	v_pk_mul_f32 v[80:81], v[84:85], v[80:81]
	v_pk_mul_f32 v[72:73], v[76:77], v[72:73]
	v_pk_mul_f32 v[74:75], v[78:79], v[74:75]
	v_pk_mul_f32 v[66:67], v[70:71], v[66:67]
	v_pk_mul_f32 v[64:65], v[68:69], v[64:65]
	s_waitcnt vmcnt(4)
; DI u32x4 pack8v(f32x4 a, f32x4 b) { return u32x4{cvtpk(a[0], a[1]), cvtpk(a[2], a[3]), cvtpk(b[0], b[1]), cvtpk(b[2], b[3])}; }
;   DI void operator()(AccRef acc, const pg8::Unit& u, int wr, int wc, int fr, int fq) const {
;     ...
;       for (int m = 0; m < 4; ++m) rs[m] = ss[row0 + ai * 128 + m * 16];
; #pragma unroll
;       for (int m = 0; m < 4; ++m) rs[m] = rsqrtf(rs[m] * (1.f / DM) + EPS);
; #pragma unroll
;       for (int m = 0; m < 4; ++m) {
;         const int row = row0 + ai * 128 + m * 16;
;         const float ne = rs[m] * -1.4426950408889634f, r2 = rs[m] * rs[m];
;         f32x4 y[2];
; #pragma unroll
;         for (int n = 0; n < 2; ++n)
; #pragma unroll
;           for (int e = 0; e < 4; ++e) {
;             const float a = acc[ai][0][m][n][e], b = acc[ai][1][m][n][e];
;             y[n][e] = a * b * r2 * __builtin_amdgcn_rcpf(1.f + __builtin_amdgcn_exp2f(a * ne));
;           }
;         *(u32x4*)(act + (size_t)row * FFN + col0) = pack8v(y[0], y[1]);
	v_fmamk_f32 v145, v145, 0x3a800000, v158
	v_mul_f32_e32 v159, 0x4b800000, v145
	v_cmp_gt_f32_e32 vcc, s55, v145
	v_fmamk_f32 v147, v147, 0x3a800000, v158
	v_fmamk_f32 v149, v149, 0x3a800000, v158
	v_fmamk_f32 v151, v151, 0x3a800000, v158
	v_cndmask_b32_e32 v145, v145, v159, vcc
	v_mul_f32_e32 v159, 0x4b800000, v147
	v_cmp_gt_f32_e64 s[4:5], s55, v147
	v_mul_f32_e32 v164, 0x4b800000, v149
	v_mul_f32_e32 v165, 0x4b800000, v151
	v_rsq_f32_e32 v145, v145
	v_cndmask_b32_e64 v147, v147, v159, s[4:5]
	v_cmp_gt_f32_e64 s[6:7], s55, v149
	v_cmp_gt_f32_e64 s[8:9], s55, v151
	v_rsq_f32_e32 v147, v147
	v_cndmask_b32_e64 v149, v149, v164, s[6:7]
	v_cndmask_b32_e64 v151, v151, v165, s[8:9]
	v_rsq_f32_e32 v149, v149
	v_rsq_f32_e32 v151, v151
	v_mul_f32_e32 v159, 0x45800000, v145
	v_cndmask_b32_e32 v145, v145, v159, vcc
	v_mul_f32_e32 v159, 0x45800000, v147
	v_mul_f32_e32 v164, 0x45800000, v149
	v_mul_f32_e32 v165, 0x45800000, v151
	v_cndmask_b32_e64 v147, v147, v159, s[4:5]
	v_mul_f32_e32 v159, 0xbfb8aa3b, v145
	v_cndmask_b32_e64 v149, v149, v164, s[6:7]
	v_cndmask_b32_e64 v151, v151, v165, s[8:9]
	v_mul_f32_e32 v164, v145, v145
	v_mul_f32_e32 v165, v117, v159
	v_mul_f32_e32 v145, v116, v159
	v_pk_mul_f32 v[116:117], v[124:125], v[164:165] op_sel_hi:[1,0]
	v_mul_f32_e32 v124, v118, v159
	v_mul_f32_e32 v125, v119, v159
	v_pk_mul_f32 v[118:119], v[126:127], v[164:165] op_sel_hi:[1,0]
	v_mul_f32_e32 v126, v112, v159
	v_mul_f32_e32 v127, v113, v159
	v_pk_mul_f32 v[112:113], v[160:161], v[164:165] op_sel_hi:[1,0]
	v_mul_f32_e32 v160, v114, v159
	v_mul_f32_e32 v159, v115, v159
	v_pk_mul_f32 v[114:115], v[122:123], v[164:165] op_sel_hi:[1,0]
	v_mul_f32_e32 v123, 0xbfb8aa3b, v147
	v_mul_f32_e32 v161, v108, v123
	v_mul_f32_e32 v164, v109, v123
	v_mul_f32_e32 v108, v110, v123
	v_mul_f32_e32 v109, v111, v123
	v_mul_f32_e32 v122, v147, v147
	v_exp_f32_e32 v145, v145
	v_exp_f32_e32 v147, v165
	v_exp_f32_e32 v124, v124
	v_exp_f32_e32 v125, v125
	v_exp_f32_e32 v126, v126
	v_exp_f32_e32 v127, v127
	v_exp_f32_e32 v160, v160
	v_exp_f32_e32 v159, v159
	v_exp_f32_e32 v108, v108
	v_exp_f32_e32 v109, v109
	v_exp_f32_e32 v166, v161
	v_exp_f32_e32 v167, v164
	v_add_f32_e32 v145, 1.0, v145
	v_add_f32_e32 v147, 1.0, v147
	v_add_f32_e32 v161, 1.0, v124
	v_add_f32_e32 v164, 1.0, v125
	v_add_f32_e32 v165, 1.0, v126
	v_add_f32_e32 v168, 1.0, v127
	v_add_f32_e32 v169, 1.0, v160
	v_add_f32_e32 v159, 1.0, v159
	v_add_f32_e32 v108, 1.0, v108
	v_add_f32_e32 v109, 1.0, v109
	v_mul_f32_e32 v110, v100, v123
	v_mul_f32_e32 v111, v101, v123
	v_rcp_f32_e32 v124, v145
	v_rcp_f32_e32 v125, v147
	v_rcp_f32_e32 v126, v161
	v_rcp_f32_e32 v127, v164
	v_rcp_f32_e32 v160, v165
	v_rcp_f32_e32 v161, v168
	v_rcp_f32_e32 v164, v169
	v_rcp_f32_e32 v165, v159
	v_rcp_f32_e32 v108, v108
	v_rcp_f32_e32 v109, v109
	v_exp_f32_e32 v110, v110
	v_exp_f32_e32 v111, v111
	v_mul_f32_e32 v102, v102, v123
	v_mul_f32_e32 v103, v103, v123
	v_exp_f32_e32 v102, v102
	v_exp_f32_e32 v103, v103
	v_pk_mul_f32 v[106:107], v[106:107], v[122:123] op_sel_hi:[1,0]
	v_pk_mul_f32 v[116:117], v[116:117], v[124:125]
	v_pk_mul_f32 v[118:119], v[118:119], v[126:127]
	v_pk_mul_f32 v[124:125], v[112:113], v[160:161]
	v_pk_mul_f32 v[126:127], v[114:115], v[164:165]
	v_pk_mul_f32 v[106:107], v[106:107], v[108:109]
	v_add_f32_e32 v108, 1.0, v110
	v_add_f32_e32 v109, 1.0, v111
	v_cvt_pk_bf16_f32 v112, v116, v117
	v_cvt_pk_bf16_f32 v113, v118, v119
	v_cvt_pk_bf16_f32 v114, v124, v125
	v_cvt_pk_bf16_f32 v115, v126, v127
	v_rcp_f32_e32 v108, v108
	v_rcp_f32_e32 v109, v109
	v_add_f32_e32 v100, 1.0, v102
	v_add_f32_e32 v101, 1.0, v103
	v_add_f32_e32 v145, 1.0, v166
	global_store_dwordx4 v[162:163], v[112:115], off
	v_rcp_f32_e32 v100, v100
	v_rcp_f32_e32 v101, v101
	v_add_f32_e32 v113, 1.0, v167
	v_rcp_f32_e32 v112, v145
	v_rcp_f32_e32 v113, v113
; DI u32x4 pack8v(f32x4 a, f32x4 b) { return u32x4{cvtpk(a[0], a[1]), cvtpk(a[2], a[3]), cvtpk(b[0], b[1]), cvtpk(b[2], b[3])}; }
;   DI void operator()(AccRef acc, const pg8::Unit& u, int wr, int wc, int fr, int fq) const {
;     ...
;       for (int m = 0; m < 4; ++m) {
;         const int row = row0 + ai * 128 + m * 16;
;         const float ne = rs[m] * -1.4426950408889634f, r2 = rs[m] * rs[m];
;         f32x4 y[2];
; #pragma unroll
;         for (int n = 0; n < 2; ++n)
; #pragma unroll
;           for (int e = 0; e < 4; ++e) {
;             const float a = acc[ai][0][m][n][e], b = acc[ai][1][m][n][e];
;             y[n][e] = a * b * r2 * __builtin_amdgcn_rcpf(1.f + __builtin_amdgcn_exp2f(a * ne));
;           }
;         *(u32x4*)(act + (size_t)row * FFN + col0) = pack8v(y[0], y[1]);
;       }
	v_pk_mul_f32 v[96:97], v[96:97], v[122:123] op_sel_hi:[1,0]
	v_pk_mul_f32 v[104:105], v[104:105], v[122:123] op_sel_hi:[1,0]
	v_pk_mul_f32 v[102:103], v[96:97], v[108:109]
	v_pk_mul_f32 v[96:97], v[98:99], v[122:123] op_sel_hi:[1,0]
	v_pk_mul_f32 v[104:105], v[104:105], v[112:113]
	v_pk_mul_f32 v[100:101], v[96:97], v[100:101]
	v_cvt_pk_bf16_f32 v96, v104, v105
	v_cvt_pk_bf16_f32 v99, v100, v101
	v_mad_i64_i32 v[100:101], s[4:5], v150, s57, v[120:121]
	v_cvt_pk_bf16_f32 v97, v106, v107
	v_cvt_pk_bf16_f32 v98, v102, v103
	v_lshl_add_u64 v[100:101], v[100:101], 0, v[142:143]
	global_store_dwordx4 v[100:101], v[96:99], off
	s_nop 1
	v_mul_f32_e32 v97, 0xbfb8aa3b, v149
	v_mul_f32_e32 v96, v92, v97
	v_exp_f32_e32 v98, v96
	v_mul_f32_e32 v96, v93, v97
	v_mul_f32_e32 v92, v94, v97
	v_mul_f32_e32 v93, v95, v97
	v_exp_f32_e32 v92, v92
	v_exp_f32_e32 v93, v93
	v_mul_f32_e32 v94, v84, v97
	v_mul_f32_e32 v95, v85, v97
	v_add_f32_e32 v92, 1.0, v92
	v_add_f32_e32 v93, 1.0, v93
	v_rcp_f32_e32 v92, v92
	v_rcp_f32_e32 v93, v93
	v_exp_f32_e32 v94, v94
	v_exp_f32_e32 v95, v95
	v_mul_f32_e32 v86, v86, v97
	v_mul_f32_e32 v87, v87, v97
	v_exp_f32_e32 v86, v86
	v_exp_f32_e32 v87, v87
	v_exp_f32_e32 v99, v96
	v_mul_f32_e32 v96, v149, v149
	v_pk_mul_f32 v[90:91], v[90:91], v[96:97] op_sel_hi:[1,0]
	v_add_f32_e32 v84, 1.0, v86
	v_pk_mul_f32 v[90:91], v[90:91], v[92:93]
	v_add_f32_e32 v92, 1.0, v94
	v_add_f32_e32 v93, 1.0, v95
	v_rcp_f32_e32 v92, v92
	v_rcp_f32_e32 v93, v93
	v_add_f32_e32 v85, 1.0, v87
	v_add_f32_e32 v98, 1.0, v98
	v_add_f32_e32 v99, 1.0, v99
	v_rcp_f32_e32 v84, v84
	v_rcp_f32_e32 v85, v85
	v_rcp_f32_e32 v98, v98
	v_rcp_f32_e32 v99, v99
	v_pk_mul_f32 v[80:81], v[80:81], v[96:97] op_sel_hi:[1,0]
	v_pk_mul_f32 v[88:89], v[88:89], v[96:97] op_sel_hi:[1,0]
	v_pk_mul_f32 v[86:87], v[80:81], v[92:93]
	v_pk_mul_f32 v[80:81], v[82:83], v[96:97] op_sel_hi:[1,0]
	v_pk_mul_f32 v[88:89], v[88:89], v[98:99]
	v_pk_mul_f32 v[84:85], v[80:81], v[84:85]
	v_cvt_pk_bf16_f32 v80, v88, v89
	v_cvt_pk_bf16_f32 v83, v84, v85
	v_mad_i64_i32 v[84:85], s[4:5], v148, s57, v[120:121]
	v_cvt_pk_bf16_f32 v81, v90, v91
	v_cvt_pk_bf16_f32 v82, v86, v87
	v_lshl_add_u64 v[84:85], v[84:85], 0, v[142:143]
	global_store_dwordx4 v[84:85], v[80:83], off
	s_nop 1
	v_mul_f32_e32 v81, 0xbfb8aa3b, v151
	v_mul_f32_e32 v80, v76, v81
	v_exp_f32_e32 v82, v80
	v_mul_f32_e32 v80, v77, v81
	v_mul_f32_e32 v76, v78, v81
	v_mul_f32_e32 v77, v79, v81
	v_exp_f32_e32 v76, v76
	v_exp_f32_e32 v77, v77
	v_mul_f32_e32 v78, v68, v81
	v_mul_f32_e32 v79, v69, v81
	v_add_f32_e32 v76, 1.0, v76
	v_add_f32_e32 v77, 1.0, v77
	v_rcp_f32_e32 v76, v76
	v_rcp_f32_e32 v77, v77
	v_exp_f32_e32 v78, v78
	v_exp_f32_e32 v79, v79
	v_mul_f32_e32 v70, v70, v81
	v_mul_f32_e32 v71, v71, v81
	v_exp_f32_e32 v70, v70
	v_exp_f32_e32 v71, v71
	v_exp_f32_e32 v83, v80
	v_mul_f32_e32 v80, v151, v151
	v_pk_mul_f32 v[74:75], v[74:75], v[80:81] op_sel_hi:[1,0]
	v_add_f32_e32 v68, 1.0, v70
	v_pk_mul_f32 v[74:75], v[74:75], v[76:77]
	v_add_f32_e32 v76, 1.0, v78
	v_add_f32_e32 v77, 1.0, v79
	v_rcp_f32_e32 v76, v76
	v_rcp_f32_e32 v77, v77
	v_add_f32_e32 v69, 1.0, v71
	v_add_f32_e32 v82, 1.0, v82
	v_add_f32_e32 v83, 1.0, v83
	v_rcp_f32_e32 v68, v68
	v_rcp_f32_e32 v69, v69
	v_rcp_f32_e32 v82, v82
	v_rcp_f32_e32 v83, v83
	v_pk_mul_f32 v[64:65], v[64:65], v[80:81] op_sel_hi:[1,0]
	v_pk_mul_f32 v[72:73], v[72:73], v[80:81] op_sel_hi:[1,0]
	v_pk_mul_f32 v[70:71], v[64:65], v[76:77]
	v_pk_mul_f32 v[64:65], v[66:67], v[80:81] op_sel_hi:[1,0]
	v_pk_mul_f32 v[72:73], v[72:73], v[82:83]
	v_pk_mul_f32 v[68:69], v[64:65], v[68:69]
	v_cvt_pk_bf16_f32 v64, v72, v73
	v_cvt_pk_bf16_f32 v67, v68, v69
	v_mad_i64_i32 v[68:69], s[4:5], v146, s57, v[120:121]
	v_cvt_pk_bf16_f32 v65, v74, v75
	v_cvt_pk_bf16_f32 v66, v70, v71
	v_lshl_add_u64 v[68:69], v[68:69], 0, v[142:143]
	global_store_dwordx4 v[68:69], v[64:67], off

; #define PG8_STAGE(bufoff, gbase, voff) do { _Pragma("unroll") for (int _i = 0; _i < 2; ++_i) \
;     __builtin_amdgcn_global_load_lds((const unsigned*)((const char*)(gbase) + (voff)[_i]), (PG8_LAS unsigned*)(lds + (bufoff) + ldsw + _i * 8192), 16, 0, 0); } while (0)
; #define PG8_LDA(dst, b, h) do { _Pragma("unroll") for (int m = 0; m < 4; ++m) _Pragma("unroll") for (int k = 0; k < 2; ++k) dst[m][k] = *(const PG8_LAS bf16x8*)(lds + PG8_SA(b, h) + aoff + m * 2048 + k * 1024); } while (0)
; #define PG8_LDB(dst, b, h) do { _Pragma("unroll") for (int n = 0; n < 2; ++n) _Pragma("unroll") for (int k = 0; k < 2; ++k) dst[n][k] = *(const PG8_LAS bf16x8*)(lds + PG8_SB(b, h) + boff + n * 2048 + k * 1024); } while (0)
; #define PG8_MMA(ai, bj, At, Bt) do { __builtin_amdgcn_s_setprio(1); _Pragma("unroll") for (int m = 0; m < 4; ++m) _Pragma("unroll") for (int n = 0; n < 2; ++n) _Pragma("unroll") for (int k = 0; k < 2; ++k) \
;     acc[ai][bj][m][n] = __builtin_amdgcn_mfma_f32_16x16x32_bf16(Bt[n][k], At[m][k], acc[ai][bj][m][n], 0, 0, 0); __builtin_amdgcn_s_setprio(0); } while (0)
; #define PG8_WAIT_V(n) asm volatile("s_waitcnt vmcnt(" #n ")" ::: "memory")
; #define PG8_WAIT_L(n) asm volatile("s_waitcnt lgkmcnt(" #n ")" ::: "memory")
; #define PG8_BAR __builtin_amdgcn_s_barrier()
; #define PG8_SCHED __builtin_amdgcn_sched_barrier(0)
; template <class Epi>
; DI void gemm_phase(PG8_LAS unsigned char* lds, const Gemm g, const StaticOrder& S, const Epi& E, const int wv) {
;     ...
;     for (int t = 0; t < nt; t += 2) {
;       const bool last = (t == nt - 2);
;       const char* a1 = cA + (size_t)(t + 1) * kstep;
;       const char* a2 = last ? nA : cA + (size_t)(t + 2) * kstep; const char* b2 = last ? nB : cB + (size_t)(t + 2) * kstep;
;       const char* a3 = a2 + kstep; const char* b3 = b2 + kstep;
;       PG8_LDB(B0, 0, 0); PG8_SCHED; PG8_LDA(At, 0, 0); PG8_STAGE(PG8_SA(1, 1), a1 + hstep, voffA);
;       PG8_WAIT_L(8); PG8_BAR; PG8_WAIT_L(0); PG8_MMA(0, 0, At, B0); PG8_BAR; PG8_SCHED;
;       PG8_LDB(B1, 0, 1); PG8_STAGE(PG8_SB(0, 0), b2, voffB);
;       PG8_BAR; PG8_WAIT_L(0); PG8_MMA(0, 1, At, B1); PG8_BAR;
;       PG8_LDA(At, 0, 1); PG8_STAGE(PG8_SA(0, 0), a2, voffA);
;       PG8_BAR; PG8_WAIT_L(0); PG8_MMA(1, 0, At, B0); PG8_BAR; PG8_SCHED;
;       PG8_STAGE(PG8_SB(0, 1), b2 + hstep, voffB);
;       PG8_WAIT_V(6); PG8_BAR; PG8_MMA(1, 1, At, B1); PG8_BAR;
.LBB0_1439:
	ds_read_b128 v[142:145], v151
	ds_read_b128 v[154:157], v151 offset:1024
	ds_read_b128 v[158:161], v151 offset:2048
	ds_read_b128 v[162:165], v151 offset:3072
	s_add_u32 s16, s14, 0x100
	s_addc_u32 s17, s15, 0
	s_cmp_eq_u32 s47, 40
	s_cselect_b32 s21, s11, s17
	s_cselect_b32 s20, s10, s16
	s_cselect_b32 s19, s1, s46
	s_cselect_b32 s18, s0, s45
	v_lshl_add_u64 v[146:147], s[14:15], 0, v[136:137]
	s_add_i32 m0, s30, 0xc000
	ds_read_b128 v[166:169], v152
	ds_read_b128 v[170:173], v152 offset:1024
	ds_read_b128 v[174:177], v152 offset:2048
	ds_read_b128 v[178:181], v152 offset:3072
	ds_read_b128 v[182:185], v152 offset:4096
	ds_read_b128 v[186:189], v152 offset:5120
	ds_read_b128 v[190:193], v152 offset:6144
	ds_read_b128 v[194:197], v152 offset:7168
	global_load_lds_dwordx4 v[146:147], off
	v_lshl_add_u64 v[146:147], s[14:15], 0, v[138:139]
	s_add_i32 m0, s30, 0xe000
	s_nop 0
	global_load_lds_dwordx4 v[146:147], off
	s_waitcnt lgkmcnt(8)
	s_barrier
	s_waitcnt lgkmcnt(0)
	s_setprio 1
	s_waitcnt lgkmcnt(0)
	v_mfma_f32_16x16x32_bf16 v[124:127], v[142:145], v[166:169], v[124:127]
	v_mfma_f32_16x16x32_bf16 v[120:123], v[158:161], v[166:169], v[120:123]
	v_mfma_f32_16x16x32_bf16 v[112:115], v[142:145], v[174:177], v[112:115]
	v_mfma_f32_16x16x32_bf16 v[104:107], v[158:161], v[174:177], v[104:107]
	v_mfma_f32_16x16x32_bf16 v[96:99], v[142:145], v[182:185], v[96:99]
	v_mfma_f32_16x16x32_bf16 v[88:91], v[158:161], v[182:185], v[88:91]
	v_mfma_f32_16x16x32_bf16 v[80:83], v[142:145], v[190:193], v[80:83]
	v_mfma_f32_16x16x32_bf16 v[72:75], v[158:161], v[190:193], v[72:75]
	v_mfma_f32_16x16x32_bf16 v[124:127], v[154:157], v[170:173], v[124:127]
	v_mfma_f32_16x16x32_bf16 v[120:123], v[162:165], v[170:173], v[120:123]
	v_mfma_f32_16x16x32_bf16 v[112:115], v[154:157], v[178:181], v[112:115]
	v_mfma_f32_16x16x32_bf16 v[104:107], v[162:165], v[178:181], v[104:107]
	v_mfma_f32_16x16x32_bf16 v[96:99], v[154:157], v[186:189], v[96:99]
	v_mfma_f32_16x16x32_bf16 v[88:91], v[162:165], v[186:189], v[88:91]
	v_mfma_f32_16x16x32_bf16 v[80:83], v[154:157], v[194:197], v[80:83]
	v_mfma_f32_16x16x32_bf16 v[72:75], v[162:165], v[194:197], v[72:75]
	s_setprio 0
	s_barrier
	s_add_i32 s14, s39, s27
	v_lshl_add_u64 v[146:147], s[18:19], 0, v[132:133]
	s_mov_b32 m0, s14
	ds_read_b128 v[198:201], v153
	ds_read_b128 v[202:205], v153 offset:1024
	ds_read_b128 v[206:209], v153 offset:2048
	ds_read_b128 v[210:213], v153 offset:3072
	global_load_lds_dwordx4 v[146:147], off
	v_lshl_add_u64 v[214:215], s[18:19], 0, v[128:129]
	s_add_i32 m0, s14, 0x2000
	s_nop 0
	global_load_lds_dwordx4 v[214:215], off
	s_barrier
	s_waitcnt lgkmcnt(0)
	s_setprio 1
	v_mfma_f32_16x16x32_bf16 v[116:119], v[198:201], v[166:169], v[116:119]
	v_mfma_f32_16x16x32_bf16 v[108:111], v[206:209], v[166:169], v[108:111]
	v_mfma_f32_16x16x32_bf16 v[100:103], v[198:201], v[174:177], v[100:103]
	v_mfma_f32_16x16x32_bf16 v[92:95], v[206:209], v[174:177], v[92:95]
	v_mfma_f32_16x16x32_bf16 v[84:87], v[198:201], v[182:185], v[84:87]
	v_mfma_f32_16x16x32_bf16 v[76:79], v[206:209], v[182:185], v[76:79]
	v_mfma_f32_16x16x32_bf16 v[68:71], v[198:201], v[190:193], v[68:71]
	v_mfma_f32_16x16x32_bf16 v[64:67], v[206:209], v[190:193], v[64:67]
	v_mfma_f32_16x16x32_bf16 v[116:119], v[202:205], v[170:173], v[116:119]
	v_mfma_f32_16x16x32_bf16 v[108:111], v[210:213], v[170:173], v[108:111]
	v_mfma_f32_16x16x32_bf16 v[100:103], v[202:205], v[178:181], v[100:103]
	v_mfma_f32_16x16x32_bf16 v[92:95], v[210:213], v[178:181], v[92:95]
	v_mfma_f32_16x16x32_bf16 v[84:87], v[202:205], v[186:189], v[84:87]
	v_mfma_f32_16x16x32_bf16 v[76:79], v[210:213], v[186:189], v[76:79]
	v_mfma_f32_16x16x32_bf16 v[68:71], v[202:205], v[194:197], v[68:71]
	v_mfma_f32_16x16x32_bf16 v[64:67], v[210:213], v[194:197], v[64:67]
	s_setprio 0
	s_mov_b32 m0, s30
	v_lshl_add_u64 v[216:217], s[20:21], 0, v[134:135]
	s_barrier
	ds_read_b128 v[166:169], v152 offset:16384
	ds_read_b128 v[170:173], v152 offset:17408
	ds_read_b128 v[174:177], v152 offset:18432
	ds_read_b128 v[178:181], v152 offset:19456
	ds_read_b128 v[182:185], v152 offset:20480
	ds_read_b128 v[186:189], v152 offset:21504
	ds_read_b128 v[190:193], v152 offset:22528
	ds_read_b128 v[194:197], v152 offset:23552
	global_load_lds_dwordx4 v[216:217], off
	v_lshl_add_u64 v[218:219], s[20:21], 0, v[130:131]
	s_mov_b32 m0, s31
	s_nop 0
	global_load_lds_dwordx4 v[218:219], off
	s_barrier
	s_waitcnt lgkmcnt(0)
	s_setprio 1
	v_mfma_f32_16x16x32_bf16 v[60:63], v[142:145], v[166:169], v[60:63]
	v_mfma_f32_16x16x32_bf16 v[56:59], v[158:161], v[166:169], v[56:59]
	v_mfma_f32_16x16x32_bf16 v[48:51], v[142:145], v[174:177], v[48:51]
	v_mfma_f32_16x16x32_bf16 v[40:43], v[158:161], v[174:177], v[40:43]
	v_mfma_f32_16x16x32_bf16 v[32:35], v[142:145], v[182:185], v[32:35]
	v_mfma_f32_16x16x32_bf16 v[24:27], v[158:161], v[182:185], v[24:27]
	v_mfma_f32_16x16x32_bf16 v[16:19], v[142:145], v[190:193], v[16:19]
	v_mfma_f32_16x16x32_bf16 v[8:11], v[158:161], v[190:193], v[8:11]
	v_mfma_f32_16x16x32_bf16 v[60:63], v[154:157], v[170:173], v[60:63]
	v_mfma_f32_16x16x32_bf16 v[56:59], v[162:165], v[170:173], v[56:59]
	v_mfma_f32_16x16x32_bf16 v[48:51], v[154:157], v[178:181], v[48:51]
	v_mfma_f32_16x16x32_bf16 v[40:43], v[162:165], v[178:181], v[40:43]
	v_mfma_f32_16x16x32_bf16 v[32:35], v[154:157], v[186:189], v[32:35]
	v_mfma_f32_16x16x32_bf16 v[24:27], v[162:165], v[186:189], v[24:27]
	v_mfma_f32_16x16x32_bf16 v[16:19], v[154:157], v[194:197], v[16:19]
	v_mfma_f32_16x16x32_bf16 v[8:11], v[162:165], v[194:197], v[8:11]
	s_setprio 0
	s_barrier
; #define PG8_STAGE(bufoff, gbase, voff) do { _Pragma("unroll") for (int _i = 0; _i < 2; ++_i) \
;     __builtin_amdgcn_global_load_lds((const unsigned*)((const char*)(gbase) + (voff)[_i]), (PG8_LAS unsigned*)(lds + (bufoff) + ldsw + _i * 8192), 16, 0, 0); } while (0)
; #define PG8_LDA(dst, b, h) do { _Pragma("unroll") for (int m = 0; m < 4; ++m) _Pragma("unroll") for (int k = 0; k < 2; ++k) dst[m][k] = *(const PG8_LAS bf16x8*)(lds + PG8_SA(b, h) + aoff + m * 2048 + k * 1024); } while (0)
; #define PG8_LDB(dst, b, h) do { _Pragma("unroll") for (int n = 0; n < 2; ++n) _Pragma("unroll") for (int k = 0; k < 2; ++k) dst[n][k] = *(const PG8_LAS bf16x8*)(lds + PG8_SB(b, h) + boff + n * 2048 + k * 1024); } while (0)
; #define PG8_MMA(ai, bj, At, Bt) do { __builtin_amdgcn_s_setprio(1); _Pragma("unroll") for (int m = 0; m < 4; ++m) _Pragma("unroll") for (int n = 0; n < 2; ++n) _Pragma("unroll") for (int k = 0; k < 2; ++k) \
;     acc[ai][bj][m][n] = __builtin_amdgcn_mfma_f32_16x16x32_bf16(Bt[n][k], At[m][k], acc[ai][bj][m][n], 0, 0, 0); __builtin_amdgcn_s_setprio(0); } while (0)
; #define PG8_WAIT_V(n) asm volatile("s_waitcnt vmcnt(" #n ")" ::: "memory")
; #define PG8_WAIT_L(n) asm volatile("s_waitcnt lgkmcnt(" #n ")" ::: "memory")
; #define PG8_BAR __builtin_amdgcn_s_barrier()
; #define PG8_SCHED __builtin_amdgcn_sched_barrier(0)
; template <class Epi>
; DI void gemm_phase(PG8_LAS unsigned char* lds, const Gemm g, const StaticOrder& S, const Epi& E, const int wv) {
;     ...
;       PG8_WAIT_V(6); PG8_BAR; PG8_MMA(1, 1, At, B1); PG8_BAR;
;       PG8_LDB(B0, 1, 0); PG8_SCHED; PG8_LDA(At, 1, 0); PG8_STAGE(PG8_SA(0, 1), a2 + hstep, voffA);
;       PG8_WAIT_L(8); PG8_BAR; PG8_WAIT_L(0); PG8_MMA(0, 0, At, B0); PG8_BAR; PG8_SCHED;
;       PG8_LDB(B1, 1, 1); PG8_STAGE(PG8_SB(1, 0), b3, voffB);
;       PG8_BAR; PG8_WAIT_L(0); PG8_MMA(0, 1, At, B1); PG8_BAR;
;       PG8_LDA(At, 1, 1); PG8_STAGE(PG8_SA(1, 0), a3, voffA);
	s_add_u32 s14, s18, 0xb0000
	s_addc_u32 s15, s19, 0
	s_add_i32 s48, s40, s27
	v_lshl_add_u64 v[142:143], s[14:15], 0, v[132:133]
	s_mov_b32 m0, s48
	s_nop 0
	global_load_lds_dwordx4 v[142:143], off
	v_lshl_add_u64 v[142:143], s[14:15], 0, v[128:129]
	s_add_i32 m0, s48, 0x2000
	s_nop 0
	global_load_lds_dwordx4 v[142:143], off
	s_waitcnt vmcnt(6)
	s_barrier
	s_setprio 1
	v_mfma_f32_16x16x32_bf16 v[52:55], v[198:201], v[166:169], v[52:55]
	v_mfma_f32_16x16x32_bf16 v[44:47], v[206:209], v[166:169], v[44:47]
	v_mfma_f32_16x16x32_bf16 v[36:39], v[198:201], v[174:177], v[36:39]
	v_mfma_f32_16x16x32_bf16 v[28:31], v[206:209], v[174:177], v[28:31]
	v_mfma_f32_16x16x32_bf16 v[20:23], v[198:201], v[182:185], v[20:23]
	v_mfma_f32_16x16x32_bf16 v[12:15], v[206:209], v[182:185], v[12:15]
	v_mfma_f32_16x16x32_bf16 v[4:7], v[198:201], v[190:193], v[4:7]
	v_mfma_f32_16x16x32_bf16 v[0:3], v[206:209], v[190:193], v[0:3]
	v_mfma_f32_16x16x32_bf16 v[52:55], v[202:205], v[170:173], v[52:55]
	v_mfma_f32_16x16x32_bf16 v[44:47], v[210:213], v[170:173], v[44:47]
	v_mfma_f32_16x16x32_bf16 v[36:39], v[202:205], v[178:181], v[36:39]
	v_mfma_f32_16x16x32_bf16 v[28:31], v[210:213], v[178:181], v[28:31]
	v_mfma_f32_16x16x32_bf16 v[20:23], v[202:205], v[186:189], v[20:23]
	v_mfma_f32_16x16x32_bf16 v[12:15], v[210:213], v[186:189], v[12:15]
	v_mfma_f32_16x16x32_bf16 v[4:7], v[202:205], v[194:197], v[4:7]
	v_mfma_f32_16x16x32_bf16 v[0:3], v[210:213], v[194:197], v[0:3]
	s_setprio 0
	s_add_i32 s48, 0, 0x18000
	v_add_u32_e32 v162, s48, v149
	s_barrier
	ds_read_b128 v[142:145], v162
	ds_read_b128 v[154:157], v162 offset:1024
	ds_read_b128 v[158:161], v162 offset:2048
	ds_read_b128 v[162:165], v162 offset:3072
	s_add_u32 s14, s20, 0xb0000
	s_addc_u32 s15, s21, 0
	s_mov_b32 m0, s33
	v_lshl_add_u64 v[198:199], s[14:15], 0, v[134:135]
	ds_read_b128 v[166:169], v152 offset:32768
	ds_read_b128 v[170:173], v152 offset:33792
	ds_read_b128 v[174:177], v152 offset:34816
	ds_read_b128 v[178:181], v152 offset:35840
	ds_read_b128 v[182:185], v152 offset:36864
	ds_read_b128 v[186:189], v152 offset:37888
	ds_read_b128 v[190:193], v152 offset:38912
	ds_read_b128 v[194:197], v152 offset:39936
	global_load_lds_dwordx4 v[198:199], off
	v_lshl_add_u64 v[198:199], s[14:15], 0, v[130:131]
	s_mov_b32 m0, s34
	s_nop 0
	global_load_lds_dwordx4 v[198:199], off
	s_waitcnt lgkmcnt(8)
	s_barrier
	s_waitcnt lgkmcnt(0)
	s_setprio 1
	s_waitcnt lgkmcnt(0)
	v_mfma_f32_16x16x32_bf16 v[124:127], v[142:145], v[166:169], v[124:127]
	v_mfma_f32_16x16x32_bf16 v[120:123], v[158:161], v[166:169], v[120:123]
	v_mfma_f32_16x16x32_bf16 v[112:115], v[142:145], v[174:177], v[112:115]
	v_mfma_f32_16x16x32_bf16 v[104:107], v[158:161], v[174:177], v[104:107]
	v_mfma_f32_16x16x32_bf16 v[96:99], v[142:145], v[182:185], v[96:99]
	v_mfma_f32_16x16x32_bf16 v[88:91], v[158:161], v[182:185], v[88:91]
	v_mfma_f32_16x16x32_bf16 v[80:83], v[142:145], v[190:193], v[80:83]
	v_mfma_f32_16x16x32_bf16 v[72:75], v[158:161], v[190:193], v[72:75]
	v_mfma_f32_16x16x32_bf16 v[124:127], v[154:157], v[170:173], v[124:127]
	v_mfma_f32_16x16x32_bf16 v[120:123], v[162:165], v[170:173], v[120:123]
	v_mfma_f32_16x16x32_bf16 v[112:115], v[154:157], v[178:181], v[112:115]
	v_mfma_f32_16x16x32_bf16 v[104:107], v[162:165], v[178:181], v[104:107]
	v_mfma_f32_16x16x32_bf16 v[96:99], v[154:157], v[186:189], v[96:99]
	v_mfma_f32_16x16x32_bf16 v[88:91], v[162:165], v[186:189], v[88:91]
	v_mfma_f32_16x16x32_bf16 v[80:83], v[154:157], v[194:197], v[80:83]
	v_mfma_f32_16x16x32_bf16 v[72:75], v[162:165], v[194:197], v[72:75]
	s_setprio 0
	s_barrier
	s_add_i32 s20, 0, 0x1c000
	s_add_i32 s14, s48, s27
	v_add_u32_e32 v210, s20, v149
	v_lshl_add_u64 v[146:147], v[146:147], 0, s[6:7]
	s_mov_b32 m0, s14
	ds_read_b128 v[198:201], v210
	ds_read_b128 v[202:205], v210 offset:1024
	ds_read_b128 v[206:209], v210 offset:2048
	ds_read_b128 v[210:213], v210 offset:3072
	global_load_lds_dwordx4 v[146:147], off
	v_lshl_add_u64 v[146:147], v[214:215], 0, s[6:7]
	s_add_i32 m0, s14, 0x2000
	s_nop 0
	global_load_lds_dwordx4 v[146:147], off
	s_barrier
	s_waitcnt lgkmcnt(0)
	s_setprio 1
	s_waitcnt lgkmcnt(0)
	v_mfma_f32_16x16x32_bf16 v[116:119], v[198:201], v[166:169], v[116:119]
	v_mfma_f32_16x16x32_bf16 v[108:111], v[206:209], v[166:169], v[108:111]
	v_mfma_f32_16x16x32_bf16 v[100:103], v[198:201], v[174:177], v[100:103]
	v_mfma_f32_16x16x32_bf16 v[92:95], v[206:209], v[174:177], v[92:95]
	v_mfma_f32_16x16x32_bf16 v[84:87], v[198:201], v[182:185], v[84:87]
	v_mfma_f32_16x16x32_bf16 v[76:79], v[206:209], v[182:185], v[76:79]
	v_mfma_f32_16x16x32_bf16 v[68:71], v[198:201], v[190:193], v[68:71]
	v_mfma_f32_16x16x32_bf16 v[64:67], v[206:209], v[190:193], v[64:67]
	v_mfma_f32_16x16x32_bf16 v[116:119], v[202:205], v[170:173], v[116:119]
	v_mfma_f32_16x16x32_bf16 v[108:111], v[210:213], v[170:173], v[108:111]
	v_mfma_f32_16x16x32_bf16 v[100:103], v[202:205], v[178:181], v[100:103]
	v_mfma_f32_16x16x32_bf16 v[92:95], v[210:213], v[178:181], v[92:95]
	v_mfma_f32_16x16x32_bf16 v[84:87], v[202:205], v[186:189], v[84:87]
	v_mfma_f32_16x16x32_bf16 v[76:79], v[210:213], v[186:189], v[76:79]
	v_mfma_f32_16x16x32_bf16 v[68:71], v[202:205], v[194:197], v[68:71]
	v_mfma_f32_16x16x32_bf16 v[64:67], v[210:213], v[194:197], v[64:67]
	s_setprio 0
	s_mov_b32 m0, s36
	v_lshl_add_u64 v[146:147], v[216:217], 0, s[6:7]
	s_barrier
	ds_read_b128 v[166:169], v152 offset:49152
	ds_read_b128 v[170:173], v152 offset:50176
	ds_read_b128 v[174:177], v152 offset:51200
	ds_read_b128 v[178:181], v152 offset:52224
	ds_read_b128 v[182:185], v152 offset:53248
	ds_read_b128 v[186:189], v152 offset:54272
	ds_read_b128 v[190:193], v152 offset:55296
	ds_read_b128 v[194:197], v152 offset:56320
	global_load_lds_dwordx4 v[146:147], off
	v_lshl_add_u64 v[146:147], v[218:219], 0, s[6:7]
	s_mov_b32 m0, s37
	s_nop 0
	global_load_lds_dwordx4 v[146:147], off
	s_barrier
; #define PG8_STAGE(bufoff, gbase, voff) do { _Pragma("unroll") for (int _i = 0; _i < 2; ++_i) \
;     __builtin_amdgcn_global_load_lds((const unsigned*)((const char*)(gbase) + (voff)[_i]), (PG8_LAS unsigned*)(lds + (bufoff) + ldsw + _i * 8192), 16, 0, 0); } while (0)
; #define PG8_MMA(ai, bj, At, Bt) do { __builtin_amdgcn_s_setprio(1); _Pragma("unroll") for (int m = 0; m < 4; ++m) _Pragma("unroll") for (int n = 0; n < 2; ++n) _Pragma("unroll") for (int k = 0; k < 2; ++k) \
;     acc[ai][bj][m][n] = __builtin_amdgcn_mfma_f32_16x16x32_bf16(Bt[n][k], At[m][k], acc[ai][bj][m][n], 0, 0, 0); __builtin_amdgcn_s_setprio(0); } while (0)
; #define PG8_WAIT_V(n) asm volatile("s_waitcnt vmcnt(" #n ")" ::: "memory")
; #define PG8_WAIT_L(n) asm volatile("s_waitcnt lgkmcnt(" #n ")" ::: "memory")
; #define PG8_BAR __builtin_amdgcn_s_barrier()
; #define PG8_SCHED __builtin_amdgcn_sched_barrier(0)
; #define EPI_ROWS_BEGIN() \
;   _Pragma("unroll") for (int ai = 0; ai < 2; ++ai) { if (u.pm * 256 + ai * 128 >= T) continue;
; template <class Epi>
; DI void gemm_phase(PG8_LAS unsigned char* lds, const Gemm g, const StaticOrder& S, const Epi& E, const int wv) {
;     ...
;       PG8_BAR; PG8_WAIT_L(0); PG8_MMA(1, 0, At, B0); PG8_BAR; PG8_SCHED;
;       PG8_STAGE(PG8_SB(1, 1), b3 + hstep, voffB);
;       PG8_WAIT_V(6); PG8_BAR; PG8_MMA(1, 1, At, B1); PG8_BAR;
;     }
;   DI void operator()(AccRef acc, const pg8::Unit& u, int wr, int wc, int fr, int fq) const {
;     const int row0 = u.pm * 256 + wr * 64 + fr, col0 = u.pn * 256 + wc * 32 + 8 * fq;
;     EPI_ROWS_BEGIN()
	s_waitcnt lgkmcnt(0)
	s_setprio 1
	v_mfma_f32_16x16x32_bf16 v[60:63], v[142:145], v[166:169], v[60:63]
	v_mfma_f32_16x16x32_bf16 v[56:59], v[158:161], v[166:169], v[56:59]
	v_mfma_f32_16x16x32_bf16 v[48:51], v[142:145], v[174:177], v[48:51]
	v_mfma_f32_16x16x32_bf16 v[40:43], v[158:161], v[174:177], v[40:43]
	v_mfma_f32_16x16x32_bf16 v[32:35], v[142:145], v[182:185], v[32:35]
	v_mfma_f32_16x16x32_bf16 v[24:27], v[158:161], v[182:185], v[24:27]
	v_mfma_f32_16x16x32_bf16 v[16:19], v[142:145], v[190:193], v[16:19]
	v_mfma_f32_16x16x32_bf16 v[8:11], v[158:161], v[190:193], v[8:11]
	v_mfma_f32_16x16x32_bf16 v[60:63], v[154:157], v[170:173], v[60:63]
	v_mfma_f32_16x16x32_bf16 v[56:59], v[162:165], v[170:173], v[56:59]
	v_mfma_f32_16x16x32_bf16 v[48:51], v[154:157], v[178:181], v[48:51]
	v_mfma_f32_16x16x32_bf16 v[40:43], v[162:165], v[178:181], v[40:43]
	v_mfma_f32_16x16x32_bf16 v[32:35], v[154:157], v[186:189], v[32:35]
	v_mfma_f32_16x16x32_bf16 v[24:27], v[162:165], v[186:189], v[24:27]
	v_mfma_f32_16x16x32_bf16 v[16:19], v[154:157], v[194:197], v[16:19]
	v_mfma_f32_16x16x32_bf16 v[8:11], v[162:165], v[194:197], v[8:11]
	s_setprio 0
	s_barrier
	s_add_u32 s14, s18, 0xb0080
	s_addc_u32 s15, s19, 0
	s_add_i32 s18, s20, s27
	v_lshl_add_u64 v[142:143], s[14:15], 0, v[132:133]
	s_mov_b32 m0, s18
	s_nop 0
	global_load_lds_dwordx4 v[142:143], off
	v_lshl_add_u64 v[142:143], s[14:15], 0, v[128:129]
	s_add_i32 m0, s18, 0x2000
	s_nop 0
	global_load_lds_dwordx4 v[142:143], off
	s_waitcnt vmcnt(6)
	s_barrier
	s_setprio 1
	v_mfma_f32_16x16x32_bf16 v[52:55], v[198:201], v[166:169], v[52:55]
	v_mfma_f32_16x16x32_bf16 v[44:47], v[206:209], v[166:169], v[44:47]
	v_mfma_f32_16x16x32_bf16 v[36:39], v[198:201], v[174:177], v[36:39]
	v_mfma_f32_16x16x32_bf16 v[28:31], v[206:209], v[174:177], v[28:31]
	v_mfma_f32_16x16x32_bf16 v[20:23], v[198:201], v[182:185], v[20:23]
	v_mfma_f32_16x16x32_bf16 v[12:15], v[206:209], v[182:185], v[12:15]
	v_mfma_f32_16x16x32_bf16 v[4:7], v[198:201], v[190:193], v[4:7]
	v_mfma_f32_16x16x32_bf16 v[0:3], v[206:209], v[190:193], v[0:3]
	v_mfma_f32_16x16x32_bf16 v[52:55], v[202:205], v[170:173], v[52:55]
	v_mfma_f32_16x16x32_bf16 v[44:47], v[210:213], v[170:173], v[44:47]
	v_mfma_f32_16x16x32_bf16 v[36:39], v[202:205], v[178:181], v[36:39]
	v_mfma_f32_16x16x32_bf16 v[28:31], v[210:213], v[178:181], v[28:31]
	v_mfma_f32_16x16x32_bf16 v[20:23], v[202:205], v[186:189], v[20:23]
	v_mfma_f32_16x16x32_bf16 v[12:15], v[210:213], v[186:189], v[12:15]
	v_mfma_f32_16x16x32_bf16 v[4:7], v[202:205], v[194:197], v[4:7]
	v_mfma_f32_16x16x32_bf16 v[0:3], v[210:213], v[194:197], v[0:3]
	s_setprio 0
	s_add_i32 s47, s47, 2
	s_add_u32 s45, s45, 0x100
	s_addc_u32 s46, s46, 0
	s_cmp_gt_u32 s47, 41
	s_mov_b64 s[14:15], s[16:17]
	s_barrier
	s_cbranch_scc0 .LBB0_1439
	v_lshl_or_b32 v146, s44, 8, v150
	v_ashrrev_i32_e32 v147, 31, v146
	v_lshl_add_u32 v144, s43, 8, v148
	s_cmpk_gt_i32 s43, 0x181
	v_lshlrev_b64 v[142:143], 2, v[146:147]
	v_lshl_add_u64 v[146:147], v[146:147], 1, s[2:3]
	s_cbranch_scc1 .LBB0_1442
; DI float bf_lo(unsigned u) { return __uint_as_float(u << 16); }
; DI float bf_hi(unsigned u) { return __uint_as_float(u & 0xffff0000u); }
;   DI void operator()(AccRef acc, const pg8::Unit& u, int wr, int wc, int fr, int fq) const {
;     ...
;         u32x4 rb[4][2];
; #pragma unroll
;         for (int m = 0; m < 4; ++m)
; #pragma unroll
;           for (int bj = 0; bj < 2; ++bj) {
;             const int rr = row0 + ai * 128 + m * 16;
;             const int sr = (MODE == 3) ? rr + NMETA * ((rr >> 12) + 1) : rr;
;             rb[m][bj] = *(const u32x4*)(hsrc + (size_t)sr * DM + col0 + bj * 128);
;           }
; #pragma unroll
;         for (int m = 0; m < 4; ++m)
; #pragma unroll
;           for (int bj = 0; bj < 2; ++bj) {
;             r[m][bj][0] = f32x4{bf_lo(rb[m][bj][0]), bf_hi(rb[m][bj][0]), bf_lo(rb[m][bj][1]), bf_hi(rb[m][bj][1])};
;             r[m][bj][1] = f32x4{bf_lo(rb[m][bj][2]), bf_hi(rb[m][bj][2]), bf_lo(rb[m][bj][3]), bf_hi(rb[m][bj][3])};
;           }
;       }
; #pragma unroll
;       for (int m = 0; m < 4; ++m) {
;         const int row = row0 + ai * 128 + m * 16;
;         if constexpr (MODE == 4) {
;           float* dst = P.out + (size_t)row * DM + col0;
; #pragma unroll
;           for (int bj = 0; bj < 2; ++bj) {
;             *(f32x4*)(dst + bj * 128) = r[m][bj][0] + acc[ai][bj][m][0];
;             *(f32x4*)(dst + bj * 128 + 4) = r[m][bj][1] + acc[ai][bj][m][1];
;           }
	v_ashrrev_i32_e32 v145, 31, v144
	v_lshlrev_b64 v[154:155], 11, v[144:145]
	v_lshl_add_u64 v[158:159], v[146:147], 0, v[154:155]
	v_or_b32_e32 v186, 16, v144
	global_load_dwordx4 v[154:157], v[158:159], off
	s_nop 0
	global_load_dwordx4 v[158:161], v[158:159], off offset:256
	v_ashrrev_i32_e32 v187, 31, v186
	v_lshlrev_b64 v[162:163], 11, v[186:187]
	v_lshl_add_u64 v[166:167], v[146:147], 0, v[162:163]
	v_or_b32_e32 v188, 32, v144
	global_load_dwordx4 v[162:165], v[166:167], off
	s_nop 0
	global_load_dwordx4 v[166:169], v[166:167], off offset:256
	v_ashrrev_i32_e32 v189, 31, v188
	v_lshlrev_b64 v[170:171], 11, v[188:189]
	v_lshl_add_u64 v[174:175], v[146:147], 0, v[170:171]
	v_or_b32_e32 v190, 48, v144
	global_load_dwordx4 v[170:173], v[174:175], off
	s_nop 0
	global_load_dwordx4 v[174:177], v[174:175], off offset:256
	v_ashrrev_i32_e32 v191, 31, v190
	v_lshlrev_b64 v[178:179], 11, v[190:191]
	v_lshl_add_u64 v[182:183], v[146:147], 0, v[178:179]
	global_load_dwordx4 v[178:181], v[182:183], off
	s_nop 0
	global_load_dwordx4 v[182:185], v[182:183], off offset:256
	v_lshlrev_b64 v[224:225], 12, v[144:145]
	v_lshl_add_u64 v[224:225], s[4:5], 0, v[224:225]
	v_lshl_add_u64 v[224:225], v[224:225], 0, v[142:143]
	s_waitcnt vmcnt(0)
	v_lshlrev_b32_e32 v192, 16, v154
	v_lshlrev_b32_e32 v198, 16, v160
	v_and_b32_e32 v199, 0xffff0000, v160
	v_lshlrev_b32_e32 v160, 16, v161
	v_and_b32_e32 v161, 0xffff0000, v161
	v_pk_add_f32 v[110:111], v[110:111], v[160:161]
	v_pk_add_f32 v[108:109], v[108:109], v[198:199]
	v_lshlrev_b32_e32 v196, 16, v158
	v_and_b32_e32 v197, 0xffff0000, v158
	v_lshlrev_b32_e32 v158, 16, v159
	v_and_b32_e32 v159, 0xffff0000, v159
	global_store_dwordx4 v[224:225], v[108:111], off offset:528
	v_lshlrev_b32_e32 v206, 16, v168
	v_and_b32_e32 v207, 0xffff0000, v168
	v_lshlrev_b64 v[108:109], 12, v[186:187]
	v_lshlrev_b32_e32 v168, 16, v169
	v_and_b32_e32 v169, 0xffff0000, v169
	v_pk_add_f32 v[118:119], v[118:119], v[158:159]
	v_pk_add_f32 v[116:117], v[116:117], v[196:197]
	v_lshl_add_u64 v[108:109], s[4:5], 0, v[108:109]
	global_store_dwordx4 v[224:225], v[116:119], off offset:512
	v_pk_add_f32 v[94:95], v[94:95], v[168:169]
	v_pk_add_f32 v[92:93], v[92:93], v[206:207]
	v_lshl_add_u64 v[116:117], v[108:109], 0, v[142:143]
	v_lshlrev_b32_e32 v204, 16, v166
	v_and_b32_e32 v205, 0xffff0000, v166
	v_lshlrev_b32_e32 v166, 16, v167
	v_and_b32_e32 v167, 0xffff0000, v167
	global_store_dwordx4 v[116:117], v[92:95], off offset:528
	v_lshlrev_b32_e32 v214, 16, v176
	v_and_b32_e32 v215, 0xffff0000, v176
	v_lshlrev_b64 v[92:93], 12, v[188:189]
	v_lshlrev_b32_e32 v176, 16, v177
	v_and_b32_e32 v177, 0xffff0000, v177
	v_pk_add_f32 v[102:103], v[102:103], v[166:167]
	v_pk_add_f32 v[100:101], v[100:101], v[204:205]
	v_lshl_add_u64 v[92:93], s[4:5], 0, v[92:93]
	global_store_dwordx4 v[116:117], v[100:103], off offset:512
	v_pk_add_f32 v[78:79], v[78:79], v[176:177]
	v_pk_add_f32 v[76:77], v[76:77], v[214:215]
	v_lshl_add_u64 v[100:101], v[92:93], 0, v[142:143]
	v_lshlrev_b32_e32 v212, 16, v174
	v_and_b32_e32 v213, 0xffff0000, v174
	v_lshlrev_b32_e32 v174, 16, v175
	v_and_b32_e32 v175, 0xffff0000, v175
	global_store_dwordx4 v[100:101], v[76:79], off offset:528
	v_and_b32_e32 v193, 0xffff0000, v154
	v_lshlrev_b32_e32 v154, 16, v155
	v_lshlrev_b64 v[76:77], 12, v[190:191]
	v_and_b32_e32 v155, 0xffff0000, v155
	v_lshlrev_b32_e32 v194, 16, v156
	v_and_b32_e32 v195, 0xffff0000, v156
	v_lshlrev_b32_e32 v156, 16, v157
	v_and_b32_e32 v157, 0xffff0000, v157
	v_lshlrev_b32_e32 v200, 16, v162
	v_and_b32_e32 v201, 0xffff0000, v162
	v_lshlrev_b32_e32 v162, 16, v163
	v_and_b32_e32 v163, 0xffff0000, v163
	v_lshlrev_b32_e32 v202, 16, v164
	v_and_b32_e32 v203, 0xffff0000, v164
	v_lshlrev_b32_e32 v164, 16, v165
	v_and_b32_e32 v165, 0xffff0000, v165
	v_lshlrev_b32_e32 v208, 16, v170
	v_and_b32_e32 v209, 0xffff0000, v170
	v_lshlrev_b32_e32 v170, 16, v171
	v_and_b32_e32 v171, 0xffff0000, v171
	v_lshlrev_b32_e32 v210, 16, v172
	v_and_b32_e32 v211, 0xffff0000, v172
	v_lshlrev_b32_e32 v172, 16, v173
	v_and_b32_e32 v173, 0xffff0000, v173
	v_lshlrev_b32_e32 v216, 16, v178
	v_and_b32_e32 v217, 0xffff0000, v178
	v_lshlrev_b32_e32 v178, 16, v179
	v_and_b32_e32 v179, 0xffff0000, v179
	v_lshlrev_b32_e32 v218, 16, v180
	v_and_b32_e32 v219, 0xffff0000, v180
	v_lshlrev_b32_e32 v180, 16, v181
	v_and_b32_e32 v181, 0xffff0000, v181
	v_lshlrev_b32_e32 v220, 16, v182
	v_and_b32_e32 v221, 0xffff0000, v182
	v_lshlrev_b32_e32 v182, 16, v183
	v_and_b32_e32 v183, 0xffff0000, v183
	v_lshlrev_b32_e32 v222, 16, v184
	v_and_b32_e32 v223, 0xffff0000, v184
	v_lshlrev_b32_e32 v184, 16, v185
	v_and_b32_e32 v185, 0xffff0000, v185
	v_pk_add_f32 v[86:87], v[86:87], v[174:175]
	v_pk_add_f32 v[84:85], v[84:85], v[212:213]
	v_lshl_add_u64 v[76:77], s[4:5], 0, v[76:77]
	v_pk_add_f32 v[126:127], v[126:127], v[154:155]
	v_pk_add_f32 v[124:125], v[124:125], v[192:193]
	v_pk_add_f32 v[122:123], v[122:123], v[156:157]
	v_pk_add_f32 v[120:121], v[120:121], v[194:195]
	v_pk_add_f32 v[110:111], v[114:115], v[162:163]
	v_pk_add_f32 v[108:109], v[112:113], v[200:201]
	v_pk_add_f32 v[106:107], v[106:107], v[164:165]
	v_pk_add_f32 v[104:105], v[104:105], v[202:203]
	v_pk_add_f32 v[94:95], v[98:99], v[170:171]
	v_pk_add_f32 v[92:93], v[96:97], v[208:209]
	v_pk_add_f32 v[90:91], v[90:91], v[172:173]
	v_pk_add_f32 v[88:89], v[88:89], v[210:211]
	global_store_dwordx4 v[100:101], v[84:87], off offset:512
	v_pk_add_f32 v[78:79], v[82:83], v[178:179]
	v_pk_add_f32 v[74:75], v[74:75], v[180:181]
	v_lshl_add_u64 v[84:85], v[76:77], 0, v[142:143]
	v_pk_add_f32 v[76:77], v[80:81], v[216:217]
	v_pk_add_f32 v[72:73], v[72:73], v[218:219]
	v_pk_add_f32 v[70:71], v[70:71], v[182:183]
	v_pk_add_f32 v[68:69], v[68:69], v[220:221]
	v_pk_add_f32 v[66:67], v[66:67], v[184:185]
	v_pk_add_f32 v[64:65], v[64:65], v[222:223]
	global_store_dwordx4 v[224:225], v[124:127], off
	global_store_dwordx4 v[224:225], v[120:123], off offset:16
	global_store_dwordx4 v[116:117], v[108:111], off
	global_store_dwordx4 v[116:117], v[104:107], off offset:16
	global_store_dwordx4 v[100:101], v[92:95], off
	global_store_dwordx4 v[100:101], v[88:91], off offset:16
	global_store_dwordx4 v[84:85], v[76:79], off
	global_store_dwordx4 v[84:85], v[72:75], off offset:16
	global_store_dwordx4 v[84:85], v[68:71], off offset:512
	global_store_dwordx4 v[84:85], v[64:67], off offset:528
